# v16 + last-unit write-through epilogue: each GEMM phase's epilogue is cloned with sc1 stores and a workgroup's final unit runs the clone, so the XCD leader's L2 writeback at the grid barrier finds the
# baseline (speedup 1.0000x reference)
.LBB0_114:
	s_and_b64 vcc, exec, s[2:3]
	s_cbranch_vccz .Lwtp1_entry
	s_cmp_gt_i32 s41, 64
	v_add_u32_e32 v163, 0x80, v154
	v_add_u32_e32 v162, 0x90, v154
	v_add_u32_e32 v161, 0xa0, v154
	v_add_u32_e32 v155, 0xb0, v154
	v_cvt_pk_bf16_f32 v130, v62, v63
	v_cvt_pk_bf16_f32 v131, v64, v65
	v_cvt_pk_bf16_f32 v132, v58, v59
	v_cvt_pk_bf16_f32 v133, v60, v61
	v_cvt_pk_bf16_f32 v126, v126, v127
	v_cvt_pk_bf16_f32 v127, v128, v129
	v_cvt_pk_bf16_f32 v128, v122, v123
	v_cvt_pk_bf16_f32 v129, v124, v125
	v_cvt_pk_bf16_f32 v122, v54, v55
	v_cvt_pk_bf16_f32 v123, v56, v57
	v_cvt_pk_bf16_f32 v124, v50, v51
	v_cvt_pk_bf16_f32 v125, v52, v53
	v_cvt_pk_bf16_f32 v118, v118, v119
	v_cvt_pk_bf16_f32 v119, v120, v121
	v_cvt_pk_bf16_f32 v120, v114, v115
	v_cvt_pk_bf16_f32 v121, v116, v117
	v_cvt_pk_bf16_f32 v114, v46, v47
	v_cvt_pk_bf16_f32 v115, v48, v49
	v_cvt_pk_bf16_f32 v116, v42, v43
	v_cvt_pk_bf16_f32 v117, v44, v45
	v_cvt_pk_bf16_f32 v110, v110, v111
	v_cvt_pk_bf16_f32 v111, v112, v113
	v_cvt_pk_bf16_f32 v112, v106, v107
	v_cvt_pk_bf16_f32 v113, v108, v109
	v_cvt_pk_bf16_f32 v106, v38, v39
	v_cvt_pk_bf16_f32 v107, v40, v41
	v_cvt_pk_bf16_f32 v108, v34, v35
	v_cvt_pk_bf16_f32 v109, v36, v37
	v_cvt_pk_bf16_f32 v102, v102, v103
	v_cvt_pk_bf16_f32 v103, v104, v105
	v_cvt_pk_bf16_f32 v104, v98, v99
	v_cvt_pk_bf16_f32 v105, v100, v101
	v_cvt_pk_bf16_f32 v98, v30, v31
	v_cvt_pk_bf16_f32 v99, v32, v33
	v_cvt_pk_bf16_f32 v100, v26, v27
	v_cvt_pk_bf16_f32 v101, v28, v29
	v_cvt_pk_bf16_f32 v94, v94, v95
	v_cvt_pk_bf16_f32 v95, v96, v97
	v_cvt_pk_bf16_f32 v96, v90, v91
	v_cvt_pk_bf16_f32 v97, v92, v93
	v_cvt_pk_bf16_f32 v90, v22, v23
	v_cvt_pk_bf16_f32 v91, v24, v25
	v_cvt_pk_bf16_f32 v92, v18, v19
	v_cvt_pk_bf16_f32 v93, v20, v21
	v_cvt_pk_bf16_f32 v86, v86, v87
	v_cvt_pk_bf16_f32 v87, v88, v89
	v_cvt_pk_bf16_f32 v88, v82, v83
	v_cvt_pk_bf16_f32 v89, v84, v85
	v_cvt_pk_bf16_f32 v82, v14, v15
	v_cvt_pk_bf16_f32 v83, v16, v17
	v_cvt_pk_bf16_f32 v84, v10, v11
	v_cvt_pk_bf16_f32 v85, v12, v13
	v_cvt_pk_bf16_f32 v78, v78, v79
	v_cvt_pk_bf16_f32 v79, v80, v81
	v_cvt_pk_bf16_f32 v80, v74, v75
	v_cvt_pk_bf16_f32 v81, v76, v77
	v_cvt_pk_bf16_f32 v74, v6, v7
	v_cvt_pk_bf16_f32 v75, v8, v9
	v_cvt_pk_bf16_f32 v76, v2, v3
	v_cvt_pk_bf16_f32 v77, v4, v5
	v_cvt_pk_bf16_f32 v70, v70, v71
	v_cvt_pk_bf16_f32 v71, v72, v73
	v_cvt_pk_bf16_f32 v72, v66, v67
	v_cvt_pk_bf16_f32 v73, v68, v69
	s_cbranch_scc1 .LBB0_116
	v_lshl_or_b32 v66, s41, 8, v157
	v_mov_b64_e32 v[68:69], s[84:85]
	v_ashrrev_i32_e32 v67, 31, v66
	v_mad_i64_i32 v[164:165], s[20:21], v154, s38, v[68:69]
	v_lshlrev_b64 v[66:67], 1, v[66:67]
	v_lshl_add_u64 v[164:165], v[164:165], 0, v[66:67]
	global_store_dwordx4 v[164:165], v[130:133], off
	global_store_dwordx4 v[164:165], v[126:129], off offset:256
	v_or_b32_e32 v164, 16, v154
	v_mad_i64_i32 v[164:165], s[20:21], v164, s38, v[68:69]
	v_lshl_add_u64 v[164:165], v[164:165], 0, v[66:67]
	global_store_dwordx4 v[164:165], v[122:125], off
	global_store_dwordx4 v[164:165], v[118:121], off offset:256
	v_or_b32_e32 v164, 32, v154
	v_mad_i64_i32 v[164:165], s[20:21], v164, s38, v[68:69]
	v_lshl_add_u64 v[164:165], v[164:165], 0, v[66:67]
	global_store_dwordx4 v[164:165], v[114:117], off
	global_store_dwordx4 v[164:165], v[110:113], off offset:256
	v_or_b32_e32 v164, 48, v154
	v_mad_i64_i32 v[164:165], s[20:21], v164, s38, v[68:69]
	v_lshl_add_u64 v[164:165], v[164:165], 0, v[66:67]
	global_store_dwordx4 v[164:165], v[106:109], off
	global_store_dwordx4 v[164:165], v[102:105], off offset:256
	v_mad_i64_i32 v[164:165], s[20:21], v163, s38, v[68:69]
	v_lshl_add_u64 v[164:165], v[164:165], 0, v[66:67]
	global_store_dwordx4 v[164:165], v[98:101], off
	global_store_dwordx4 v[164:165], v[94:97], off offset:256
	v_mad_i64_i32 v[164:165], s[20:21], v162, s38, v[68:69]
	v_lshl_add_u64 v[164:165], v[164:165], 0, v[66:67]
	global_store_dwordx4 v[164:165], v[90:93], off
	global_store_dwordx4 v[164:165], v[86:89], off offset:256
	v_mad_i64_i32 v[164:165], s[20:21], v161, s38, v[68:69]
	v_lshl_add_u64 v[164:165], v[164:165], 0, v[66:67]
	v_mad_i64_i32 v[68:69], s[20:21], v155, s38, v[68:69]
	global_store_dwordx4 v[164:165], v[82:85], off
	global_store_dwordx4 v[164:165], v[78:81], off offset:256
	v_lshl_add_u64 v[66:67], v[68:69], 0, v[66:67]
	global_store_dwordx4 v[66:67], v[74:77], off
	global_store_dwordx4 v[66:67], v[70:73], off offset:256
	s_mov_b64 s[20:21], 0

.Lwtp1_entry:
	s_cmp_gt_i32 s41, 64
	v_add_u32_e32 v163, 0x80, v154
	v_add_u32_e32 v162, 0x90, v154
	v_add_u32_e32 v161, 0xa0, v154
	v_add_u32_e32 v155, 0xb0, v154
	v_cvt_pk_bf16_f32 v130, v62, v63
	v_cvt_pk_bf16_f32 v131, v64, v65
	v_cvt_pk_bf16_f32 v132, v58, v59
	v_cvt_pk_bf16_f32 v133, v60, v61
	v_cvt_pk_bf16_f32 v126, v126, v127
	v_cvt_pk_bf16_f32 v127, v128, v129
	v_cvt_pk_bf16_f32 v128, v122, v123
	v_cvt_pk_bf16_f32 v129, v124, v125
	v_cvt_pk_bf16_f32 v122, v54, v55
	v_cvt_pk_bf16_f32 v123, v56, v57
	v_cvt_pk_bf16_f32 v124, v50, v51
	v_cvt_pk_bf16_f32 v125, v52, v53
	v_cvt_pk_bf16_f32 v118, v118, v119
	v_cvt_pk_bf16_f32 v119, v120, v121
	v_cvt_pk_bf16_f32 v120, v114, v115
	v_cvt_pk_bf16_f32 v121, v116, v117
	v_cvt_pk_bf16_f32 v114, v46, v47
	v_cvt_pk_bf16_f32 v115, v48, v49
	v_cvt_pk_bf16_f32 v116, v42, v43
	v_cvt_pk_bf16_f32 v117, v44, v45
	v_cvt_pk_bf16_f32 v110, v110, v111
	v_cvt_pk_bf16_f32 v111, v112, v113
	v_cvt_pk_bf16_f32 v112, v106, v107
	v_cvt_pk_bf16_f32 v113, v108, v109
	v_cvt_pk_bf16_f32 v106, v38, v39
	v_cvt_pk_bf16_f32 v107, v40, v41
	v_cvt_pk_bf16_f32 v108, v34, v35
	v_cvt_pk_bf16_f32 v109, v36, v37
	v_cvt_pk_bf16_f32 v102, v102, v103
	v_cvt_pk_bf16_f32 v103, v104, v105
	v_cvt_pk_bf16_f32 v104, v98, v99
	v_cvt_pk_bf16_f32 v105, v100, v101
	v_cvt_pk_bf16_f32 v98, v30, v31
	v_cvt_pk_bf16_f32 v99, v32, v33
	v_cvt_pk_bf16_f32 v100, v26, v27
	v_cvt_pk_bf16_f32 v101, v28, v29
	v_cvt_pk_bf16_f32 v94, v94, v95
	v_cvt_pk_bf16_f32 v95, v96, v97
	v_cvt_pk_bf16_f32 v96, v90, v91
	v_cvt_pk_bf16_f32 v97, v92, v93
	v_cvt_pk_bf16_f32 v90, v22, v23
	v_cvt_pk_bf16_f32 v91, v24, v25
	v_cvt_pk_bf16_f32 v92, v18, v19
	v_cvt_pk_bf16_f32 v93, v20, v21
	v_cvt_pk_bf16_f32 v86, v86, v87
	v_cvt_pk_bf16_f32 v87, v88, v89
	v_cvt_pk_bf16_f32 v88, v82, v83
	v_cvt_pk_bf16_f32 v89, v84, v85
	v_cvt_pk_bf16_f32 v82, v14, v15
	v_cvt_pk_bf16_f32 v83, v16, v17
	v_cvt_pk_bf16_f32 v84, v10, v11
	v_cvt_pk_bf16_f32 v85, v12, v13
	v_cvt_pk_bf16_f32 v78, v78, v79
	v_cvt_pk_bf16_f32 v79, v80, v81
	v_cvt_pk_bf16_f32 v80, v74, v75
	v_cvt_pk_bf16_f32 v81, v76, v77
	v_cvt_pk_bf16_f32 v74, v6, v7
	v_cvt_pk_bf16_f32 v75, v8, v9
	v_cvt_pk_bf16_f32 v76, v2, v3
	v_cvt_pk_bf16_f32 v77, v4, v5
	v_cvt_pk_bf16_f32 v70, v70, v71
	v_cvt_pk_bf16_f32 v71, v72, v73
	v_cvt_pk_bf16_f32 v72, v66, v67
	v_cvt_pk_bf16_f32 v73, v68, v69
	s_cbranch_scc1 .Lwtp1_0
	v_lshl_or_b32 v66, s41, 8, v157
	v_mov_b64_e32 v[68:69], s[84:85]
	v_ashrrev_i32_e32 v67, 31, v66
	v_mad_i64_i32 v[164:165], s[20:21], v154, s38, v[68:69]
	v_lshlrev_b64 v[66:67], 1, v[66:67]
	v_lshl_add_u64 v[164:165], v[164:165], 0, v[66:67]
	global_store_dwordx4 v[164:165], v[130:133], off sc1
	global_store_dwordx4 v[164:165], v[126:129], off offset:256 sc1
	v_or_b32_e32 v164, 16, v154
	v_mad_i64_i32 v[164:165], s[20:21], v164, s38, v[68:69]
	v_lshl_add_u64 v[164:165], v[164:165], 0, v[66:67]
	global_store_dwordx4 v[164:165], v[122:125], off sc1
	global_store_dwordx4 v[164:165], v[118:121], off offset:256 sc1
	v_or_b32_e32 v164, 32, v154
	v_mad_i64_i32 v[164:165], s[20:21], v164, s38, v[68:69]
	v_lshl_add_u64 v[164:165], v[164:165], 0, v[66:67]
	global_store_dwordx4 v[164:165], v[114:117], off sc1
	global_store_dwordx4 v[164:165], v[110:113], off offset:256 sc1
	v_or_b32_e32 v164, 48, v154
	v_mad_i64_i32 v[164:165], s[20:21], v164, s38, v[68:69]
	v_lshl_add_u64 v[164:165], v[164:165], 0, v[66:67]
	global_store_dwordx4 v[164:165], v[106:109], off sc1
	global_store_dwordx4 v[164:165], v[102:105], off offset:256 sc1
	v_mad_i64_i32 v[164:165], s[20:21], v163, s38, v[68:69]
	v_lshl_add_u64 v[164:165], v[164:165], 0, v[66:67]
	global_store_dwordx4 v[164:165], v[98:101], off sc1
	global_store_dwordx4 v[164:165], v[94:97], off offset:256 sc1
	v_mad_i64_i32 v[164:165], s[20:21], v162, s38, v[68:69]
	v_lshl_add_u64 v[164:165], v[164:165], 0, v[66:67]
	global_store_dwordx4 v[164:165], v[90:93], off sc1
	global_store_dwordx4 v[164:165], v[86:89], off offset:256 sc1
	v_mad_i64_i32 v[164:165], s[20:21], v161, s38, v[68:69]
	v_lshl_add_u64 v[164:165], v[164:165], 0, v[66:67]
	v_mad_i64_i32 v[68:69], s[20:21], v155, s38, v[68:69]
	global_store_dwordx4 v[164:165], v[82:85], off sc1
	global_store_dwordx4 v[164:165], v[78:81], off offset:256 sc1
	v_lshl_add_u64 v[66:67], v[68:69], 0, v[66:67]
	global_store_dwordx4 v[66:67], v[74:77], off sc1
	global_store_dwordx4 v[66:67], v[70:73], off offset:256 sc1
	s_mov_b64 s[20:21], 0
.Lwtp1_0:
	s_andn2_b64 vcc, exec, s[20:21]
	s_cbranch_vccnz .LBB0_118
	s_add_i32 s4, s41, 0xffffffbf
	s_mul_hi_u32 s13, s4, 0xaaaaaaab
	s_lshr_b32 s13, s13, 3
	s_mul_i32 s15, s13, 12
	s_sub_i32 s15, s4, s15
	s_lshr_b32 s15, s15, 2
	s_mul_i32 s13, s13, 3
	s_lshl_b32 s4, s4, 1
	s_add_i32 s13, s13, s15
	s_and_b32 s4, s4, 6
	s_lshl_b32 s13, s13, 3
	s_lshl_b32 s22, s15, 1
	s_or_b32 s4, s13, s4
	s_lshl_b64 s[20:21], s[4:5], 21
	s_sub_i32 s4, 13, s22
	v_lshlrev_b32_e32 v68, s4, v154
	v_and_b32_e32 v68, 0x1ffe, v68
	v_ashrrev_i32_e32 v69, s22, v154
	v_add_u32_e32 v68, v68, v69
	v_ashrrev_i32_e32 v69, 31, v68
	v_lshl_add_u64 v[66:67], v[142:143], 0, s[20:21]
	v_lshlrev_b64 v[68:69], 8, v[68:69]
	v_lshl_add_u64 v[68:69], v[66:67], 0, v[68:69]
	global_store_dwordx4 v[68:69], v[130:133], off sc1
	v_add_co_u32_e32 v68, vcc, s39, v68
	s_nop 1
	v_addc_co_u32_e32 v69, vcc, 0, v69, vcc
	global_store_dwordx4 v[68:69], v[126:129], off sc1
	v_or_b32_e32 v68, 16, v154
	v_lshlrev_b32_e32 v69, s4, v68
	v_and_b32_e32 v69, 0x1ffe, v69
	v_ashrrev_i32_e32 v68, s22, v68
	v_add_u32_e32 v68, v69, v68
	v_ashrrev_i32_e32 v69, 31, v68
	v_lshlrev_b64 v[68:69], 8, v[68:69]
	v_lshl_add_u64 v[68:69], v[66:67], 0, v[68:69]
	global_store_dwordx4 v[68:69], v[122:125], off sc1
	v_add_co_u32_e32 v68, vcc, s39, v68
	s_nop 1
	v_addc_co_u32_e32 v69, vcc, 0, v69, vcc
	global_store_dwordx4 v[68:69], v[118:121], off sc1
	v_or_b32_e32 v68, 32, v154
	v_lshlrev_b32_e32 v69, s4, v68
	v_and_b32_e32 v69, 0x1ffe, v69
	v_ashrrev_i32_e32 v68, s22, v68
	v_add_u32_e32 v68, v69, v68
	v_ashrrev_i32_e32 v69, 31, v68
	v_lshlrev_b64 v[68:69], 8, v[68:69]
	v_lshl_add_u64 v[68:69], v[66:67], 0, v[68:69]
	global_store_dwordx4 v[68:69], v[114:117], off sc1
	v_add_co_u32_e32 v68, vcc, s39, v68
	s_nop 1
	v_addc_co_u32_e32 v69, vcc, 0, v69, vcc
	global_store_dwordx4 v[68:69], v[110:113], off sc1
	v_or_b32_e32 v68, 48, v154
	v_lshlrev_b32_e32 v69, s4, v68
	v_and_b32_e32 v69, 0x1ffe, v69
	v_ashrrev_i32_e32 v68, s22, v68
	v_add_u32_e32 v68, v69, v68
	v_ashrrev_i32_e32 v69, 31, v68
	v_lshlrev_b64 v[68:69], 8, v[68:69]
	v_lshl_add_u64 v[68:69], v[66:67], 0, v[68:69]
	global_store_dwordx4 v[68:69], v[106:109], off sc1
	v_add_co_u32_e32 v68, vcc, s39, v68
	s_nop 1
	v_addc_co_u32_e32 v69, vcc, 0, v69, vcc
	global_store_dwordx4 v[68:69], v[102:105], off sc1
	v_lshlrev_b32_e32 v68, s4, v163
	v_and_b32_e32 v68, 0x1ffe, v68
	v_ashrrev_i32_e32 v69, s22, v163
	v_add_u32_e32 v68, v68, v69
	v_ashrrev_i32_e32 v69, 31, v68
	v_lshlrev_b64 v[68:69], 8, v[68:69]
	v_lshl_add_u64 v[68:69], v[66:67], 0, v[68:69]
	global_store_dwordx4 v[68:69], v[98:101], off sc1
	v_add_co_u32_e32 v68, vcc, s39, v68
	s_nop 1
	v_addc_co_u32_e32 v69, vcc, 0, v69, vcc
	global_store_dwordx4 v[68:69], v[94:97], off sc1
	v_lshlrev_b32_e32 v68, s4, v162
	v_and_b32_e32 v68, 0x1ffe, v68
	v_ashrrev_i32_e32 v69, s22, v162
	v_add_u32_e32 v68, v68, v69
	v_ashrrev_i32_e32 v69, 31, v68
	v_lshlrev_b64 v[68:69], 8, v[68:69]
	v_lshl_add_u64 v[68:69], v[66:67], 0, v[68:69]
	global_store_dwordx4 v[68:69], v[90:93], off sc1
	v_add_co_u32_e32 v68, vcc, s39, v68
	s_nop 1
	v_addc_co_u32_e32 v69, vcc, 0, v69, vcc
	global_store_dwordx4 v[68:69], v[86:89], off sc1
	v_lshlrev_b32_e32 v68, s4, v161
	v_and_b32_e32 v68, 0x1ffe, v68
	v_ashrrev_i32_e32 v69, s22, v161
	v_add_u32_e32 v68, v68, v69
	v_ashrrev_i32_e32 v69, 31, v68
	v_lshlrev_b64 v[68:69], 8, v[68:69]
	v_lshl_add_u64 v[68:69], v[66:67], 0, v[68:69]
	global_store_dwordx4 v[68:69], v[82:85], off sc1
	v_add_co_u32_e32 v68, vcc, s39, v68
	s_nop 1
	v_addc_co_u32_e32 v69, vcc, 0, v69, vcc
	global_store_dwordx4 v[68:69], v[78:81], off sc1
	v_lshlrev_b32_e32 v68, s4, v155
	v_and_b32_e32 v68, 0x1ffe, v68
	v_ashrrev_i32_e32 v69, s22, v155
	v_add_u32_e32 v68, v68, v69
	v_ashrrev_i32_e32 v69, 31, v68
	v_lshlrev_b64 v[68:69], 8, v[68:69]
	v_lshl_add_u64 v[66:67], v[66:67], 0, v[68:69]
	global_store_dwordx4 v[66:67], v[74:77], off sc1
	v_add_co_u32_e32 v66, vcc, 0x200000, v66
	s_nop 1
	v_addc_co_u32_e32 v67, vcc, 0, v67, vcc
	global_store_dwordx4 v[66:67], v[70:73], off sc1
	s_branch .LBB0_118

.LBB0_379:
	s_cmp_lg_u32 s79, -1
	v_lshl_add_u32 v154, s6, 8, v1
	v_readlane_b32 s81, v251, 56
	s_mov_b64 s[26:27], -1
	s_cbranch_scc0 .LBB0_385
	s_and_b64 vcc, exec, s[2:3]
	s_cbranch_vccz .Lwtp4_entry
	s_cmp_gt_i32 s79, 32
	v_add_u32_e32 v164, 0x80, v154
	v_add_u32_e32 v163, 0x90, v154
	v_add_u32_e32 v162, 0xa0, v154
	v_add_u32_e32 v155, 0xb0, v154
	v_cvt_pk_bf16_f32 v130, v62, v63
	v_cvt_pk_bf16_f32 v131, v64, v65
	v_cvt_pk_bf16_f32 v132, v58, v59
	v_cvt_pk_bf16_f32 v133, v60, v61
	v_cvt_pk_bf16_f32 v126, v126, v127
	v_cvt_pk_bf16_f32 v127, v128, v129
	v_cvt_pk_bf16_f32 v128, v122, v123
	v_cvt_pk_bf16_f32 v129, v124, v125
	v_cvt_pk_bf16_f32 v122, v54, v55
	v_cvt_pk_bf16_f32 v123, v56, v57
	v_cvt_pk_bf16_f32 v124, v50, v51
	v_cvt_pk_bf16_f32 v125, v52, v53
	v_cvt_pk_bf16_f32 v118, v118, v119
	v_cvt_pk_bf16_f32 v119, v120, v121
	v_cvt_pk_bf16_f32 v120, v114, v115
	v_cvt_pk_bf16_f32 v121, v116, v117
	v_cvt_pk_bf16_f32 v114, v46, v47
	v_cvt_pk_bf16_f32 v115, v48, v49
	v_cvt_pk_bf16_f32 v116, v42, v43
	v_cvt_pk_bf16_f32 v117, v44, v45
	v_cvt_pk_bf16_f32 v110, v110, v111
	v_cvt_pk_bf16_f32 v111, v112, v113
	v_cvt_pk_bf16_f32 v112, v106, v107
	v_cvt_pk_bf16_f32 v113, v108, v109
	v_cvt_pk_bf16_f32 v106, v38, v39
	v_cvt_pk_bf16_f32 v107, v40, v41
	v_cvt_pk_bf16_f32 v108, v34, v35
	v_cvt_pk_bf16_f32 v109, v36, v37
	v_cvt_pk_bf16_f32 v102, v102, v103
	v_cvt_pk_bf16_f32 v103, v104, v105
	v_cvt_pk_bf16_f32 v104, v98, v99
	v_cvt_pk_bf16_f32 v105, v100, v101
	v_cvt_pk_bf16_f32 v98, v30, v31
	v_cvt_pk_bf16_f32 v99, v32, v33
	v_cvt_pk_bf16_f32 v100, v26, v27
	v_cvt_pk_bf16_f32 v101, v28, v29
	v_cvt_pk_bf16_f32 v94, v94, v95
	v_cvt_pk_bf16_f32 v95, v96, v97
	v_cvt_pk_bf16_f32 v96, v90, v91
	v_cvt_pk_bf16_f32 v97, v92, v93
	v_cvt_pk_bf16_f32 v90, v22, v23
	v_cvt_pk_bf16_f32 v91, v24, v25
	v_cvt_pk_bf16_f32 v92, v18, v19
	v_cvt_pk_bf16_f32 v93, v20, v21
	v_cvt_pk_bf16_f32 v86, v86, v87
	v_cvt_pk_bf16_f32 v87, v88, v89
	v_cvt_pk_bf16_f32 v88, v82, v83
	v_cvt_pk_bf16_f32 v89, v84, v85
	v_cvt_pk_bf16_f32 v82, v14, v15
	v_cvt_pk_bf16_f32 v83, v16, v17
	v_cvt_pk_bf16_f32 v84, v10, v11
	v_cvt_pk_bf16_f32 v85, v12, v13
	v_cvt_pk_bf16_f32 v78, v78, v79
	v_cvt_pk_bf16_f32 v79, v80, v81
	v_cvt_pk_bf16_f32 v80, v74, v75
	v_cvt_pk_bf16_f32 v81, v76, v77
	v_cvt_pk_bf16_f32 v74, v6, v7
	v_cvt_pk_bf16_f32 v75, v8, v9
	v_cvt_pk_bf16_f32 v76, v2, v3
	v_cvt_pk_bf16_f32 v77, v4, v5
	v_cvt_pk_bf16_f32 v70, v70, v71
	v_cvt_pk_bf16_f32 v71, v72, v73
	v_cvt_pk_bf16_f32 v72, v66, v67
	v_cvt_pk_bf16_f32 v73, v68, v69
	s_cbranch_scc1 .LBB0_382
	v_lshl_or_b32 v66, s79, 8, v158
	v_mov_b64_e32 v[68:69], s[12:13]
	v_ashrrev_i32_e32 v67, 31, v66
	v_mad_i64_i32 v[166:167], s[26:27], v154, s74, v[68:69]
	v_lshlrev_b64 v[66:67], 1, v[66:67]
	v_lshl_add_u64 v[166:167], v[166:167], 0, v[66:67]
	v_or_b32_e32 v165, 16, v154
	global_store_dwordx4 v[166:167], v[130:133], off
	global_store_dwordx4 v[166:167], v[126:129], off offset:256
	v_mad_i64_i32 v[166:167], s[26:27], v165, s74, v[68:69]
	v_lshl_add_u64 v[166:167], v[166:167], 0, v[66:67]
	v_or_b32_e32 v165, 32, v154
	global_store_dwordx4 v[166:167], v[122:125], off
	global_store_dwordx4 v[166:167], v[118:121], off offset:256
	v_mad_i64_i32 v[166:167], s[26:27], v165, s74, v[68:69]
	v_lshl_add_u64 v[166:167], v[166:167], 0, v[66:67]
	v_or_b32_e32 v165, 48, v154
	global_store_dwordx4 v[166:167], v[114:117], off
	global_store_dwordx4 v[166:167], v[110:113], off offset:256
	v_mad_i64_i32 v[166:167], s[26:27], v165, s74, v[68:69]
	v_lshl_add_u64 v[166:167], v[166:167], 0, v[66:67]
	global_store_dwordx4 v[166:167], v[106:109], off
	global_store_dwordx4 v[166:167], v[102:105], off offset:256
	v_mad_i64_i32 v[166:167], s[26:27], v164, s74, v[68:69]
	v_lshl_add_u64 v[166:167], v[166:167], 0, v[66:67]
	global_store_dwordx4 v[166:167], v[98:101], off
	global_store_dwordx4 v[166:167], v[94:97], off offset:256
	v_mad_i64_i32 v[166:167], s[26:27], v163, s74, v[68:69]
	v_lshl_add_u64 v[166:167], v[166:167], 0, v[66:67]
	global_store_dwordx4 v[166:167], v[90:93], off
	global_store_dwordx4 v[166:167], v[86:89], off offset:256
	v_mad_i64_i32 v[166:167], s[26:27], v162, s74, v[68:69]
	v_lshl_add_u64 v[166:167], v[166:167], 0, v[66:67]
	v_mad_i64_i32 v[68:69], s[26:27], v155, s74, v[68:69]
	global_store_dwordx4 v[166:167], v[82:85], off
	global_store_dwordx4 v[166:167], v[78:81], off offset:256
	v_lshl_add_u64 v[66:67], v[68:69], 0, v[66:67]
	global_store_dwordx4 v[66:67], v[74:77], off
	global_store_dwordx4 v[66:67], v[70:73], off offset:256
	s_mov_b64 s[26:27], 0

.Lwtp4_entry:
	s_cmp_gt_i32 s79, 32
	v_add_u32_e32 v164, 0x80, v154
	v_add_u32_e32 v163, 0x90, v154
	v_add_u32_e32 v162, 0xa0, v154
	v_add_u32_e32 v155, 0xb0, v154
	v_cvt_pk_bf16_f32 v130, v62, v63
	v_cvt_pk_bf16_f32 v131, v64, v65
	v_cvt_pk_bf16_f32 v132, v58, v59
	v_cvt_pk_bf16_f32 v133, v60, v61
	v_cvt_pk_bf16_f32 v126, v126, v127
	v_cvt_pk_bf16_f32 v127, v128, v129
	v_cvt_pk_bf16_f32 v128, v122, v123
	v_cvt_pk_bf16_f32 v129, v124, v125
	v_cvt_pk_bf16_f32 v122, v54, v55
	v_cvt_pk_bf16_f32 v123, v56, v57
	v_cvt_pk_bf16_f32 v124, v50, v51
	v_cvt_pk_bf16_f32 v125, v52, v53
	v_cvt_pk_bf16_f32 v118, v118, v119
	v_cvt_pk_bf16_f32 v119, v120, v121
	v_cvt_pk_bf16_f32 v120, v114, v115
	v_cvt_pk_bf16_f32 v121, v116, v117
	v_cvt_pk_bf16_f32 v114, v46, v47
	v_cvt_pk_bf16_f32 v115, v48, v49
	v_cvt_pk_bf16_f32 v116, v42, v43
	v_cvt_pk_bf16_f32 v117, v44, v45
	v_cvt_pk_bf16_f32 v110, v110, v111
	v_cvt_pk_bf16_f32 v111, v112, v113
	v_cvt_pk_bf16_f32 v112, v106, v107
	v_cvt_pk_bf16_f32 v113, v108, v109
	v_cvt_pk_bf16_f32 v106, v38, v39
	v_cvt_pk_bf16_f32 v107, v40, v41
	v_cvt_pk_bf16_f32 v108, v34, v35
	v_cvt_pk_bf16_f32 v109, v36, v37
	v_cvt_pk_bf16_f32 v102, v102, v103
	v_cvt_pk_bf16_f32 v103, v104, v105
	v_cvt_pk_bf16_f32 v104, v98, v99
	v_cvt_pk_bf16_f32 v105, v100, v101
	v_cvt_pk_bf16_f32 v98, v30, v31
	v_cvt_pk_bf16_f32 v99, v32, v33
	v_cvt_pk_bf16_f32 v100, v26, v27
	v_cvt_pk_bf16_f32 v101, v28, v29
	v_cvt_pk_bf16_f32 v94, v94, v95
	v_cvt_pk_bf16_f32 v95, v96, v97
	v_cvt_pk_bf16_f32 v96, v90, v91
	v_cvt_pk_bf16_f32 v97, v92, v93
	v_cvt_pk_bf16_f32 v90, v22, v23
	v_cvt_pk_bf16_f32 v91, v24, v25
	v_cvt_pk_bf16_f32 v92, v18, v19
	v_cvt_pk_bf16_f32 v93, v20, v21
	v_cvt_pk_bf16_f32 v86, v86, v87
	v_cvt_pk_bf16_f32 v87, v88, v89
	v_cvt_pk_bf16_f32 v88, v82, v83
	v_cvt_pk_bf16_f32 v89, v84, v85
	v_cvt_pk_bf16_f32 v82, v14, v15
	v_cvt_pk_bf16_f32 v83, v16, v17
	v_cvt_pk_bf16_f32 v84, v10, v11
	v_cvt_pk_bf16_f32 v85, v12, v13
	v_cvt_pk_bf16_f32 v78, v78, v79
	v_cvt_pk_bf16_f32 v79, v80, v81
	v_cvt_pk_bf16_f32 v80, v74, v75
	v_cvt_pk_bf16_f32 v81, v76, v77
	v_cvt_pk_bf16_f32 v74, v6, v7
	v_cvt_pk_bf16_f32 v75, v8, v9
	v_cvt_pk_bf16_f32 v76, v2, v3
	v_cvt_pk_bf16_f32 v77, v4, v5
	v_cvt_pk_bf16_f32 v70, v70, v71
	v_cvt_pk_bf16_f32 v71, v72, v73
	v_cvt_pk_bf16_f32 v72, v66, v67
	v_cvt_pk_bf16_f32 v73, v68, v69
	s_cbranch_scc1 .Lwtp4_0
	v_lshl_or_b32 v66, s79, 8, v158
	v_mov_b64_e32 v[68:69], s[12:13]
	v_ashrrev_i32_e32 v67, 31, v66
	v_mad_i64_i32 v[166:167], s[26:27], v154, s74, v[68:69]
	v_lshlrev_b64 v[66:67], 1, v[66:67]
	v_lshl_add_u64 v[166:167], v[166:167], 0, v[66:67]
	v_or_b32_e32 v165, 16, v154
	global_store_dwordx4 v[166:167], v[130:133], off sc1
	global_store_dwordx4 v[166:167], v[126:129], off offset:256 sc1
	v_mad_i64_i32 v[166:167], s[26:27], v165, s74, v[68:69]
	v_lshl_add_u64 v[166:167], v[166:167], 0, v[66:67]
	v_or_b32_e32 v165, 32, v154
	global_store_dwordx4 v[166:167], v[122:125], off sc1
	global_store_dwordx4 v[166:167], v[118:121], off offset:256 sc1
	v_mad_i64_i32 v[166:167], s[26:27], v165, s74, v[68:69]
	v_lshl_add_u64 v[166:167], v[166:167], 0, v[66:67]
	v_or_b32_e32 v165, 48, v154
	global_store_dwordx4 v[166:167], v[114:117], off sc1
	global_store_dwordx4 v[166:167], v[110:113], off offset:256 sc1
	v_mad_i64_i32 v[166:167], s[26:27], v165, s74, v[68:69]
	v_lshl_add_u64 v[166:167], v[166:167], 0, v[66:67]
	global_store_dwordx4 v[166:167], v[106:109], off sc1
	global_store_dwordx4 v[166:167], v[102:105], off offset:256 sc1
	v_mad_i64_i32 v[166:167], s[26:27], v164, s74, v[68:69]
	v_lshl_add_u64 v[166:167], v[166:167], 0, v[66:67]
	global_store_dwordx4 v[166:167], v[98:101], off sc1
	global_store_dwordx4 v[166:167], v[94:97], off offset:256 sc1
	v_mad_i64_i32 v[166:167], s[26:27], v163, s74, v[68:69]
	v_lshl_add_u64 v[166:167], v[166:167], 0, v[66:67]
	global_store_dwordx4 v[166:167], v[90:93], off sc1
	global_store_dwordx4 v[166:167], v[86:89], off offset:256 sc1
	v_mad_i64_i32 v[166:167], s[26:27], v162, s74, v[68:69]
	v_lshl_add_u64 v[166:167], v[166:167], 0, v[66:67]
	v_mad_i64_i32 v[68:69], s[26:27], v155, s74, v[68:69]
	global_store_dwordx4 v[166:167], v[82:85], off sc1
	global_store_dwordx4 v[166:167], v[78:81], off offset:256 sc1
	v_lshl_add_u64 v[66:67], v[68:69], 0, v[66:67]
	global_store_dwordx4 v[66:67], v[74:77], off sc1
	global_store_dwordx4 v[66:67], v[70:73], off offset:256 sc1
	s_mov_b64 s[26:27], 0
.Lwtp4_0:
	s_andn2_b64 vcc, exec, s[26:27]
	s_cbranch_vccnz .LBB0_384
	s_sub_i32 s6, s79, 33
	s_mul_hi_u32 s19, s6, 0xaaaaaaab
	s_lshr_b32 s19, s19, 3
	s_mul_i32 s21, s19, 12
	s_sub_i32 s21, s6, s21
	s_lshr_b32 s21, s21, 2
	s_mul_i32 s19, s19, 3
	s_lshl_b32 s6, s6, 1
	s_add_i32 s19, s19, s21
	s_and_b32 s6, s6, 6
	s_lshl_b32 s19, s19, 3
	s_lshl_b32 s34, s21, 1
	s_or_b32 s6, s19, s6
	s_lshl_b64 s[26:27], s[6:7], 21
	s_sub_i32 s6, 13, s34
	v_lshlrev_b32_e32 v68, s6, v154
	v_and_b32_e32 v68, 0x1ffe, v68
	v_ashrrev_i32_e32 v69, s34, v154
	v_add_u32_e32 v68, v68, v69
	v_ashrrev_i32_e32 v69, 31, v68
	v_lshl_add_u64 v[66:67], v[142:143], 0, s[26:27]
	v_lshlrev_b64 v[68:69], 8, v[68:69]
	v_lshl_add_u64 v[68:69], v[66:67], 0, v[68:69]
	global_store_dwordx4 v[68:69], v[130:133], off sc1
	v_add_co_u32_e32 v68, vcc, s75, v68
	s_nop 1
	v_addc_co_u32_e32 v69, vcc, 0, v69, vcc
	global_store_dwordx4 v[68:69], v[126:129], off sc1
	v_or_b32_e32 v68, 16, v154
	v_lshlrev_b32_e32 v69, s6, v68
	v_and_b32_e32 v69, 0x1ffe, v69
	v_ashrrev_i32_e32 v68, s34, v68
	v_add_u32_e32 v68, v69, v68
	v_ashrrev_i32_e32 v69, 31, v68
	v_lshlrev_b64 v[68:69], 8, v[68:69]
	v_lshl_add_u64 v[68:69], v[66:67], 0, v[68:69]
	global_store_dwordx4 v[68:69], v[122:125], off sc1
	v_add_co_u32_e32 v68, vcc, s75, v68
	s_nop 1
	v_addc_co_u32_e32 v69, vcc, 0, v69, vcc
	global_store_dwordx4 v[68:69], v[118:121], off sc1
	v_or_b32_e32 v68, 32, v154
	v_lshlrev_b32_e32 v69, s6, v68
	v_and_b32_e32 v69, 0x1ffe, v69
	v_ashrrev_i32_e32 v68, s34, v68
	v_add_u32_e32 v68, v69, v68
	v_ashrrev_i32_e32 v69, 31, v68
	v_lshlrev_b64 v[68:69], 8, v[68:69]
	v_lshl_add_u64 v[68:69], v[66:67], 0, v[68:69]
	global_store_dwordx4 v[68:69], v[114:117], off sc1
	v_add_co_u32_e32 v68, vcc, s75, v68
	s_nop 1
	v_addc_co_u32_e32 v69, vcc, 0, v69, vcc
	global_store_dwordx4 v[68:69], v[110:113], off sc1
	v_or_b32_e32 v68, 48, v154
	v_lshlrev_b32_e32 v69, s6, v68
	v_and_b32_e32 v69, 0x1ffe, v69
	v_ashrrev_i32_e32 v68, s34, v68
	v_add_u32_e32 v68, v69, v68
	v_ashrrev_i32_e32 v69, 31, v68
	v_lshlrev_b64 v[68:69], 8, v[68:69]
	v_lshl_add_u64 v[68:69], v[66:67], 0, v[68:69]
	global_store_dwordx4 v[68:69], v[106:109], off sc1
	v_add_co_u32_e32 v68, vcc, s75, v68
	s_nop 1
	v_addc_co_u32_e32 v69, vcc, 0, v69, vcc
	global_store_dwordx4 v[68:69], v[102:105], off sc1
	v_lshlrev_b32_e32 v68, s6, v164
	v_and_b32_e32 v68, 0x1ffe, v68
	v_ashrrev_i32_e32 v69, s34, v164
	v_add_u32_e32 v68, v68, v69
	v_ashrrev_i32_e32 v69, 31, v68
	v_lshlrev_b64 v[68:69], 8, v[68:69]
	v_lshl_add_u64 v[68:69], v[66:67], 0, v[68:69]
	global_store_dwordx4 v[68:69], v[98:101], off sc1
	v_add_co_u32_e32 v68, vcc, s75, v68
	s_nop 1
	v_addc_co_u32_e32 v69, vcc, 0, v69, vcc
	global_store_dwordx4 v[68:69], v[94:97], off sc1
	v_lshlrev_b32_e32 v68, s6, v163
	v_and_b32_e32 v68, 0x1ffe, v68
	v_ashrrev_i32_e32 v69, s34, v163
	v_add_u32_e32 v68, v68, v69
	v_ashrrev_i32_e32 v69, 31, v68
	v_lshlrev_b64 v[68:69], 8, v[68:69]
	v_lshl_add_u64 v[68:69], v[66:67], 0, v[68:69]
	global_store_dwordx4 v[68:69], v[90:93], off sc1
	v_add_co_u32_e32 v68, vcc, s75, v68
	s_nop 1
	v_addc_co_u32_e32 v69, vcc, 0, v69, vcc
	global_store_dwordx4 v[68:69], v[86:89], off sc1
	v_lshlrev_b32_e32 v68, s6, v162
	v_and_b32_e32 v68, 0x1ffe, v68
	v_ashrrev_i32_e32 v69, s34, v162
	v_add_u32_e32 v68, v68, v69
	v_ashrrev_i32_e32 v69, 31, v68
	v_lshlrev_b64 v[68:69], 8, v[68:69]
	v_lshl_add_u64 v[68:69], v[66:67], 0, v[68:69]
	global_store_dwordx4 v[68:69], v[82:85], off sc1
	v_add_co_u32_e32 v68, vcc, s75, v68
	s_nop 1
	v_addc_co_u32_e32 v69, vcc, 0, v69, vcc
	global_store_dwordx4 v[68:69], v[78:81], off sc1
	v_lshlrev_b32_e32 v68, s6, v155
	v_and_b32_e32 v68, 0x1ffe, v68
	v_ashrrev_i32_e32 v69, s34, v155
	v_add_u32_e32 v68, v68, v69
	v_ashrrev_i32_e32 v69, 31, v68
	v_lshlrev_b64 v[68:69], 8, v[68:69]
	v_lshl_add_u64 v[66:67], v[66:67], 0, v[68:69]
	global_store_dwordx4 v[66:67], v[74:77], off sc1
	v_add_co_u32_e32 v66, vcc, 0x200000, v66
	s_nop 1
	v_addc_co_u32_e32 v67, vcc, 0, v67, vcc
	global_store_dwordx4 v[66:67], v[70:73], off sc1
	s_branch .LBB0_384

.LBB0_539:
	s_cmp_lg_u32 s67, -1
	v_lshl_add_u32 v154, s6, 8, v156
	v_readlane_b32 s78, v251, 57
	v_readlane_b32 s79, v251, 58
	s_mov_b64 s[26:27], -1
	s_cbranch_scc0 .LBB0_545
	s_and_b64 vcc, exec, s[2:3]
	s_cbranch_vccz .Lwtp5_entry
	s_cmp_gt_i32 s67, -16
	v_add_u32_e32 v164, 0x80, v154
	v_add_u32_e32 v163, 0x90, v154
	v_add_u32_e32 v162, 0xa0, v154
	v_add_u32_e32 v155, 0xb0, v154
	v_cvt_pk_bf16_f32 v130, v62, v63
	v_cvt_pk_bf16_f32 v131, v64, v65
	v_cvt_pk_bf16_f32 v132, v58, v59
	v_cvt_pk_bf16_f32 v133, v60, v61
	v_cvt_pk_bf16_f32 v126, v126, v127
	v_cvt_pk_bf16_f32 v127, v128, v129
	v_cvt_pk_bf16_f32 v128, v122, v123
	v_cvt_pk_bf16_f32 v129, v124, v125
	v_cvt_pk_bf16_f32 v122, v54, v55
	v_cvt_pk_bf16_f32 v123, v56, v57
	v_cvt_pk_bf16_f32 v124, v50, v51
	v_cvt_pk_bf16_f32 v125, v52, v53
	v_cvt_pk_bf16_f32 v118, v118, v119
	v_cvt_pk_bf16_f32 v119, v120, v121
	v_cvt_pk_bf16_f32 v120, v114, v115
	v_cvt_pk_bf16_f32 v121, v116, v117
	v_cvt_pk_bf16_f32 v114, v46, v47
	v_cvt_pk_bf16_f32 v115, v48, v49
	v_cvt_pk_bf16_f32 v116, v42, v43
	v_cvt_pk_bf16_f32 v117, v44, v45
	v_cvt_pk_bf16_f32 v110, v110, v111
	v_cvt_pk_bf16_f32 v111, v112, v113
	v_cvt_pk_bf16_f32 v112, v106, v107
	v_cvt_pk_bf16_f32 v113, v108, v109
	v_cvt_pk_bf16_f32 v106, v38, v39
	v_cvt_pk_bf16_f32 v107, v40, v41
	v_cvt_pk_bf16_f32 v108, v34, v35
	v_cvt_pk_bf16_f32 v109, v36, v37
	v_cvt_pk_bf16_f32 v102, v102, v103
	v_cvt_pk_bf16_f32 v103, v104, v105
	v_cvt_pk_bf16_f32 v104, v98, v99
	v_cvt_pk_bf16_f32 v105, v100, v101
	v_cvt_pk_bf16_f32 v98, v30, v31
	v_cvt_pk_bf16_f32 v99, v32, v33
	v_cvt_pk_bf16_f32 v100, v26, v27
	v_cvt_pk_bf16_f32 v101, v28, v29
	v_cvt_pk_bf16_f32 v94, v94, v95
	v_cvt_pk_bf16_f32 v95, v96, v97
	v_cvt_pk_bf16_f32 v96, v90, v91
	v_cvt_pk_bf16_f32 v97, v92, v93
	v_cvt_pk_bf16_f32 v90, v22, v23
	v_cvt_pk_bf16_f32 v91, v24, v25
	v_cvt_pk_bf16_f32 v92, v18, v19
	v_cvt_pk_bf16_f32 v93, v20, v21
	v_cvt_pk_bf16_f32 v86, v86, v87
	v_cvt_pk_bf16_f32 v87, v88, v89
	v_cvt_pk_bf16_f32 v88, v82, v83
	v_cvt_pk_bf16_f32 v89, v84, v85
	v_cvt_pk_bf16_f32 v82, v14, v15
	v_cvt_pk_bf16_f32 v83, v16, v17
	v_cvt_pk_bf16_f32 v84, v10, v11
	v_cvt_pk_bf16_f32 v85, v12, v13
	v_cvt_pk_bf16_f32 v78, v78, v79
	v_cvt_pk_bf16_f32 v79, v80, v81
	v_cvt_pk_bf16_f32 v80, v74, v75
	v_cvt_pk_bf16_f32 v81, v76, v77
	v_cvt_pk_bf16_f32 v74, v6, v7
	v_cvt_pk_bf16_f32 v75, v8, v9
	v_cvt_pk_bf16_f32 v76, v2, v3
	v_cvt_pk_bf16_f32 v77, v4, v5
	v_cvt_pk_bf16_f32 v70, v70, v71
	v_cvt_pk_bf16_f32 v71, v72, v73
	v_cvt_pk_bf16_f32 v72, v66, v67
	v_cvt_pk_bf16_f32 v73, v68, v69
	s_cbranch_scc1 .LBB0_542
	v_lshl_or_b32 v66, s67, 8, v158
	v_mov_b64_e32 v[68:69], s[12:13]
	v_ashrrev_i32_e32 v67, 31, v66
	v_mad_i64_i32 v[166:167], s[26:27], v154, s64, v[68:69]
	v_lshlrev_b64 v[66:67], 1, v[66:67]
	v_lshl_add_u64 v[166:167], v[166:167], 0, v[66:67]
	v_or_b32_e32 v165, 16, v154
	global_store_dwordx4 v[166:167], v[130:133], off
	global_store_dwordx4 v[166:167], v[126:129], off offset:256
	v_mad_i64_i32 v[166:167], s[26:27], v165, s64, v[68:69]
	v_lshl_add_u64 v[166:167], v[166:167], 0, v[66:67]
	v_or_b32_e32 v165, 32, v154
	global_store_dwordx4 v[166:167], v[122:125], off
	global_store_dwordx4 v[166:167], v[118:121], off offset:256
	v_mad_i64_i32 v[166:167], s[26:27], v165, s64, v[68:69]
	v_lshl_add_u64 v[166:167], v[166:167], 0, v[66:67]
	v_or_b32_e32 v165, 48, v154
	global_store_dwordx4 v[166:167], v[114:117], off
	global_store_dwordx4 v[166:167], v[110:113], off offset:256
	v_mad_i64_i32 v[166:167], s[26:27], v165, s64, v[68:69]
	v_lshl_add_u64 v[166:167], v[166:167], 0, v[66:67]
	global_store_dwordx4 v[166:167], v[106:109], off
	global_store_dwordx4 v[166:167], v[102:105], off offset:256
	v_mad_i64_i32 v[166:167], s[26:27], v164, s64, v[68:69]
	v_lshl_add_u64 v[166:167], v[166:167], 0, v[66:67]
	global_store_dwordx4 v[166:167], v[98:101], off
	global_store_dwordx4 v[166:167], v[94:97], off offset:256
	v_mad_i64_i32 v[166:167], s[26:27], v163, s64, v[68:69]
	v_lshl_add_u64 v[166:167], v[166:167], 0, v[66:67]
	global_store_dwordx4 v[166:167], v[90:93], off
	global_store_dwordx4 v[166:167], v[86:89], off offset:256
	v_mad_i64_i32 v[166:167], s[26:27], v162, s64, v[68:69]
	v_lshl_add_u64 v[166:167], v[166:167], 0, v[66:67]
	v_mad_i64_i32 v[68:69], s[26:27], v155, s64, v[68:69]
	global_store_dwordx4 v[166:167], v[82:85], off
	global_store_dwordx4 v[166:167], v[78:81], off offset:256
	v_lshl_add_u64 v[66:67], v[68:69], 0, v[66:67]
	global_store_dwordx4 v[66:67], v[74:77], off
	global_store_dwordx4 v[66:67], v[70:73], off offset:256
	s_mov_b64 s[26:27], 0

.Lwtp5_entry:
	s_cmp_gt_i32 s67, -16
	v_add_u32_e32 v164, 0x80, v154
	v_add_u32_e32 v163, 0x90, v154
	v_add_u32_e32 v162, 0xa0, v154
	v_add_u32_e32 v155, 0xb0, v154
	v_cvt_pk_bf16_f32 v130, v62, v63
	v_cvt_pk_bf16_f32 v131, v64, v65
	v_cvt_pk_bf16_f32 v132, v58, v59
	v_cvt_pk_bf16_f32 v133, v60, v61
	v_cvt_pk_bf16_f32 v126, v126, v127
	v_cvt_pk_bf16_f32 v127, v128, v129
	v_cvt_pk_bf16_f32 v128, v122, v123
	v_cvt_pk_bf16_f32 v129, v124, v125
	v_cvt_pk_bf16_f32 v122, v54, v55
	v_cvt_pk_bf16_f32 v123, v56, v57
	v_cvt_pk_bf16_f32 v124, v50, v51
	v_cvt_pk_bf16_f32 v125, v52, v53
	v_cvt_pk_bf16_f32 v118, v118, v119
	v_cvt_pk_bf16_f32 v119, v120, v121
	v_cvt_pk_bf16_f32 v120, v114, v115
	v_cvt_pk_bf16_f32 v121, v116, v117
	v_cvt_pk_bf16_f32 v114, v46, v47
	v_cvt_pk_bf16_f32 v115, v48, v49
	v_cvt_pk_bf16_f32 v116, v42, v43
	v_cvt_pk_bf16_f32 v117, v44, v45
	v_cvt_pk_bf16_f32 v110, v110, v111
	v_cvt_pk_bf16_f32 v111, v112, v113
	v_cvt_pk_bf16_f32 v112, v106, v107
	v_cvt_pk_bf16_f32 v113, v108, v109
	v_cvt_pk_bf16_f32 v106, v38, v39
	v_cvt_pk_bf16_f32 v107, v40, v41
	v_cvt_pk_bf16_f32 v108, v34, v35
	v_cvt_pk_bf16_f32 v109, v36, v37
	v_cvt_pk_bf16_f32 v102, v102, v103
	v_cvt_pk_bf16_f32 v103, v104, v105
	v_cvt_pk_bf16_f32 v104, v98, v99
	v_cvt_pk_bf16_f32 v105, v100, v101
	v_cvt_pk_bf16_f32 v98, v30, v31
	v_cvt_pk_bf16_f32 v99, v32, v33
	v_cvt_pk_bf16_f32 v100, v26, v27
	v_cvt_pk_bf16_f32 v101, v28, v29
	v_cvt_pk_bf16_f32 v94, v94, v95
	v_cvt_pk_bf16_f32 v95, v96, v97
	v_cvt_pk_bf16_f32 v96, v90, v91
	v_cvt_pk_bf16_f32 v97, v92, v93
	v_cvt_pk_bf16_f32 v90, v22, v23
	v_cvt_pk_bf16_f32 v91, v24, v25
	v_cvt_pk_bf16_f32 v92, v18, v19
	v_cvt_pk_bf16_f32 v93, v20, v21
	v_cvt_pk_bf16_f32 v86, v86, v87
	v_cvt_pk_bf16_f32 v87, v88, v89
	v_cvt_pk_bf16_f32 v88, v82, v83
	v_cvt_pk_bf16_f32 v89, v84, v85
	v_cvt_pk_bf16_f32 v82, v14, v15
	v_cvt_pk_bf16_f32 v83, v16, v17
	v_cvt_pk_bf16_f32 v84, v10, v11
	v_cvt_pk_bf16_f32 v85, v12, v13
	v_cvt_pk_bf16_f32 v78, v78, v79
	v_cvt_pk_bf16_f32 v79, v80, v81
	v_cvt_pk_bf16_f32 v80, v74, v75
	v_cvt_pk_bf16_f32 v81, v76, v77
	v_cvt_pk_bf16_f32 v74, v6, v7
	v_cvt_pk_bf16_f32 v75, v8, v9
	v_cvt_pk_bf16_f32 v76, v2, v3
	v_cvt_pk_bf16_f32 v77, v4, v5
	v_cvt_pk_bf16_f32 v70, v70, v71
	v_cvt_pk_bf16_f32 v71, v72, v73
	v_cvt_pk_bf16_f32 v72, v66, v67
	v_cvt_pk_bf16_f32 v73, v68, v69
	s_cbranch_scc1 .Lwtp5_0
	v_lshl_or_b32 v66, s67, 8, v158
	v_mov_b64_e32 v[68:69], s[12:13]
	v_ashrrev_i32_e32 v67, 31, v66
	v_mad_i64_i32 v[166:167], s[26:27], v154, s64, v[68:69]
	v_lshlrev_b64 v[66:67], 1, v[66:67]
	v_lshl_add_u64 v[166:167], v[166:167], 0, v[66:67]
	v_or_b32_e32 v165, 16, v154
	global_store_dwordx4 v[166:167], v[130:133], off sc1
	global_store_dwordx4 v[166:167], v[126:129], off offset:256 sc1
	v_mad_i64_i32 v[166:167], s[26:27], v165, s64, v[68:69]
	v_lshl_add_u64 v[166:167], v[166:167], 0, v[66:67]
	v_or_b32_e32 v165, 32, v154
	global_store_dwordx4 v[166:167], v[122:125], off sc1
	global_store_dwordx4 v[166:167], v[118:121], off offset:256 sc1
	v_mad_i64_i32 v[166:167], s[26:27], v165, s64, v[68:69]
	v_lshl_add_u64 v[166:167], v[166:167], 0, v[66:67]
	v_or_b32_e32 v165, 48, v154
	global_store_dwordx4 v[166:167], v[114:117], off sc1
	global_store_dwordx4 v[166:167], v[110:113], off offset:256 sc1
	v_mad_i64_i32 v[166:167], s[26:27], v165, s64, v[68:69]
	v_lshl_add_u64 v[166:167], v[166:167], 0, v[66:67]
	global_store_dwordx4 v[166:167], v[106:109], off sc1
	global_store_dwordx4 v[166:167], v[102:105], off offset:256 sc1
	v_mad_i64_i32 v[166:167], s[26:27], v164, s64, v[68:69]
	v_lshl_add_u64 v[166:167], v[166:167], 0, v[66:67]
	global_store_dwordx4 v[166:167], v[98:101], off sc1
	global_store_dwordx4 v[166:167], v[94:97], off offset:256 sc1
	v_mad_i64_i32 v[166:167], s[26:27], v163, s64, v[68:69]
	v_lshl_add_u64 v[166:167], v[166:167], 0, v[66:67]
	global_store_dwordx4 v[166:167], v[90:93], off sc1
	global_store_dwordx4 v[166:167], v[86:89], off offset:256 sc1
	v_mad_i64_i32 v[166:167], s[26:27], v162, s64, v[68:69]
	v_lshl_add_u64 v[166:167], v[166:167], 0, v[66:67]
	v_mad_i64_i32 v[68:69], s[26:27], v155, s64, v[68:69]
	global_store_dwordx4 v[166:167], v[82:85], off sc1
	global_store_dwordx4 v[166:167], v[78:81], off offset:256 sc1
	v_lshl_add_u64 v[66:67], v[68:69], 0, v[66:67]
	global_store_dwordx4 v[66:67], v[74:77], off sc1
	global_store_dwordx4 v[66:67], v[70:73], off offset:256 sc1
	s_mov_b64 s[26:27], 0
.Lwtp5_0:
	s_andn2_b64 vcc, exec, s[26:27]
	v_readlane_b32 s81, v251, 56
	s_cbranch_vccnz .LBB0_544
	s_add_i32 s6, s67, 15
	s_mul_hi_u32 s19, s6, 0xaaaaaaab
	s_lshr_b32 s19, s19, 3
	s_mul_i32 s21, s19, 12
	s_sub_i32 s21, s6, s21
	s_lshr_b32 s21, s21, 2
	s_mul_i32 s19, s19, 3
	s_lshl_b32 s6, s6, 1
	s_add_i32 s19, s19, s21
	s_and_b32 s6, s6, 6
	s_lshl_b32 s19, s19, 3
	s_lshl_b32 s30, s21, 1
	s_or_b32 s6, s19, s6
	s_lshl_b64 s[26:27], s[6:7], 21
	s_sub_i32 s6, 13, s30
	v_lshlrev_b32_e32 v68, s6, v154
	v_and_b32_e32 v68, 0x1ffe, v68
	v_ashrrev_i32_e32 v69, s30, v154
	v_add_u32_e32 v68, v68, v69
	v_ashrrev_i32_e32 v69, 31, v68
	v_lshl_add_u64 v[66:67], v[142:143], 0, s[26:27]
	v_lshlrev_b64 v[68:69], 8, v[68:69]
	v_lshl_add_u64 v[68:69], v[66:67], 0, v[68:69]
	global_store_dwordx4 v[68:69], v[130:133], off sc1
	v_add_co_u32_e32 v68, vcc, s65, v68
	s_nop 1
	v_addc_co_u32_e32 v69, vcc, 0, v69, vcc
	global_store_dwordx4 v[68:69], v[126:129], off sc1
	v_or_b32_e32 v68, 16, v154
	v_lshlrev_b32_e32 v69, s6, v68
	v_and_b32_e32 v69, 0x1ffe, v69
	v_ashrrev_i32_e32 v68, s30, v68
	v_add_u32_e32 v68, v69, v68
	v_ashrrev_i32_e32 v69, 31, v68
	v_lshlrev_b64 v[68:69], 8, v[68:69]
	v_lshl_add_u64 v[68:69], v[66:67], 0, v[68:69]
	global_store_dwordx4 v[68:69], v[122:125], off sc1
	v_add_co_u32_e32 v68, vcc, s65, v68
	s_nop 1
	v_addc_co_u32_e32 v69, vcc, 0, v69, vcc
	global_store_dwordx4 v[68:69], v[118:121], off sc1
	v_or_b32_e32 v68, 32, v154
	v_lshlrev_b32_e32 v69, s6, v68
	v_and_b32_e32 v69, 0x1ffe, v69
	v_ashrrev_i32_e32 v68, s30, v68
	v_add_u32_e32 v68, v69, v68
	v_ashrrev_i32_e32 v69, 31, v68
	v_lshlrev_b64 v[68:69], 8, v[68:69]
	v_lshl_add_u64 v[68:69], v[66:67], 0, v[68:69]
	global_store_dwordx4 v[68:69], v[114:117], off sc1
	v_add_co_u32_e32 v68, vcc, s65, v68
	s_nop 1
	v_addc_co_u32_e32 v69, vcc, 0, v69, vcc
	global_store_dwordx4 v[68:69], v[110:113], off sc1
	v_or_b32_e32 v68, 48, v154
	v_lshlrev_b32_e32 v69, s6, v68
	v_and_b32_e32 v69, 0x1ffe, v69
	v_ashrrev_i32_e32 v68, s30, v68
	v_add_u32_e32 v68, v69, v68
	v_ashrrev_i32_e32 v69, 31, v68
	v_lshlrev_b64 v[68:69], 8, v[68:69]
	v_lshl_add_u64 v[68:69], v[66:67], 0, v[68:69]
	global_store_dwordx4 v[68:69], v[106:109], off sc1
	v_add_co_u32_e32 v68, vcc, s65, v68
	s_nop 1
	v_addc_co_u32_e32 v69, vcc, 0, v69, vcc
	global_store_dwordx4 v[68:69], v[102:105], off sc1
	v_lshlrev_b32_e32 v68, s6, v164
	v_and_b32_e32 v68, 0x1ffe, v68
	v_ashrrev_i32_e32 v69, s30, v164
	v_add_u32_e32 v68, v68, v69
	v_ashrrev_i32_e32 v69, 31, v68
	v_lshlrev_b64 v[68:69], 8, v[68:69]
	v_lshl_add_u64 v[68:69], v[66:67], 0, v[68:69]
	global_store_dwordx4 v[68:69], v[98:101], off sc1
	v_add_co_u32_e32 v68, vcc, s65, v68
	s_nop 1
	v_addc_co_u32_e32 v69, vcc, 0, v69, vcc
	global_store_dwordx4 v[68:69], v[94:97], off sc1
	v_lshlrev_b32_e32 v68, s6, v163
	v_and_b32_e32 v68, 0x1ffe, v68
	v_ashrrev_i32_e32 v69, s30, v163
	v_add_u32_e32 v68, v68, v69
	v_ashrrev_i32_e32 v69, 31, v68
	v_lshlrev_b64 v[68:69], 8, v[68:69]
	v_lshl_add_u64 v[68:69], v[66:67], 0, v[68:69]
	global_store_dwordx4 v[68:69], v[90:93], off sc1
	v_add_co_u32_e32 v68, vcc, s65, v68
	s_nop 1
	v_addc_co_u32_e32 v69, vcc, 0, v69, vcc
	global_store_dwordx4 v[68:69], v[86:89], off sc1
	v_lshlrev_b32_e32 v68, s6, v162
	v_and_b32_e32 v68, 0x1ffe, v68
	v_ashrrev_i32_e32 v69, s30, v162
	v_add_u32_e32 v68, v68, v69
	v_ashrrev_i32_e32 v69, 31, v68
	v_lshlrev_b64 v[68:69], 8, v[68:69]
	v_lshl_add_u64 v[68:69], v[66:67], 0, v[68:69]
	global_store_dwordx4 v[68:69], v[82:85], off sc1
	v_add_co_u32_e32 v68, vcc, s65, v68
	s_nop 1
	v_addc_co_u32_e32 v69, vcc, 0, v69, vcc
	global_store_dwordx4 v[68:69], v[78:81], off sc1
	v_lshlrev_b32_e32 v68, s6, v155
	v_and_b32_e32 v68, 0x1ffe, v68
	v_ashrrev_i32_e32 v69, s30, v155
	v_add_u32_e32 v68, v68, v69
	v_ashrrev_i32_e32 v69, 31, v68
	v_lshlrev_b64 v[68:69], 8, v[68:69]
	v_lshl_add_u64 v[66:67], v[66:67], 0, v[68:69]
	global_store_dwordx4 v[66:67], v[74:77], off sc1
	v_add_co_u32_e32 v66, vcc, 0x200000, v66
	s_nop 1
	v_addc_co_u32_e32 v67, vcc, 0, v67, vcc
	global_store_dwordx4 v[66:67], v[70:73], off sc1
	s_branch .LBB0_544

.Lwtp9_entry:
	s_lshl_b32 s24, s64, 8
	s_or_b32 s26, s24, s41
	v_or_b32_e32 v130, s26, v188
	v_ashrrev_i32_e32 v131, 31, v130
	v_lshl_add_u64 v[166:167], v[130:131], 1, s[16:17]
	v_mad_i64_i32 v[130:131], s[24:25], v162, s59, v[166:167]
	global_load_dwordx4 v[158:161], v[130:131], off
	global_load_dwordx4 v[154:157], v[130:131], off offset:256
	v_or_b32_e32 v176, 16, v162
	v_mad_i64_i32 v[130:131], s[24:25], v176, s59, v[166:167]
	global_load_dwordx4 v[150:153], v[130:131], off
	global_load_dwordx4 v[146:149], v[130:131], off offset:256
	v_or_b32_e32 v175, 32, v162
	v_mad_i64_i32 v[130:131], s[24:25], v175, s59, v[166:167]
	global_load_dwordx4 v[142:145], v[130:131], off
	global_load_dwordx4 v[138:141], v[130:131], off offset:256
	v_or_b32_e32 v174, 48, v162
	v_ashrrev_i32_e32 v163, 31, v162
	v_mad_i64_i32 v[130:131], s[24:25], v174, s59, v[166:167]
	s_ashr_i32 s24, s26, 6
	s_ashr_i32 s25, s24, 31
	v_bitop3_b32 v177, s26, 56, v188 bitop3:0xc8
	global_load_dwordx4 v[134:137], v[130:131], off
	s_nop 0
	global_load_dwordx4 v[130:133], v[130:131], off offset:256
	s_or_b32 s26, s24, 2
	s_ashr_i32 s27, s26, 31
	s_waitcnt vmcnt(0)
	v_lshlrev_b32_e32 v164, 16, v158
	v_and_b32_e32 v165, 0xffff0000, v158
	v_lshlrev_b32_e32 v168, 16, v159
	v_and_b32_e32 v169, 0xffff0000, v159
	v_lshlrev_b32_e32 v170, 16, v160
	v_and_b32_e32 v171, 0xffff0000, v160
	v_lshlrev_b32_e32 v172, 16, v161
	v_and_b32_e32 v173, 0xffff0000, v161
	v_mul_f32_e32 v158, 0xbfb8aa3b, v164
	v_mul_f32_e32 v159, 0xbfb8aa3b, v165
	v_mul_f32_e32 v160, 0xbfb8aa3b, v168
	v_mul_f32_e32 v161, 0xbfb8aa3b, v169
	v_mul_f32_e32 v164, 0xbfb8aa3b, v170
	v_mul_f32_e32 v165, 0xbfb8aa3b, v171
	v_exp_f32_e32 v158, v158
	v_exp_f32_e32 v159, v159
	v_exp_f32_e32 v160, v160
	v_exp_f32_e32 v161, v161
	v_exp_f32_e32 v164, v164
	v_exp_f32_e32 v165, v165
	v_mul_f32_e32 v168, 0xbfb8aa3b, v172
	v_mul_f32_e32 v169, 0xbfb8aa3b, v173
	v_add_f32_e32 v158, 1.0, v158
	v_add_f32_e32 v159, 1.0, v159
	v_add_f32_e32 v160, 1.0, v160
	v_add_f32_e32 v161, 1.0, v161
	v_add_f32_e32 v164, 1.0, v164
	v_add_f32_e32 v165, 1.0, v165
	v_exp_f32_e32 v168, v168
	v_exp_f32_e32 v169, v169
	v_rcp_f32_e32 v158, v158
	v_rcp_f32_e32 v159, v159
	v_rcp_f32_e32 v160, v160
	v_rcp_f32_e32 v161, v161
	v_rcp_f32_e32 v164, v164
	v_rcp_f32_e32 v165, v165
	v_add_f32_e32 v168, 1.0, v168
	v_add_f32_e32 v169, 1.0, v169
	v_pk_mul_f32 v[160:161], v[128:129], v[160:161]
	v_pk_mul_f32 v[158:159], v[126:127], v[158:159]
	v_rcp_f32_e32 v168, v168
	v_rcp_f32_e32 v169, v169
	v_pk_mul_f32 v[164:165], v[122:123], v[164:165]
	v_cvt_pk_bf16_f32 v158, v158, v159
	v_cvt_pk_bf16_f32 v159, v160, v161
	v_cvt_pk_bf16_f32 v160, v164, v165
	v_lshrrev_b64 v[164:165], 1, v[162:163]
	v_and_b32_e32 v171, 0x7fffffff, v165
	v_and_b32_e32 v170, 0xffffffc0, v164
	v_lshl_add_u64 v[164:165], v[170:171], 0, s[24:25]
	v_pk_mul_f32 v[168:169], v[124:125], v[168:169]
	v_lshlrev_b64 v[164:165], 14, v[164:165]
	v_lshlrev_b32_e32 v163, 7, v162
	v_cvt_pk_bf16_f32 v161, v168, v169
	v_lshl_add_u64 v[168:169], s[28:29], 0, v[164:165]
	v_and_b32_e32 v172, 0x2780, v163
	v_mov_b32_e32 v173, v187
	v_lshl_add_u64 v[198:199], v[168:169], 0, v[172:173]
	v_lshlrev_b32_e32 v164, 1, v177
	v_mov_b32_e32 v165, v187
	v_lshl_add_u64 v[198:199], v[198:199], 0, v[164:165]
	global_store_dwordx4 v[198:199], v[158:161], off sc1
	v_lshlrev_b32_e32 v163, 16, v156
	v_and_b32_e32 v177, 0xffff0000, v156
	v_lshlrev_b32_e32 v160, 16, v155
	v_and_b32_e32 v161, 0xffff0000, v155
	v_lshlrev_b32_e32 v198, 16, v157
	v_and_b32_e32 v199, 0xffff0000, v157
	v_mul_f32_e32 v156, 0xbfb8aa3b, v160
	v_mul_f32_e32 v157, 0xbfb8aa3b, v161
	v_exp_f32_e32 v156, v156
	v_exp_f32_e32 v157, v157
	v_lshlrev_b32_e32 v158, 16, v154
	v_and_b32_e32 v159, 0xffff0000, v154
	v_add_f32_e32 v156, 1.0, v156
	v_add_f32_e32 v157, 1.0, v157
	v_rcp_f32_e32 v156, v156
	v_rcp_f32_e32 v157, v157
	v_mul_f32_e32 v154, 0xbfb8aa3b, v158
	v_mul_f32_e32 v155, 0xbfb8aa3b, v159
	v_exp_f32_e32 v154, v154
	v_exp_f32_e32 v155, v155
	v_pk_mul_f32 v[158:159], v[96:97], v[156:157]
	v_mul_f32_e32 v156, 0xbfb8aa3b, v163
	v_mul_f32_e32 v157, 0xbfb8aa3b, v177
	v_exp_f32_e32 v156, v156
	v_exp_f32_e32 v157, v157
	v_mul_f32_e32 v160, 0xbfb8aa3b, v198
	v_mul_f32_e32 v161, 0xbfb8aa3b, v199
	v_exp_f32_e32 v160, v160
	v_exp_f32_e32 v161, v161
	v_add_f32_e32 v154, 1.0, v154
	v_add_f32_e32 v155, 1.0, v155
	v_rcp_f32_e32 v154, v154
	v_rcp_f32_e32 v155, v155
	v_add_f32_e32 v156, 1.0, v156
	v_add_f32_e32 v157, 1.0, v157
	v_rcp_f32_e32 v156, v156
	v_rcp_f32_e32 v157, v157
	v_add_f32_e32 v160, 1.0, v160
	v_add_f32_e32 v161, 1.0, v161
	v_rcp_f32_e32 v160, v160
	v_rcp_f32_e32 v161, v161
	v_pk_mul_f32 v[154:155], v[94:95], v[154:155]
	v_pk_mul_f32 v[198:199], v[90:91], v[156:157]
	v_cvt_pk_bf16_f32 v156, v154, v155
	v_lshl_add_u64 v[154:155], v[170:171], 0, s[26:27]
	v_lshlrev_b64 v[154:155], 14, v[154:155]
	v_pk_mul_f32 v[160:161], v[92:93], v[160:161]
	v_lshl_add_u64 v[154:155], s[28:29], 0, v[154:155]
	v_cvt_pk_bf16_f32 v157, v158, v159
	v_cvt_pk_bf16_f32 v159, v160, v161
	v_lshl_add_u64 v[160:161], v[154:155], 0, v[172:173]
	v_cvt_pk_bf16_f32 v158, v198, v199
	v_lshl_add_u64 v[160:161], v[160:161], 0, v[164:165]
	global_store_dwordx4 v[160:161], v[156:159], off sc1
	v_lshlrev_b32_e32 v160, 16, v152
	v_and_b32_e32 v161, 0xffff0000, v152
	v_lshlrev_b32_e32 v156, 16, v150
	v_and_b32_e32 v157, 0xffff0000, v150
	v_lshlrev_b32_e32 v158, 16, v151
	v_and_b32_e32 v159, 0xffff0000, v151
	v_lshlrev_b32_e32 v163, 16, v153
	v_and_b32_e32 v170, 0xffff0000, v153
	v_mul_f32_e32 v150, 0xbfb8aa3b, v156
	v_mul_f32_e32 v151, 0xbfb8aa3b, v157
	v_mul_f32_e32 v152, 0xbfb8aa3b, v158
	v_mul_f32_e32 v153, 0xbfb8aa3b, v159
	v_mul_f32_e32 v156, 0xbfb8aa3b, v160
	v_mul_f32_e32 v157, 0xbfb8aa3b, v161
	v_exp_f32_e32 v150, v150
	v_exp_f32_e32 v151, v151
	v_exp_f32_e32 v152, v152
	v_exp_f32_e32 v153, v153
	v_exp_f32_e32 v156, v156
	v_exp_f32_e32 v157, v157
	v_mul_f32_e32 v158, 0xbfb8aa3b, v163
	v_mul_f32_e32 v159, 0xbfb8aa3b, v170
	v_exp_f32_e32 v158, v158
	v_exp_f32_e32 v159, v159
	v_add_f32_e32 v150, 1.0, v150
	v_add_f32_e32 v151, 1.0, v151
	v_add_f32_e32 v152, 1.0, v152
	v_add_f32_e32 v153, 1.0, v153
	v_add_f32_e32 v156, 1.0, v156
	v_add_f32_e32 v157, 1.0, v157
	v_rcp_f32_e32 v150, v150
	v_rcp_f32_e32 v151, v151
	v_rcp_f32_e32 v152, v152
	v_rcp_f32_e32 v153, v153
	v_rcp_f32_e32 v156, v156
	v_rcp_f32_e32 v157, v157
	v_add_f32_e32 v158, 1.0, v158
	v_add_f32_e32 v159, 1.0, v159
	v_rcp_f32_e32 v158, v158
	v_rcp_f32_e32 v159, v159
	v_pk_mul_f32 v[152:153], v[120:121], v[152:153]
	v_pk_mul_f32 v[150:151], v[118:119], v[150:151]
	v_pk_mul_f32 v[156:157], v[114:115], v[156:157]
	v_cvt_pk_bf16_f32 v150, v150, v151
	v_cvt_pk_bf16_f32 v151, v152, v153
	v_cvt_pk_bf16_f32 v152, v156, v157
	v_lshlrev_b32_e32 v156, 7, v176
	v_pk_mul_f32 v[158:159], v[116:117], v[158:159]
	v_and_b32_e32 v156, 0x3f80, v156
	v_mov_b32_e32 v157, v187
	v_cvt_pk_bf16_f32 v153, v158, v159
	v_lshl_add_u64 v[158:159], v[168:169], 0, v[156:157]
	v_lshl_add_u64 v[158:159], v[158:159], 0, v[164:165]
	global_store_dwordx4 v[158:159], v[150:153], off sc1
	v_lshlrev_b32_e32 v158, 16, v148
	v_and_b32_e32 v159, 0xffff0000, v148
	v_lshlrev_b32_e32 v150, 16, v146
	v_and_b32_e32 v151, 0xffff0000, v146
	v_lshlrev_b32_e32 v152, 16, v147
	v_and_b32_e32 v153, 0xffff0000, v147
	v_lshlrev_b32_e32 v160, 16, v149
	v_and_b32_e32 v161, 0xffff0000, v149
	v_mul_f32_e32 v146, 0xbfb8aa3b, v150
	v_mul_f32_e32 v147, 0xbfb8aa3b, v151
	v_mul_f32_e32 v148, 0xbfb8aa3b, v152
	v_mul_f32_e32 v149, 0xbfb8aa3b, v153
	v_mul_f32_e32 v150, 0xbfb8aa3b, v158
	v_mul_f32_e32 v151, 0xbfb8aa3b, v159
	v_exp_f32_e32 v146, v146
	v_exp_f32_e32 v147, v147
	v_exp_f32_e32 v148, v148
	v_exp_f32_e32 v149, v149
	v_exp_f32_e32 v150, v150
	v_exp_f32_e32 v151, v151
	v_mul_f32_e32 v152, 0xbfb8aa3b, v160
	v_mul_f32_e32 v153, 0xbfb8aa3b, v161
	v_exp_f32_e32 v152, v152
	v_exp_f32_e32 v153, v153
	v_add_f32_e32 v146, 1.0, v146
	v_add_f32_e32 v147, 1.0, v147
	v_add_f32_e32 v148, 1.0, v148
	v_add_f32_e32 v149, 1.0, v149
	v_add_f32_e32 v150, 1.0, v150
	v_add_f32_e32 v151, 1.0, v151
	v_rcp_f32_e32 v146, v146
	v_rcp_f32_e32 v147, v147
	v_rcp_f32_e32 v148, v148
	v_rcp_f32_e32 v149, v149
	v_rcp_f32_e32 v150, v150
	v_rcp_f32_e32 v151, v151
	v_add_f32_e32 v152, 1.0, v152
	v_add_f32_e32 v153, 1.0, v153
	v_rcp_f32_e32 v152, v152
	v_rcp_f32_e32 v153, v153
	v_pk_mul_f32 v[148:149], v[88:89], v[148:149]
	v_pk_mul_f32 v[146:147], v[86:87], v[146:147]
	v_pk_mul_f32 v[150:151], v[82:83], v[150:151]
	v_pk_mul_f32 v[152:153], v[84:85], v[152:153]
	v_cvt_pk_bf16_f32 v146, v146, v147
	v_cvt_pk_bf16_f32 v147, v148, v149
	v_cvt_pk_bf16_f32 v148, v150, v151
	v_lshl_add_u64 v[150:151], v[154:155], 0, v[156:157]
	v_cvt_pk_bf16_f32 v149, v152, v153
	v_lshl_add_u64 v[150:151], v[150:151], 0, v[164:165]
	global_store_dwordx4 v[150:151], v[146:149], off sc1
	v_lshlrev_b32_e32 v150, 16, v144
	v_and_b32_e32 v151, 0xffff0000, v144
	v_lshlrev_b32_e32 v146, 16, v142
	v_and_b32_e32 v147, 0xffff0000, v142
	v_lshlrev_b32_e32 v148, 16, v143
	v_and_b32_e32 v149, 0xffff0000, v143
	v_lshlrev_b32_e32 v152, 16, v145
	v_and_b32_e32 v153, 0xffff0000, v145
	v_mul_f32_e32 v142, 0xbfb8aa3b, v146
	v_mul_f32_e32 v143, 0xbfb8aa3b, v147
	v_mul_f32_e32 v144, 0xbfb8aa3b, v148
	v_mul_f32_e32 v145, 0xbfb8aa3b, v149
	v_mul_f32_e32 v146, 0xbfb8aa3b, v150
	v_mul_f32_e32 v147, 0xbfb8aa3b, v151
	v_exp_f32_e32 v142, v142
	v_exp_f32_e32 v143, v143
	v_exp_f32_e32 v144, v144
	v_exp_f32_e32 v145, v145
	v_exp_f32_e32 v146, v146
	v_exp_f32_e32 v147, v147
	v_mul_f32_e32 v148, 0xbfb8aa3b, v152
	v_mul_f32_e32 v149, 0xbfb8aa3b, v153
	v_exp_f32_e32 v148, v148
	v_exp_f32_e32 v149, v149
	v_add_f32_e32 v142, 1.0, v142
	v_add_f32_e32 v143, 1.0, v143
	v_add_f32_e32 v144, 1.0, v144
	v_add_f32_e32 v145, 1.0, v145
	v_add_f32_e32 v146, 1.0, v146
	v_add_f32_e32 v147, 1.0, v147
	v_rcp_f32_e32 v142, v142
	v_rcp_f32_e32 v143, v143
	v_rcp_f32_e32 v144, v144
	v_rcp_f32_e32 v145, v145
	v_rcp_f32_e32 v146, v146
	v_rcp_f32_e32 v147, v147
	v_add_f32_e32 v148, 1.0, v148
	v_add_f32_e32 v149, 1.0, v149
	v_rcp_f32_e32 v148, v148
	v_rcp_f32_e32 v149, v149
	v_pk_mul_f32 v[144:145], v[112:113], v[144:145]
	v_pk_mul_f32 v[142:143], v[110:111], v[142:143]
	v_pk_mul_f32 v[146:147], v[106:107], v[146:147]
	v_cvt_pk_bf16_f32 v142, v142, v143
	v_cvt_pk_bf16_f32 v143, v144, v145
	v_cvt_pk_bf16_f32 v144, v146, v147
	v_lshlrev_b32_e32 v146, 7, v175
	v_pk_mul_f32 v[148:149], v[108:109], v[148:149]
	v_and_b32_e32 v146, 0x3f80, v146
	v_mov_b32_e32 v147, v187
	v_cvt_pk_bf16_f32 v145, v148, v149
	v_lshl_add_u64 v[148:149], v[168:169], 0, v[146:147]
	v_lshl_add_u64 v[148:149], v[148:149], 0, v[164:165]
	global_store_dwordx4 v[148:149], v[142:145], off sc1
	v_lshlrev_b32_e32 v148, 16, v140
	v_and_b32_e32 v149, 0xffff0000, v140
	v_lshlrev_b32_e32 v142, 16, v138
	v_and_b32_e32 v143, 0xffff0000, v138
	v_lshlrev_b32_e32 v144, 16, v139
	v_and_b32_e32 v145, 0xffff0000, v139
	v_lshlrev_b32_e32 v150, 16, v141
	v_and_b32_e32 v151, 0xffff0000, v141
	v_mul_f32_e32 v138, 0xbfb8aa3b, v142
	v_mul_f32_e32 v139, 0xbfb8aa3b, v143
	v_mul_f32_e32 v140, 0xbfb8aa3b, v144
	v_mul_f32_e32 v141, 0xbfb8aa3b, v145
	v_mul_f32_e32 v142, 0xbfb8aa3b, v148
	v_mul_f32_e32 v143, 0xbfb8aa3b, v149
	v_exp_f32_e32 v138, v138
	v_exp_f32_e32 v139, v139
	v_exp_f32_e32 v140, v140
	v_exp_f32_e32 v141, v141
	v_exp_f32_e32 v142, v142
	v_exp_f32_e32 v143, v143
	v_mul_f32_e32 v144, 0xbfb8aa3b, v150
	v_mul_f32_e32 v145, 0xbfb8aa3b, v151
	v_exp_f32_e32 v144, v144
	v_exp_f32_e32 v145, v145
	v_add_f32_e32 v138, 1.0, v138
	v_add_f32_e32 v139, 1.0, v139
	v_add_f32_e32 v140, 1.0, v140
	v_add_f32_e32 v141, 1.0, v141
	v_add_f32_e32 v142, 1.0, v142
	v_add_f32_e32 v143, 1.0, v143
	v_rcp_f32_e32 v138, v138
	v_rcp_f32_e32 v139, v139
	v_rcp_f32_e32 v140, v140
	v_rcp_f32_e32 v141, v141
	v_rcp_f32_e32 v142, v142
	v_rcp_f32_e32 v143, v143
	v_add_f32_e32 v144, 1.0, v144
	v_add_f32_e32 v145, 1.0, v145
	v_rcp_f32_e32 v144, v144
	v_rcp_f32_e32 v145, v145
	v_pk_mul_f32 v[140:141], v[80:81], v[140:141]
	v_pk_mul_f32 v[138:139], v[78:79], v[138:139]
	v_pk_mul_f32 v[142:143], v[74:75], v[142:143]
	v_pk_mul_f32 v[144:145], v[76:77], v[144:145]
	v_cvt_pk_bf16_f32 v138, v138, v139
	v_cvt_pk_bf16_f32 v139, v140, v141
	v_cvt_pk_bf16_f32 v140, v142, v143
	v_lshl_add_u64 v[142:143], v[154:155], 0, v[146:147]
	v_cvt_pk_bf16_f32 v141, v144, v145
	v_lshl_add_u64 v[142:143], v[142:143], 0, v[164:165]
	global_store_dwordx4 v[142:143], v[138:141], off sc1
	v_lshlrev_b32_e32 v142, 16, v136
	v_and_b32_e32 v143, 0xffff0000, v136
	v_lshlrev_b32_e32 v138, 16, v134
	v_and_b32_e32 v139, 0xffff0000, v134
	v_lshlrev_b32_e32 v140, 16, v135
	v_and_b32_e32 v141, 0xffff0000, v135
	v_lshlrev_b32_e32 v144, 16, v137
	v_and_b32_e32 v145, 0xffff0000, v137
	v_mul_f32_e32 v134, 0xbfb8aa3b, v138
	v_mul_f32_e32 v135, 0xbfb8aa3b, v139
	v_mul_f32_e32 v136, 0xbfb8aa3b, v140
	v_mul_f32_e32 v137, 0xbfb8aa3b, v141
	v_mul_f32_e32 v138, 0xbfb8aa3b, v142
	v_mul_f32_e32 v139, 0xbfb8aa3b, v143
	v_exp_f32_e32 v134, v134
	v_exp_f32_e32 v135, v135
	v_exp_f32_e32 v136, v136
	v_exp_f32_e32 v137, v137
	v_exp_f32_e32 v138, v138
	v_exp_f32_e32 v139, v139
	v_mul_f32_e32 v140, 0xbfb8aa3b, v144
	v_mul_f32_e32 v141, 0xbfb8aa3b, v145
	v_exp_f32_e32 v140, v140
	v_exp_f32_e32 v141, v141
	v_add_f32_e32 v134, 1.0, v134
	v_add_f32_e32 v135, 1.0, v135
	v_add_f32_e32 v136, 1.0, v136
	v_add_f32_e32 v137, 1.0, v137
	v_add_f32_e32 v138, 1.0, v138
	v_add_f32_e32 v139, 1.0, v139
	v_rcp_f32_e32 v134, v134
	v_rcp_f32_e32 v135, v135
	v_rcp_f32_e32 v136, v136
	v_rcp_f32_e32 v137, v137
	v_rcp_f32_e32 v138, v138
	v_rcp_f32_e32 v139, v139
	v_add_f32_e32 v140, 1.0, v140
	v_add_f32_e32 v141, 1.0, v141
	v_rcp_f32_e32 v140, v140
	v_rcp_f32_e32 v141, v141
	v_pk_mul_f32 v[136:137], v[104:105], v[136:137]
	v_pk_mul_f32 v[134:135], v[102:103], v[134:135]
	v_pk_mul_f32 v[138:139], v[98:99], v[138:139]
	v_cvt_pk_bf16_f32 v134, v134, v135
	v_cvt_pk_bf16_f32 v135, v136, v137
	v_cvt_pk_bf16_f32 v136, v138, v139
	v_lshlrev_b32_e32 v138, 7, v174
	v_pk_mul_f32 v[140:141], v[100:101], v[140:141]
	v_and_b32_e32 v138, 0x3f80, v138
	v_mov_b32_e32 v139, v187
	v_cvt_pk_bf16_f32 v137, v140, v141
	v_lshl_add_u64 v[140:141], v[168:169], 0, v[138:139]
	v_lshl_add_u64 v[140:141], v[140:141], 0, v[164:165]
	global_store_dwordx4 v[140:141], v[134:137], off sc1
	v_lshlrev_b32_e32 v140, 16, v132
	v_and_b32_e32 v141, 0xffff0000, v132
	v_lshlrev_b32_e32 v134, 16, v130
	v_and_b32_e32 v135, 0xffff0000, v130
	v_lshlrev_b32_e32 v136, 16, v131
	v_and_b32_e32 v137, 0xffff0000, v131
	v_lshlrev_b32_e32 v142, 16, v133
	v_and_b32_e32 v143, 0xffff0000, v133
	v_mul_f32_e32 v130, 0xbfb8aa3b, v134
	v_mul_f32_e32 v131, 0xbfb8aa3b, v135
	v_mul_f32_e32 v132, 0xbfb8aa3b, v136
	v_mul_f32_e32 v133, 0xbfb8aa3b, v137
	v_mul_f32_e32 v134, 0xbfb8aa3b, v140
	v_mul_f32_e32 v135, 0xbfb8aa3b, v141
	v_exp_f32_e32 v130, v130
	v_exp_f32_e32 v131, v131
	v_exp_f32_e32 v132, v132
	v_exp_f32_e32 v133, v133
	v_exp_f32_e32 v134, v134
	v_exp_f32_e32 v135, v135
	v_mul_f32_e32 v136, 0xbfb8aa3b, v142
	v_mul_f32_e32 v137, 0xbfb8aa3b, v143
	v_exp_f32_e32 v136, v136
	v_exp_f32_e32 v137, v137
	v_add_f32_e32 v130, 1.0, v130
	v_add_f32_e32 v131, 1.0, v131
	v_add_f32_e32 v132, 1.0, v132
	v_add_f32_e32 v133, 1.0, v133
	v_add_f32_e32 v134, 1.0, v134
	v_add_f32_e32 v135, 1.0, v135
	v_rcp_f32_e32 v130, v130
	v_rcp_f32_e32 v131, v131
	v_rcp_f32_e32 v132, v132
	v_rcp_f32_e32 v133, v133
	v_rcp_f32_e32 v134, v134
	v_rcp_f32_e32 v135, v135
	v_add_f32_e32 v136, 1.0, v136
	v_add_f32_e32 v137, 1.0, v137
	v_rcp_f32_e32 v136, v136
	v_rcp_f32_e32 v137, v137
	v_pk_mul_f32 v[132:133], v[68:69], v[132:133]
	v_pk_mul_f32 v[130:131], v[66:67], v[130:131]
	v_pk_mul_f32 v[134:135], v[58:59], v[134:135]
	v_pk_mul_f32 v[136:137], v[60:61], v[136:137]
	v_cvt_pk_bf16_f32 v130, v130, v131
	v_cvt_pk_bf16_f32 v131, v132, v133
	v_cvt_pk_bf16_f32 v132, v134, v135
	v_lshl_add_u64 v[134:135], v[154:155], 0, v[138:139]
	v_cvt_pk_bf16_f32 v133, v136, v137
	v_lshl_add_u64 v[134:135], v[134:135], 0, v[164:165]
	global_store_dwordx4 v[134:135], v[130:133], off sc1
	v_add_u32_e32 v160, 0x80, v162
	v_add_u32_e32 v158, 0x90, v162
	v_mad_i64_i32 v[130:131], s[30:31], v160, s59, v[166:167]
	global_load_dwordx4 v[168:171], v[130:131], off
	global_load_dwordx4 v[172:175], v[130:131], off offset:256
	v_mad_i64_i32 v[130:131], s[30:31], v158, s59, v[166:167]
	v_add_u32_e32 v156, 0xa0, v162
	global_load_dwordx4 v[150:153], v[130:131], off
	global_load_dwordx4 v[146:149], v[130:131], off offset:256
	v_mad_i64_i32 v[130:131], s[30:31], v156, s59, v[166:167]
	v_add_u32_e32 v154, 0xb0, v162
	global_load_dwordx4 v[142:145], v[130:131], off
	global_load_dwordx4 v[138:141], v[130:131], off offset:256
	v_mad_i64_i32 v[130:131], s[30:31], v154, s59, v[166:167]
	v_ashrrev_i32_e32 v161, 31, v160
	global_load_dwordx4 v[134:137], v[130:131], off
	s_nop 0
	global_load_dwordx4 v[130:133], v[130:131], off offset:256
	v_ashrrev_i32_e32 v159, 31, v158
	v_ashrrev_i32_e32 v157, 31, v156
	v_ashrrev_i32_e32 v155, 31, v154
	s_waitcnt vmcnt(7)
	v_lshlrev_b32_e32 v163, 16, v168
	v_mul_f32_e32 v163, 0xbfb8aa3b, v163
	v_exp_f32_e32 v163, v163
	v_and_b32_e32 v167, 0xffff0000, v168
	v_lshlrev_b32_e32 v168, 16, v169
	v_and_b32_e32 v169, 0xffff0000, v169
	v_add_f32_e32 v163, 1.0, v163
	v_rcp_f32_e32 v166, v163
	v_mul_f32_e32 v163, 0xbfb8aa3b, v167
	v_exp_f32_e32 v163, v163
	v_lshlrev_b32_e32 v176, 16, v170
	v_and_b32_e32 v177, 0xffff0000, v170
	v_lshlrev_b32_e32 v198, 16, v171
	v_add_f32_e32 v163, 1.0, v163
	v_rcp_f32_e32 v167, v163
	v_mul_f32_e32 v163, 0xbfb8aa3b, v168
	v_exp_f32_e32 v163, v163
	v_and_b32_e32 v199, 0xffff0000, v171
	v_pk_mul_f32 v[166:167], v[70:71], v[166:167]
	v_add_f32_e32 v163, 1.0, v163
	v_rcp_f32_e32 v168, v163
	v_mul_f32_e32 v163, 0xbfb8aa3b, v169
	v_exp_f32_e32 v163, v163
	v_cvt_pk_bf16_f32 v166, v166, v167
	v_add_f32_e32 v163, 1.0, v163
	v_rcp_f32_e32 v169, v163
	v_mul_f32_e32 v163, 0xbfb8aa3b, v176
	v_exp_f32_e32 v163, v163
	v_pk_mul_f32 v[168:169], v[72:73], v[168:169]
	s_nop 0
	v_cvt_pk_bf16_f32 v167, v168, v169
	v_add_f32_e32 v163, 1.0, v163
	v_rcp_f32_e32 v170, v163
	v_mul_f32_e32 v163, 0xbfb8aa3b, v177
	v_exp_f32_e32 v163, v163
	s_nop 0
	v_add_f32_e32 v163, 1.0, v163
	v_rcp_f32_e32 v171, v163
	v_mul_f32_e32 v163, 0xbfb8aa3b, v198
	v_exp_f32_e32 v163, v163
	v_pk_mul_f32 v[170:171], v[62:63], v[170:171]
	s_nop 0
	v_cvt_pk_bf16_f32 v168, v170, v171
	v_add_f32_e32 v163, 1.0, v163
	v_rcp_f32_e32 v176, v163
	v_mul_f32_e32 v163, 0xbfb8aa3b, v199
	v_exp_f32_e32 v163, v163
	v_lshrrev_b64 v[170:171], 1, v[160:161]
	v_and_b32_e32 v171, 0x7fffffff, v171
	v_and_b32_e32 v170, 0xffffffc0, v170
	v_add_f32_e32 v163, 1.0, v163
	v_rcp_f32_e32 v177, v163
	s_waitcnt vmcnt(6)
	v_lshlrev_b32_e32 v163, 16, v172
	v_mul_f32_e32 v163, 0xbfb8aa3b, v163
	v_lshlrev_b32_e32 v160, 7, v160
	v_pk_mul_f32 v[176:177], v[64:65], v[176:177]
	v_exp_f32_e32 v163, v163
	v_cvt_pk_bf16_f32 v169, v176, v177
	v_lshl_add_u64 v[176:177], v[170:171], 0, s[24:25]
	v_lshlrev_b64 v[176:177], 14, v[176:177]
	v_lshl_add_u64 v[176:177], s[28:29], 0, v[176:177]
	v_and_b32_e32 v160, 0x3f80, v160
	v_mov_b32_e32 v161, v187
	v_lshl_add_u64 v[176:177], v[176:177], 0, v[160:161]
	v_lshl_add_u64 v[176:177], v[176:177], 0, v[164:165]
	global_store_dwordx4 v[176:177], v[166:169], off sc1
	v_add_f32_e32 v163, 1.0, v163
	v_lshl_add_u64 v[170:171], v[170:171], 0, s[26:27]
	v_and_b32_e32 v167, 0xffff0000, v172
	v_rcp_f32_e32 v166, v163
	v_mul_f32_e32 v163, 0xbfb8aa3b, v167
	v_exp_f32_e32 v163, v163
	v_lshlrev_b32_e32 v168, 16, v173
	v_and_b32_e32 v169, 0xffff0000, v173
	v_lshlrev_b32_e32 v172, 16, v174
	v_add_f32_e32 v163, 1.0, v163
	v_rcp_f32_e32 v167, v163
	v_mul_f32_e32 v163, 0xbfb8aa3b, v168
	v_exp_f32_e32 v163, v163
	v_and_b32_e32 v173, 0xffff0000, v174
	v_lshlrev_b32_e32 v174, 16, v175
	v_and_b32_e32 v175, 0xffff0000, v175
	v_add_f32_e32 v163, 1.0, v163
	v_rcp_f32_e32 v168, v163
	v_mul_f32_e32 v163, 0xbfb8aa3b, v169
	v_exp_f32_e32 v163, v163
	v_lshlrev_b64 v[170:171], 14, v[170:171]
	v_lshl_add_u64 v[170:171], s[28:29], 0, v[170:171]
	v_pk_mul_f32 v[166:167], v[30:31], v[166:167]
	v_add_f32_e32 v163, 1.0, v163
	v_rcp_f32_e32 v169, v163
	v_mul_f32_e32 v163, 0xbfb8aa3b, v172
	v_exp_f32_e32 v163, v163
	v_lshl_add_u64 v[160:161], v[170:171], 0, v[160:161]
	v_pk_mul_f32 v[168:169], v[32:33], v[168:169]
	v_cvt_pk_bf16_f32 v166, v166, v167
	v_add_f32_e32 v163, 1.0, v163
	v_rcp_f32_e32 v172, v163
	v_mul_f32_e32 v163, 0xbfb8aa3b, v173
	v_exp_f32_e32 v163, v163
	v_cvt_pk_bf16_f32 v167, v168, v169
	v_lshl_add_u64 v[160:161], v[160:161], 0, v[164:165]
	s_waitcnt vmcnt(6)
	v_and_b32_e32 v170, 0xffff0000, v153
	v_add_f32_e32 v163, 1.0, v163
	v_rcp_f32_e32 v173, v163
	v_mul_f32_e32 v163, 0xbfb8aa3b, v174
	v_exp_f32_e32 v163, v163
	v_pk_mul_f32 v[172:173], v[26:27], v[172:173]
	s_nop 0
	v_cvt_pk_bf16_f32 v168, v172, v173
	v_add_f32_e32 v163, 1.0, v163
	v_rcp_f32_e32 v174, v163
	v_mul_f32_e32 v163, 0xbfb8aa3b, v175
	v_exp_f32_e32 v163, v163
	s_nop 0
	v_add_f32_e32 v163, 1.0, v163
	v_rcp_f32_e32 v175, v163
	v_lshlrev_b32_e32 v163, 16, v151
	v_pk_mul_f32 v[174:175], v[28:29], v[174:175]
	s_nop 0
	v_cvt_pk_bf16_f32 v169, v174, v175
	global_store_dwordx4 v[160:161], v[166:169], off sc1
	v_lshlrev_b32_e32 v160, 16, v150
	v_and_b32_e32 v161, 0xffff0000, v150
	v_lshlrev_b32_e32 v169, 16, v153
	v_lshlrev_b32_e32 v167, 16, v152
	v_and_b32_e32 v168, 0xffff0000, v152
	v_mul_f32_e32 v152, 0xbfb8aa3b, v163
	v_mul_f32_e32 v163, 0xbfb8aa3b, v169
	v_exp_f32_e32 v163, v163
	v_and_b32_e32 v166, 0xffff0000, v151
	v_mul_f32_e32 v150, 0xbfb8aa3b, v160
	v_mul_f32_e32 v151, 0xbfb8aa3b, v161
	v_mul_f32_e32 v153, 0xbfb8aa3b, v166
	v_mul_f32_e32 v160, 0xbfb8aa3b, v167
	v_mul_f32_e32 v161, 0xbfb8aa3b, v168
	v_exp_f32_e32 v150, v150
	v_exp_f32_e32 v151, v151
	v_exp_f32_e32 v152, v152
	v_exp_f32_e32 v153, v153
	v_exp_f32_e32 v160, v160
	v_exp_f32_e32 v161, v161
	v_add_f32_e32 v163, 1.0, v163
	v_rcp_f32_e32 v166, v163
	v_mul_f32_e32 v163, 0xbfb8aa3b, v170
	v_exp_f32_e32 v163, v163
	v_add_f32_e32 v150, 1.0, v150
	v_add_f32_e32 v151, 1.0, v151
	v_add_f32_e32 v152, 1.0, v152
	v_add_f32_e32 v153, 1.0, v153
	v_add_f32_e32 v160, 1.0, v160
	v_add_f32_e32 v161, 1.0, v161
	v_rcp_f32_e32 v150, v150
	v_rcp_f32_e32 v151, v151
	v_rcp_f32_e32 v152, v152
	v_rcp_f32_e32 v153, v153
	v_rcp_f32_e32 v160, v160
	v_rcp_f32_e32 v161, v161
	v_add_f32_e32 v163, 1.0, v163
	v_rcp_f32_e32 v167, v163
	v_pk_mul_f32 v[152:153], v[56:57], v[152:153]
	v_pk_mul_f32 v[150:151], v[54:55], v[150:151]
	v_pk_mul_f32 v[160:161], v[50:51], v[160:161]
	v_cvt_pk_bf16_f32 v150, v150, v151
	v_cvt_pk_bf16_f32 v151, v152, v153
	v_cvt_pk_bf16_f32 v152, v160, v161
	v_lshrrev_b64 v[160:161], 1, v[158:159]
	v_pk_mul_f32 v[166:167], v[52:53], v[166:167]
	v_and_b32_e32 v161, 0x7fffffff, v161
	v_and_b32_e32 v160, 0xffffffc0, v160
	v_cvt_pk_bf16_f32 v153, v166, v167
	v_lshl_add_u64 v[166:167], v[160:161], 0, s[24:25]
	v_lshlrev_b64 v[166:167], 14, v[166:167]
	v_lshlrev_b32_e32 v158, 7, v158
	v_lshl_add_u64 v[166:167], s[28:29], 0, v[166:167]
	v_and_b32_e32 v158, 0x3f80, v158
	v_mov_b32_e32 v159, v187
	v_lshl_add_u64 v[166:167], v[166:167], 0, v[158:159]
	v_lshl_add_u64 v[166:167], v[166:167], 0, v[164:165]
	global_store_dwordx4 v[166:167], v[150:153], off sc1
	s_waitcnt vmcnt(7)
	v_lshlrev_b32_e32 v163, 16, v148
	v_and_b32_e32 v166, 0xffff0000, v148
	v_lshlrev_b32_e32 v150, 16, v146
	v_and_b32_e32 v151, 0xffff0000, v146
	v_lshlrev_b32_e32 v152, 16, v147
	v_and_b32_e32 v153, 0xffff0000, v147
	v_lshlrev_b32_e32 v167, 16, v149
	v_and_b32_e32 v168, 0xffff0000, v149
	v_mul_f32_e32 v146, 0xbfb8aa3b, v150
	v_mul_f32_e32 v147, 0xbfb8aa3b, v151
	v_mul_f32_e32 v148, 0xbfb8aa3b, v152
	v_mul_f32_e32 v149, 0xbfb8aa3b, v153
	v_mul_f32_e32 v150, 0xbfb8aa3b, v163
	v_mul_f32_e32 v151, 0xbfb8aa3b, v166
	v_exp_f32_e32 v146, v146
	v_exp_f32_e32 v147, v147
	v_exp_f32_e32 v148, v148
	v_exp_f32_e32 v149, v149
	v_exp_f32_e32 v150, v150
	v_exp_f32_e32 v151, v151
	v_mul_f32_e32 v152, 0xbfb8aa3b, v167
	v_mul_f32_e32 v153, 0xbfb8aa3b, v168
	v_add_f32_e32 v146, 1.0, v146
	v_add_f32_e32 v147, 1.0, v147
	v_add_f32_e32 v148, 1.0, v148
	v_add_f32_e32 v149, 1.0, v149
	v_add_f32_e32 v150, 1.0, v150
	v_add_f32_e32 v151, 1.0, v151
	v_exp_f32_e32 v152, v152
	v_exp_f32_e32 v153, v153
	v_rcp_f32_e32 v146, v146
	v_rcp_f32_e32 v147, v147
	v_rcp_f32_e32 v148, v148
	v_rcp_f32_e32 v149, v149
	v_rcp_f32_e32 v150, v150
	v_rcp_f32_e32 v151, v151
	v_add_f32_e32 v152, 1.0, v152
	v_add_f32_e32 v153, 1.0, v153
	v_pk_mul_f32 v[148:149], v[24:25], v[148:149]
	v_pk_mul_f32 v[146:147], v[22:23], v[146:147]
	v_rcp_f32_e32 v152, v152
	v_rcp_f32_e32 v153, v153
	v_pk_mul_f32 v[150:151], v[18:19], v[150:151]
	v_cvt_pk_bf16_f32 v146, v146, v147
	v_cvt_pk_bf16_f32 v147, v148, v149
	v_cvt_pk_bf16_f32 v148, v150, v151
	v_lshl_add_u64 v[150:151], v[160:161], 0, s[26:27]
	v_lshlrev_b64 v[150:151], 14, v[150:151]
	v_lshl_add_u64 v[150:151], s[28:29], 0, v[150:151]
	v_pk_mul_f32 v[152:153], v[20:21], v[152:153]
	v_lshl_add_u64 v[150:151], v[150:151], 0, v[158:159]
	v_cvt_pk_bf16_f32 v149, v152, v153
	v_lshl_add_u64 v[150:151], v[150:151], 0, v[164:165]
	global_store_dwordx4 v[150:151], v[146:149], off sc1
	s_waitcnt vmcnt(7)
	v_lshlrev_b32_e32 v150, 16, v144
	v_and_b32_e32 v151, 0xffff0000, v144
	v_lshlrev_b32_e32 v146, 16, v142
	v_and_b32_e32 v147, 0xffff0000, v142
	v_lshlrev_b32_e32 v148, 16, v143
	v_and_b32_e32 v149, 0xffff0000, v143
	v_lshlrev_b32_e32 v152, 16, v145
	v_and_b32_e32 v153, 0xffff0000, v145
	v_mul_f32_e32 v142, 0xbfb8aa3b, v146
	v_mul_f32_e32 v143, 0xbfb8aa3b, v147
	v_mul_f32_e32 v144, 0xbfb8aa3b, v148
	v_mul_f32_e32 v145, 0xbfb8aa3b, v149
	v_mul_f32_e32 v146, 0xbfb8aa3b, v150
	v_mul_f32_e32 v147, 0xbfb8aa3b, v151
	v_exp_f32_e32 v142, v142
	v_exp_f32_e32 v143, v143
	v_exp_f32_e32 v144, v144
	v_exp_f32_e32 v145, v145
	v_exp_f32_e32 v146, v146
	v_exp_f32_e32 v147, v147
	v_mul_f32_e32 v148, 0xbfb8aa3b, v152
	v_mul_f32_e32 v149, 0xbfb8aa3b, v153
	v_exp_f32_e32 v148, v148
	v_exp_f32_e32 v149, v149
	v_add_f32_e32 v142, 1.0, v142
	v_add_f32_e32 v143, 1.0, v143
	v_add_f32_e32 v144, 1.0, v144
	v_add_f32_e32 v145, 1.0, v145
	v_add_f32_e32 v146, 1.0, v146
	v_add_f32_e32 v147, 1.0, v147
	v_rcp_f32_e32 v142, v142
	v_rcp_f32_e32 v143, v143
	v_rcp_f32_e32 v144, v144
	v_rcp_f32_e32 v145, v145
	v_rcp_f32_e32 v146, v146
	v_rcp_f32_e32 v147, v147
	v_add_f32_e32 v148, 1.0, v148
	v_add_f32_e32 v149, 1.0, v149
	v_rcp_f32_e32 v148, v148
	v_rcp_f32_e32 v149, v149
	v_pk_mul_f32 v[144:145], v[48:49], v[144:145]
	v_pk_mul_f32 v[142:143], v[46:47], v[142:143]
	v_pk_mul_f32 v[146:147], v[42:43], v[146:147]
	v_cvt_pk_bf16_f32 v142, v142, v143
	v_cvt_pk_bf16_f32 v143, v144, v145
	v_cvt_pk_bf16_f32 v144, v146, v147
	v_lshrrev_b64 v[146:147], 1, v[156:157]
	v_pk_mul_f32 v[148:149], v[44:45], v[148:149]
	v_and_b32_e32 v147, 0x7fffffff, v147
	v_and_b32_e32 v146, 0xffffffc0, v146
	v_cvt_pk_bf16_f32 v145, v148, v149
	v_lshl_add_u64 v[148:149], v[146:147], 0, s[24:25]
	v_lshlrev_b64 v[148:149], 14, v[148:149]
	v_lshlrev_b32_e32 v150, 7, v156
	v_lshl_add_u64 v[148:149], s[28:29], 0, v[148:149]
	v_and_b32_e32 v150, 0x3f80, v150
	v_mov_b32_e32 v151, v187
	v_lshl_add_u64 v[148:149], v[148:149], 0, v[150:151]
	v_lshl_add_u64 v[148:149], v[148:149], 0, v[164:165]
	global_store_dwordx4 v[148:149], v[142:145], off sc1
	s_waitcnt vmcnt(7)
	v_lshlrev_b32_e32 v148, 16, v140
	v_and_b32_e32 v149, 0xffff0000, v140
	v_lshlrev_b32_e32 v142, 16, v138
	v_and_b32_e32 v143, 0xffff0000, v138
	v_lshlrev_b32_e32 v144, 16, v139
	v_and_b32_e32 v145, 0xffff0000, v139
	v_lshlrev_b32_e32 v152, 16, v141
	v_and_b32_e32 v153, 0xffff0000, v141
	v_mul_f32_e32 v138, 0xbfb8aa3b, v142
	v_mul_f32_e32 v139, 0xbfb8aa3b, v143
	v_mul_f32_e32 v140, 0xbfb8aa3b, v144
	v_mul_f32_e32 v141, 0xbfb8aa3b, v145
	v_mul_f32_e32 v142, 0xbfb8aa3b, v148
	v_mul_f32_e32 v143, 0xbfb8aa3b, v149
	v_exp_f32_e32 v138, v138
	v_exp_f32_e32 v139, v139
	v_exp_f32_e32 v140, v140
	v_exp_f32_e32 v141, v141
	v_exp_f32_e32 v142, v142
	v_exp_f32_e32 v143, v143
	v_mul_f32_e32 v144, 0xbfb8aa3b, v152
	v_mul_f32_e32 v145, 0xbfb8aa3b, v153
	v_add_f32_e32 v138, 1.0, v138
	v_add_f32_e32 v139, 1.0, v139
	v_add_f32_e32 v140, 1.0, v140
	v_add_f32_e32 v141, 1.0, v141
	v_add_f32_e32 v142, 1.0, v142
	v_add_f32_e32 v143, 1.0, v143
	v_exp_f32_e32 v144, v144
	v_exp_f32_e32 v145, v145
	v_rcp_f32_e32 v138, v138
	v_rcp_f32_e32 v139, v139
	v_rcp_f32_e32 v140, v140
	v_rcp_f32_e32 v141, v141
	v_rcp_f32_e32 v142, v142
	v_rcp_f32_e32 v143, v143
	v_add_f32_e32 v144, 1.0, v144
	v_add_f32_e32 v145, 1.0, v145
	v_pk_mul_f32 v[140:141], v[16:17], v[140:141]
	v_pk_mul_f32 v[138:139], v[14:15], v[138:139]
	v_rcp_f32_e32 v144, v144
	v_rcp_f32_e32 v145, v145
	v_pk_mul_f32 v[142:143], v[10:11], v[142:143]
	v_cvt_pk_bf16_f32 v138, v138, v139
	v_cvt_pk_bf16_f32 v139, v140, v141
	v_cvt_pk_bf16_f32 v140, v142, v143
	v_lshl_add_u64 v[142:143], v[146:147], 0, s[26:27]
	v_lshlrev_b64 v[142:143], 14, v[142:143]
	v_lshl_add_u64 v[142:143], s[28:29], 0, v[142:143]
	v_pk_mul_f32 v[144:145], v[12:13], v[144:145]
	v_lshl_add_u64 v[142:143], v[142:143], 0, v[150:151]
	v_cvt_pk_bf16_f32 v141, v144, v145
	v_lshl_add_u64 v[142:143], v[142:143], 0, v[164:165]
	global_store_dwordx4 v[142:143], v[138:141], off sc1
	s_waitcnt vmcnt(7)
	v_lshlrev_b32_e32 v142, 16, v136
	v_and_b32_e32 v143, 0xffff0000, v136
	v_lshlrev_b32_e32 v138, 16, v134
	v_and_b32_e32 v139, 0xffff0000, v134
	v_lshlrev_b32_e32 v140, 16, v135
	v_and_b32_e32 v141, 0xffff0000, v135
	v_lshlrev_b32_e32 v144, 16, v137
	v_and_b32_e32 v145, 0xffff0000, v137
	v_mul_f32_e32 v134, 0xbfb8aa3b, v138
	v_mul_f32_e32 v135, 0xbfb8aa3b, v139
	v_mul_f32_e32 v136, 0xbfb8aa3b, v140
	v_mul_f32_e32 v137, 0xbfb8aa3b, v141
	v_mul_f32_e32 v138, 0xbfb8aa3b, v142
	v_mul_f32_e32 v139, 0xbfb8aa3b, v143
	v_exp_f32_e32 v134, v134
	v_exp_f32_e32 v135, v135
	v_exp_f32_e32 v136, v136
	v_exp_f32_e32 v137, v137
	v_exp_f32_e32 v138, v138
	v_exp_f32_e32 v139, v139
	v_mul_f32_e32 v140, 0xbfb8aa3b, v144
	v_mul_f32_e32 v141, 0xbfb8aa3b, v145
	v_exp_f32_e32 v140, v140
	v_exp_f32_e32 v141, v141
	v_add_f32_e32 v134, 1.0, v134
	v_add_f32_e32 v135, 1.0, v135
	v_add_f32_e32 v136, 1.0, v136
	v_add_f32_e32 v137, 1.0, v137
	v_add_f32_e32 v138, 1.0, v138
	v_add_f32_e32 v139, 1.0, v139
	v_rcp_f32_e32 v134, v134
	v_rcp_f32_e32 v135, v135
	v_rcp_f32_e32 v136, v136
	v_rcp_f32_e32 v137, v137
	v_rcp_f32_e32 v138, v138
	v_rcp_f32_e32 v139, v139
	v_add_f32_e32 v140, 1.0, v140
	v_add_f32_e32 v141, 1.0, v141
	v_rcp_f32_e32 v140, v140
	v_rcp_f32_e32 v141, v141
	v_pk_mul_f32 v[136:137], v[40:41], v[136:137]
	v_pk_mul_f32 v[134:135], v[38:39], v[134:135]
	v_pk_mul_f32 v[138:139], v[34:35], v[138:139]
	v_cvt_pk_bf16_f32 v134, v134, v135
	v_cvt_pk_bf16_f32 v135, v136, v137
	v_cvt_pk_bf16_f32 v136, v138, v139
	v_lshrrev_b64 v[138:139], 1, v[154:155]
	v_pk_mul_f32 v[140:141], v[36:37], v[140:141]
	v_and_b32_e32 v139, 0x7fffffff, v139
	v_and_b32_e32 v138, 0xffffffc0, v138
	v_cvt_pk_bf16_f32 v137, v140, v141
	v_lshl_add_u64 v[140:141], v[138:139], 0, s[24:25]
	v_lshlrev_b64 v[140:141], 14, v[140:141]
	v_lshlrev_b32_e32 v142, 7, v154
	v_lshl_add_u64 v[140:141], s[28:29], 0, v[140:141]
	v_and_b32_e32 v142, 0x3f80, v142
	v_mov_b32_e32 v143, v187
	v_lshl_add_u64 v[140:141], v[140:141], 0, v[142:143]
	v_lshl_add_u64 v[140:141], v[140:141], 0, v[164:165]
	global_store_dwordx4 v[140:141], v[134:137], off sc1
	s_waitcnt vmcnt(7)
	v_lshlrev_b32_e32 v140, 16, v132
	v_and_b32_e32 v141, 0xffff0000, v132
	v_lshlrev_b32_e32 v134, 16, v130
	v_and_b32_e32 v135, 0xffff0000, v130
	v_lshlrev_b32_e32 v136, 16, v131
	v_and_b32_e32 v137, 0xffff0000, v131
	v_lshlrev_b32_e32 v144, 16, v133
	v_and_b32_e32 v145, 0xffff0000, v133
	v_mul_f32_e32 v130, 0xbfb8aa3b, v134
	v_mul_f32_e32 v131, 0xbfb8aa3b, v135
	v_mul_f32_e32 v132, 0xbfb8aa3b, v136
	v_mul_f32_e32 v133, 0xbfb8aa3b, v137
	v_mul_f32_e32 v134, 0xbfb8aa3b, v140
	v_mul_f32_e32 v135, 0xbfb8aa3b, v141
	v_exp_f32_e32 v130, v130
	v_exp_f32_e32 v131, v131
	v_exp_f32_e32 v132, v132
	v_exp_f32_e32 v133, v133
	v_exp_f32_e32 v134, v134
	v_exp_f32_e32 v135, v135
	v_mul_f32_e32 v136, 0xbfb8aa3b, v144
	v_mul_f32_e32 v137, 0xbfb8aa3b, v145
	v_add_f32_e32 v130, 1.0, v130
	v_add_f32_e32 v131, 1.0, v131
	v_add_f32_e32 v132, 1.0, v132
	v_add_f32_e32 v133, 1.0, v133
	v_add_f32_e32 v134, 1.0, v134
	v_add_f32_e32 v135, 1.0, v135
	v_exp_f32_e32 v136, v136
	v_exp_f32_e32 v137, v137
	v_rcp_f32_e32 v130, v130
	v_rcp_f32_e32 v131, v131
	v_rcp_f32_e32 v132, v132
	v_rcp_f32_e32 v133, v133
	v_rcp_f32_e32 v134, v134
	v_rcp_f32_e32 v135, v135
	v_add_f32_e32 v136, 1.0, v136
	v_add_f32_e32 v137, 1.0, v137
	v_pk_mul_f32 v[132:133], v[8:9], v[132:133]
	v_pk_mul_f32 v[130:131], v[6:7], v[130:131]
	v_rcp_f32_e32 v136, v136
	v_rcp_f32_e32 v137, v137
	v_pk_mul_f32 v[134:135], v[2:3], v[134:135]
	v_cvt_pk_bf16_f32 v130, v130, v131
	v_cvt_pk_bf16_f32 v131, v132, v133
	v_cvt_pk_bf16_f32 v132, v134, v135
	v_lshl_add_u64 v[134:135], v[138:139], 0, s[26:27]
	v_lshlrev_b64 v[134:135], 14, v[134:135]
	v_lshl_add_u64 v[134:135], s[28:29], 0, v[134:135]
	v_pk_mul_f32 v[136:137], v[4:5], v[136:137]
	v_lshl_add_u64 v[134:135], v[134:135], 0, v[142:143]
	v_cvt_pk_bf16_f32 v133, v136, v137
	v_lshl_add_u64 v[134:135], v[134:135], 0, v[164:165]
	global_store_dwordx4 v[134:135], v[130:133], off sc1
	s_branch .LBB0_1009

.LBB0_1011:
	s_and_b64 vcc, exec, s[4:5]
	s_cbranch_vccnz .Lwtp9_entry
	s_lshl_b32 s24, s64, 8
	s_or_b32 s26, s24, s41
	v_or_b32_e32 v130, s26, v188
	v_ashrrev_i32_e32 v131, 31, v130
	v_lshl_add_u64 v[166:167], v[130:131], 1, s[16:17]
	v_mad_i64_i32 v[130:131], s[24:25], v162, s59, v[166:167]
	global_load_dwordx4 v[158:161], v[130:131], off
	global_load_dwordx4 v[154:157], v[130:131], off offset:256
	v_or_b32_e32 v176, 16, v162
	v_mad_i64_i32 v[130:131], s[24:25], v176, s59, v[166:167]
	global_load_dwordx4 v[150:153], v[130:131], off
	global_load_dwordx4 v[146:149], v[130:131], off offset:256
	v_or_b32_e32 v175, 32, v162
	v_mad_i64_i32 v[130:131], s[24:25], v175, s59, v[166:167]
	global_load_dwordx4 v[142:145], v[130:131], off
	global_load_dwordx4 v[138:141], v[130:131], off offset:256
	v_or_b32_e32 v174, 48, v162
	v_ashrrev_i32_e32 v163, 31, v162
	v_mad_i64_i32 v[130:131], s[24:25], v174, s59, v[166:167]
	s_ashr_i32 s24, s26, 6
	s_ashr_i32 s25, s24, 31
	v_bitop3_b32 v177, s26, 56, v188 bitop3:0xc8
	global_load_dwordx4 v[134:137], v[130:131], off
	s_nop 0
	global_load_dwordx4 v[130:133], v[130:131], off offset:256
	s_or_b32 s26, s24, 2
	s_ashr_i32 s27, s26, 31
	s_waitcnt vmcnt(0)
	v_lshlrev_b32_e32 v164, 16, v158
	v_and_b32_e32 v165, 0xffff0000, v158
	v_lshlrev_b32_e32 v168, 16, v159
	v_and_b32_e32 v169, 0xffff0000, v159
	v_lshlrev_b32_e32 v170, 16, v160
	v_and_b32_e32 v171, 0xffff0000, v160
	v_lshlrev_b32_e32 v172, 16, v161
	v_and_b32_e32 v173, 0xffff0000, v161
	v_mul_f32_e32 v158, 0xbfb8aa3b, v164
	v_mul_f32_e32 v159, 0xbfb8aa3b, v165
	v_mul_f32_e32 v160, 0xbfb8aa3b, v168
	v_mul_f32_e32 v161, 0xbfb8aa3b, v169
	v_mul_f32_e32 v164, 0xbfb8aa3b, v170
	v_mul_f32_e32 v165, 0xbfb8aa3b, v171
	v_exp_f32_e32 v158, v158
	v_exp_f32_e32 v159, v159
	v_exp_f32_e32 v160, v160
	v_exp_f32_e32 v161, v161
	v_exp_f32_e32 v164, v164
	v_exp_f32_e32 v165, v165
	v_mul_f32_e32 v168, 0xbfb8aa3b, v172
	v_mul_f32_e32 v169, 0xbfb8aa3b, v173
	v_add_f32_e32 v158, 1.0, v158
	v_add_f32_e32 v159, 1.0, v159
	v_add_f32_e32 v160, 1.0, v160
	v_add_f32_e32 v161, 1.0, v161
	v_add_f32_e32 v164, 1.0, v164
	v_add_f32_e32 v165, 1.0, v165
	v_exp_f32_e32 v168, v168
	v_exp_f32_e32 v169, v169
	v_rcp_f32_e32 v158, v158
	v_rcp_f32_e32 v159, v159
	v_rcp_f32_e32 v160, v160
	v_rcp_f32_e32 v161, v161
	v_rcp_f32_e32 v164, v164
	v_rcp_f32_e32 v165, v165
	v_add_f32_e32 v168, 1.0, v168
	v_add_f32_e32 v169, 1.0, v169
	v_pk_mul_f32 v[160:161], v[128:129], v[160:161]
	v_pk_mul_f32 v[158:159], v[126:127], v[158:159]
	v_rcp_f32_e32 v168, v168
	v_rcp_f32_e32 v169, v169
	v_pk_mul_f32 v[164:165], v[122:123], v[164:165]
	v_cvt_pk_bf16_f32 v158, v158, v159
	v_cvt_pk_bf16_f32 v159, v160, v161
	v_cvt_pk_bf16_f32 v160, v164, v165
	v_lshrrev_b64 v[164:165], 1, v[162:163]
	v_and_b32_e32 v171, 0x7fffffff, v165
	v_and_b32_e32 v170, 0xffffffc0, v164
	v_lshl_add_u64 v[164:165], v[170:171], 0, s[24:25]
	v_pk_mul_f32 v[168:169], v[124:125], v[168:169]
	v_lshlrev_b64 v[164:165], 14, v[164:165]
	v_lshlrev_b32_e32 v163, 7, v162
	v_cvt_pk_bf16_f32 v161, v168, v169
	v_lshl_add_u64 v[168:169], s[28:29], 0, v[164:165]
	v_and_b32_e32 v172, 0x2780, v163
	v_mov_b32_e32 v173, v187
	v_lshl_add_u64 v[198:199], v[168:169], 0, v[172:173]
	v_lshlrev_b32_e32 v164, 1, v177
	v_mov_b32_e32 v165, v187
	v_lshl_add_u64 v[198:199], v[198:199], 0, v[164:165]
	global_store_dwordx4 v[198:199], v[158:161], off
	v_lshlrev_b32_e32 v163, 16, v156
	v_and_b32_e32 v177, 0xffff0000, v156
	v_lshlrev_b32_e32 v160, 16, v155
	v_and_b32_e32 v161, 0xffff0000, v155
	v_lshlrev_b32_e32 v198, 16, v157
	v_and_b32_e32 v199, 0xffff0000, v157
	v_mul_f32_e32 v156, 0xbfb8aa3b, v160
	v_mul_f32_e32 v157, 0xbfb8aa3b, v161
	v_exp_f32_e32 v156, v156
	v_exp_f32_e32 v157, v157
	v_lshlrev_b32_e32 v158, 16, v154
	v_and_b32_e32 v159, 0xffff0000, v154
	v_add_f32_e32 v156, 1.0, v156
	v_add_f32_e32 v157, 1.0, v157
	v_rcp_f32_e32 v156, v156
	v_rcp_f32_e32 v157, v157
	v_mul_f32_e32 v154, 0xbfb8aa3b, v158
	v_mul_f32_e32 v155, 0xbfb8aa3b, v159
	v_exp_f32_e32 v154, v154
	v_exp_f32_e32 v155, v155
	v_pk_mul_f32 v[158:159], v[96:97], v[156:157]
	v_mul_f32_e32 v156, 0xbfb8aa3b, v163
	v_mul_f32_e32 v157, 0xbfb8aa3b, v177
	v_exp_f32_e32 v156, v156
	v_exp_f32_e32 v157, v157
	v_mul_f32_e32 v160, 0xbfb8aa3b, v198
	v_mul_f32_e32 v161, 0xbfb8aa3b, v199
	v_exp_f32_e32 v160, v160
	v_exp_f32_e32 v161, v161
	v_add_f32_e32 v154, 1.0, v154
	v_add_f32_e32 v155, 1.0, v155
	v_rcp_f32_e32 v154, v154
	v_rcp_f32_e32 v155, v155
	v_add_f32_e32 v156, 1.0, v156
	v_add_f32_e32 v157, 1.0, v157
	v_rcp_f32_e32 v156, v156
	v_rcp_f32_e32 v157, v157
	v_add_f32_e32 v160, 1.0, v160
	v_add_f32_e32 v161, 1.0, v161
	v_rcp_f32_e32 v160, v160
	v_rcp_f32_e32 v161, v161
	v_pk_mul_f32 v[154:155], v[94:95], v[154:155]
	v_pk_mul_f32 v[198:199], v[90:91], v[156:157]
	v_cvt_pk_bf16_f32 v156, v154, v155
	v_lshl_add_u64 v[154:155], v[170:171], 0, s[26:27]
	v_lshlrev_b64 v[154:155], 14, v[154:155]
	v_pk_mul_f32 v[160:161], v[92:93], v[160:161]
	v_lshl_add_u64 v[154:155], s[28:29], 0, v[154:155]
	v_cvt_pk_bf16_f32 v157, v158, v159
	v_cvt_pk_bf16_f32 v159, v160, v161
	v_lshl_add_u64 v[160:161], v[154:155], 0, v[172:173]
	v_cvt_pk_bf16_f32 v158, v198, v199
	v_lshl_add_u64 v[160:161], v[160:161], 0, v[164:165]
	global_store_dwordx4 v[160:161], v[156:159], off
	v_lshlrev_b32_e32 v160, 16, v152
	v_and_b32_e32 v161, 0xffff0000, v152
	v_lshlrev_b32_e32 v156, 16, v150
	v_and_b32_e32 v157, 0xffff0000, v150
	v_lshlrev_b32_e32 v158, 16, v151
	v_and_b32_e32 v159, 0xffff0000, v151
	v_lshlrev_b32_e32 v163, 16, v153
	v_and_b32_e32 v170, 0xffff0000, v153
	v_mul_f32_e32 v150, 0xbfb8aa3b, v156
	v_mul_f32_e32 v151, 0xbfb8aa3b, v157
	v_mul_f32_e32 v152, 0xbfb8aa3b, v158
	v_mul_f32_e32 v153, 0xbfb8aa3b, v159
	v_mul_f32_e32 v156, 0xbfb8aa3b, v160
	v_mul_f32_e32 v157, 0xbfb8aa3b, v161
	v_exp_f32_e32 v150, v150
	v_exp_f32_e32 v151, v151
	v_exp_f32_e32 v152, v152
	v_exp_f32_e32 v153, v153
	v_exp_f32_e32 v156, v156
	v_exp_f32_e32 v157, v157
	v_mul_f32_e32 v158, 0xbfb8aa3b, v163
	v_mul_f32_e32 v159, 0xbfb8aa3b, v170
	v_exp_f32_e32 v158, v158
	v_exp_f32_e32 v159, v159
	v_add_f32_e32 v150, 1.0, v150
	v_add_f32_e32 v151, 1.0, v151
	v_add_f32_e32 v152, 1.0, v152
	v_add_f32_e32 v153, 1.0, v153
	v_add_f32_e32 v156, 1.0, v156
	v_add_f32_e32 v157, 1.0, v157
	v_rcp_f32_e32 v150, v150
	v_rcp_f32_e32 v151, v151
	v_rcp_f32_e32 v152, v152
	v_rcp_f32_e32 v153, v153
	v_rcp_f32_e32 v156, v156
	v_rcp_f32_e32 v157, v157
	v_add_f32_e32 v158, 1.0, v158
	v_add_f32_e32 v159, 1.0, v159
	v_rcp_f32_e32 v158, v158
	v_rcp_f32_e32 v159, v159
	v_pk_mul_f32 v[152:153], v[120:121], v[152:153]
	v_pk_mul_f32 v[150:151], v[118:119], v[150:151]
	v_pk_mul_f32 v[156:157], v[114:115], v[156:157]
	v_cvt_pk_bf16_f32 v150, v150, v151
	v_cvt_pk_bf16_f32 v151, v152, v153
	v_cvt_pk_bf16_f32 v152, v156, v157
	v_lshlrev_b32_e32 v156, 7, v176
	v_pk_mul_f32 v[158:159], v[116:117], v[158:159]
	v_and_b32_e32 v156, 0x3f80, v156
	v_mov_b32_e32 v157, v187
	v_cvt_pk_bf16_f32 v153, v158, v159
	v_lshl_add_u64 v[158:159], v[168:169], 0, v[156:157]
	v_lshl_add_u64 v[158:159], v[158:159], 0, v[164:165]
	global_store_dwordx4 v[158:159], v[150:153], off
	v_lshlrev_b32_e32 v158, 16, v148
	v_and_b32_e32 v159, 0xffff0000, v148
	v_lshlrev_b32_e32 v150, 16, v146
	v_and_b32_e32 v151, 0xffff0000, v146
	v_lshlrev_b32_e32 v152, 16, v147
	v_and_b32_e32 v153, 0xffff0000, v147
	v_lshlrev_b32_e32 v160, 16, v149
	v_and_b32_e32 v161, 0xffff0000, v149
	v_mul_f32_e32 v146, 0xbfb8aa3b, v150
	v_mul_f32_e32 v147, 0xbfb8aa3b, v151
	v_mul_f32_e32 v148, 0xbfb8aa3b, v152
	v_mul_f32_e32 v149, 0xbfb8aa3b, v153
	v_mul_f32_e32 v150, 0xbfb8aa3b, v158
	v_mul_f32_e32 v151, 0xbfb8aa3b, v159
	v_exp_f32_e32 v146, v146
	v_exp_f32_e32 v147, v147
	v_exp_f32_e32 v148, v148
	v_exp_f32_e32 v149, v149
	v_exp_f32_e32 v150, v150
	v_exp_f32_e32 v151, v151
	v_mul_f32_e32 v152, 0xbfb8aa3b, v160
	v_mul_f32_e32 v153, 0xbfb8aa3b, v161
	v_exp_f32_e32 v152, v152
	v_exp_f32_e32 v153, v153
	v_add_f32_e32 v146, 1.0, v146
	v_add_f32_e32 v147, 1.0, v147
	v_add_f32_e32 v148, 1.0, v148
	v_add_f32_e32 v149, 1.0, v149
	v_add_f32_e32 v150, 1.0, v150
	v_add_f32_e32 v151, 1.0, v151
	v_rcp_f32_e32 v146, v146
	v_rcp_f32_e32 v147, v147
	v_rcp_f32_e32 v148, v148
	v_rcp_f32_e32 v149, v149
	v_rcp_f32_e32 v150, v150
	v_rcp_f32_e32 v151, v151
	v_add_f32_e32 v152, 1.0, v152
	v_add_f32_e32 v153, 1.0, v153
	v_rcp_f32_e32 v152, v152
	v_rcp_f32_e32 v153, v153
	v_pk_mul_f32 v[148:149], v[88:89], v[148:149]
	v_pk_mul_f32 v[146:147], v[86:87], v[146:147]
	v_pk_mul_f32 v[150:151], v[82:83], v[150:151]
	v_pk_mul_f32 v[152:153], v[84:85], v[152:153]
	v_cvt_pk_bf16_f32 v146, v146, v147
	v_cvt_pk_bf16_f32 v147, v148, v149
	v_cvt_pk_bf16_f32 v148, v150, v151
	v_lshl_add_u64 v[150:151], v[154:155], 0, v[156:157]
	v_cvt_pk_bf16_f32 v149, v152, v153
	v_lshl_add_u64 v[150:151], v[150:151], 0, v[164:165]
	global_store_dwordx4 v[150:151], v[146:149], off
	v_lshlrev_b32_e32 v150, 16, v144
	v_and_b32_e32 v151, 0xffff0000, v144
	v_lshlrev_b32_e32 v146, 16, v142
	v_and_b32_e32 v147, 0xffff0000, v142
	v_lshlrev_b32_e32 v148, 16, v143
	v_and_b32_e32 v149, 0xffff0000, v143
	v_lshlrev_b32_e32 v152, 16, v145
	v_and_b32_e32 v153, 0xffff0000, v145
	v_mul_f32_e32 v142, 0xbfb8aa3b, v146
	v_mul_f32_e32 v143, 0xbfb8aa3b, v147
	v_mul_f32_e32 v144, 0xbfb8aa3b, v148
	v_mul_f32_e32 v145, 0xbfb8aa3b, v149
	v_mul_f32_e32 v146, 0xbfb8aa3b, v150
	v_mul_f32_e32 v147, 0xbfb8aa3b, v151
	v_exp_f32_e32 v142, v142
	v_exp_f32_e32 v143, v143
	v_exp_f32_e32 v144, v144
	v_exp_f32_e32 v145, v145
	v_exp_f32_e32 v146, v146
	v_exp_f32_e32 v147, v147
	v_mul_f32_e32 v148, 0xbfb8aa3b, v152
	v_mul_f32_e32 v149, 0xbfb8aa3b, v153
	v_exp_f32_e32 v148, v148
	v_exp_f32_e32 v149, v149
	v_add_f32_e32 v142, 1.0, v142
	v_add_f32_e32 v143, 1.0, v143
	v_add_f32_e32 v144, 1.0, v144
	v_add_f32_e32 v145, 1.0, v145
	v_add_f32_e32 v146, 1.0, v146
	v_add_f32_e32 v147, 1.0, v147
	v_rcp_f32_e32 v142, v142
	v_rcp_f32_e32 v143, v143
	v_rcp_f32_e32 v144, v144
	v_rcp_f32_e32 v145, v145
	v_rcp_f32_e32 v146, v146
	v_rcp_f32_e32 v147, v147
	v_add_f32_e32 v148, 1.0, v148
	v_add_f32_e32 v149, 1.0, v149
	v_rcp_f32_e32 v148, v148
	v_rcp_f32_e32 v149, v149
	v_pk_mul_f32 v[144:145], v[112:113], v[144:145]
	v_pk_mul_f32 v[142:143], v[110:111], v[142:143]
	v_pk_mul_f32 v[146:147], v[106:107], v[146:147]
	v_cvt_pk_bf16_f32 v142, v142, v143
	v_cvt_pk_bf16_f32 v143, v144, v145
	v_cvt_pk_bf16_f32 v144, v146, v147
	v_lshlrev_b32_e32 v146, 7, v175
	v_pk_mul_f32 v[148:149], v[108:109], v[148:149]
	v_and_b32_e32 v146, 0x3f80, v146
	v_mov_b32_e32 v147, v187
	v_cvt_pk_bf16_f32 v145, v148, v149
	v_lshl_add_u64 v[148:149], v[168:169], 0, v[146:147]
	v_lshl_add_u64 v[148:149], v[148:149], 0, v[164:165]
	global_store_dwordx4 v[148:149], v[142:145], off
	v_lshlrev_b32_e32 v148, 16, v140
	v_and_b32_e32 v149, 0xffff0000, v140
	v_lshlrev_b32_e32 v142, 16, v138
	v_and_b32_e32 v143, 0xffff0000, v138
	v_lshlrev_b32_e32 v144, 16, v139
	v_and_b32_e32 v145, 0xffff0000, v139
	v_lshlrev_b32_e32 v150, 16, v141
	v_and_b32_e32 v151, 0xffff0000, v141
	v_mul_f32_e32 v138, 0xbfb8aa3b, v142
	v_mul_f32_e32 v139, 0xbfb8aa3b, v143
	v_mul_f32_e32 v140, 0xbfb8aa3b, v144
	v_mul_f32_e32 v141, 0xbfb8aa3b, v145
	v_mul_f32_e32 v142, 0xbfb8aa3b, v148
	v_mul_f32_e32 v143, 0xbfb8aa3b, v149
	v_exp_f32_e32 v138, v138
	v_exp_f32_e32 v139, v139
	v_exp_f32_e32 v140, v140
	v_exp_f32_e32 v141, v141
	v_exp_f32_e32 v142, v142
	v_exp_f32_e32 v143, v143
	v_mul_f32_e32 v144, 0xbfb8aa3b, v150
	v_mul_f32_e32 v145, 0xbfb8aa3b, v151
	v_exp_f32_e32 v144, v144
	v_exp_f32_e32 v145, v145
	v_add_f32_e32 v138, 1.0, v138
	v_add_f32_e32 v139, 1.0, v139
	v_add_f32_e32 v140, 1.0, v140
	v_add_f32_e32 v141, 1.0, v141
	v_add_f32_e32 v142, 1.0, v142
	v_add_f32_e32 v143, 1.0, v143
	v_rcp_f32_e32 v138, v138
	v_rcp_f32_e32 v139, v139
	v_rcp_f32_e32 v140, v140
	v_rcp_f32_e32 v141, v141
	v_rcp_f32_e32 v142, v142
	v_rcp_f32_e32 v143, v143
	v_add_f32_e32 v144, 1.0, v144
	v_add_f32_e32 v145, 1.0, v145
	v_rcp_f32_e32 v144, v144
	v_rcp_f32_e32 v145, v145
	v_pk_mul_f32 v[140:141], v[80:81], v[140:141]
	v_pk_mul_f32 v[138:139], v[78:79], v[138:139]
	v_pk_mul_f32 v[142:143], v[74:75], v[142:143]
	v_pk_mul_f32 v[144:145], v[76:77], v[144:145]
	v_cvt_pk_bf16_f32 v138, v138, v139
	v_cvt_pk_bf16_f32 v139, v140, v141
	v_cvt_pk_bf16_f32 v140, v142, v143
	v_lshl_add_u64 v[142:143], v[154:155], 0, v[146:147]
	v_cvt_pk_bf16_f32 v141, v144, v145
	v_lshl_add_u64 v[142:143], v[142:143], 0, v[164:165]
	global_store_dwordx4 v[142:143], v[138:141], off
	v_lshlrev_b32_e32 v142, 16, v136
	v_and_b32_e32 v143, 0xffff0000, v136
	v_lshlrev_b32_e32 v138, 16, v134
	v_and_b32_e32 v139, 0xffff0000, v134
	v_lshlrev_b32_e32 v140, 16, v135
	v_and_b32_e32 v141, 0xffff0000, v135
	v_lshlrev_b32_e32 v144, 16, v137
	v_and_b32_e32 v145, 0xffff0000, v137
	v_mul_f32_e32 v134, 0xbfb8aa3b, v138
	v_mul_f32_e32 v135, 0xbfb8aa3b, v139
	v_mul_f32_e32 v136, 0xbfb8aa3b, v140
	v_mul_f32_e32 v137, 0xbfb8aa3b, v141
	v_mul_f32_e32 v138, 0xbfb8aa3b, v142
	v_mul_f32_e32 v139, 0xbfb8aa3b, v143
	v_exp_f32_e32 v134, v134
	v_exp_f32_e32 v135, v135
	v_exp_f32_e32 v136, v136
	v_exp_f32_e32 v137, v137
	v_exp_f32_e32 v138, v138
	v_exp_f32_e32 v139, v139
	v_mul_f32_e32 v140, 0xbfb8aa3b, v144
	v_mul_f32_e32 v141, 0xbfb8aa3b, v145
	v_exp_f32_e32 v140, v140
	v_exp_f32_e32 v141, v141
	v_add_f32_e32 v134, 1.0, v134
	v_add_f32_e32 v135, 1.0, v135
	v_add_f32_e32 v136, 1.0, v136
	v_add_f32_e32 v137, 1.0, v137
	v_add_f32_e32 v138, 1.0, v138
	v_add_f32_e32 v139, 1.0, v139
	v_rcp_f32_e32 v134, v134
	v_rcp_f32_e32 v135, v135
	v_rcp_f32_e32 v136, v136
	v_rcp_f32_e32 v137, v137
	v_rcp_f32_e32 v138, v138
	v_rcp_f32_e32 v139, v139
	v_add_f32_e32 v140, 1.0, v140
	v_add_f32_e32 v141, 1.0, v141
	v_rcp_f32_e32 v140, v140
	v_rcp_f32_e32 v141, v141
	v_pk_mul_f32 v[136:137], v[104:105], v[136:137]
	v_pk_mul_f32 v[134:135], v[102:103], v[134:135]
	v_pk_mul_f32 v[138:139], v[98:99], v[138:139]
	v_cvt_pk_bf16_f32 v134, v134, v135
	v_cvt_pk_bf16_f32 v135, v136, v137
	v_cvt_pk_bf16_f32 v136, v138, v139
	v_lshlrev_b32_e32 v138, 7, v174
	v_pk_mul_f32 v[140:141], v[100:101], v[140:141]
	v_and_b32_e32 v138, 0x3f80, v138
	v_mov_b32_e32 v139, v187
	v_cvt_pk_bf16_f32 v137, v140, v141
	v_lshl_add_u64 v[140:141], v[168:169], 0, v[138:139]
	v_lshl_add_u64 v[140:141], v[140:141], 0, v[164:165]
	global_store_dwordx4 v[140:141], v[134:137], off
	v_lshlrev_b32_e32 v140, 16, v132
	v_and_b32_e32 v141, 0xffff0000, v132
	v_lshlrev_b32_e32 v134, 16, v130
	v_and_b32_e32 v135, 0xffff0000, v130
	v_lshlrev_b32_e32 v136, 16, v131
	v_and_b32_e32 v137, 0xffff0000, v131
	v_lshlrev_b32_e32 v142, 16, v133
	v_and_b32_e32 v143, 0xffff0000, v133
	v_mul_f32_e32 v130, 0xbfb8aa3b, v134
	v_mul_f32_e32 v131, 0xbfb8aa3b, v135
	v_mul_f32_e32 v132, 0xbfb8aa3b, v136
	v_mul_f32_e32 v133, 0xbfb8aa3b, v137
	v_mul_f32_e32 v134, 0xbfb8aa3b, v140
	v_mul_f32_e32 v135, 0xbfb8aa3b, v141
	v_exp_f32_e32 v130, v130
	v_exp_f32_e32 v131, v131
	v_exp_f32_e32 v132, v132
	v_exp_f32_e32 v133, v133
	v_exp_f32_e32 v134, v134
	v_exp_f32_e32 v135, v135
	v_mul_f32_e32 v136, 0xbfb8aa3b, v142
	v_mul_f32_e32 v137, 0xbfb8aa3b, v143
	v_exp_f32_e32 v136, v136
	v_exp_f32_e32 v137, v137
	v_add_f32_e32 v130, 1.0, v130
	v_add_f32_e32 v131, 1.0, v131
	v_add_f32_e32 v132, 1.0, v132
	v_add_f32_e32 v133, 1.0, v133
	v_add_f32_e32 v134, 1.0, v134
	v_add_f32_e32 v135, 1.0, v135
	v_rcp_f32_e32 v130, v130
	v_rcp_f32_e32 v131, v131
	v_rcp_f32_e32 v132, v132
	v_rcp_f32_e32 v133, v133
	v_rcp_f32_e32 v134, v134
	v_rcp_f32_e32 v135, v135
	v_add_f32_e32 v136, 1.0, v136
	v_add_f32_e32 v137, 1.0, v137
	v_rcp_f32_e32 v136, v136
	v_rcp_f32_e32 v137, v137
	v_pk_mul_f32 v[132:133], v[68:69], v[132:133]
	v_pk_mul_f32 v[130:131], v[66:67], v[130:131]
	v_pk_mul_f32 v[134:135], v[58:59], v[134:135]
	v_pk_mul_f32 v[136:137], v[60:61], v[136:137]
	v_cvt_pk_bf16_f32 v130, v130, v131
	v_cvt_pk_bf16_f32 v131, v132, v133
	v_cvt_pk_bf16_f32 v132, v134, v135
	v_lshl_add_u64 v[134:135], v[154:155], 0, v[138:139]
	v_cvt_pk_bf16_f32 v133, v136, v137
	v_lshl_add_u64 v[134:135], v[134:135], 0, v[164:165]
	global_store_dwordx4 v[134:135], v[130:133], off
	v_add_u32_e32 v160, 0x80, v162
	v_add_u32_e32 v158, 0x90, v162
	v_mad_i64_i32 v[130:131], s[30:31], v160, s59, v[166:167]
	global_load_dwordx4 v[168:171], v[130:131], off
	global_load_dwordx4 v[172:175], v[130:131], off offset:256
	v_mad_i64_i32 v[130:131], s[30:31], v158, s59, v[166:167]
	v_add_u32_e32 v156, 0xa0, v162
	global_load_dwordx4 v[150:153], v[130:131], off
	global_load_dwordx4 v[146:149], v[130:131], off offset:256
	v_mad_i64_i32 v[130:131], s[30:31], v156, s59, v[166:167]
	v_add_u32_e32 v154, 0xb0, v162
	global_load_dwordx4 v[142:145], v[130:131], off
	global_load_dwordx4 v[138:141], v[130:131], off offset:256
	v_mad_i64_i32 v[130:131], s[30:31], v154, s59, v[166:167]
	v_ashrrev_i32_e32 v161, 31, v160
	global_load_dwordx4 v[134:137], v[130:131], off
	s_nop 0
	global_load_dwordx4 v[130:133], v[130:131], off offset:256
	v_ashrrev_i32_e32 v159, 31, v158
	v_ashrrev_i32_e32 v157, 31, v156
	v_ashrrev_i32_e32 v155, 31, v154
	s_waitcnt vmcnt(7)
	v_lshlrev_b32_e32 v163, 16, v168
	v_mul_f32_e32 v163, 0xbfb8aa3b, v163
	v_exp_f32_e32 v163, v163
	v_and_b32_e32 v167, 0xffff0000, v168
	v_lshlrev_b32_e32 v168, 16, v169
	v_and_b32_e32 v169, 0xffff0000, v169
	v_add_f32_e32 v163, 1.0, v163
	v_rcp_f32_e32 v166, v163
	v_mul_f32_e32 v163, 0xbfb8aa3b, v167
	v_exp_f32_e32 v163, v163
	v_lshlrev_b32_e32 v176, 16, v170
	v_and_b32_e32 v177, 0xffff0000, v170
	v_lshlrev_b32_e32 v198, 16, v171
	v_add_f32_e32 v163, 1.0, v163
	v_rcp_f32_e32 v167, v163
	v_mul_f32_e32 v163, 0xbfb8aa3b, v168
	v_exp_f32_e32 v163, v163
	v_and_b32_e32 v199, 0xffff0000, v171
	v_pk_mul_f32 v[166:167], v[70:71], v[166:167]
	v_add_f32_e32 v163, 1.0, v163
	v_rcp_f32_e32 v168, v163
	v_mul_f32_e32 v163, 0xbfb8aa3b, v169
	v_exp_f32_e32 v163, v163
	v_cvt_pk_bf16_f32 v166, v166, v167
	v_add_f32_e32 v163, 1.0, v163
	v_rcp_f32_e32 v169, v163
	v_mul_f32_e32 v163, 0xbfb8aa3b, v176
	v_exp_f32_e32 v163, v163
	v_pk_mul_f32 v[168:169], v[72:73], v[168:169]
	s_nop 0
	v_cvt_pk_bf16_f32 v167, v168, v169
	v_add_f32_e32 v163, 1.0, v163
	v_rcp_f32_e32 v170, v163
	v_mul_f32_e32 v163, 0xbfb8aa3b, v177
	v_exp_f32_e32 v163, v163
	s_nop 0
	v_add_f32_e32 v163, 1.0, v163
	v_rcp_f32_e32 v171, v163
	v_mul_f32_e32 v163, 0xbfb8aa3b, v198
	v_exp_f32_e32 v163, v163
	v_pk_mul_f32 v[170:171], v[62:63], v[170:171]
	s_nop 0
	v_cvt_pk_bf16_f32 v168, v170, v171
	v_add_f32_e32 v163, 1.0, v163
	v_rcp_f32_e32 v176, v163
	v_mul_f32_e32 v163, 0xbfb8aa3b, v199
	v_exp_f32_e32 v163, v163
	v_lshrrev_b64 v[170:171], 1, v[160:161]
	v_and_b32_e32 v171, 0x7fffffff, v171
	v_and_b32_e32 v170, 0xffffffc0, v170
	v_add_f32_e32 v163, 1.0, v163
	v_rcp_f32_e32 v177, v163
	s_waitcnt vmcnt(6)
	v_lshlrev_b32_e32 v163, 16, v172
	v_mul_f32_e32 v163, 0xbfb8aa3b, v163
	v_lshlrev_b32_e32 v160, 7, v160
	v_pk_mul_f32 v[176:177], v[64:65], v[176:177]
	v_exp_f32_e32 v163, v163
	v_cvt_pk_bf16_f32 v169, v176, v177
	v_lshl_add_u64 v[176:177], v[170:171], 0, s[24:25]
	v_lshlrev_b64 v[176:177], 14, v[176:177]
	v_lshl_add_u64 v[176:177], s[28:29], 0, v[176:177]
	v_and_b32_e32 v160, 0x3f80, v160
	v_mov_b32_e32 v161, v187
	v_lshl_add_u64 v[176:177], v[176:177], 0, v[160:161]
	v_lshl_add_u64 v[176:177], v[176:177], 0, v[164:165]
	global_store_dwordx4 v[176:177], v[166:169], off
	v_add_f32_e32 v163, 1.0, v163
	v_lshl_add_u64 v[170:171], v[170:171], 0, s[26:27]
	v_and_b32_e32 v167, 0xffff0000, v172
	v_rcp_f32_e32 v166, v163
	v_mul_f32_e32 v163, 0xbfb8aa3b, v167
	v_exp_f32_e32 v163, v163
	v_lshlrev_b32_e32 v168, 16, v173
	v_and_b32_e32 v169, 0xffff0000, v173
	v_lshlrev_b32_e32 v172, 16, v174
	v_add_f32_e32 v163, 1.0, v163
	v_rcp_f32_e32 v167, v163
	v_mul_f32_e32 v163, 0xbfb8aa3b, v168
	v_exp_f32_e32 v163, v163
	v_and_b32_e32 v173, 0xffff0000, v174
	v_lshlrev_b32_e32 v174, 16, v175
	v_and_b32_e32 v175, 0xffff0000, v175
	v_add_f32_e32 v163, 1.0, v163
	v_rcp_f32_e32 v168, v163
	v_mul_f32_e32 v163, 0xbfb8aa3b, v169
	v_exp_f32_e32 v163, v163
	v_lshlrev_b64 v[170:171], 14, v[170:171]
	v_lshl_add_u64 v[170:171], s[28:29], 0, v[170:171]
	v_pk_mul_f32 v[166:167], v[30:31], v[166:167]
	v_add_f32_e32 v163, 1.0, v163
	v_rcp_f32_e32 v169, v163
	v_mul_f32_e32 v163, 0xbfb8aa3b, v172
	v_exp_f32_e32 v163, v163
	v_lshl_add_u64 v[160:161], v[170:171], 0, v[160:161]
	v_pk_mul_f32 v[168:169], v[32:33], v[168:169]
	v_cvt_pk_bf16_f32 v166, v166, v167
	v_add_f32_e32 v163, 1.0, v163
	v_rcp_f32_e32 v172, v163
	v_mul_f32_e32 v163, 0xbfb8aa3b, v173
	v_exp_f32_e32 v163, v163
	v_cvt_pk_bf16_f32 v167, v168, v169
	v_lshl_add_u64 v[160:161], v[160:161], 0, v[164:165]
	s_waitcnt vmcnt(6)
	v_and_b32_e32 v170, 0xffff0000, v153
	v_add_f32_e32 v163, 1.0, v163
	v_rcp_f32_e32 v173, v163
	v_mul_f32_e32 v163, 0xbfb8aa3b, v174
	v_exp_f32_e32 v163, v163
	v_pk_mul_f32 v[172:173], v[26:27], v[172:173]
	s_nop 0
	v_cvt_pk_bf16_f32 v168, v172, v173
	v_add_f32_e32 v163, 1.0, v163
	v_rcp_f32_e32 v174, v163
	v_mul_f32_e32 v163, 0xbfb8aa3b, v175
	v_exp_f32_e32 v163, v163
	s_nop 0
	v_add_f32_e32 v163, 1.0, v163
	v_rcp_f32_e32 v175, v163
	v_lshlrev_b32_e32 v163, 16, v151
	v_pk_mul_f32 v[174:175], v[28:29], v[174:175]
	s_nop 0
	v_cvt_pk_bf16_f32 v169, v174, v175
	global_store_dwordx4 v[160:161], v[166:169], off
	v_lshlrev_b32_e32 v160, 16, v150
	v_and_b32_e32 v161, 0xffff0000, v150
	v_lshlrev_b32_e32 v169, 16, v153
	v_lshlrev_b32_e32 v167, 16, v152
	v_and_b32_e32 v168, 0xffff0000, v152
	v_mul_f32_e32 v152, 0xbfb8aa3b, v163
	v_mul_f32_e32 v163, 0xbfb8aa3b, v169
	v_exp_f32_e32 v163, v163
	v_and_b32_e32 v166, 0xffff0000, v151
	v_mul_f32_e32 v150, 0xbfb8aa3b, v160
	v_mul_f32_e32 v151, 0xbfb8aa3b, v161
	v_mul_f32_e32 v153, 0xbfb8aa3b, v166
	v_mul_f32_e32 v160, 0xbfb8aa3b, v167
	v_mul_f32_e32 v161, 0xbfb8aa3b, v168
	v_exp_f32_e32 v150, v150
	v_exp_f32_e32 v151, v151
	v_exp_f32_e32 v152, v152
	v_exp_f32_e32 v153, v153
	v_exp_f32_e32 v160, v160
	v_exp_f32_e32 v161, v161
	v_add_f32_e32 v163, 1.0, v163
	v_rcp_f32_e32 v166, v163
	v_mul_f32_e32 v163, 0xbfb8aa3b, v170
	v_exp_f32_e32 v163, v163
	v_add_f32_e32 v150, 1.0, v150
	v_add_f32_e32 v151, 1.0, v151
	v_add_f32_e32 v152, 1.0, v152
	v_add_f32_e32 v153, 1.0, v153
	v_add_f32_e32 v160, 1.0, v160
	v_add_f32_e32 v161, 1.0, v161
	v_rcp_f32_e32 v150, v150
	v_rcp_f32_e32 v151, v151
	v_rcp_f32_e32 v152, v152
	v_rcp_f32_e32 v153, v153
	v_rcp_f32_e32 v160, v160
	v_rcp_f32_e32 v161, v161
	v_add_f32_e32 v163, 1.0, v163
	v_rcp_f32_e32 v167, v163
	v_pk_mul_f32 v[152:153], v[56:57], v[152:153]
	v_pk_mul_f32 v[150:151], v[54:55], v[150:151]
	v_pk_mul_f32 v[160:161], v[50:51], v[160:161]
	v_cvt_pk_bf16_f32 v150, v150, v151
	v_cvt_pk_bf16_f32 v151, v152, v153
	v_cvt_pk_bf16_f32 v152, v160, v161
	v_lshrrev_b64 v[160:161], 1, v[158:159]
	v_pk_mul_f32 v[166:167], v[52:53], v[166:167]
	v_and_b32_e32 v161, 0x7fffffff, v161
	v_and_b32_e32 v160, 0xffffffc0, v160
	v_cvt_pk_bf16_f32 v153, v166, v167
	v_lshl_add_u64 v[166:167], v[160:161], 0, s[24:25]
	v_lshlrev_b64 v[166:167], 14, v[166:167]
	v_lshlrev_b32_e32 v158, 7, v158
	v_lshl_add_u64 v[166:167], s[28:29], 0, v[166:167]
	v_and_b32_e32 v158, 0x3f80, v158
	v_mov_b32_e32 v159, v187
	v_lshl_add_u64 v[166:167], v[166:167], 0, v[158:159]
	v_lshl_add_u64 v[166:167], v[166:167], 0, v[164:165]
	global_store_dwordx4 v[166:167], v[150:153], off
	s_waitcnt vmcnt(7)
	v_lshlrev_b32_e32 v163, 16, v148
	v_and_b32_e32 v166, 0xffff0000, v148
	v_lshlrev_b32_e32 v150, 16, v146
	v_and_b32_e32 v151, 0xffff0000, v146
	v_lshlrev_b32_e32 v152, 16, v147
	v_and_b32_e32 v153, 0xffff0000, v147
	v_lshlrev_b32_e32 v167, 16, v149
	v_and_b32_e32 v168, 0xffff0000, v149
	v_mul_f32_e32 v146, 0xbfb8aa3b, v150
	v_mul_f32_e32 v147, 0xbfb8aa3b, v151
	v_mul_f32_e32 v148, 0xbfb8aa3b, v152
	v_mul_f32_e32 v149, 0xbfb8aa3b, v153
	v_mul_f32_e32 v150, 0xbfb8aa3b, v163
	v_mul_f32_e32 v151, 0xbfb8aa3b, v166
	v_exp_f32_e32 v146, v146
	v_exp_f32_e32 v147, v147
	v_exp_f32_e32 v148, v148
	v_exp_f32_e32 v149, v149
	v_exp_f32_e32 v150, v150
	v_exp_f32_e32 v151, v151
	v_mul_f32_e32 v152, 0xbfb8aa3b, v167
	v_mul_f32_e32 v153, 0xbfb8aa3b, v168
	v_add_f32_e32 v146, 1.0, v146
	v_add_f32_e32 v147, 1.0, v147
	v_add_f32_e32 v148, 1.0, v148
	v_add_f32_e32 v149, 1.0, v149
	v_add_f32_e32 v150, 1.0, v150
	v_add_f32_e32 v151, 1.0, v151
	v_exp_f32_e32 v152, v152
	v_exp_f32_e32 v153, v153
	v_rcp_f32_e32 v146, v146
	v_rcp_f32_e32 v147, v147
	v_rcp_f32_e32 v148, v148
	v_rcp_f32_e32 v149, v149
	v_rcp_f32_e32 v150, v150
	v_rcp_f32_e32 v151, v151
	v_add_f32_e32 v152, 1.0, v152
	v_add_f32_e32 v153, 1.0, v153
	v_pk_mul_f32 v[148:149], v[24:25], v[148:149]
	v_pk_mul_f32 v[146:147], v[22:23], v[146:147]
	v_rcp_f32_e32 v152, v152
	v_rcp_f32_e32 v153, v153
	v_pk_mul_f32 v[150:151], v[18:19], v[150:151]
	v_cvt_pk_bf16_f32 v146, v146, v147
	v_cvt_pk_bf16_f32 v147, v148, v149
	v_cvt_pk_bf16_f32 v148, v150, v151
	v_lshl_add_u64 v[150:151], v[160:161], 0, s[26:27]
	v_lshlrev_b64 v[150:151], 14, v[150:151]
	v_lshl_add_u64 v[150:151], s[28:29], 0, v[150:151]
	v_pk_mul_f32 v[152:153], v[20:21], v[152:153]
	v_lshl_add_u64 v[150:151], v[150:151], 0, v[158:159]
	v_cvt_pk_bf16_f32 v149, v152, v153
	v_lshl_add_u64 v[150:151], v[150:151], 0, v[164:165]
	global_store_dwordx4 v[150:151], v[146:149], off
	s_waitcnt vmcnt(7)
	v_lshlrev_b32_e32 v150, 16, v144
	v_and_b32_e32 v151, 0xffff0000, v144
	v_lshlrev_b32_e32 v146, 16, v142
	v_and_b32_e32 v147, 0xffff0000, v142
	v_lshlrev_b32_e32 v148, 16, v143
	v_and_b32_e32 v149, 0xffff0000, v143
	v_lshlrev_b32_e32 v152, 16, v145
	v_and_b32_e32 v153, 0xffff0000, v145
	v_mul_f32_e32 v142, 0xbfb8aa3b, v146
	v_mul_f32_e32 v143, 0xbfb8aa3b, v147
	v_mul_f32_e32 v144, 0xbfb8aa3b, v148
	v_mul_f32_e32 v145, 0xbfb8aa3b, v149
	v_mul_f32_e32 v146, 0xbfb8aa3b, v150
	v_mul_f32_e32 v147, 0xbfb8aa3b, v151
	v_exp_f32_e32 v142, v142
	v_exp_f32_e32 v143, v143
	v_exp_f32_e32 v144, v144
	v_exp_f32_e32 v145, v145
	v_exp_f32_e32 v146, v146
	v_exp_f32_e32 v147, v147
	v_mul_f32_e32 v148, 0xbfb8aa3b, v152
	v_mul_f32_e32 v149, 0xbfb8aa3b, v153
	v_exp_f32_e32 v148, v148
	v_exp_f32_e32 v149, v149
	v_add_f32_e32 v142, 1.0, v142
	v_add_f32_e32 v143, 1.0, v143
	v_add_f32_e32 v144, 1.0, v144
	v_add_f32_e32 v145, 1.0, v145
	v_add_f32_e32 v146, 1.0, v146
	v_add_f32_e32 v147, 1.0, v147
	v_rcp_f32_e32 v142, v142
	v_rcp_f32_e32 v143, v143
	v_rcp_f32_e32 v144, v144
	v_rcp_f32_e32 v145, v145
	v_rcp_f32_e32 v146, v146
	v_rcp_f32_e32 v147, v147
	v_add_f32_e32 v148, 1.0, v148
	v_add_f32_e32 v149, 1.0, v149
	v_rcp_f32_e32 v148, v148
	v_rcp_f32_e32 v149, v149
	v_pk_mul_f32 v[144:145], v[48:49], v[144:145]
	v_pk_mul_f32 v[142:143], v[46:47], v[142:143]
	v_pk_mul_f32 v[146:147], v[42:43], v[146:147]
	v_cvt_pk_bf16_f32 v142, v142, v143
	v_cvt_pk_bf16_f32 v143, v144, v145
	v_cvt_pk_bf16_f32 v144, v146, v147
	v_lshrrev_b64 v[146:147], 1, v[156:157]
	v_pk_mul_f32 v[148:149], v[44:45], v[148:149]
	v_and_b32_e32 v147, 0x7fffffff, v147
	v_and_b32_e32 v146, 0xffffffc0, v146
	v_cvt_pk_bf16_f32 v145, v148, v149
	v_lshl_add_u64 v[148:149], v[146:147], 0, s[24:25]
	v_lshlrev_b64 v[148:149], 14, v[148:149]
	v_lshlrev_b32_e32 v150, 7, v156
	v_lshl_add_u64 v[148:149], s[28:29], 0, v[148:149]
	v_and_b32_e32 v150, 0x3f80, v150
	v_mov_b32_e32 v151, v187
	v_lshl_add_u64 v[148:149], v[148:149], 0, v[150:151]
	v_lshl_add_u64 v[148:149], v[148:149], 0, v[164:165]
	global_store_dwordx4 v[148:149], v[142:145], off
	s_waitcnt vmcnt(7)
	v_lshlrev_b32_e32 v148, 16, v140
	v_and_b32_e32 v149, 0xffff0000, v140
	v_lshlrev_b32_e32 v142, 16, v138
	v_and_b32_e32 v143, 0xffff0000, v138
	v_lshlrev_b32_e32 v144, 16, v139
	v_and_b32_e32 v145, 0xffff0000, v139
	v_lshlrev_b32_e32 v152, 16, v141
	v_and_b32_e32 v153, 0xffff0000, v141
	v_mul_f32_e32 v138, 0xbfb8aa3b, v142
	v_mul_f32_e32 v139, 0xbfb8aa3b, v143
	v_mul_f32_e32 v140, 0xbfb8aa3b, v144
	v_mul_f32_e32 v141, 0xbfb8aa3b, v145
	v_mul_f32_e32 v142, 0xbfb8aa3b, v148
	v_mul_f32_e32 v143, 0xbfb8aa3b, v149
	v_exp_f32_e32 v138, v138
	v_exp_f32_e32 v139, v139
	v_exp_f32_e32 v140, v140
	v_exp_f32_e32 v141, v141
	v_exp_f32_e32 v142, v142
	v_exp_f32_e32 v143, v143
	v_mul_f32_e32 v144, 0xbfb8aa3b, v152
	v_mul_f32_e32 v145, 0xbfb8aa3b, v153
	v_add_f32_e32 v138, 1.0, v138
	v_add_f32_e32 v139, 1.0, v139
	v_add_f32_e32 v140, 1.0, v140
	v_add_f32_e32 v141, 1.0, v141
	v_add_f32_e32 v142, 1.0, v142
	v_add_f32_e32 v143, 1.0, v143
	v_exp_f32_e32 v144, v144
	v_exp_f32_e32 v145, v145
	v_rcp_f32_e32 v138, v138
	v_rcp_f32_e32 v139, v139
	v_rcp_f32_e32 v140, v140
	v_rcp_f32_e32 v141, v141
	v_rcp_f32_e32 v142, v142
	v_rcp_f32_e32 v143, v143
	v_add_f32_e32 v144, 1.0, v144
	v_add_f32_e32 v145, 1.0, v145
	v_pk_mul_f32 v[140:141], v[16:17], v[140:141]
	v_pk_mul_f32 v[138:139], v[14:15], v[138:139]
	v_rcp_f32_e32 v144, v144
	v_rcp_f32_e32 v145, v145
	v_pk_mul_f32 v[142:143], v[10:11], v[142:143]
	v_cvt_pk_bf16_f32 v138, v138, v139
	v_cvt_pk_bf16_f32 v139, v140, v141
	v_cvt_pk_bf16_f32 v140, v142, v143
	v_lshl_add_u64 v[142:143], v[146:147], 0, s[26:27]
	v_lshlrev_b64 v[142:143], 14, v[142:143]
	v_lshl_add_u64 v[142:143], s[28:29], 0, v[142:143]
	v_pk_mul_f32 v[144:145], v[12:13], v[144:145]
	v_lshl_add_u64 v[142:143], v[142:143], 0, v[150:151]
	v_cvt_pk_bf16_f32 v141, v144, v145
	v_lshl_add_u64 v[142:143], v[142:143], 0, v[164:165]
	global_store_dwordx4 v[142:143], v[138:141], off
	s_waitcnt vmcnt(7)
	v_lshlrev_b32_e32 v142, 16, v136
	v_and_b32_e32 v143, 0xffff0000, v136
	v_lshlrev_b32_e32 v138, 16, v134
	v_and_b32_e32 v139, 0xffff0000, v134
	v_lshlrev_b32_e32 v140, 16, v135
	v_and_b32_e32 v141, 0xffff0000, v135
	v_lshlrev_b32_e32 v144, 16, v137
	v_and_b32_e32 v145, 0xffff0000, v137
	v_mul_f32_e32 v134, 0xbfb8aa3b, v138
	v_mul_f32_e32 v135, 0xbfb8aa3b, v139
	v_mul_f32_e32 v136, 0xbfb8aa3b, v140
	v_mul_f32_e32 v137, 0xbfb8aa3b, v141
	v_mul_f32_e32 v138, 0xbfb8aa3b, v142
	v_mul_f32_e32 v139, 0xbfb8aa3b, v143
	v_exp_f32_e32 v134, v134
	v_exp_f32_e32 v135, v135
	v_exp_f32_e32 v136, v136
	v_exp_f32_e32 v137, v137
	v_exp_f32_e32 v138, v138
	v_exp_f32_e32 v139, v139
	v_mul_f32_e32 v140, 0xbfb8aa3b, v144
	v_mul_f32_e32 v141, 0xbfb8aa3b, v145
	v_exp_f32_e32 v140, v140
	v_exp_f32_e32 v141, v141
	v_add_f32_e32 v134, 1.0, v134
	v_add_f32_e32 v135, 1.0, v135
	v_add_f32_e32 v136, 1.0, v136
	v_add_f32_e32 v137, 1.0, v137
	v_add_f32_e32 v138, 1.0, v138
	v_add_f32_e32 v139, 1.0, v139
	v_rcp_f32_e32 v134, v134
	v_rcp_f32_e32 v135, v135
	v_rcp_f32_e32 v136, v136
	v_rcp_f32_e32 v137, v137
	v_rcp_f32_e32 v138, v138
	v_rcp_f32_e32 v139, v139
	v_add_f32_e32 v140, 1.0, v140
	v_add_f32_e32 v141, 1.0, v141
	v_rcp_f32_e32 v140, v140
	v_rcp_f32_e32 v141, v141
	v_pk_mul_f32 v[136:137], v[40:41], v[136:137]
	v_pk_mul_f32 v[134:135], v[38:39], v[134:135]
	v_pk_mul_f32 v[138:139], v[34:35], v[138:139]
	v_cvt_pk_bf16_f32 v134, v134, v135
	v_cvt_pk_bf16_f32 v135, v136, v137
	v_cvt_pk_bf16_f32 v136, v138, v139
	v_lshrrev_b64 v[138:139], 1, v[154:155]
	v_pk_mul_f32 v[140:141], v[36:37], v[140:141]
	v_and_b32_e32 v139, 0x7fffffff, v139
	v_and_b32_e32 v138, 0xffffffc0, v138
	v_cvt_pk_bf16_f32 v137, v140, v141
	v_lshl_add_u64 v[140:141], v[138:139], 0, s[24:25]
	v_lshlrev_b64 v[140:141], 14, v[140:141]
	v_lshlrev_b32_e32 v142, 7, v154
	v_lshl_add_u64 v[140:141], s[28:29], 0, v[140:141]
	v_and_b32_e32 v142, 0x3f80, v142
	v_mov_b32_e32 v143, v187
	v_lshl_add_u64 v[140:141], v[140:141], 0, v[142:143]
	v_lshl_add_u64 v[140:141], v[140:141], 0, v[164:165]
	global_store_dwordx4 v[140:141], v[134:137], off
	s_waitcnt vmcnt(7)
	v_lshlrev_b32_e32 v140, 16, v132
	v_and_b32_e32 v141, 0xffff0000, v132
	v_lshlrev_b32_e32 v134, 16, v130
	v_and_b32_e32 v135, 0xffff0000, v130
	v_lshlrev_b32_e32 v136, 16, v131
	v_and_b32_e32 v137, 0xffff0000, v131
	v_lshlrev_b32_e32 v144, 16, v133
	v_and_b32_e32 v145, 0xffff0000, v133
	v_mul_f32_e32 v130, 0xbfb8aa3b, v134
	v_mul_f32_e32 v131, 0xbfb8aa3b, v135
	v_mul_f32_e32 v132, 0xbfb8aa3b, v136
	v_mul_f32_e32 v133, 0xbfb8aa3b, v137
	v_mul_f32_e32 v134, 0xbfb8aa3b, v140
	v_mul_f32_e32 v135, 0xbfb8aa3b, v141
	v_exp_f32_e32 v130, v130
	v_exp_f32_e32 v131, v131
	v_exp_f32_e32 v132, v132
	v_exp_f32_e32 v133, v133
	v_exp_f32_e32 v134, v134
	v_exp_f32_e32 v135, v135
	v_mul_f32_e32 v136, 0xbfb8aa3b, v144
	v_mul_f32_e32 v137, 0xbfb8aa3b, v145
	v_add_f32_e32 v130, 1.0, v130
	v_add_f32_e32 v131, 1.0, v131
	v_add_f32_e32 v132, 1.0, v132
	v_add_f32_e32 v133, 1.0, v133
	v_add_f32_e32 v134, 1.0, v134
	v_add_f32_e32 v135, 1.0, v135
	v_exp_f32_e32 v136, v136
	v_exp_f32_e32 v137, v137
	v_rcp_f32_e32 v130, v130
	v_rcp_f32_e32 v131, v131
	v_rcp_f32_e32 v132, v132
	v_rcp_f32_e32 v133, v133
	v_rcp_f32_e32 v134, v134
	v_rcp_f32_e32 v135, v135
	v_add_f32_e32 v136, 1.0, v136
	v_add_f32_e32 v137, 1.0, v137
	v_pk_mul_f32 v[132:133], v[8:9], v[132:133]
	v_pk_mul_f32 v[130:131], v[6:7], v[130:131]
	v_rcp_f32_e32 v136, v136
	v_rcp_f32_e32 v137, v137
	v_pk_mul_f32 v[134:135], v[2:3], v[134:135]
	v_cvt_pk_bf16_f32 v130, v130, v131
	v_cvt_pk_bf16_f32 v131, v132, v133
	v_cvt_pk_bf16_f32 v132, v134, v135
	v_lshl_add_u64 v[134:135], v[138:139], 0, s[26:27]
	v_lshlrev_b64 v[134:135], 14, v[134:135]
	v_lshl_add_u64 v[134:135], s[28:29], 0, v[134:135]
	v_pk_mul_f32 v[136:137], v[4:5], v[136:137]
	v_lshl_add_u64 v[134:135], v[134:135], 0, v[142:143]
	v_cvt_pk_bf16_f32 v133, v136, v137
	v_lshl_add_u64 v[134:135], v[134:135], 0, v[164:165]
	global_store_dwordx4 v[134:135], v[130:133], off
	s_cbranch_execnz .LBB0_1009

.LBB0_1091:
	s_and_b64 vcc, exec, s[6:7]
	s_cbranch_vccz .Lwtp10_entry
	s_lshl_b32 s23, s16, 8
	v_lshl_add_u32 v196, s34, 8, v206
	s_or_b32 s23, s23, s63
	v_or_b32_e32 v130, s23, v207
	v_ashrrev_i32_e32 v197, 31, v196
	v_ashrrev_i32_e32 v131, 31, v130
	v_lshlrev_b64 v[132:133], 14, v[196:197]
	v_lshl_add_u64 v[132:133], s[56:57], 0, v[132:133]
	v_lshlrev_b64 v[198:199], 2, v[130:131]
	v_lshl_add_u64 v[130:131], v[132:133], 0, v[198:199]
	global_load_dwordx4 v[216:219], v[130:131], off
	global_load_dwordx4 v[220:223], v[130:131], off offset:16
	global_load_dwordx4 v[224:227], v[130:131], off offset:512
	global_load_dwordx4 v[228:231], v[130:131], off offset:528
	v_or_b32_e32 v204, 16, v196
	v_or_b32_e32 v202, 32, v196
	v_or_b32_e32 v200, 48, v196
	v_ashrrev_i32_e32 v205, 31, v204
	v_ashrrev_i32_e32 v203, 31, v202
	v_ashrrev_i32_e32 v201, 31, v200
	v_lshlrev_b64 v[130:131], 14, v[204:205]
	v_lshlrev_b64 v[132:133], 14, v[202:203]
	v_lshlrev_b64 v[134:135], 14, v[200:201]
	v_lshl_add_u64 v[130:131], s[56:57], 0, v[130:131]
	v_lshl_add_u64 v[132:133], s[56:57], 0, v[132:133]
	v_lshl_add_u64 v[134:135], s[56:57], 0, v[134:135]
	v_lshl_add_u64 v[130:131], v[130:131], 0, v[198:199]
	v_lshl_add_u64 v[132:133], v[132:133], 0, v[198:199]
	v_lshl_add_u64 v[134:135], v[134:135], 0, v[198:199]
	global_load_dwordx4 v[170:173], v[130:131], off offset:16
	global_load_dwordx4 v[174:177], v[130:131], off
	global_load_dwordx4 v[162:165], v[130:131], off offset:528
	global_load_dwordx4 v[166:169], v[130:131], off offset:512
	global_load_dwordx4 v[154:157], v[132:133], off offset:16
	global_load_dwordx4 v[158:161], v[132:133], off
	global_load_dwordx4 v[146:149], v[132:133], off offset:528
	global_load_dwordx4 v[150:153], v[132:133], off offset:512
	global_load_dwordx4 v[138:141], v[134:135], off offset:16
	global_load_dwordx4 v[142:145], v[134:135], off
	s_nop 0
	global_load_dwordx4 v[130:133], v[134:135], off offset:528
	s_nop 0
	global_load_dwordx4 v[134:137], v[134:135], off offset:512
	v_and_b32_e32 v213, 64, v212
	v_xor_b32_e32 v186, 16, v212
	v_add_u32_e32 v213, 64, v213
	v_xor_b32_e32 v214, 32, v212
	v_cmp_lt_i32_e32 vcc, v186, v213
	v_lshrrev_b64 v[234:235], 1, v[196:197]
	s_ashr_i32 s36, s23, 6
	v_bitop3_b32 v236, s23, 56, v207 bitop3:0xc8
	v_cndmask_b32_e32 v186, v212, v186, vcc
	v_cmp_lt_i32_e32 vcc, v214, v213
	v_and_b32_e32 v234, 0xffffffc0, v234
	s_ashr_i32 s37, s36, 31
	v_cndmask_b32_e32 v213, v212, v214, vcc
	v_lshlrev_b32_e32 v214, 2, v186
	v_lshlrev_b32_e32 v186, 1, v236
	v_lshl_add_u64 v[236:237], v[234:235], 0, s[36:37]
	v_lshlrev_b32_e32 v215, 7, v196
	v_lshlrev_b64 v[236:237], 14, v[236:237]
	v_mov_b32_e32 v233, v187
	v_and_b32_e32 v232, 0x2780, v215
	v_lshl_add_u64 v[236:237], s[10:11], 0, v[236:237]
	v_lshl_add_u64 v[236:237], v[236:237], 0, v[232:233]
	v_lshl_add_u64 v[236:237], v[236:237], 0, v[186:187]
	s_or_b32 s38, s36, 2
	s_ashr_i32 s39, s38, 31
	v_lshlrev_b32_e32 v213, 2, v213
	s_lshl_b32 s34, s16, 2
	s_ashr_i32 s35, s34, 31
	s_waitcnt vmcnt(0)
	v_pk_add_f32 v[128:129], v[128:129], v[218:219]
	v_pk_add_f32 v[126:127], v[126:127], v[216:217]
	v_pk_add_f32 v[124:125], v[124:125], v[222:223]
	v_pk_add_f32 v[122:123], v[122:123], v[220:221]
	v_pk_add_f32 v[216:217], v[118:119], v[224:225]
	v_pk_add_f32 v[218:219], v[116:117], v[230:231]
	v_cvt_pk_bf16_f32 v116, v122, v123
	v_cvt_pk_bf16_f32 v117, v124, v125
	v_mul_f32_e32 v118, v127, v127
	v_mul_f32_e32 v119, v129, v129
	v_mul_f32_e32 v123, v123, v123
	v_mul_f32_e32 v125, v125, v125
	v_pk_add_f32 v[220:221], v[114:115], v[228:229]
	v_cvt_pk_bf16_f32 v114, v126, v127
	v_cvt_pk_bf16_f32 v115, v128, v129
	v_fmac_f32_e32 v118, v126, v126
	v_fmac_f32_e32 v119, v128, v128
	v_fmac_f32_e32 v123, v122, v122
	v_fmac_f32_e32 v125, v124, v124
	v_pk_add_f32 v[120:121], v[120:121], v[226:227]
	global_store_dwordx4 v[236:237], v[114:117], off
	s_nop 1
	v_add_f32_e32 v114, v118, v119
	v_add_f32_e32 v115, v123, v125
	v_add_f32_e32 v114, v114, v115
	v_cvt_pk_bf16_f32 v117, v120, v121
	v_mul_f32_e32 v115, v217, v217
	v_mul_f32_e32 v121, v121, v121
	v_fmac_f32_e32 v115, v216, v216
	v_fmac_f32_e32 v121, v120, v120
	v_add_f32_e32 v115, v115, v121
	v_mul_f32_e32 v120, v221, v221
	v_mul_f32_e32 v121, v219, v219
	v_fmac_f32_e32 v120, v220, v220
	v_fmac_f32_e32 v121, v218, v218
	v_add_f32_e32 v120, v120, v121
	v_add_f32_e32 v115, v115, v120
	v_add_f32_e32 v122, v114, v115
	ds_bpermute_b32 v123, v214, v122
	v_lshl_add_u64 v[114:115], v[234:235], 0, s[38:39]
	v_lshlrev_b64 v[120:121], 14, v[114:115]
	v_lshl_add_u64 v[120:121], s[10:11], 0, v[120:121]
	v_lshl_add_u64 v[120:121], v[120:121], 0, v[232:233]
	s_waitcnt lgkmcnt(0)
	v_add_f32_e32 v114, v122, v123
	ds_bpermute_b32 v115, v213, v114
	v_cvt_pk_bf16_f32 v116, v216, v217
	v_cvt_pk_bf16_f32 v118, v220, v221
	v_cvt_pk_bf16_f32 v119, v218, v219
	v_lshl_add_u64 v[120:121], v[120:121], 0, v[186:187]
	global_store_dwordx4 v[120:121], v[116:119], off
	s_and_saveexec_b64 s[40:41], s[4:5]
	s_cbranch_execz .LBB0_1093
	v_lshlrev_b64 v[116:117], 8, v[196:197]
	v_lshl_add_u64 v[116:117], s[14:15], 0, v[116:117]
	v_lshl_add_u64 v[116:117], s[34:35], 2, v[116:117]
	s_lshl_b32 s16, s62, 2
	v_lshl_add_u64 v[116:117], v[116:117], 0, s[16:17]
	s_waitcnt lgkmcnt(0)
	v_add_f32_e32 v114, v114, v115
	global_store_dword v[116:117], v114, off

.Lwtp10_join:
	s_cbranch_vccnz .LBB0_1080
	s_andn2_b64 vcc, exec, s[18:19]
	s_cbranch_vccnz .LBB0_1079
	s_barrier
	s_branch .LBB0_1079
.Lwtp10_entry:
	s_lshl_b32 s23, s16, 8
	v_lshl_add_u32 v196, s34, 8, v206
	s_or_b32 s23, s23, s63
	v_or_b32_e32 v130, s23, v207
	v_ashrrev_i32_e32 v197, 31, v196
	v_ashrrev_i32_e32 v131, 31, v130
	v_lshlrev_b64 v[132:133], 14, v[196:197]
	v_lshl_add_u64 v[132:133], s[56:57], 0, v[132:133]
	v_lshlrev_b64 v[198:199], 2, v[130:131]
	v_lshl_add_u64 v[130:131], v[132:133], 0, v[198:199]
	global_load_dwordx4 v[216:219], v[130:131], off
	global_load_dwordx4 v[220:223], v[130:131], off offset:16
	global_load_dwordx4 v[224:227], v[130:131], off offset:512
	global_load_dwordx4 v[228:231], v[130:131], off offset:528
	v_or_b32_e32 v204, 16, v196
	v_or_b32_e32 v202, 32, v196
	v_or_b32_e32 v200, 48, v196
	v_ashrrev_i32_e32 v205, 31, v204
	v_ashrrev_i32_e32 v203, 31, v202
	v_ashrrev_i32_e32 v201, 31, v200
	v_lshlrev_b64 v[130:131], 14, v[204:205]
	v_lshlrev_b64 v[132:133], 14, v[202:203]
	v_lshlrev_b64 v[134:135], 14, v[200:201]
	v_lshl_add_u64 v[130:131], s[56:57], 0, v[130:131]
	v_lshl_add_u64 v[132:133], s[56:57], 0, v[132:133]
	v_lshl_add_u64 v[134:135], s[56:57], 0, v[134:135]
	v_lshl_add_u64 v[130:131], v[130:131], 0, v[198:199]
	v_lshl_add_u64 v[132:133], v[132:133], 0, v[198:199]
	v_lshl_add_u64 v[134:135], v[134:135], 0, v[198:199]
	global_load_dwordx4 v[170:173], v[130:131], off offset:16
	global_load_dwordx4 v[174:177], v[130:131], off
	global_load_dwordx4 v[162:165], v[130:131], off offset:528
	global_load_dwordx4 v[166:169], v[130:131], off offset:512
	global_load_dwordx4 v[154:157], v[132:133], off offset:16
	global_load_dwordx4 v[158:161], v[132:133], off
	global_load_dwordx4 v[146:149], v[132:133], off offset:528
	global_load_dwordx4 v[150:153], v[132:133], off offset:512
	global_load_dwordx4 v[138:141], v[134:135], off offset:16
	global_load_dwordx4 v[142:145], v[134:135], off
	s_nop 0
	global_load_dwordx4 v[130:133], v[134:135], off offset:528
	s_nop 0
	global_load_dwordx4 v[134:137], v[134:135], off offset:512
	v_and_b32_e32 v213, 64, v212
	v_xor_b32_e32 v186, 16, v212
	v_add_u32_e32 v213, 64, v213
	v_xor_b32_e32 v214, 32, v212
	v_cmp_lt_i32_e32 vcc, v186, v213
	v_lshrrev_b64 v[234:235], 1, v[196:197]
	s_ashr_i32 s36, s23, 6
	v_bitop3_b32 v236, s23, 56, v207 bitop3:0xc8
	v_cndmask_b32_e32 v186, v212, v186, vcc
	v_cmp_lt_i32_e32 vcc, v214, v213
	v_and_b32_e32 v234, 0xffffffc0, v234
	s_ashr_i32 s37, s36, 31
	v_cndmask_b32_e32 v213, v212, v214, vcc
	v_lshlrev_b32_e32 v214, 2, v186
	v_lshlrev_b32_e32 v186, 1, v236
	v_lshl_add_u64 v[236:237], v[234:235], 0, s[36:37]
	v_lshlrev_b32_e32 v215, 7, v196
	v_lshlrev_b64 v[236:237], 14, v[236:237]
	v_mov_b32_e32 v233, v187
	v_and_b32_e32 v232, 0x2780, v215
	v_lshl_add_u64 v[236:237], s[10:11], 0, v[236:237]
	v_lshl_add_u64 v[236:237], v[236:237], 0, v[232:233]
	v_lshl_add_u64 v[236:237], v[236:237], 0, v[186:187]
	s_or_b32 s38, s36, 2
	s_ashr_i32 s39, s38, 31
	v_lshlrev_b32_e32 v213, 2, v213
	s_lshl_b32 s34, s16, 2
	s_ashr_i32 s35, s34, 31
	s_waitcnt vmcnt(0)
	v_pk_add_f32 v[128:129], v[128:129], v[218:219]
	v_pk_add_f32 v[126:127], v[126:127], v[216:217]
	v_pk_add_f32 v[124:125], v[124:125], v[222:223]
	v_pk_add_f32 v[122:123], v[122:123], v[220:221]
	v_pk_add_f32 v[216:217], v[118:119], v[224:225]
	v_pk_add_f32 v[218:219], v[116:117], v[230:231]
	v_cvt_pk_bf16_f32 v116, v122, v123
	v_cvt_pk_bf16_f32 v117, v124, v125
	v_mul_f32_e32 v118, v127, v127
	v_mul_f32_e32 v119, v129, v129
	v_mul_f32_e32 v123, v123, v123
	v_mul_f32_e32 v125, v125, v125
	v_pk_add_f32 v[220:221], v[114:115], v[228:229]
	v_cvt_pk_bf16_f32 v114, v126, v127
	v_cvt_pk_bf16_f32 v115, v128, v129
	v_fmac_f32_e32 v118, v126, v126
	v_fmac_f32_e32 v119, v128, v128
	v_fmac_f32_e32 v123, v122, v122
	v_fmac_f32_e32 v125, v124, v124
	v_pk_add_f32 v[120:121], v[120:121], v[226:227]
	global_store_dwordx4 v[236:237], v[114:117], off sc1
	s_nop 1
	v_add_f32_e32 v114, v118, v119
	v_add_f32_e32 v115, v123, v125
	v_add_f32_e32 v114, v114, v115
	v_cvt_pk_bf16_f32 v117, v120, v121
	v_mul_f32_e32 v115, v217, v217
	v_mul_f32_e32 v121, v121, v121
	v_fmac_f32_e32 v115, v216, v216
	v_fmac_f32_e32 v121, v120, v120
	v_add_f32_e32 v115, v115, v121
	v_mul_f32_e32 v120, v221, v221
	v_mul_f32_e32 v121, v219, v219
	v_fmac_f32_e32 v120, v220, v220
	v_fmac_f32_e32 v121, v218, v218
	v_add_f32_e32 v120, v120, v121
	v_add_f32_e32 v115, v115, v120
	v_add_f32_e32 v122, v114, v115
	ds_bpermute_b32 v123, v214, v122
	v_lshl_add_u64 v[114:115], v[234:235], 0, s[38:39]
	v_lshlrev_b64 v[120:121], 14, v[114:115]
	v_lshl_add_u64 v[120:121], s[10:11], 0, v[120:121]
	v_lshl_add_u64 v[120:121], v[120:121], 0, v[232:233]
	s_waitcnt lgkmcnt(0)
	v_add_f32_e32 v114, v122, v123
	ds_bpermute_b32 v115, v213, v114
	v_cvt_pk_bf16_f32 v116, v216, v217
	v_cvt_pk_bf16_f32 v118, v220, v221
	v_cvt_pk_bf16_f32 v119, v218, v219
	v_lshl_add_u64 v[120:121], v[120:121], 0, v[186:187]
	global_store_dwordx4 v[120:121], v[116:119], off sc1
	s_and_saveexec_b64 s[40:41], s[4:5]
	s_cbranch_execz .Lwtp10_0
	v_lshlrev_b64 v[116:117], 8, v[196:197]
	v_lshl_add_u64 v[116:117], s[14:15], 0, v[116:117]
	v_lshl_add_u64 v[116:117], s[34:35], 2, v[116:117]
	s_lshl_b32 s16, s62, 2
	v_lshl_add_u64 v[116:117], v[116:117], 0, s[16:17]
	s_waitcnt lgkmcnt(0)
	v_add_f32_e32 v114, v114, v115
	global_store_dword v[116:117], v114, off sc1
.Lwtp10_0:
	s_or_b64 exec, exec, s[40:41]
	v_lshrrev_b64 v[118:119], 1, v[204:205]
	v_and_b32_e32 v118, 0xffffffc0, v118
	v_lshl_add_u64 v[120:121], v[118:119], 0, s[36:37]
	v_lshlrev_b64 v[120:121], 14, v[120:121]
	v_lshlrev_b32_e32 v122, 7, v204
	v_lshl_add_u64 v[120:121], s[10:11], 0, v[120:121]
	v_and_b32_e32 v122, 0x3f80, v122
	v_mov_b32_e32 v123, v187
	v_pk_add_f32 v[112:113], v[112:113], v[176:177]
	v_pk_add_f32 v[110:111], v[110:111], v[174:175]
	s_waitcnt lgkmcnt(0)
	v_pk_add_f32 v[114:115], v[108:109], v[172:173]
	v_pk_add_f32 v[116:117], v[106:107], v[170:171]
	v_lshl_add_u64 v[120:121], v[120:121], 0, v[122:123]
	v_cvt_pk_bf16_f32 v106, v110, v111
	v_cvt_pk_bf16_f32 v107, v112, v113
	v_cvt_pk_bf16_f32 v108, v116, v117
	v_cvt_pk_bf16_f32 v109, v114, v115
	v_lshl_add_u64 v[120:121], v[120:121], 0, v[186:187]
	global_store_dwordx4 v[120:121], v[106:109], off sc1
	v_pk_add_f32 v[102:103], v[102:103], v[166:167]
	v_pk_add_f32 v[104:105], v[104:105], v[168:169]
	v_mul_f32_e32 v106, v111, v111
	v_mul_f32_e32 v107, v113, v113
	v_fmac_f32_e32 v106, v110, v110
	v_fmac_f32_e32 v107, v112, v112
	v_add_f32_e32 v106, v106, v107
	v_mul_f32_e32 v107, v117, v117
	v_mul_f32_e32 v108, v115, v115
	v_fmac_f32_e32 v107, v116, v116
	v_fmac_f32_e32 v108, v114, v114
	v_add_f32_e32 v107, v107, v108
	v_add_f32_e32 v108, v106, v107
	v_pk_add_f32 v[106:107], v[100:101], v[164:165]
	v_cvt_pk_bf16_f32 v100, v102, v103
	v_mul_f32_e32 v103, v103, v103
	v_fmac_f32_e32 v103, v102, v102
	v_mul_f32_e32 v102, v105, v105
	v_pk_add_f32 v[98:99], v[98:99], v[162:163]
	v_fmac_f32_e32 v102, v104, v104
	v_cvt_pk_bf16_f32 v101, v104, v105
	v_add_f32_e32 v102, v103, v102
	v_mul_f32_e32 v103, v99, v99
	v_mul_f32_e32 v104, v107, v107
	v_fmac_f32_e32 v103, v98, v98
	v_fmac_f32_e32 v104, v106, v106
	v_add_f32_e32 v103, v103, v104
	v_add_f32_e32 v102, v102, v103
	v_add_f32_e32 v108, v108, v102
	ds_bpermute_b32 v109, v214, v108
	v_cvt_pk_bf16_f32 v102, v98, v99
	v_lshl_add_u64 v[98:99], v[118:119], 0, s[38:39]
	v_lshlrev_b64 v[104:105], 14, v[98:99]
	v_lshl_add_u64 v[104:105], s[10:11], 0, v[104:105]
	s_waitcnt lgkmcnt(0)
	v_add_f32_e32 v98, v108, v109
	ds_bpermute_b32 v99, v213, v98
	v_lshl_add_u64 v[104:105], v[104:105], 0, v[122:123]
	v_cvt_pk_bf16_f32 v103, v106, v107
	v_lshl_add_u64 v[104:105], v[104:105], 0, v[186:187]
	global_store_dwordx4 v[104:105], v[100:103], off sc1
	s_and_saveexec_b64 s[40:41], s[4:5]
	s_cbranch_execz .Lwtp10_1
	v_lshlrev_b64 v[100:101], 8, v[204:205]
	v_lshl_add_u64 v[100:101], s[14:15], 0, v[100:101]
	v_lshl_add_u64 v[100:101], s[34:35], 2, v[100:101]
	s_lshl_b32 s16, s62, 2
	v_lshl_add_u64 v[100:101], v[100:101], 0, s[16:17]
	s_waitcnt lgkmcnt(0)
	v_add_f32_e32 v98, v98, v99
	global_store_dword v[100:101], v98, off sc1
.Lwtp10_1:
	s_or_b64 exec, exec, s[40:41]
	v_lshrrev_b64 v[102:103], 1, v[202:203]
	v_and_b32_e32 v102, 0xffffffc0, v102
	v_lshl_add_u64 v[104:105], v[102:103], 0, s[36:37]
	v_lshlrev_b64 v[104:105], 14, v[104:105]
	v_lshlrev_b32_e32 v106, 7, v202
	v_lshl_add_u64 v[104:105], s[10:11], 0, v[104:105]
	v_and_b32_e32 v106, 0x3f80, v106
	v_mov_b32_e32 v107, v187
	v_pk_add_f32 v[96:97], v[96:97], v[160:161]
	v_pk_add_f32 v[94:95], v[94:95], v[158:159]
	s_waitcnt lgkmcnt(0)
	v_pk_add_f32 v[98:99], v[92:93], v[156:157]
	v_pk_add_f32 v[100:101], v[90:91], v[154:155]
	v_lshl_add_u64 v[104:105], v[104:105], 0, v[106:107]
	v_cvt_pk_bf16_f32 v90, v94, v95
	v_cvt_pk_bf16_f32 v91, v96, v97
	v_cvt_pk_bf16_f32 v92, v100, v101
	v_cvt_pk_bf16_f32 v93, v98, v99
	v_lshl_add_u64 v[104:105], v[104:105], 0, v[186:187]
	global_store_dwordx4 v[104:105], v[90:93], off sc1
	v_pk_add_f32 v[86:87], v[86:87], v[150:151]
	v_pk_add_f32 v[88:89], v[88:89], v[152:153]
	v_mul_f32_e32 v90, v95, v95
	v_mul_f32_e32 v91, v97, v97
	v_fmac_f32_e32 v90, v94, v94
	v_fmac_f32_e32 v91, v96, v96
	v_add_f32_e32 v90, v90, v91
	v_mul_f32_e32 v91, v101, v101
	v_mul_f32_e32 v92, v99, v99
	v_fmac_f32_e32 v91, v100, v100
	v_fmac_f32_e32 v92, v98, v98
	v_add_f32_e32 v91, v91, v92
	v_add_f32_e32 v92, v90, v91
	v_pk_add_f32 v[90:91], v[84:85], v[148:149]
	v_cvt_pk_bf16_f32 v84, v86, v87
	v_mul_f32_e32 v87, v87, v87
	v_fmac_f32_e32 v87, v86, v86
	v_mul_f32_e32 v86, v89, v89
	v_pk_add_f32 v[82:83], v[82:83], v[146:147]
	v_fmac_f32_e32 v86, v88, v88
	v_cvt_pk_bf16_f32 v85, v88, v89
	v_add_f32_e32 v86, v87, v86
	v_mul_f32_e32 v87, v83, v83
	v_mul_f32_e32 v88, v91, v91
	v_fmac_f32_e32 v87, v82, v82
	v_fmac_f32_e32 v88, v90, v90
	v_add_f32_e32 v87, v87, v88
	v_add_f32_e32 v86, v86, v87
	v_add_f32_e32 v92, v92, v86
	ds_bpermute_b32 v93, v214, v92
	v_cvt_pk_bf16_f32 v86, v82, v83
	v_lshl_add_u64 v[82:83], v[102:103], 0, s[38:39]
	v_lshlrev_b64 v[88:89], 14, v[82:83]
	v_lshl_add_u64 v[88:89], s[10:11], 0, v[88:89]
	s_waitcnt lgkmcnt(0)
	v_add_f32_e32 v82, v92, v93
	ds_bpermute_b32 v83, v213, v82
	v_lshl_add_u64 v[88:89], v[88:89], 0, v[106:107]
	v_cvt_pk_bf16_f32 v87, v90, v91
	v_lshl_add_u64 v[88:89], v[88:89], 0, v[186:187]
	global_store_dwordx4 v[88:89], v[84:87], off sc1
	s_and_saveexec_b64 s[40:41], s[4:5]
	s_cbranch_execz .Lwtp10_2
	v_lshlrev_b64 v[84:85], 8, v[202:203]
	v_lshl_add_u64 v[84:85], s[14:15], 0, v[84:85]
	v_lshl_add_u64 v[84:85], s[34:35], 2, v[84:85]
	s_lshl_b32 s16, s62, 2
	v_lshl_add_u64 v[84:85], v[84:85], 0, s[16:17]
	s_waitcnt lgkmcnt(0)
	v_add_f32_e32 v82, v82, v83
	global_store_dword v[84:85], v82, off sc1
.Lwtp10_2:
	s_or_b64 exec, exec, s[40:41]
	v_lshrrev_b64 v[86:87], 1, v[200:201]
	v_and_b32_e32 v86, 0xffffffc0, v86
	v_lshl_add_u64 v[88:89], v[86:87], 0, s[36:37]
	v_lshlrev_b64 v[88:89], 14, v[88:89]
	v_lshlrev_b32_e32 v90, 7, v200
	v_lshl_add_u64 v[88:89], s[10:11], 0, v[88:89]
	v_and_b32_e32 v90, 0x3f80, v90
	v_mov_b32_e32 v91, v187
	v_pk_add_f32 v[80:81], v[80:81], v[144:145]
	v_pk_add_f32 v[78:79], v[78:79], v[142:143]
	s_waitcnt lgkmcnt(0)
	v_pk_add_f32 v[82:83], v[76:77], v[140:141]
	v_pk_add_f32 v[84:85], v[74:75], v[138:139]
	v_lshl_add_u64 v[88:89], v[88:89], 0, v[90:91]
	v_cvt_pk_bf16_f32 v74, v78, v79
	v_cvt_pk_bf16_f32 v75, v80, v81
	v_cvt_pk_bf16_f32 v76, v84, v85
	v_cvt_pk_bf16_f32 v77, v82, v83
	v_lshl_add_u64 v[88:89], v[88:89], 0, v[186:187]
	global_store_dwordx4 v[88:89], v[74:77], off sc1
	v_pk_add_f32 v[70:71], v[70:71], v[134:135]
	v_pk_add_f32 v[72:73], v[72:73], v[136:137]
	v_mul_f32_e32 v74, v79, v79
	v_mul_f32_e32 v75, v81, v81
	v_fmac_f32_e32 v74, v78, v78
	v_fmac_f32_e32 v75, v80, v80
	v_add_f32_e32 v74, v74, v75
	v_mul_f32_e32 v75, v85, v85
	v_mul_f32_e32 v76, v83, v83
	v_fmac_f32_e32 v75, v84, v84
	v_fmac_f32_e32 v76, v82, v82
	v_add_f32_e32 v75, v75, v76
	v_add_f32_e32 v76, v74, v75
	v_pk_add_f32 v[74:75], v[68:69], v[132:133]
	v_cvt_pk_bf16_f32 v68, v70, v71
	v_mul_f32_e32 v71, v71, v71
	v_fmac_f32_e32 v71, v70, v70
	v_mul_f32_e32 v70, v73, v73
	v_pk_add_f32 v[66:67], v[66:67], v[130:131]
	v_fmac_f32_e32 v70, v72, v72
	v_cvt_pk_bf16_f32 v69, v72, v73
	v_add_f32_e32 v70, v71, v70
	v_mul_f32_e32 v71, v67, v67
	v_mul_f32_e32 v72, v75, v75
	v_fmac_f32_e32 v71, v66, v66
	v_fmac_f32_e32 v72, v74, v74
	v_add_f32_e32 v71, v71, v72
	v_add_f32_e32 v70, v70, v71
	v_add_f32_e32 v76, v76, v70
	ds_bpermute_b32 v77, v214, v76
	v_cvt_pk_bf16_f32 v70, v66, v67
	v_lshl_add_u64 v[66:67], v[86:87], 0, s[38:39]
	v_lshlrev_b64 v[72:73], 14, v[66:67]
	v_lshl_add_u64 v[72:73], s[10:11], 0, v[72:73]
	s_waitcnt lgkmcnt(0)
	v_add_f32_e32 v66, v76, v77
	ds_bpermute_b32 v67, v213, v66
	v_lshl_add_u64 v[72:73], v[72:73], 0, v[90:91]
	v_cvt_pk_bf16_f32 v71, v74, v75
	v_lshl_add_u64 v[72:73], v[72:73], 0, v[186:187]
	global_store_dwordx4 v[72:73], v[68:71], off sc1
	s_and_saveexec_b64 s[40:41], s[4:5]
	s_cbranch_execz .Lwtp10_3
	v_lshlrev_b64 v[68:69], 8, v[200:201]
	v_lshl_add_u64 v[68:69], s[14:15], 0, v[68:69]
	v_lshl_add_u64 v[68:69], s[34:35], 2, v[68:69]
	s_lshl_b32 s16, s62, 2
	v_lshl_add_u64 v[68:69], v[68:69], 0, s[16:17]
	s_waitcnt lgkmcnt(0)
	v_add_f32_e32 v66, v66, v67
	global_store_dword v[68:69], v66, off sc1
.Lwtp10_3:
	s_or_b64 exec, exec, s[40:41]
	v_add_u32_e32 v120, 0x80, v196
	v_ashrrev_i32_e32 v121, 31, v120
	s_waitcnt lgkmcnt(0)
	v_lshlrev_b64 v[66:67], 14, v[120:121]
	v_lshl_add_u64 v[66:67], s[56:57], 0, v[66:67]
	v_lshl_add_u64 v[66:67], v[66:67], 0, v[198:199]
	global_load_dwordx4 v[122:125], v[66:67], off
	global_load_dwordx4 v[126:129], v[66:67], off offset:16
	global_load_dwordx4 v[130:133], v[66:67], off offset:512
	global_load_dwordx4 v[134:137], v[66:67], off offset:528
	v_add_u32_e32 v118, 0x90, v196
	v_add_u32_e32 v116, 0xa0, v196
	v_add_u32_e32 v114, 0xb0, v196
	v_ashrrev_i32_e32 v119, 31, v118
	v_ashrrev_i32_e32 v117, 31, v116
	v_ashrrev_i32_e32 v115, 31, v114
	v_lshlrev_b64 v[66:67], 14, v[118:119]
	v_lshlrev_b64 v[68:69], 14, v[116:117]
	v_lshlrev_b64 v[70:71], 14, v[114:115]
	v_lshl_add_u64 v[66:67], s[56:57], 0, v[66:67]
	v_lshl_add_u64 v[68:69], s[56:57], 0, v[68:69]
	v_lshl_add_u64 v[70:71], s[56:57], 0, v[70:71]
	v_lshl_add_u64 v[66:67], v[66:67], 0, v[198:199]
	v_lshl_add_u64 v[68:69], v[68:69], 0, v[198:199]
	v_lshl_add_u64 v[70:71], v[70:71], 0, v[198:199]
	global_load_dwordx4 v[106:109], v[66:67], off offset:16
	global_load_dwordx4 v[110:113], v[66:67], off
	global_load_dwordx4 v[98:101], v[66:67], off offset:528
	global_load_dwordx4 v[102:105], v[66:67], off offset:512
	global_load_dwordx4 v[90:93], v[68:69], off offset:16
	global_load_dwordx4 v[94:97], v[68:69], off
	global_load_dwordx4 v[82:85], v[68:69], off offset:528
	global_load_dwordx4 v[86:89], v[68:69], off offset:512
	global_load_dwordx4 v[74:77], v[70:71], off offset:16
	global_load_dwordx4 v[78:81], v[70:71], off
	s_nop 0
	global_load_dwordx4 v[66:69], v[70:71], off offset:528
	s_nop 0
	global_load_dwordx4 v[70:73], v[70:71], off offset:512
	v_lshrrev_b64 v[140:141], 1, v[120:121]
	v_and_b32_e32 v140, 0xffffffc0, v140
	v_lshl_add_u64 v[142:143], v[140:141], 0, s[36:37]
	v_lshlrev_b32_e32 v138, 7, v120
	v_lshlrev_b64 v[142:143], 14, v[142:143]
	v_mov_b32_e32 v139, v187
	v_and_b32_e32 v138, 0x3f80, v138
	v_lshl_add_u64 v[142:143], s[10:11], 0, v[142:143]
	v_lshl_add_u64 v[142:143], v[142:143], 0, v[138:139]
	v_lshl_add_u64 v[142:143], v[142:143], 0, v[186:187]
	s_waitcnt vmcnt(15)
	v_pk_add_f32 v[64:65], v[64:65], v[124:125]
	v_pk_add_f32 v[62:63], v[62:63], v[122:123]
	s_waitcnt vmcnt(14)
	v_pk_add_f32 v[60:61], v[60:61], v[128:129]
	v_pk_add_f32 v[58:59], v[58:59], v[126:127]
	s_waitcnt vmcnt(13)
	v_pk_add_f32 v[56:57], v[56:57], v[132:133]
	v_pk_add_f32 v[122:123], v[54:55], v[130:131]
	s_waitcnt vmcnt(12)
	v_pk_add_f32 v[124:125], v[52:53], v[136:137]
	v_pk_add_f32 v[126:127], v[50:51], v[134:135]
	v_cvt_pk_bf16_f32 v50, v62, v63
	v_cvt_pk_bf16_f32 v51, v64, v65
	v_cvt_pk_bf16_f32 v52, v58, v59
	v_cvt_pk_bf16_f32 v53, v60, v61
	v_mul_f32_e32 v63, v63, v63
	v_mul_f32_e32 v65, v65, v65
	v_mul_f32_e32 v59, v59, v59
	v_mul_f32_e32 v61, v61, v61
	v_cvt_pk_bf16_f32 v54, v122, v123
	v_cvt_pk_bf16_f32 v55, v56, v57
	v_mul_f32_e32 v123, v123, v123
	v_mul_f32_e32 v57, v57, v57
	v_mul_f32_e32 v128, v127, v127
	v_mul_f32_e32 v129, v125, v125
	v_fmac_f32_e32 v63, v62, v62
	v_fmac_f32_e32 v65, v64, v64
	v_fmac_f32_e32 v59, v58, v58
	v_fmac_f32_e32 v61, v60, v60
	v_fmac_f32_e32 v123, v122, v122
	v_fmac_f32_e32 v57, v56, v56
	v_fmac_f32_e32 v128, v126, v126
	v_fmac_f32_e32 v129, v124, v124
	global_store_dwordx4 v[142:143], v[50:53], off sc1
	v_cvt_pk_bf16_f32 v56, v126, v127
	s_nop 0
	v_add_f32_e32 v50, v63, v65
	v_add_f32_e32 v51, v59, v61
	v_add_f32_e32 v52, v123, v57
	v_add_f32_e32 v53, v128, v129
	v_add_f32_e32 v50, v50, v51
	v_add_f32_e32 v51, v52, v53
	v_add_f32_e32 v58, v50, v51
	ds_bpermute_b32 v59, v214, v58
	v_lshl_add_u64 v[50:51], v[140:141], 0, s[38:39]
	v_lshlrev_b64 v[52:53], 14, v[50:51]
	v_lshl_add_u64 v[52:53], s[10:11], 0, v[52:53]
	v_lshl_add_u64 v[52:53], v[52:53], 0, v[138:139]
	s_waitcnt lgkmcnt(0)
	v_add_f32_e32 v50, v58, v59
	ds_bpermute_b32 v51, v213, v50
	v_cvt_pk_bf16_f32 v57, v124, v125
	v_lshl_add_u64 v[52:53], v[52:53], 0, v[186:187]
	global_store_dwordx4 v[52:53], v[54:57], off sc1
	s_and_saveexec_b64 s[40:41], s[4:5]
	s_cbranch_execz .Lwtp10_4
	v_lshlrev_b64 v[52:53], 8, v[120:121]
	v_lshl_add_u64 v[52:53], s[14:15], 0, v[52:53]
	v_lshl_add_u64 v[52:53], s[34:35], 2, v[52:53]
	s_lshl_b32 s16, s62, 2
	v_lshl_add_u64 v[52:53], v[52:53], 0, s[16:17]
	s_waitcnt lgkmcnt(0)
	v_add_f32_e32 v50, v50, v51
	global_store_dword v[52:53], v50, off sc1
.Lwtp10_4:
	s_or_b64 exec, exec, s[40:41]
	v_lshrrev_b64 v[54:55], 1, v[118:119]
	v_and_b32_e32 v54, 0xffffffc0, v54
	v_lshl_add_u64 v[56:57], v[54:55], 0, s[36:37]
	v_lshlrev_b64 v[56:57], 14, v[56:57]
	v_lshlrev_b32_e32 v58, 7, v118
	v_lshl_add_u64 v[56:57], s[10:11], 0, v[56:57]
	v_and_b32_e32 v58, 0x3f80, v58
	v_mov_b32_e32 v59, v187
	s_waitcnt vmcnt(12)
	v_pk_add_f32 v[48:49], v[48:49], v[112:113]
	v_pk_add_f32 v[46:47], v[46:47], v[110:111]
	s_waitcnt lgkmcnt(0)
	v_pk_add_f32 v[50:51], v[44:45], v[108:109]
	v_pk_add_f32 v[52:53], v[42:43], v[106:107]
	v_lshl_add_u64 v[56:57], v[56:57], 0, v[58:59]
	v_cvt_pk_bf16_f32 v42, v46, v47
	v_cvt_pk_bf16_f32 v43, v48, v49
	v_cvt_pk_bf16_f32 v44, v52, v53
	v_cvt_pk_bf16_f32 v45, v50, v51
	v_lshl_add_u64 v[56:57], v[56:57], 0, v[186:187]
	global_store_dwordx4 v[56:57], v[42:45], off sc1
	s_waitcnt vmcnt(11)
	v_pk_add_f32 v[38:39], v[38:39], v[102:103]
	v_pk_add_f32 v[40:41], v[40:41], v[104:105]
	v_mul_f32_e32 v42, v47, v47
	v_mul_f32_e32 v43, v49, v49
	v_fmac_f32_e32 v42, v46, v46
	v_fmac_f32_e32 v43, v48, v48
	v_add_f32_e32 v42, v42, v43
	v_mul_f32_e32 v43, v53, v53
	v_mul_f32_e32 v44, v51, v51
	v_fmac_f32_e32 v43, v52, v52
	v_fmac_f32_e32 v44, v50, v50
	v_add_f32_e32 v43, v43, v44
	v_add_f32_e32 v44, v42, v43
	v_pk_add_f32 v[42:43], v[36:37], v[100:101]
	v_cvt_pk_bf16_f32 v36, v38, v39
	v_mul_f32_e32 v39, v39, v39
	v_fmac_f32_e32 v39, v38, v38
	v_mul_f32_e32 v38, v41, v41
	v_pk_add_f32 v[34:35], v[34:35], v[98:99]
	v_fmac_f32_e32 v38, v40, v40
	v_cvt_pk_bf16_f32 v37, v40, v41
	v_add_f32_e32 v38, v39, v38
	v_mul_f32_e32 v39, v35, v35
	v_mul_f32_e32 v40, v43, v43
	v_fmac_f32_e32 v39, v34, v34
	v_fmac_f32_e32 v40, v42, v42
	v_add_f32_e32 v39, v39, v40
	v_add_f32_e32 v38, v38, v39
	v_add_f32_e32 v44, v44, v38
	ds_bpermute_b32 v45, v214, v44
	v_cvt_pk_bf16_f32 v38, v34, v35
	v_lshl_add_u64 v[34:35], v[54:55], 0, s[38:39]
	v_lshlrev_b64 v[40:41], 14, v[34:35]
	v_lshl_add_u64 v[40:41], s[10:11], 0, v[40:41]
	s_waitcnt lgkmcnt(0)
	v_add_f32_e32 v34, v44, v45
	ds_bpermute_b32 v35, v213, v34
	v_lshl_add_u64 v[40:41], v[40:41], 0, v[58:59]
	v_cvt_pk_bf16_f32 v39, v42, v43
	v_lshl_add_u64 v[40:41], v[40:41], 0, v[186:187]
	global_store_dwordx4 v[40:41], v[36:39], off sc1
	s_and_saveexec_b64 s[40:41], s[4:5]
	s_cbranch_execz .Lwtp10_5
	v_lshlrev_b64 v[36:37], 8, v[118:119]
	v_lshl_add_u64 v[36:37], s[14:15], 0, v[36:37]
	v_lshl_add_u64 v[36:37], s[34:35], 2, v[36:37]
	s_lshl_b32 s16, s62, 2
	v_lshl_add_u64 v[36:37], v[36:37], 0, s[16:17]
	s_waitcnt lgkmcnt(0)
	v_add_f32_e32 v34, v34, v35
	global_store_dword v[36:37], v34, off sc1
.Lwtp10_5:
	s_or_b64 exec, exec, s[40:41]
	v_lshrrev_b64 v[38:39], 1, v[116:117]
	v_and_b32_e32 v38, 0xffffffc0, v38
	v_lshl_add_u64 v[40:41], v[38:39], 0, s[36:37]
	v_lshlrev_b64 v[40:41], 14, v[40:41]
	v_lshlrev_b32_e32 v42, 7, v116
	v_lshl_add_u64 v[40:41], s[10:11], 0, v[40:41]
	v_and_b32_e32 v42, 0x3f80, v42
	v_mov_b32_e32 v43, v187
	s_waitcnt vmcnt(10)
	v_pk_add_f32 v[32:33], v[32:33], v[96:97]
	v_pk_add_f32 v[30:31], v[30:31], v[94:95]
	s_waitcnt lgkmcnt(0)
	v_pk_add_f32 v[34:35], v[28:29], v[92:93]
	v_pk_add_f32 v[36:37], v[26:27], v[90:91]
	v_lshl_add_u64 v[40:41], v[40:41], 0, v[42:43]
	v_cvt_pk_bf16_f32 v26, v30, v31
	v_cvt_pk_bf16_f32 v27, v32, v33
	v_cvt_pk_bf16_f32 v28, v36, v37
	v_cvt_pk_bf16_f32 v29, v34, v35
	v_lshl_add_u64 v[40:41], v[40:41], 0, v[186:187]
	global_store_dwordx4 v[40:41], v[26:29], off sc1
	s_waitcnt vmcnt(9)
	v_pk_add_f32 v[22:23], v[22:23], v[86:87]
	v_pk_add_f32 v[24:25], v[24:25], v[88:89]
	v_mul_f32_e32 v26, v31, v31
	v_mul_f32_e32 v27, v33, v33
	v_fmac_f32_e32 v26, v30, v30
	v_fmac_f32_e32 v27, v32, v32
	v_add_f32_e32 v26, v26, v27
	v_mul_f32_e32 v27, v37, v37
	v_mul_f32_e32 v28, v35, v35
	v_fmac_f32_e32 v27, v36, v36
	v_fmac_f32_e32 v28, v34, v34
	v_add_f32_e32 v27, v27, v28
	v_add_f32_e32 v28, v26, v27
	v_pk_add_f32 v[26:27], v[20:21], v[84:85]
	v_cvt_pk_bf16_f32 v20, v22, v23
	v_mul_f32_e32 v23, v23, v23
	v_fmac_f32_e32 v23, v22, v22
	v_mul_f32_e32 v22, v25, v25
	v_pk_add_f32 v[18:19], v[18:19], v[82:83]
	v_fmac_f32_e32 v22, v24, v24
	v_cvt_pk_bf16_f32 v21, v24, v25
	v_add_f32_e32 v22, v23, v22
	v_mul_f32_e32 v23, v19, v19
	v_mul_f32_e32 v24, v27, v27
	v_fmac_f32_e32 v23, v18, v18
	v_fmac_f32_e32 v24, v26, v26
	v_add_f32_e32 v23, v23, v24
	v_add_f32_e32 v22, v22, v23
	v_add_f32_e32 v28, v28, v22
	ds_bpermute_b32 v29, v214, v28
	v_cvt_pk_bf16_f32 v22, v18, v19
	v_lshl_add_u64 v[18:19], v[38:39], 0, s[38:39]
	v_lshlrev_b64 v[24:25], 14, v[18:19]
	v_lshl_add_u64 v[24:25], s[10:11], 0, v[24:25]
	s_waitcnt lgkmcnt(0)
	v_add_f32_e32 v18, v28, v29
	ds_bpermute_b32 v19, v213, v18
	v_lshl_add_u64 v[24:25], v[24:25], 0, v[42:43]
	v_cvt_pk_bf16_f32 v23, v26, v27
	v_lshl_add_u64 v[24:25], v[24:25], 0, v[186:187]
	global_store_dwordx4 v[24:25], v[20:23], off sc1
	s_and_saveexec_b64 s[40:41], s[4:5]
	s_cbranch_execz .Lwtp10_6
	v_lshlrev_b64 v[20:21], 8, v[116:117]
	v_lshl_add_u64 v[20:21], s[14:15], 0, v[20:21]
	v_lshl_add_u64 v[20:21], s[34:35], 2, v[20:21]
	s_lshl_b32 s16, s62, 2
	v_lshl_add_u64 v[20:21], v[20:21], 0, s[16:17]
	s_waitcnt lgkmcnt(0)
	v_add_f32_e32 v18, v18, v19
	global_store_dword v[20:21], v18, off sc1
.Lwtp10_6:
	s_or_b64 exec, exec, s[40:41]
	v_lshrrev_b64 v[22:23], 1, v[114:115]
	v_and_b32_e32 v22, 0xffffffc0, v22
	v_lshl_add_u64 v[24:25], v[22:23], 0, s[36:37]
	v_lshlrev_b64 v[24:25], 14, v[24:25]
	v_lshlrev_b32_e32 v26, 7, v114
	v_lshl_add_u64 v[24:25], s[10:11], 0, v[24:25]
	v_and_b32_e32 v26, 0x3f80, v26
	v_mov_b32_e32 v27, v187
	s_waitcnt vmcnt(8)
	v_pk_add_f32 v[16:17], v[16:17], v[80:81]
	v_pk_add_f32 v[14:15], v[14:15], v[78:79]
	s_waitcnt lgkmcnt(0)
	v_pk_add_f32 v[18:19], v[12:13], v[76:77]
	v_pk_add_f32 v[20:21], v[10:11], v[74:75]
	v_lshl_add_u64 v[24:25], v[24:25], 0, v[26:27]
	v_cvt_pk_bf16_f32 v10, v14, v15
	v_cvt_pk_bf16_f32 v11, v16, v17
	v_cvt_pk_bf16_f32 v12, v20, v21
	v_cvt_pk_bf16_f32 v13, v18, v19
	v_lshl_add_u64 v[24:25], v[24:25], 0, v[186:187]
	global_store_dwordx4 v[24:25], v[10:13], off sc1
	s_waitcnt vmcnt(7)
	v_pk_add_f32 v[6:7], v[6:7], v[70:71]
	v_pk_add_f32 v[8:9], v[8:9], v[72:73]
	v_mul_f32_e32 v10, v15, v15
	v_mul_f32_e32 v11, v17, v17
	v_fmac_f32_e32 v10, v14, v14
	v_fmac_f32_e32 v11, v16, v16
	v_add_f32_e32 v10, v10, v11
	v_mul_f32_e32 v11, v21, v21
	v_mul_f32_e32 v12, v19, v19
	v_fmac_f32_e32 v11, v20, v20
	v_fmac_f32_e32 v12, v18, v18
	v_add_f32_e32 v11, v11, v12
	v_add_f32_e32 v12, v10, v11
	v_pk_add_f32 v[10:11], v[4:5], v[68:69]
	v_cvt_pk_bf16_f32 v4, v6, v7
	v_mul_f32_e32 v7, v7, v7
	v_fmac_f32_e32 v7, v6, v6
	v_mul_f32_e32 v6, v9, v9
	v_pk_add_f32 v[2:3], v[2:3], v[66:67]
	v_fmac_f32_e32 v6, v8, v8
	v_cvt_pk_bf16_f32 v5, v8, v9
	v_add_f32_e32 v6, v7, v6
	v_mul_f32_e32 v7, v3, v3
	v_mul_f32_e32 v8, v11, v11
	v_fmac_f32_e32 v7, v2, v2
	v_fmac_f32_e32 v8, v10, v10
	v_add_f32_e32 v7, v7, v8
	v_add_f32_e32 v6, v6, v7
	v_add_f32_e32 v12, v12, v6
	ds_bpermute_b32 v13, v214, v12
	v_cvt_pk_bf16_f32 v6, v2, v3
	v_lshl_add_u64 v[2:3], v[22:23], 0, s[38:39]
	v_lshlrev_b64 v[8:9], 14, v[2:3]
	v_lshl_add_u64 v[8:9], s[10:11], 0, v[8:9]
	s_waitcnt lgkmcnt(0)
	v_add_f32_e32 v2, v12, v13
	ds_bpermute_b32 v3, v213, v2
	v_lshl_add_u64 v[8:9], v[8:9], 0, v[26:27]
	v_cvt_pk_bf16_f32 v7, v10, v11
	v_lshl_add_u64 v[8:9], v[8:9], 0, v[186:187]
	global_store_dwordx4 v[8:9], v[4:7], off sc1
	s_and_saveexec_b64 s[36:37], s[4:5]
	s_cbranch_execz .Lwtp10_7
	v_lshlrev_b64 v[4:5], 8, v[114:115]
	v_lshl_add_u64 v[4:5], s[14:15], 0, v[4:5]
	v_lshl_add_u64 v[4:5], s[34:35], 2, v[4:5]
	s_lshl_b32 s16, s62, 2
	v_lshl_add_u64 v[4:5], v[4:5], 0, s[16:17]
	s_waitcnt lgkmcnt(0)
	v_add_f32_e32 v2, v2, v3
	global_store_dword v[4:5], v2, off sc1
.Lwtp10_7:
	s_or_b64 exec, exec, s[36:37]
	s_andn2_b64 vcc, exec, s[6:7]
	s_mov_b64 s[6:7], -1
	s_branch .Lwtp10_join

.LBB0_1218:
	s_and_b64 vcc, exec, s[4:5]
	s_cbranch_vccz .Lwtp12_entry
	v_max_f32_e32 v129, v129, v129
	v_max_f32_e32 v128, v128, v128
	v_lshl_add_u32 v150, s26, 8, v152
	s_lshl_b32 s19, s27, 8
	v_max_f32_e32 v129, 0, v129
	v_max_f32_e32 v128, 0, v128
	v_max_f32_e32 v125, v125, v125
	v_max_f32_e32 v124, v124, v124
	s_or_b32 s19, s19, s44
	v_ashrrev_i32_e32 v151, 31, v150
	v_max_f32_e32 v127, v127, v127
	v_max_f32_e32 v126, v126, v126
	v_max_f32_e32 v123, v123, v123
	v_max_f32_e32 v122, v122, v122
	v_max_f32_e32 v125, 0, v125
	v_max_f32_e32 v124, 0, v124
	v_pk_mul_f32 v[128:129], v[128:129], v[128:129]
	v_max_f32_e32 v127, 0, v127
	v_max_f32_e32 v126, 0, v126
	v_max_f32_e32 v123, 0, v123
	v_max_f32_e32 v122, 0, v122
	v_pk_mul_f32 v[160:161], v[124:125], v[124:125]
	v_cvt_pk_bf16_f32 v125, v128, v129
	v_lshlrev_b64 v[128:129], 1, v[150:151]
	s_ashr_i32 s26, s19, 6
	v_pk_mul_f32 v[126:127], v[126:127], v[126:127]
	v_pk_mul_f32 v[122:123], v[122:123], v[122:123]
	v_and_b32_e32 v128, 0xffffff00, v128
	s_ashr_i32 s27, s26, 31
	v_cvt_pk_bf16_f32 v124, v126, v127
	v_cvt_pk_bf16_f32 v126, v122, v123
	v_lshl_add_u64 v[122:123], v[128:129], 0, s[26:27]
	v_lshlrev_b64 v[122:123], 14, v[122:123]
	v_lshlrev_b32_e32 v151, 7, v150
	v_lshl_add_u64 v[122:123], s[84:85], 0, v[122:123]
	v_and_b32_e32 v138, 0x2780, v151
	v_max_f32_e32 v119, v119, v119
	v_max_f32_e32 v118, v118, v118
	v_cvt_pk_bf16_f32 v127, v160, v161
	v_lshl_add_u64 v[160:161], v[122:123], 0, v[138:139]
	v_mov_b32_e32 v149, v139
	v_max_f32_e32 v119, 0, v119
	v_max_f32_e32 v118, 0, v118
	v_max_f32_e32 v115, v115, v115
	v_max_f32_e32 v114, v114, v114
	v_max_f32_e32 v117, v117, v117
	v_max_f32_e32 v116, v116, v116
	s_or_b32 s28, s26, 2
	v_lshl_add_u64 v[160:161], v[160:161], 0, v[148:149]
	v_max_f32_e32 v115, 0, v115
	v_max_f32_e32 v114, 0, v114
	v_max_f32_e32 v117, 0, v117
	v_max_f32_e32 v116, 0, v116
	v_pk_mul_f32 v[118:119], v[118:119], v[118:119]
	s_ashr_i32 s29, s28, 31
	global_store_dwordx4 v[160:161], v[124:127], off
	v_max_f32_e32 v121, v121, v121
	v_max_f32_e32 v120, v120, v120
	v_pk_mul_f32 v[124:125], v[116:117], v[116:117]
	v_pk_mul_f32 v[116:117], v[114:115], v[114:115]
	v_cvt_pk_bf16_f32 v114, v118, v119
	v_lshl_add_u64 v[118:119], v[128:129], 0, s[28:29]
	v_max_f32_e32 v121, 0, v121
	v_max_f32_e32 v120, 0, v120
	v_lshlrev_b64 v[118:119], 14, v[118:119]
	v_pk_mul_f32 v[120:121], v[120:121], v[120:121]
	v_lshl_add_u64 v[118:119], s[84:85], 0, v[118:119]
	v_max_f32_e32 v111, v111, v111
	v_max_f32_e32 v110, v110, v110
	v_cvt_pk_bf16_f32 v115, v120, v121
	v_lshl_add_u64 v[120:121], v[118:119], 0, v[138:139]
	v_max_f32_e32 v111, 0, v111
	v_max_f32_e32 v110, 0, v110
	v_max_f32_e32 v113, v113, v113
	v_max_f32_e32 v112, v112, v112
	v_max_f32_e32 v107, v107, v107
	v_max_f32_e32 v106, v106, v106
	v_max_f32_e32 v109, v109, v109
	v_max_f32_e32 v108, v108, v108
	v_cvt_pk_bf16_f32 v116, v116, v117
	v_cvt_pk_bf16_f32 v117, v124, v125
	v_lshl_add_u64 v[120:121], v[120:121], 0, v[148:149]
	v_max_f32_e32 v113, 0, v113
	v_max_f32_e32 v112, 0, v112
	v_max_f32_e32 v107, 0, v107
	v_max_f32_e32 v106, 0, v106
	v_max_f32_e32 v109, 0, v109
	v_max_f32_e32 v108, 0, v108
	v_pk_mul_f32 v[110:111], v[110:111], v[110:111]
	v_bitop3_b32 v138, v151, s55, v157 bitop3:0xc8
	v_max_f32_e32 v103, v103, v103
	v_max_f32_e32 v102, v102, v102
	global_store_dwordx4 v[120:121], v[114:117], off
	v_pk_mul_f32 v[112:113], v[112:113], v[112:113]
	v_max_f32_e32 v103, 0, v103
	v_pk_mul_f32 v[114:115], v[108:109], v[108:109]
	v_pk_mul_f32 v[108:109], v[106:107], v[106:107]
	v_cvt_pk_bf16_f32 v106, v110, v111
	v_lshl_add_u64 v[110:111], v[122:123], 0, v[138:139]
	v_max_f32_e32 v102, 0, v102
	v_max_f32_e32 v105, v105, v105
	v_max_f32_e32 v104, v104, v104
	v_max_f32_e32 v99, v99, v99
	v_max_f32_e32 v98, v98, v98
	v_max_f32_e32 v101, v101, v101
	v_max_f32_e32 v100, v100, v100
	v_cvt_pk_bf16_f32 v107, v112, v113
	v_cvt_pk_bf16_f32 v108, v108, v109
	v_cvt_pk_bf16_f32 v109, v114, v115
	v_lshl_add_u64 v[110:111], v[110:111], 0, v[148:149]
	v_max_f32_e32 v105, 0, v105
	v_max_f32_e32 v104, 0, v104
	v_max_f32_e32 v99, 0, v99
	v_max_f32_e32 v98, 0, v98
	v_max_f32_e32 v101, 0, v101
	v_max_f32_e32 v100, 0, v100
	v_pk_mul_f32 v[102:103], v[102:103], v[102:103]
	v_max_f32_e32 v95, v95, v95
	v_max_f32_e32 v94, v94, v94
	global_store_dwordx4 v[110:111], v[106:109], off
	v_pk_mul_f32 v[104:105], v[104:105], v[104:105]
	v_max_f32_e32 v95, 0, v95
	v_pk_mul_f32 v[106:107], v[100:101], v[100:101]
	v_pk_mul_f32 v[100:101], v[98:99], v[98:99]
	v_cvt_pk_bf16_f32 v98, v102, v103
	v_lshl_add_u64 v[102:103], v[118:119], 0, v[138:139]
	v_max_f32_e32 v94, 0, v94
	v_max_f32_e32 v97, v97, v97
	v_max_f32_e32 v96, v96, v96
	v_max_f32_e32 v91, v91, v91
	v_max_f32_e32 v90, v90, v90
	v_max_f32_e32 v93, v93, v93
	v_max_f32_e32 v92, v92, v92
	v_cvt_pk_bf16_f32 v99, v104, v105
	v_cvt_pk_bf16_f32 v100, v100, v101
	v_cvt_pk_bf16_f32 v101, v106, v107
	v_lshl_add_u64 v[102:103], v[102:103], 0, v[148:149]
	v_max_f32_e32 v97, 0, v97
	v_max_f32_e32 v96, 0, v96
	v_max_f32_e32 v91, 0, v91
	v_max_f32_e32 v90, 0, v90
	v_max_f32_e32 v93, 0, v93
	v_max_f32_e32 v92, 0, v92
	v_pk_mul_f32 v[94:95], v[94:95], v[94:95]
	v_bitop3_b32 v138, v151, s55, v158 bitop3:0xc8
	v_max_f32_e32 v87, v87, v87
	v_max_f32_e32 v86, v86, v86
	global_store_dwordx4 v[102:103], v[98:101], off
	v_pk_mul_f32 v[96:97], v[96:97], v[96:97]
	v_max_f32_e32 v87, 0, v87
	v_pk_mul_f32 v[98:99], v[92:93], v[92:93]
	v_pk_mul_f32 v[92:93], v[90:91], v[90:91]
	v_cvt_pk_bf16_f32 v90, v94, v95
	v_lshl_add_u64 v[94:95], v[122:123], 0, v[138:139]
	v_max_f32_e32 v86, 0, v86
	v_max_f32_e32 v89, v89, v89
	v_max_f32_e32 v88, v88, v88
	v_max_f32_e32 v83, v83, v83
	v_max_f32_e32 v82, v82, v82
	v_max_f32_e32 v85, v85, v85
	v_max_f32_e32 v84, v84, v84
	v_cvt_pk_bf16_f32 v91, v96, v97
	v_cvt_pk_bf16_f32 v92, v92, v93
	v_cvt_pk_bf16_f32 v93, v98, v99
	v_lshl_add_u64 v[94:95], v[94:95], 0, v[148:149]
	v_max_f32_e32 v89, 0, v89
	v_max_f32_e32 v88, 0, v88
	v_max_f32_e32 v83, 0, v83
	v_max_f32_e32 v82, 0, v82
	v_max_f32_e32 v85, 0, v85
	v_max_f32_e32 v84, 0, v84
	v_pk_mul_f32 v[86:87], v[86:87], v[86:87]
	v_max_f32_e32 v79, v79, v79
	v_max_f32_e32 v78, v78, v78
	global_store_dwordx4 v[94:95], v[90:93], off
	v_pk_mul_f32 v[88:89], v[88:89], v[88:89]
	v_max_f32_e32 v79, 0, v79
	v_pk_mul_f32 v[90:91], v[84:85], v[84:85]
	v_pk_mul_f32 v[84:85], v[82:83], v[82:83]
	v_cvt_pk_bf16_f32 v82, v86, v87
	v_lshl_add_u64 v[86:87], v[118:119], 0, v[138:139]
	v_max_f32_e32 v78, 0, v78
	v_max_f32_e32 v81, v81, v81
	v_max_f32_e32 v80, v80, v80
	v_max_f32_e32 v75, v75, v75
	v_max_f32_e32 v74, v74, v74
	v_max_f32_e32 v77, v77, v77
	v_max_f32_e32 v76, v76, v76
	v_cvt_pk_bf16_f32 v83, v88, v89
	v_cvt_pk_bf16_f32 v84, v84, v85
	v_cvt_pk_bf16_f32 v85, v90, v91
	v_lshl_add_u64 v[86:87], v[86:87], 0, v[148:149]
	v_max_f32_e32 v81, 0, v81
	v_max_f32_e32 v80, 0, v80
	v_max_f32_e32 v75, 0, v75
	v_max_f32_e32 v74, 0, v74
	v_max_f32_e32 v77, 0, v77
	v_max_f32_e32 v76, 0, v76
	v_pk_mul_f32 v[78:79], v[78:79], v[78:79]
	v_bitop3_b32 v138, v151, s55, v159 bitop3:0xc8
	v_max_f32_e32 v71, v71, v71
	v_max_f32_e32 v70, v70, v70
	global_store_dwordx4 v[86:87], v[82:85], off
	v_pk_mul_f32 v[80:81], v[80:81], v[80:81]
	v_max_f32_e32 v71, 0, v71
	v_pk_mul_f32 v[82:83], v[76:77], v[76:77]
	v_pk_mul_f32 v[76:77], v[74:75], v[74:75]
	v_cvt_pk_bf16_f32 v74, v78, v79
	v_lshl_add_u64 v[78:79], v[122:123], 0, v[138:139]
	v_max_f32_e32 v70, 0, v70
	v_max_f32_e32 v73, v73, v73
	v_max_f32_e32 v72, v72, v72
	v_max_f32_e32 v67, v67, v67
	v_max_f32_e32 v66, v66, v66
	v_max_f32_e32 v69, v69, v69
	v_max_f32_e32 v68, v68, v68
	v_cvt_pk_bf16_f32 v75, v80, v81
	v_cvt_pk_bf16_f32 v76, v76, v77
	v_cvt_pk_bf16_f32 v77, v82, v83
	v_lshl_add_u64 v[78:79], v[78:79], 0, v[148:149]
	v_max_f32_e32 v73, 0, v73
	v_max_f32_e32 v72, 0, v72
	v_max_f32_e32 v67, 0, v67
	v_max_f32_e32 v66, 0, v66
	v_max_f32_e32 v69, 0, v69
	v_max_f32_e32 v68, 0, v68
	v_pk_mul_f32 v[70:71], v[70:71], v[70:71]
	global_store_dwordx4 v[78:79], v[74:77], off
	v_pk_mul_f32 v[72:73], v[72:73], v[72:73]
	v_max_f32_e32 v63, v63, v63
	v_pk_mul_f32 v[74:75], v[68:69], v[68:69]
	v_pk_mul_f32 v[68:69], v[66:67], v[66:67]
	v_cvt_pk_bf16_f32 v66, v70, v71
	v_lshl_add_u64 v[70:71], v[118:119], 0, v[138:139]
	v_cvt_pk_bf16_f32 v67, v72, v73
	v_cvt_pk_bf16_f32 v68, v68, v69
	v_cvt_pk_bf16_f32 v69, v74, v75
	v_lshl_add_u64 v[70:71], v[70:71], 0, v[148:149]
	v_max_f32_e32 v62, v62, v62
	global_store_dwordx4 v[70:71], v[66:69], off
	v_max_f32_e32 v63, 0, v63
	v_max_f32_e32 v62, 0, v62
	v_add_u32_e32 v66, 0x80, v150
	v_max_f32_e32 v59, v59, v59
	v_max_f32_e32 v58, v58, v58
	v_max_f32_e32 v61, v61, v61
	v_max_f32_e32 v60, v60, v60
	v_ashrrev_i32_e32 v67, 31, v66
	v_max_f32_e32 v65, v65, v65
	v_max_f32_e32 v64, v64, v64
	v_max_f32_e32 v59, 0, v59
	v_max_f32_e32 v58, 0, v58
	v_max_f32_e32 v61, 0, v61
	v_max_f32_e32 v60, 0, v60
	v_pk_mul_f32 v[62:63], v[62:63], v[62:63]
	v_max_f32_e32 v65, 0, v65
	v_max_f32_e32 v64, 0, v64
	v_pk_mul_f32 v[68:69], v[60:61], v[60:61]
	v_pk_mul_f32 v[60:61], v[58:59], v[58:59]
	v_cvt_pk_bf16_f32 v58, v62, v63
	v_lshlrev_b64 v[62:63], 1, v[66:67]
	v_pk_mul_f32 v[64:65], v[64:65], v[64:65]
	v_and_b32_e32 v62, 0xffffff00, v62
	v_cvt_pk_bf16_f32 v59, v64, v65
	v_lshl_add_u64 v[64:65], v[62:63], 0, s[26:27]
	v_lshlrev_b64 v[64:65], 14, v[64:65]
	v_lshlrev_b32_e32 v66, 7, v66
	v_lshl_add_u64 v[64:65], s[84:85], 0, v[64:65]
	v_and_b32_e32 v138, 0x3f80, v66
	v_max_f32_e32 v55, v55, v55
	v_max_f32_e32 v54, v54, v54
	v_lshl_add_u64 v[64:65], v[64:65], 0, v[138:139]
	v_max_f32_e32 v55, 0, v55
	v_max_f32_e32 v54, 0, v54
	v_max_f32_e32 v51, v51, v51
	v_max_f32_e32 v50, v50, v50
	v_max_f32_e32 v53, v53, v53
	v_max_f32_e32 v52, v52, v52
	v_cvt_pk_bf16_f32 v60, v60, v61
	v_cvt_pk_bf16_f32 v61, v68, v69
	v_lshl_add_u64 v[64:65], v[64:65], 0, v[148:149]
	v_max_f32_e32 v51, 0, v51
	v_max_f32_e32 v50, 0, v50
	v_max_f32_e32 v53, 0, v53
	v_max_f32_e32 v52, 0, v52
	v_pk_mul_f32 v[54:55], v[54:55], v[54:55]
	global_store_dwordx4 v[64:65], v[58:61], off
	v_max_f32_e32 v57, v57, v57
	v_max_f32_e32 v56, v56, v56
	v_pk_mul_f32 v[58:59], v[52:53], v[52:53]
	v_pk_mul_f32 v[52:53], v[50:51], v[50:51]
	v_cvt_pk_bf16_f32 v50, v54, v55
	v_lshl_add_u64 v[54:55], v[62:63], 0, s[28:29]
	v_lshlrev_b64 v[54:55], 14, v[54:55]
	v_max_f32_e32 v57, 0, v57
	v_max_f32_e32 v56, 0, v56
	v_lshl_add_u64 v[54:55], s[84:85], 0, v[54:55]
	v_pk_mul_f32 v[56:57], v[56:57], v[56:57]
	v_lshl_add_u64 v[54:55], v[54:55], 0, v[138:139]
	v_cvt_pk_bf16_f32 v51, v56, v57
	v_cvt_pk_bf16_f32 v52, v52, v53
	v_cvt_pk_bf16_f32 v53, v58, v59
	v_lshl_add_u64 v[54:55], v[54:55], 0, v[148:149]
	v_max_f32_e32 v47, v47, v47
	v_max_f32_e32 v46, v46, v46
	global_store_dwordx4 v[54:55], v[50:53], off
	v_max_f32_e32 v47, 0, v47
	v_max_f32_e32 v46, 0, v46
	v_add_u32_e32 v50, 0x90, v150
	v_max_f32_e32 v43, v43, v43
	v_max_f32_e32 v42, v42, v42
	v_max_f32_e32 v45, v45, v45
	v_max_f32_e32 v44, v44, v44
	v_ashrrev_i32_e32 v51, 31, v50
	v_max_f32_e32 v49, v49, v49
	v_max_f32_e32 v48, v48, v48
	v_max_f32_e32 v43, 0, v43
	v_max_f32_e32 v42, 0, v42
	v_max_f32_e32 v45, 0, v45
	v_max_f32_e32 v44, 0, v44
	v_pk_mul_f32 v[46:47], v[46:47], v[46:47]
	v_max_f32_e32 v49, 0, v49
	v_max_f32_e32 v48, 0, v48
	v_pk_mul_f32 v[52:53], v[44:45], v[44:45]
	v_pk_mul_f32 v[44:45], v[42:43], v[42:43]
	v_cvt_pk_bf16_f32 v42, v46, v47
	v_lshlrev_b64 v[46:47], 1, v[50:51]
	v_pk_mul_f32 v[48:49], v[48:49], v[48:49]
	v_and_b32_e32 v46, 0xffffff00, v46
	v_cvt_pk_bf16_f32 v43, v48, v49
	v_lshl_add_u64 v[48:49], v[46:47], 0, s[26:27]
	v_lshlrev_b64 v[48:49], 14, v[48:49]
	v_lshlrev_b32_e32 v50, 7, v50
	v_lshl_add_u64 v[48:49], s[84:85], 0, v[48:49]
	v_and_b32_e32 v138, 0x3f80, v50
	v_max_f32_e32 v39, v39, v39
	v_max_f32_e32 v38, v38, v38
	v_lshl_add_u64 v[48:49], v[48:49], 0, v[138:139]
	v_max_f32_e32 v39, 0, v39
	v_max_f32_e32 v38, 0, v38
	v_max_f32_e32 v35, v35, v35
	v_max_f32_e32 v34, v34, v34
	v_max_f32_e32 v37, v37, v37
	v_max_f32_e32 v36, v36, v36
	v_cvt_pk_bf16_f32 v44, v44, v45
	v_cvt_pk_bf16_f32 v45, v52, v53
	v_lshl_add_u64 v[48:49], v[48:49], 0, v[148:149]
	v_max_f32_e32 v35, 0, v35
	v_max_f32_e32 v34, 0, v34
	v_max_f32_e32 v37, 0, v37
	v_max_f32_e32 v36, 0, v36
	v_pk_mul_f32 v[38:39], v[38:39], v[38:39]
	global_store_dwordx4 v[48:49], v[42:45], off
	v_max_f32_e32 v41, v41, v41
	v_max_f32_e32 v40, v40, v40
	v_pk_mul_f32 v[42:43], v[36:37], v[36:37]
	v_pk_mul_f32 v[36:37], v[34:35], v[34:35]
	v_cvt_pk_bf16_f32 v34, v38, v39
	v_lshl_add_u64 v[38:39], v[46:47], 0, s[28:29]
	v_lshlrev_b64 v[38:39], 14, v[38:39]
	v_max_f32_e32 v41, 0, v41
	v_max_f32_e32 v40, 0, v40
	v_lshl_add_u64 v[38:39], s[84:85], 0, v[38:39]
	v_pk_mul_f32 v[40:41], v[40:41], v[40:41]
	v_lshl_add_u64 v[38:39], v[38:39], 0, v[138:139]
	v_cvt_pk_bf16_f32 v35, v40, v41
	v_cvt_pk_bf16_f32 v36, v36, v37
	v_cvt_pk_bf16_f32 v37, v42, v43
	v_lshl_add_u64 v[38:39], v[38:39], 0, v[148:149]
	v_max_f32_e32 v31, v31, v31
	v_max_f32_e32 v30, v30, v30
	global_store_dwordx4 v[38:39], v[34:37], off
	v_max_f32_e32 v31, 0, v31
	v_max_f32_e32 v30, 0, v30
	v_add_u32_e32 v34, 0xa0, v150
	v_max_f32_e32 v27, v27, v27
	v_max_f32_e32 v26, v26, v26
	v_max_f32_e32 v29, v29, v29
	v_max_f32_e32 v28, v28, v28
	v_ashrrev_i32_e32 v35, 31, v34
	v_max_f32_e32 v33, v33, v33
	v_max_f32_e32 v32, v32, v32
	v_max_f32_e32 v27, 0, v27
	v_max_f32_e32 v26, 0, v26
	v_max_f32_e32 v29, 0, v29
	v_max_f32_e32 v28, 0, v28
	v_pk_mul_f32 v[30:31], v[30:31], v[30:31]
	v_max_f32_e32 v33, 0, v33
	v_max_f32_e32 v32, 0, v32
	v_pk_mul_f32 v[36:37], v[28:29], v[28:29]
	v_pk_mul_f32 v[28:29], v[26:27], v[26:27]
	v_cvt_pk_bf16_f32 v26, v30, v31
	v_lshlrev_b64 v[30:31], 1, v[34:35]
	v_pk_mul_f32 v[32:33], v[32:33], v[32:33]
	v_and_b32_e32 v30, 0xffffff00, v30
	v_cvt_pk_bf16_f32 v27, v32, v33
	v_lshl_add_u64 v[32:33], v[30:31], 0, s[26:27]
	v_lshlrev_b64 v[32:33], 14, v[32:33]
	v_lshlrev_b32_e32 v34, 7, v34
	v_lshl_add_u64 v[32:33], s[84:85], 0, v[32:33]
	v_and_b32_e32 v138, 0x3f80, v34
	v_max_f32_e32 v23, v23, v23
	v_max_f32_e32 v22, v22, v22
	v_lshl_add_u64 v[32:33], v[32:33], 0, v[138:139]
	v_max_f32_e32 v23, 0, v23
	v_max_f32_e32 v22, 0, v22
	v_max_f32_e32 v19, v19, v19
	v_max_f32_e32 v18, v18, v18
	v_max_f32_e32 v21, v21, v21
	v_max_f32_e32 v20, v20, v20
	v_cvt_pk_bf16_f32 v28, v28, v29
	v_cvt_pk_bf16_f32 v29, v36, v37
	v_lshl_add_u64 v[32:33], v[32:33], 0, v[148:149]
	v_max_f32_e32 v19, 0, v19
	v_max_f32_e32 v18, 0, v18
	v_max_f32_e32 v21, 0, v21
	v_max_f32_e32 v20, 0, v20
	v_pk_mul_f32 v[22:23], v[22:23], v[22:23]
	global_store_dwordx4 v[32:33], v[26:29], off
	v_max_f32_e32 v25, v25, v25
	v_max_f32_e32 v24, v24, v24
	v_pk_mul_f32 v[26:27], v[20:21], v[20:21]
	v_pk_mul_f32 v[20:21], v[18:19], v[18:19]
	v_cvt_pk_bf16_f32 v18, v22, v23
	v_lshl_add_u64 v[22:23], v[30:31], 0, s[28:29]
	v_lshlrev_b64 v[22:23], 14, v[22:23]
	v_max_f32_e32 v25, 0, v25
	v_max_f32_e32 v24, 0, v24
	v_lshl_add_u64 v[22:23], s[84:85], 0, v[22:23]
	v_pk_mul_f32 v[24:25], v[24:25], v[24:25]
	v_lshl_add_u64 v[22:23], v[22:23], 0, v[138:139]
	v_cvt_pk_bf16_f32 v19, v24, v25
	v_cvt_pk_bf16_f32 v20, v20, v21
	v_cvt_pk_bf16_f32 v21, v26, v27
	v_lshl_add_u64 v[22:23], v[22:23], 0, v[148:149]
	v_max_f32_e32 v15, v15, v15
	v_max_f32_e32 v14, v14, v14
	global_store_dwordx4 v[22:23], v[18:21], off
	v_max_f32_e32 v15, 0, v15
	v_max_f32_e32 v14, 0, v14
	v_add_u32_e32 v18, 0xb0, v150
	v_max_f32_e32 v11, v11, v11
	v_max_f32_e32 v10, v10, v10
	v_max_f32_e32 v13, v13, v13
	v_max_f32_e32 v12, v12, v12
	v_ashrrev_i32_e32 v19, 31, v18
	v_max_f32_e32 v17, v17, v17
	v_max_f32_e32 v16, v16, v16
	v_max_f32_e32 v11, 0, v11
	v_max_f32_e32 v10, 0, v10
	v_max_f32_e32 v13, 0, v13
	v_max_f32_e32 v12, 0, v12
	v_pk_mul_f32 v[14:15], v[14:15], v[14:15]
	v_max_f32_e32 v17, 0, v17
	v_max_f32_e32 v16, 0, v16
	v_pk_mul_f32 v[20:21], v[12:13], v[12:13]
	v_pk_mul_f32 v[12:13], v[10:11], v[10:11]
	v_cvt_pk_bf16_f32 v10, v14, v15
	v_lshlrev_b64 v[14:15], 1, v[18:19]
	v_pk_mul_f32 v[16:17], v[16:17], v[16:17]
	v_and_b32_e32 v14, 0xffffff00, v14
	v_cvt_pk_bf16_f32 v11, v16, v17
	v_lshl_add_u64 v[16:17], v[14:15], 0, s[26:27]
	v_lshlrev_b64 v[16:17], 14, v[16:17]
	v_lshlrev_b32_e32 v18, 7, v18
	v_lshl_add_u64 v[16:17], s[84:85], 0, v[16:17]
	v_and_b32_e32 v138, 0x3f80, v18
	v_max_f32_e32 v7, v7, v7
	v_max_f32_e32 v6, v6, v6
	v_lshl_add_u64 v[16:17], v[16:17], 0, v[138:139]
	v_max_f32_e32 v7, 0, v7
	v_max_f32_e32 v6, 0, v6
	v_max_f32_e32 v3, v3, v3
	v_max_f32_e32 v2, v2, v2
	v_max_f32_e32 v5, v5, v5
	v_max_f32_e32 v4, v4, v4
	v_cvt_pk_bf16_f32 v12, v12, v13
	v_cvt_pk_bf16_f32 v13, v20, v21
	v_lshl_add_u64 v[16:17], v[16:17], 0, v[148:149]
	v_max_f32_e32 v3, 0, v3
	v_max_f32_e32 v2, 0, v2
	v_max_f32_e32 v5, 0, v5
	v_max_f32_e32 v4, 0, v4
	v_pk_mul_f32 v[6:7], v[6:7], v[6:7]
	global_store_dwordx4 v[16:17], v[10:13], off
	v_max_f32_e32 v9, v9, v9
	v_max_f32_e32 v8, v8, v8
	v_pk_mul_f32 v[10:11], v[4:5], v[4:5]
	v_pk_mul_f32 v[4:5], v[2:3], v[2:3]
	v_cvt_pk_bf16_f32 v2, v6, v7
	v_lshl_add_u64 v[6:7], v[14:15], 0, s[28:29]
	v_lshlrev_b64 v[6:7], 14, v[6:7]
	v_max_f32_e32 v9, 0, v9
	v_max_f32_e32 v8, 0, v8
	v_lshl_add_u64 v[6:7], s[84:85], 0, v[6:7]
	v_pk_mul_f32 v[8:9], v[8:9], v[8:9]
	v_lshl_add_u64 v[6:7], v[6:7], 0, v[138:139]
	v_cvt_pk_bf16_f32 v3, v8, v9
	v_cvt_pk_bf16_f32 v4, v4, v5
	v_cvt_pk_bf16_f32 v5, v10, v11
	v_lshl_add_u64 v[6:7], v[6:7], 0, v[148:149]
	s_andn2_b64 vcc, exec, s[4:5]
	s_mov_b64 s[4:5], -1
	global_store_dwordx4 v[6:7], v[2:5], off
.Lwtp12_join:
	s_cbranch_vccnz .LBB0_1207
	s_andn2_b64 vcc, exec, s[6:7]
	s_cbranch_vccnz .LBB0_1206
	s_barrier
	s_branch .LBB0_1206
.Lwtp12_entry:
	v_max_f32_e32 v129, v129, v129
	v_max_f32_e32 v128, v128, v128
	v_lshl_add_u32 v150, s26, 8, v152
	s_lshl_b32 s19, s27, 8
	v_max_f32_e32 v129, 0, v129
	v_max_f32_e32 v128, 0, v128
	v_max_f32_e32 v125, v125, v125
	v_max_f32_e32 v124, v124, v124
	s_or_b32 s19, s19, s44
	v_ashrrev_i32_e32 v151, 31, v150
	v_max_f32_e32 v127, v127, v127
	v_max_f32_e32 v126, v126, v126
	v_max_f32_e32 v123, v123, v123
	v_max_f32_e32 v122, v122, v122
	v_max_f32_e32 v125, 0, v125
	v_max_f32_e32 v124, 0, v124
	v_pk_mul_f32 v[128:129], v[128:129], v[128:129]
	v_max_f32_e32 v127, 0, v127
	v_max_f32_e32 v126, 0, v126
	v_max_f32_e32 v123, 0, v123
	v_max_f32_e32 v122, 0, v122
	v_pk_mul_f32 v[160:161], v[124:125], v[124:125]
	v_cvt_pk_bf16_f32 v125, v128, v129
	v_lshlrev_b64 v[128:129], 1, v[150:151]
	s_ashr_i32 s26, s19, 6
	v_pk_mul_f32 v[126:127], v[126:127], v[126:127]
	v_pk_mul_f32 v[122:123], v[122:123], v[122:123]
	v_and_b32_e32 v128, 0xffffff00, v128
	s_ashr_i32 s27, s26, 31
	v_cvt_pk_bf16_f32 v124, v126, v127
	v_cvt_pk_bf16_f32 v126, v122, v123
	v_lshl_add_u64 v[122:123], v[128:129], 0, s[26:27]
	v_lshlrev_b64 v[122:123], 14, v[122:123]
	v_lshlrev_b32_e32 v151, 7, v150
	v_lshl_add_u64 v[122:123], s[84:85], 0, v[122:123]
	v_and_b32_e32 v138, 0x2780, v151
	v_max_f32_e32 v119, v119, v119
	v_max_f32_e32 v118, v118, v118
	v_cvt_pk_bf16_f32 v127, v160, v161
	v_lshl_add_u64 v[160:161], v[122:123], 0, v[138:139]
	v_mov_b32_e32 v149, v139
	v_max_f32_e32 v119, 0, v119
	v_max_f32_e32 v118, 0, v118
	v_max_f32_e32 v115, v115, v115
	v_max_f32_e32 v114, v114, v114
	v_max_f32_e32 v117, v117, v117
	v_max_f32_e32 v116, v116, v116
	s_or_b32 s28, s26, 2
	v_lshl_add_u64 v[160:161], v[160:161], 0, v[148:149]
	v_max_f32_e32 v115, 0, v115
	v_max_f32_e32 v114, 0, v114
	v_max_f32_e32 v117, 0, v117
	v_max_f32_e32 v116, 0, v116
	v_pk_mul_f32 v[118:119], v[118:119], v[118:119]
	s_ashr_i32 s29, s28, 31
	global_store_dwordx4 v[160:161], v[124:127], off sc1
	v_max_f32_e32 v121, v121, v121
	v_max_f32_e32 v120, v120, v120
	v_pk_mul_f32 v[124:125], v[116:117], v[116:117]
	v_pk_mul_f32 v[116:117], v[114:115], v[114:115]
	v_cvt_pk_bf16_f32 v114, v118, v119
	v_lshl_add_u64 v[118:119], v[128:129], 0, s[28:29]
	v_max_f32_e32 v121, 0, v121
	v_max_f32_e32 v120, 0, v120
	v_lshlrev_b64 v[118:119], 14, v[118:119]
	v_pk_mul_f32 v[120:121], v[120:121], v[120:121]
	v_lshl_add_u64 v[118:119], s[84:85], 0, v[118:119]
	v_max_f32_e32 v111, v111, v111
	v_max_f32_e32 v110, v110, v110
	v_cvt_pk_bf16_f32 v115, v120, v121
	v_lshl_add_u64 v[120:121], v[118:119], 0, v[138:139]
	v_max_f32_e32 v111, 0, v111
	v_max_f32_e32 v110, 0, v110
	v_max_f32_e32 v113, v113, v113
	v_max_f32_e32 v112, v112, v112
	v_max_f32_e32 v107, v107, v107
	v_max_f32_e32 v106, v106, v106
	v_max_f32_e32 v109, v109, v109
	v_max_f32_e32 v108, v108, v108
	v_cvt_pk_bf16_f32 v116, v116, v117
	v_cvt_pk_bf16_f32 v117, v124, v125
	v_lshl_add_u64 v[120:121], v[120:121], 0, v[148:149]
	v_max_f32_e32 v113, 0, v113
	v_max_f32_e32 v112, 0, v112
	v_max_f32_e32 v107, 0, v107
	v_max_f32_e32 v106, 0, v106
	v_max_f32_e32 v109, 0, v109
	v_max_f32_e32 v108, 0, v108
	v_pk_mul_f32 v[110:111], v[110:111], v[110:111]
	v_bitop3_b32 v138, v151, s55, v157 bitop3:0xc8
	v_max_f32_e32 v103, v103, v103
	v_max_f32_e32 v102, v102, v102
	global_store_dwordx4 v[120:121], v[114:117], off sc1
	v_pk_mul_f32 v[112:113], v[112:113], v[112:113]
	v_max_f32_e32 v103, 0, v103
	v_pk_mul_f32 v[114:115], v[108:109], v[108:109]
	v_pk_mul_f32 v[108:109], v[106:107], v[106:107]
	v_cvt_pk_bf16_f32 v106, v110, v111
	v_lshl_add_u64 v[110:111], v[122:123], 0, v[138:139]
	v_max_f32_e32 v102, 0, v102
	v_max_f32_e32 v105, v105, v105
	v_max_f32_e32 v104, v104, v104
	v_max_f32_e32 v99, v99, v99
	v_max_f32_e32 v98, v98, v98
	v_max_f32_e32 v101, v101, v101
	v_max_f32_e32 v100, v100, v100
	v_cvt_pk_bf16_f32 v107, v112, v113
	v_cvt_pk_bf16_f32 v108, v108, v109
	v_cvt_pk_bf16_f32 v109, v114, v115
	v_lshl_add_u64 v[110:111], v[110:111], 0, v[148:149]
	v_max_f32_e32 v105, 0, v105
	v_max_f32_e32 v104, 0, v104
	v_max_f32_e32 v99, 0, v99
	v_max_f32_e32 v98, 0, v98
	v_max_f32_e32 v101, 0, v101
	v_max_f32_e32 v100, 0, v100
	v_pk_mul_f32 v[102:103], v[102:103], v[102:103]
	v_max_f32_e32 v95, v95, v95
	v_max_f32_e32 v94, v94, v94
	global_store_dwordx4 v[110:111], v[106:109], off sc1
	v_pk_mul_f32 v[104:105], v[104:105], v[104:105]
	v_max_f32_e32 v95, 0, v95
	v_pk_mul_f32 v[106:107], v[100:101], v[100:101]
	v_pk_mul_f32 v[100:101], v[98:99], v[98:99]
	v_cvt_pk_bf16_f32 v98, v102, v103
	v_lshl_add_u64 v[102:103], v[118:119], 0, v[138:139]
	v_max_f32_e32 v94, 0, v94
	v_max_f32_e32 v97, v97, v97
	v_max_f32_e32 v96, v96, v96
	v_max_f32_e32 v91, v91, v91
	v_max_f32_e32 v90, v90, v90
	v_max_f32_e32 v93, v93, v93
	v_max_f32_e32 v92, v92, v92
	v_cvt_pk_bf16_f32 v99, v104, v105
	v_cvt_pk_bf16_f32 v100, v100, v101
	v_cvt_pk_bf16_f32 v101, v106, v107
	v_lshl_add_u64 v[102:103], v[102:103], 0, v[148:149]
	v_max_f32_e32 v97, 0, v97
	v_max_f32_e32 v96, 0, v96
	v_max_f32_e32 v91, 0, v91
	v_max_f32_e32 v90, 0, v90
	v_max_f32_e32 v93, 0, v93
	v_max_f32_e32 v92, 0, v92
	v_pk_mul_f32 v[94:95], v[94:95], v[94:95]
	v_bitop3_b32 v138, v151, s55, v158 bitop3:0xc8
	v_max_f32_e32 v87, v87, v87
	v_max_f32_e32 v86, v86, v86
	global_store_dwordx4 v[102:103], v[98:101], off sc1
	v_pk_mul_f32 v[96:97], v[96:97], v[96:97]
	v_max_f32_e32 v87, 0, v87
	v_pk_mul_f32 v[98:99], v[92:93], v[92:93]
	v_pk_mul_f32 v[92:93], v[90:91], v[90:91]
	v_cvt_pk_bf16_f32 v90, v94, v95
	v_lshl_add_u64 v[94:95], v[122:123], 0, v[138:139]
	v_max_f32_e32 v86, 0, v86
	v_max_f32_e32 v89, v89, v89
	v_max_f32_e32 v88, v88, v88
	v_max_f32_e32 v83, v83, v83
	v_max_f32_e32 v82, v82, v82
	v_max_f32_e32 v85, v85, v85
	v_max_f32_e32 v84, v84, v84
	v_cvt_pk_bf16_f32 v91, v96, v97
	v_cvt_pk_bf16_f32 v92, v92, v93
	v_cvt_pk_bf16_f32 v93, v98, v99
	v_lshl_add_u64 v[94:95], v[94:95], 0, v[148:149]
	v_max_f32_e32 v89, 0, v89
	v_max_f32_e32 v88, 0, v88
	v_max_f32_e32 v83, 0, v83
	v_max_f32_e32 v82, 0, v82
	v_max_f32_e32 v85, 0, v85
	v_max_f32_e32 v84, 0, v84
	v_pk_mul_f32 v[86:87], v[86:87], v[86:87]
	v_max_f32_e32 v79, v79, v79
	v_max_f32_e32 v78, v78, v78
	global_store_dwordx4 v[94:95], v[90:93], off sc1
	v_pk_mul_f32 v[88:89], v[88:89], v[88:89]
	v_max_f32_e32 v79, 0, v79
	v_pk_mul_f32 v[90:91], v[84:85], v[84:85]
	v_pk_mul_f32 v[84:85], v[82:83], v[82:83]
	v_cvt_pk_bf16_f32 v82, v86, v87
	v_lshl_add_u64 v[86:87], v[118:119], 0, v[138:139]
	v_max_f32_e32 v78, 0, v78
	v_max_f32_e32 v81, v81, v81
	v_max_f32_e32 v80, v80, v80
	v_max_f32_e32 v75, v75, v75
	v_max_f32_e32 v74, v74, v74
	v_max_f32_e32 v77, v77, v77
	v_max_f32_e32 v76, v76, v76
	v_cvt_pk_bf16_f32 v83, v88, v89
	v_cvt_pk_bf16_f32 v84, v84, v85
	v_cvt_pk_bf16_f32 v85, v90, v91
	v_lshl_add_u64 v[86:87], v[86:87], 0, v[148:149]
	v_max_f32_e32 v81, 0, v81
	v_max_f32_e32 v80, 0, v80
	v_max_f32_e32 v75, 0, v75
	v_max_f32_e32 v74, 0, v74
	v_max_f32_e32 v77, 0, v77
	v_max_f32_e32 v76, 0, v76
	v_pk_mul_f32 v[78:79], v[78:79], v[78:79]
	v_bitop3_b32 v138, v151, s55, v159 bitop3:0xc8
	v_max_f32_e32 v71, v71, v71
	v_max_f32_e32 v70, v70, v70
	global_store_dwordx4 v[86:87], v[82:85], off sc1
	v_pk_mul_f32 v[80:81], v[80:81], v[80:81]
	v_max_f32_e32 v71, 0, v71
	v_pk_mul_f32 v[82:83], v[76:77], v[76:77]
	v_pk_mul_f32 v[76:77], v[74:75], v[74:75]
	v_cvt_pk_bf16_f32 v74, v78, v79
	v_lshl_add_u64 v[78:79], v[122:123], 0, v[138:139]
	v_max_f32_e32 v70, 0, v70
	v_max_f32_e32 v73, v73, v73
	v_max_f32_e32 v72, v72, v72
	v_max_f32_e32 v67, v67, v67
	v_max_f32_e32 v66, v66, v66
	v_max_f32_e32 v69, v69, v69
	v_max_f32_e32 v68, v68, v68
	v_cvt_pk_bf16_f32 v75, v80, v81
	v_cvt_pk_bf16_f32 v76, v76, v77
	v_cvt_pk_bf16_f32 v77, v82, v83
	v_lshl_add_u64 v[78:79], v[78:79], 0, v[148:149]
	v_max_f32_e32 v73, 0, v73
	v_max_f32_e32 v72, 0, v72
	v_max_f32_e32 v67, 0, v67
	v_max_f32_e32 v66, 0, v66
	v_max_f32_e32 v69, 0, v69
	v_max_f32_e32 v68, 0, v68
	v_pk_mul_f32 v[70:71], v[70:71], v[70:71]
	global_store_dwordx4 v[78:79], v[74:77], off sc1
	v_pk_mul_f32 v[72:73], v[72:73], v[72:73]
	v_max_f32_e32 v63, v63, v63
	v_pk_mul_f32 v[74:75], v[68:69], v[68:69]
	v_pk_mul_f32 v[68:69], v[66:67], v[66:67]
	v_cvt_pk_bf16_f32 v66, v70, v71
	v_lshl_add_u64 v[70:71], v[118:119], 0, v[138:139]
	v_cvt_pk_bf16_f32 v67, v72, v73
	v_cvt_pk_bf16_f32 v68, v68, v69
	v_cvt_pk_bf16_f32 v69, v74, v75
	v_lshl_add_u64 v[70:71], v[70:71], 0, v[148:149]
	v_max_f32_e32 v62, v62, v62
	global_store_dwordx4 v[70:71], v[66:69], off sc1
	v_max_f32_e32 v63, 0, v63
	v_max_f32_e32 v62, 0, v62
	v_add_u32_e32 v66, 0x80, v150
	v_max_f32_e32 v59, v59, v59
	v_max_f32_e32 v58, v58, v58
	v_max_f32_e32 v61, v61, v61
	v_max_f32_e32 v60, v60, v60
	v_ashrrev_i32_e32 v67, 31, v66
	v_max_f32_e32 v65, v65, v65
	v_max_f32_e32 v64, v64, v64
	v_max_f32_e32 v59, 0, v59
	v_max_f32_e32 v58, 0, v58
	v_max_f32_e32 v61, 0, v61
	v_max_f32_e32 v60, 0, v60
	v_pk_mul_f32 v[62:63], v[62:63], v[62:63]
	v_max_f32_e32 v65, 0, v65
	v_max_f32_e32 v64, 0, v64
	v_pk_mul_f32 v[68:69], v[60:61], v[60:61]
	v_pk_mul_f32 v[60:61], v[58:59], v[58:59]
	v_cvt_pk_bf16_f32 v58, v62, v63
	v_lshlrev_b64 v[62:63], 1, v[66:67]
	v_pk_mul_f32 v[64:65], v[64:65], v[64:65]
	v_and_b32_e32 v62, 0xffffff00, v62
	v_cvt_pk_bf16_f32 v59, v64, v65
	v_lshl_add_u64 v[64:65], v[62:63], 0, s[26:27]
	v_lshlrev_b64 v[64:65], 14, v[64:65]
	v_lshlrev_b32_e32 v66, 7, v66
	v_lshl_add_u64 v[64:65], s[84:85], 0, v[64:65]
	v_and_b32_e32 v138, 0x3f80, v66
	v_max_f32_e32 v55, v55, v55
	v_max_f32_e32 v54, v54, v54
	v_lshl_add_u64 v[64:65], v[64:65], 0, v[138:139]
	v_max_f32_e32 v55, 0, v55
	v_max_f32_e32 v54, 0, v54
	v_max_f32_e32 v51, v51, v51
	v_max_f32_e32 v50, v50, v50
	v_max_f32_e32 v53, v53, v53
	v_max_f32_e32 v52, v52, v52
	v_cvt_pk_bf16_f32 v60, v60, v61
	v_cvt_pk_bf16_f32 v61, v68, v69
	v_lshl_add_u64 v[64:65], v[64:65], 0, v[148:149]
	v_max_f32_e32 v51, 0, v51
	v_max_f32_e32 v50, 0, v50
	v_max_f32_e32 v53, 0, v53
	v_max_f32_e32 v52, 0, v52
	v_pk_mul_f32 v[54:55], v[54:55], v[54:55]
	global_store_dwordx4 v[64:65], v[58:61], off sc1
	v_max_f32_e32 v57, v57, v57
	v_max_f32_e32 v56, v56, v56
	v_pk_mul_f32 v[58:59], v[52:53], v[52:53]
	v_pk_mul_f32 v[52:53], v[50:51], v[50:51]
	v_cvt_pk_bf16_f32 v50, v54, v55
	v_lshl_add_u64 v[54:55], v[62:63], 0, s[28:29]
	v_lshlrev_b64 v[54:55], 14, v[54:55]
	v_max_f32_e32 v57, 0, v57
	v_max_f32_e32 v56, 0, v56
	v_lshl_add_u64 v[54:55], s[84:85], 0, v[54:55]
	v_pk_mul_f32 v[56:57], v[56:57], v[56:57]
	v_lshl_add_u64 v[54:55], v[54:55], 0, v[138:139]
	v_cvt_pk_bf16_f32 v51, v56, v57
	v_cvt_pk_bf16_f32 v52, v52, v53
	v_cvt_pk_bf16_f32 v53, v58, v59
	v_lshl_add_u64 v[54:55], v[54:55], 0, v[148:149]
	v_max_f32_e32 v47, v47, v47
	v_max_f32_e32 v46, v46, v46
	global_store_dwordx4 v[54:55], v[50:53], off sc1
	v_max_f32_e32 v47, 0, v47
	v_max_f32_e32 v46, 0, v46
	v_add_u32_e32 v50, 0x90, v150
	v_max_f32_e32 v43, v43, v43
	v_max_f32_e32 v42, v42, v42
	v_max_f32_e32 v45, v45, v45
	v_max_f32_e32 v44, v44, v44
	v_ashrrev_i32_e32 v51, 31, v50
	v_max_f32_e32 v49, v49, v49
	v_max_f32_e32 v48, v48, v48
	v_max_f32_e32 v43, 0, v43
	v_max_f32_e32 v42, 0, v42
	v_max_f32_e32 v45, 0, v45
	v_max_f32_e32 v44, 0, v44
	v_pk_mul_f32 v[46:47], v[46:47], v[46:47]
	v_max_f32_e32 v49, 0, v49
	v_max_f32_e32 v48, 0, v48
	v_pk_mul_f32 v[52:53], v[44:45], v[44:45]
	v_pk_mul_f32 v[44:45], v[42:43], v[42:43]
	v_cvt_pk_bf16_f32 v42, v46, v47
	v_lshlrev_b64 v[46:47], 1, v[50:51]
	v_pk_mul_f32 v[48:49], v[48:49], v[48:49]
	v_and_b32_e32 v46, 0xffffff00, v46
	v_cvt_pk_bf16_f32 v43, v48, v49
	v_lshl_add_u64 v[48:49], v[46:47], 0, s[26:27]
	v_lshlrev_b64 v[48:49], 14, v[48:49]
	v_lshlrev_b32_e32 v50, 7, v50
	v_lshl_add_u64 v[48:49], s[84:85], 0, v[48:49]
	v_and_b32_e32 v138, 0x3f80, v50
	v_max_f32_e32 v39, v39, v39
	v_max_f32_e32 v38, v38, v38
	v_lshl_add_u64 v[48:49], v[48:49], 0, v[138:139]
	v_max_f32_e32 v39, 0, v39
	v_max_f32_e32 v38, 0, v38
	v_max_f32_e32 v35, v35, v35
	v_max_f32_e32 v34, v34, v34
	v_max_f32_e32 v37, v37, v37
	v_max_f32_e32 v36, v36, v36
	v_cvt_pk_bf16_f32 v44, v44, v45
	v_cvt_pk_bf16_f32 v45, v52, v53
	v_lshl_add_u64 v[48:49], v[48:49], 0, v[148:149]
	v_max_f32_e32 v35, 0, v35
	v_max_f32_e32 v34, 0, v34
	v_max_f32_e32 v37, 0, v37
	v_max_f32_e32 v36, 0, v36
	v_pk_mul_f32 v[38:39], v[38:39], v[38:39]
	global_store_dwordx4 v[48:49], v[42:45], off sc1
	v_max_f32_e32 v41, v41, v41
	v_max_f32_e32 v40, v40, v40
	v_pk_mul_f32 v[42:43], v[36:37], v[36:37]
	v_pk_mul_f32 v[36:37], v[34:35], v[34:35]
	v_cvt_pk_bf16_f32 v34, v38, v39
	v_lshl_add_u64 v[38:39], v[46:47], 0, s[28:29]
	v_lshlrev_b64 v[38:39], 14, v[38:39]
	v_max_f32_e32 v41, 0, v41
	v_max_f32_e32 v40, 0, v40
	v_lshl_add_u64 v[38:39], s[84:85], 0, v[38:39]
	v_pk_mul_f32 v[40:41], v[40:41], v[40:41]
	v_lshl_add_u64 v[38:39], v[38:39], 0, v[138:139]
	v_cvt_pk_bf16_f32 v35, v40, v41
	v_cvt_pk_bf16_f32 v36, v36, v37
	v_cvt_pk_bf16_f32 v37, v42, v43
	v_lshl_add_u64 v[38:39], v[38:39], 0, v[148:149]
	v_max_f32_e32 v31, v31, v31
	v_max_f32_e32 v30, v30, v30
	global_store_dwordx4 v[38:39], v[34:37], off sc1
	v_max_f32_e32 v31, 0, v31
	v_max_f32_e32 v30, 0, v30
	v_add_u32_e32 v34, 0xa0, v150
	v_max_f32_e32 v27, v27, v27
	v_max_f32_e32 v26, v26, v26
	v_max_f32_e32 v29, v29, v29
	v_max_f32_e32 v28, v28, v28
	v_ashrrev_i32_e32 v35, 31, v34
	v_max_f32_e32 v33, v33, v33
	v_max_f32_e32 v32, v32, v32
	v_max_f32_e32 v27, 0, v27
	v_max_f32_e32 v26, 0, v26
	v_max_f32_e32 v29, 0, v29
	v_max_f32_e32 v28, 0, v28
	v_pk_mul_f32 v[30:31], v[30:31], v[30:31]
	v_max_f32_e32 v33, 0, v33
	v_max_f32_e32 v32, 0, v32
	v_pk_mul_f32 v[36:37], v[28:29], v[28:29]
	v_pk_mul_f32 v[28:29], v[26:27], v[26:27]
	v_cvt_pk_bf16_f32 v26, v30, v31
	v_lshlrev_b64 v[30:31], 1, v[34:35]
	v_pk_mul_f32 v[32:33], v[32:33], v[32:33]
	v_and_b32_e32 v30, 0xffffff00, v30
	v_cvt_pk_bf16_f32 v27, v32, v33
	v_lshl_add_u64 v[32:33], v[30:31], 0, s[26:27]
	v_lshlrev_b64 v[32:33], 14, v[32:33]
	v_lshlrev_b32_e32 v34, 7, v34
	v_lshl_add_u64 v[32:33], s[84:85], 0, v[32:33]
	v_and_b32_e32 v138, 0x3f80, v34
	v_max_f32_e32 v23, v23, v23
	v_max_f32_e32 v22, v22, v22
	v_lshl_add_u64 v[32:33], v[32:33], 0, v[138:139]
	v_max_f32_e32 v23, 0, v23
	v_max_f32_e32 v22, 0, v22
	v_max_f32_e32 v19, v19, v19
	v_max_f32_e32 v18, v18, v18
	v_max_f32_e32 v21, v21, v21
	v_max_f32_e32 v20, v20, v20
	v_cvt_pk_bf16_f32 v28, v28, v29
	v_cvt_pk_bf16_f32 v29, v36, v37
	v_lshl_add_u64 v[32:33], v[32:33], 0, v[148:149]
	v_max_f32_e32 v19, 0, v19
	v_max_f32_e32 v18, 0, v18
	v_max_f32_e32 v21, 0, v21
	v_max_f32_e32 v20, 0, v20
	v_pk_mul_f32 v[22:23], v[22:23], v[22:23]
	global_store_dwordx4 v[32:33], v[26:29], off sc1
	v_max_f32_e32 v25, v25, v25
	v_max_f32_e32 v24, v24, v24
	v_pk_mul_f32 v[26:27], v[20:21], v[20:21]
	v_pk_mul_f32 v[20:21], v[18:19], v[18:19]
	v_cvt_pk_bf16_f32 v18, v22, v23
	v_lshl_add_u64 v[22:23], v[30:31], 0, s[28:29]
	v_lshlrev_b64 v[22:23], 14, v[22:23]
	v_max_f32_e32 v25, 0, v25
	v_max_f32_e32 v24, 0, v24
	v_lshl_add_u64 v[22:23], s[84:85], 0, v[22:23]
	v_pk_mul_f32 v[24:25], v[24:25], v[24:25]
	v_lshl_add_u64 v[22:23], v[22:23], 0, v[138:139]
	v_cvt_pk_bf16_f32 v19, v24, v25
	v_cvt_pk_bf16_f32 v20, v20, v21
	v_cvt_pk_bf16_f32 v21, v26, v27
	v_lshl_add_u64 v[22:23], v[22:23], 0, v[148:149]
	v_max_f32_e32 v15, v15, v15
	v_max_f32_e32 v14, v14, v14
	global_store_dwordx4 v[22:23], v[18:21], off sc1
	v_max_f32_e32 v15, 0, v15
	v_max_f32_e32 v14, 0, v14
	v_add_u32_e32 v18, 0xb0, v150
	v_max_f32_e32 v11, v11, v11
	v_max_f32_e32 v10, v10, v10
	v_max_f32_e32 v13, v13, v13
	v_max_f32_e32 v12, v12, v12
	v_ashrrev_i32_e32 v19, 31, v18
	v_max_f32_e32 v17, v17, v17
	v_max_f32_e32 v16, v16, v16
	v_max_f32_e32 v11, 0, v11
	v_max_f32_e32 v10, 0, v10
	v_max_f32_e32 v13, 0, v13
	v_max_f32_e32 v12, 0, v12
	v_pk_mul_f32 v[14:15], v[14:15], v[14:15]
	v_max_f32_e32 v17, 0, v17
	v_max_f32_e32 v16, 0, v16
	v_pk_mul_f32 v[20:21], v[12:13], v[12:13]
	v_pk_mul_f32 v[12:13], v[10:11], v[10:11]
	v_cvt_pk_bf16_f32 v10, v14, v15
	v_lshlrev_b64 v[14:15], 1, v[18:19]
	v_pk_mul_f32 v[16:17], v[16:17], v[16:17]
	v_and_b32_e32 v14, 0xffffff00, v14
	v_cvt_pk_bf16_f32 v11, v16, v17
	v_lshl_add_u64 v[16:17], v[14:15], 0, s[26:27]
	v_lshlrev_b64 v[16:17], 14, v[16:17]
	v_lshlrev_b32_e32 v18, 7, v18
	v_lshl_add_u64 v[16:17], s[84:85], 0, v[16:17]
	v_and_b32_e32 v138, 0x3f80, v18
	v_max_f32_e32 v7, v7, v7
	v_max_f32_e32 v6, v6, v6
	v_lshl_add_u64 v[16:17], v[16:17], 0, v[138:139]
	v_max_f32_e32 v7, 0, v7
	v_max_f32_e32 v6, 0, v6
	v_max_f32_e32 v3, v3, v3
	v_max_f32_e32 v2, v2, v2
	v_max_f32_e32 v5, v5, v5
	v_max_f32_e32 v4, v4, v4
	v_cvt_pk_bf16_f32 v12, v12, v13
	v_cvt_pk_bf16_f32 v13, v20, v21
	v_lshl_add_u64 v[16:17], v[16:17], 0, v[148:149]
	v_max_f32_e32 v3, 0, v3
	v_max_f32_e32 v2, 0, v2
	v_max_f32_e32 v5, 0, v5
	v_max_f32_e32 v4, 0, v4
	v_pk_mul_f32 v[6:7], v[6:7], v[6:7]
	global_store_dwordx4 v[16:17], v[10:13], off sc1
	v_max_f32_e32 v9, v9, v9
	v_max_f32_e32 v8, v8, v8
	v_pk_mul_f32 v[10:11], v[4:5], v[4:5]
	v_pk_mul_f32 v[4:5], v[2:3], v[2:3]
	v_cvt_pk_bf16_f32 v2, v6, v7
	v_lshl_add_u64 v[6:7], v[14:15], 0, s[28:29]
	v_lshlrev_b64 v[6:7], 14, v[6:7]
	v_max_f32_e32 v9, 0, v9
	v_max_f32_e32 v8, 0, v8
	v_lshl_add_u64 v[6:7], s[84:85], 0, v[6:7]
	v_pk_mul_f32 v[8:9], v[8:9], v[8:9]
	v_lshl_add_u64 v[6:7], v[6:7], 0, v[138:139]
	v_cvt_pk_bf16_f32 v3, v8, v9
	v_cvt_pk_bf16_f32 v4, v4, v5
	v_cvt_pk_bf16_f32 v5, v10, v11
	v_lshl_add_u64 v[6:7], v[6:7], 0, v[148:149]
	s_andn2_b64 vcc, exec, s[4:5]
	s_mov_b64 s[4:5], -1
	global_store_dwordx4 v[6:7], v[2:5], off sc1
	s_branch .Lwtp12_join

.LBB0_1295:
	s_and_b64 vcc, exec, s[6:7]
	s_cbranch_vccz .Lwtp13_entry
	s_lshl_b32 s14, s36, 8
	v_lshl_add_u32 v178, s38, 8, v202
	s_or_b32 s14, s14, s59
	v_ashrrev_i32_e32 v179, 31, v178
	s_ashr_i32 s38, s14, 6
	v_lshrrev_b64 v[130:131], 1, v[178:179]
	s_or_b32 s40, s38, 2
	s_ashr_i32 s39, s38, 31
	v_and_b32_e32 v131, 0x7fffffff, v131
	v_and_b32_e32 v130, 0xffffffc0, v130
	v_lshlrev_b32_e32 v132, 7, v178
	s_ashr_i32 s41, s40, 31
	v_and_b32_e32 v220, 0x2780, v132
	v_mov_b32_e32 v221, v163
	v_lshl_add_u64 v[134:135], v[130:131], 0, s[38:39]
	v_lshl_add_u64 v[130:131], v[130:131], 0, s[40:41]
	v_lshl_add_u64 v[132:133], v[164:165], 0, v[220:221]
	v_lshlrev_b64 v[222:223], 14, v[134:135]
	v_lshlrev_b64 v[224:225], 14, v[130:131]
	v_lshl_add_u64 v[134:135], v[132:133], 0, v[222:223]
	v_lshl_add_u64 v[130:131], v[132:133], 0, v[224:225]
	global_load_dwordx4 v[212:215], v[134:135], off
	v_lshl_add_u64 v[176:177], v[178:179], 2, s[20:21]
	global_load_dwordx4 v[216:219], v[130:131], off
	global_load_dword v175, v[176:177], off
	v_or_b32_e32 v196, 16, v178
	v_or_b32_e32 v186, 32, v178
	v_ashrrev_i32_e32 v197, 31, v196
	v_ashrrev_i32_e32 v187, 31, v186
	v_or_b32_e32 v180, 48, v178
	v_lshl_add_u64 v[130:131], v[196:197], 2, s[20:21]
	v_lshl_add_u64 v[132:133], v[186:187], 2, s[20:21]
	v_ashrrev_i32_e32 v181, 31, v180
	v_lshl_add_u64 v[134:135], v[180:181], 2, s[20:21]
	global_load_dword v211, v[130:131], off
	global_load_dword v210, v[132:133], off
	global_load_dword v209, v[134:135], off
	v_lshrrev_b64 v[130:131], 1, v[196:197]
	v_lshlrev_b32_e32 v132, 6, v196
	v_and_b32_e32 v131, 0x7fffffff, v131
	v_and_b32_e32 v130, 0xffffffc0, v130
	v_and_b32_e32 v132, 0x1fc0, v132
	v_lshlrev_b32_e32 v162, 1, v132
	v_lshl_add_u64 v[134:135], v[130:131], 0, s[38:39]
	v_lshl_add_u64 v[130:131], v[130:131], 0, s[40:41]
	v_lshl_add_u64 v[132:133], v[164:165], 0, v[162:163]
	v_lshlrev_b64 v[200:201], 14, v[134:135]
	v_lshlrev_b64 v[198:199], 14, v[130:131]
	v_lshl_add_u64 v[134:135], v[132:133], 0, v[200:201]
	v_lshl_add_u64 v[130:131], v[132:133], 0, v[198:199]
	global_load_dwordx4 v[150:153], v[134:135], off
	global_load_dwordx4 v[146:149], v[130:131], off
	v_lshrrev_b64 v[130:131], 1, v[186:187]
	v_lshlrev_b32_e32 v132, 6, v186
	v_and_b32_e32 v131, 0x7fffffff, v131
	v_and_b32_e32 v130, 0xffffffc0, v130
	v_and_b32_e32 v132, 0x1fc0, v132
	v_lshlrev_b32_e32 v190, 1, v132
	v_mov_b32_e32 v191, v163
	v_lshl_add_u64 v[134:135], v[130:131], 0, s[38:39]
	v_lshl_add_u64 v[130:131], v[130:131], 0, s[40:41]
	v_lshl_add_u64 v[132:133], v[164:165], 0, v[190:191]
	v_lshlrev_b64 v[194:195], 14, v[134:135]
	v_lshlrev_b64 v[192:193], 14, v[130:131]
	v_lshl_add_u64 v[134:135], v[132:133], 0, v[194:195]
	v_lshl_add_u64 v[130:131], v[132:133], 0, v[192:193]
	global_load_dwordx4 v[142:145], v[134:135], off
	global_load_dwordx4 v[138:141], v[130:131], off
	v_lshrrev_b64 v[130:131], 1, v[180:181]
	v_lshlrev_b32_e32 v132, 6, v180
	v_and_b32_e32 v131, 0x7fffffff, v131
	v_and_b32_e32 v130, 0xffffffc0, v130
	v_and_b32_e32 v132, 0x1fc0, v132
	v_lshlrev_b32_e32 v182, 1, v132
	v_mov_b32_e32 v183, v163
	v_lshl_add_u64 v[134:135], v[130:131], 0, s[38:39]
	v_lshl_add_u64 v[130:131], v[130:131], 0, s[40:41]
	v_lshl_add_u64 v[132:133], v[164:165], 0, v[182:183]
	v_lshlrev_b64 v[188:189], 14, v[134:135]
	v_lshlrev_b64 v[184:185], 14, v[130:131]
	v_lshl_add_u64 v[134:135], v[132:133], 0, v[188:189]
	v_lshl_add_u64 v[130:131], v[132:133], 0, v[184:185]
	global_load_dwordx4 v[134:137], v[134:135], off
	s_nop 0
	global_load_dwordx4 v[130:133], v[130:131], off
	v_lshl_add_u64 v[222:223], s[0:1], 0, v[222:223]
	v_lshl_add_u64 v[222:223], v[222:223], 0, v[220:221]
	s_lshl_b32 s36, s36, 2
	s_ashr_i32 s37, s36, 31
	s_waitcnt vmcnt(0)
	v_lshlrev_b32_e32 v226, 16, v212
	v_and_b32_e32 v227, 0xffff0000, v212
	v_lshlrev_b32_e32 v212, 16, v213
	v_and_b32_e32 v213, 0xffff0000, v213
	v_lshlrev_b32_e32 v228, 16, v214
	v_and_b32_e32 v229, 0xffff0000, v214
	v_lshlrev_b32_e32 v214, 16, v215
	v_and_b32_e32 v215, 0xffff0000, v215
	v_mul_f32_e32 v234, v175, v175
	v_pk_fma_f32 v[128:129], v[128:129], v[234:235], v[212:213] op_sel_hi:[1,0,1]
	v_pk_fma_f32 v[126:127], v[126:127], v[234:235], v[226:227] op_sel_hi:[1,0,1]
	v_pk_fma_f32 v[212:213], v[124:125], v[234:235], v[214:215] op_sel_hi:[1,0,1]
	v_pk_fma_f32 v[214:215], v[122:123], v[234:235], v[228:229] op_sel_hi:[1,0,1]
	v_mov_b32_e32 v175, v163
	v_cvt_pk_bf16_f32 v122, v126, v127
	v_cvt_pk_bf16_f32 v123, v128, v129
	v_cvt_pk_bf16_f32 v124, v214, v215
	v_cvt_pk_bf16_f32 v125, v212, v213
	v_lshl_add_u64 v[222:223], v[222:223], 0, v[174:175]
	global_store_dwordx4 v[222:223], v[122:125], off
	v_lshlrev_b32_e32 v230, 16, v216
	v_and_b32_e32 v231, 0xffff0000, v216
	v_mul_f32_e32 v122, v127, v127
	v_mul_f32_e32 v123, v129, v129
	v_fmac_f32_e32 v122, v126, v126
	v_fmac_f32_e32 v123, v128, v128
	v_add_f32_e32 v122, v122, v123
	v_mul_f32_e32 v123, v215, v215
	v_mul_f32_e32 v124, v213, v213
	v_lshlrev_b32_e32 v216, 16, v217
	v_and_b32_e32 v217, 0xffff0000, v217
	v_fmac_f32_e32 v123, v214, v214
	v_fmac_f32_e32 v124, v212, v212
	v_lshlrev_b32_e32 v232, 16, v218
	v_and_b32_e32 v233, 0xffff0000, v218
	v_lshlrev_b32_e32 v218, 16, v219
	v_and_b32_e32 v219, 0xffff0000, v219
	v_add_f32_e32 v123, v123, v124
	v_pk_fma_f32 v[120:121], v[120:121], v[234:235], v[216:217] op_sel_hi:[1,0,1]
	v_pk_fma_f32 v[118:119], v[118:119], v[234:235], v[230:231] op_sel_hi:[1,0,1]
	v_add_f32_e32 v124, v122, v123
	v_pk_fma_f32 v[122:123], v[116:117], v[234:235], v[218:219] op_sel_hi:[1,0,1]
	v_mul_f32_e32 v116, v119, v119
	v_mul_f32_e32 v117, v121, v121
	v_pk_fma_f32 v[114:115], v[114:115], v[234:235], v[232:233] op_sel_hi:[1,0,1]
	v_fmac_f32_e32 v116, v118, v118
	v_fmac_f32_e32 v117, v120, v120
	v_add_f32_e32 v116, v116, v117
	v_mul_f32_e32 v117, v115, v115
	v_mul_f32_e32 v125, v123, v123
	v_fmac_f32_e32 v117, v114, v114
	v_fmac_f32_e32 v125, v122, v122
	v_add_f32_e32 v117, v117, v125
	v_add_f32_e32 v116, v116, v117
	v_add_f32_e32 v124, v124, v116
	ds_bpermute_b32 v125, v204, v124
	v_cvt_pk_bf16_f32 v116, v118, v119
	v_cvt_pk_bf16_f32 v118, v114, v115
	v_cvt_pk_bf16_f32 v117, v120, v121
	v_lshl_add_u64 v[120:121], s[0:1], 0, v[224:225]
	s_waitcnt lgkmcnt(0)
	v_add_f32_e32 v114, v124, v125
	ds_bpermute_b32 v115, v205, v114
	v_lshl_add_u64 v[120:121], v[120:121], 0, v[220:221]
	v_cvt_pk_bf16_f32 v119, v122, v123
	v_lshl_add_u64 v[120:121], v[120:121], 0, v[174:175]
	global_store_dwordx4 v[120:121], v[116:119], off
	s_and_saveexec_b64 s[42:43], s[4:5]
	s_cbranch_execz .LBB0_1297
	v_lshlrev_b64 v[116:117], 8, v[178:179]
	v_lshl_add_u64 v[116:117], s[18:19], 0, v[116:117]
	v_lshl_add_u64 v[116:117], s[36:37], 2, v[116:117]
	s_lshl_b32 s14, s57, 2
	v_lshl_add_u64 v[116:117], v[116:117], 0, s[14:15]
	s_waitcnt lgkmcnt(0)
	v_add_f32_e32 v114, v114, v115
	global_store_dword v[116:117], v114, off

.Lwtp13_join:
	s_cbranch_vccnz .LBB0_1284
	s_andn2_b64 vcc, exec, s[22:23]
	s_cbranch_vccnz .LBB0_1283
	s_barrier
	s_branch .LBB0_1283
.Lwtp13_entry:
	s_lshl_b32 s14, s36, 8
	v_lshl_add_u32 v178, s38, 8, v202
	s_or_b32 s14, s14, s59
	v_ashrrev_i32_e32 v179, 31, v178
	s_ashr_i32 s38, s14, 6
	v_lshrrev_b64 v[130:131], 1, v[178:179]
	s_or_b32 s40, s38, 2
	s_ashr_i32 s39, s38, 31
	v_and_b32_e32 v131, 0x7fffffff, v131
	v_and_b32_e32 v130, 0xffffffc0, v130
	v_lshlrev_b32_e32 v132, 7, v178
	s_ashr_i32 s41, s40, 31
	v_and_b32_e32 v220, 0x2780, v132
	v_mov_b32_e32 v221, v163
	v_lshl_add_u64 v[134:135], v[130:131], 0, s[38:39]
	v_lshl_add_u64 v[130:131], v[130:131], 0, s[40:41]
	v_lshl_add_u64 v[132:133], v[164:165], 0, v[220:221]
	v_lshlrev_b64 v[222:223], 14, v[134:135]
	v_lshlrev_b64 v[224:225], 14, v[130:131]
	v_lshl_add_u64 v[134:135], v[132:133], 0, v[222:223]
	v_lshl_add_u64 v[130:131], v[132:133], 0, v[224:225]
	global_load_dwordx4 v[212:215], v[134:135], off
	v_lshl_add_u64 v[176:177], v[178:179], 2, s[20:21]
	global_load_dwordx4 v[216:219], v[130:131], off
	global_load_dword v175, v[176:177], off
	v_or_b32_e32 v196, 16, v178
	v_or_b32_e32 v186, 32, v178
	v_ashrrev_i32_e32 v197, 31, v196
	v_ashrrev_i32_e32 v187, 31, v186
	v_or_b32_e32 v180, 48, v178
	v_lshl_add_u64 v[130:131], v[196:197], 2, s[20:21]
	v_lshl_add_u64 v[132:133], v[186:187], 2, s[20:21]
	v_ashrrev_i32_e32 v181, 31, v180
	v_lshl_add_u64 v[134:135], v[180:181], 2, s[20:21]
	global_load_dword v211, v[130:131], off
	global_load_dword v210, v[132:133], off
	global_load_dword v209, v[134:135], off
	v_lshrrev_b64 v[130:131], 1, v[196:197]
	v_lshlrev_b32_e32 v132, 6, v196
	v_and_b32_e32 v131, 0x7fffffff, v131
	v_and_b32_e32 v130, 0xffffffc0, v130
	v_and_b32_e32 v132, 0x1fc0, v132
	v_lshlrev_b32_e32 v162, 1, v132
	v_lshl_add_u64 v[134:135], v[130:131], 0, s[38:39]
	v_lshl_add_u64 v[130:131], v[130:131], 0, s[40:41]
	v_lshl_add_u64 v[132:133], v[164:165], 0, v[162:163]
	v_lshlrev_b64 v[200:201], 14, v[134:135]
	v_lshlrev_b64 v[198:199], 14, v[130:131]
	v_lshl_add_u64 v[134:135], v[132:133], 0, v[200:201]
	v_lshl_add_u64 v[130:131], v[132:133], 0, v[198:199]
	global_load_dwordx4 v[150:153], v[134:135], off
	global_load_dwordx4 v[146:149], v[130:131], off
	v_lshrrev_b64 v[130:131], 1, v[186:187]
	v_lshlrev_b32_e32 v132, 6, v186
	v_and_b32_e32 v131, 0x7fffffff, v131
	v_and_b32_e32 v130, 0xffffffc0, v130
	v_and_b32_e32 v132, 0x1fc0, v132
	v_lshlrev_b32_e32 v190, 1, v132
	v_mov_b32_e32 v191, v163
	v_lshl_add_u64 v[134:135], v[130:131], 0, s[38:39]
	v_lshl_add_u64 v[130:131], v[130:131], 0, s[40:41]
	v_lshl_add_u64 v[132:133], v[164:165], 0, v[190:191]
	v_lshlrev_b64 v[194:195], 14, v[134:135]
	v_lshlrev_b64 v[192:193], 14, v[130:131]
	v_lshl_add_u64 v[134:135], v[132:133], 0, v[194:195]
	v_lshl_add_u64 v[130:131], v[132:133], 0, v[192:193]
	global_load_dwordx4 v[142:145], v[134:135], off
	global_load_dwordx4 v[138:141], v[130:131], off
	v_lshrrev_b64 v[130:131], 1, v[180:181]
	v_lshlrev_b32_e32 v132, 6, v180
	v_and_b32_e32 v131, 0x7fffffff, v131
	v_and_b32_e32 v130, 0xffffffc0, v130
	v_and_b32_e32 v132, 0x1fc0, v132
	v_lshlrev_b32_e32 v182, 1, v132
	v_mov_b32_e32 v183, v163
	v_lshl_add_u64 v[134:135], v[130:131], 0, s[38:39]
	v_lshl_add_u64 v[130:131], v[130:131], 0, s[40:41]
	v_lshl_add_u64 v[132:133], v[164:165], 0, v[182:183]
	v_lshlrev_b64 v[188:189], 14, v[134:135]
	v_lshlrev_b64 v[184:185], 14, v[130:131]
	v_lshl_add_u64 v[134:135], v[132:133], 0, v[188:189]
	v_lshl_add_u64 v[130:131], v[132:133], 0, v[184:185]
	global_load_dwordx4 v[134:137], v[134:135], off
	s_nop 0
	global_load_dwordx4 v[130:133], v[130:131], off
	v_lshl_add_u64 v[222:223], s[0:1], 0, v[222:223]
	v_lshl_add_u64 v[222:223], v[222:223], 0, v[220:221]
	s_lshl_b32 s36, s36, 2
	s_ashr_i32 s37, s36, 31
	s_waitcnt vmcnt(0)
	v_lshlrev_b32_e32 v226, 16, v212
	v_and_b32_e32 v227, 0xffff0000, v212
	v_lshlrev_b32_e32 v212, 16, v213
	v_and_b32_e32 v213, 0xffff0000, v213
	v_lshlrev_b32_e32 v228, 16, v214
	v_and_b32_e32 v229, 0xffff0000, v214
	v_lshlrev_b32_e32 v214, 16, v215
	v_and_b32_e32 v215, 0xffff0000, v215
	v_mul_f32_e32 v234, v175, v175
	v_pk_fma_f32 v[128:129], v[128:129], v[234:235], v[212:213] op_sel_hi:[1,0,1]
	v_pk_fma_f32 v[126:127], v[126:127], v[234:235], v[226:227] op_sel_hi:[1,0,1]
	v_pk_fma_f32 v[212:213], v[124:125], v[234:235], v[214:215] op_sel_hi:[1,0,1]
	v_pk_fma_f32 v[214:215], v[122:123], v[234:235], v[228:229] op_sel_hi:[1,0,1]
	v_mov_b32_e32 v175, v163
	v_cvt_pk_bf16_f32 v122, v126, v127
	v_cvt_pk_bf16_f32 v123, v128, v129
	v_cvt_pk_bf16_f32 v124, v214, v215
	v_cvt_pk_bf16_f32 v125, v212, v213
	v_lshl_add_u64 v[222:223], v[222:223], 0, v[174:175]
	global_store_dwordx4 v[222:223], v[122:125], off sc1
	v_lshlrev_b32_e32 v230, 16, v216
	v_and_b32_e32 v231, 0xffff0000, v216
	v_mul_f32_e32 v122, v127, v127
	v_mul_f32_e32 v123, v129, v129
	v_fmac_f32_e32 v122, v126, v126
	v_fmac_f32_e32 v123, v128, v128
	v_add_f32_e32 v122, v122, v123
	v_mul_f32_e32 v123, v215, v215
	v_mul_f32_e32 v124, v213, v213
	v_lshlrev_b32_e32 v216, 16, v217
	v_and_b32_e32 v217, 0xffff0000, v217
	v_fmac_f32_e32 v123, v214, v214
	v_fmac_f32_e32 v124, v212, v212
	v_lshlrev_b32_e32 v232, 16, v218
	v_and_b32_e32 v233, 0xffff0000, v218
	v_lshlrev_b32_e32 v218, 16, v219
	v_and_b32_e32 v219, 0xffff0000, v219
	v_add_f32_e32 v123, v123, v124
	v_pk_fma_f32 v[120:121], v[120:121], v[234:235], v[216:217] op_sel_hi:[1,0,1]
	v_pk_fma_f32 v[118:119], v[118:119], v[234:235], v[230:231] op_sel_hi:[1,0,1]
	v_add_f32_e32 v124, v122, v123
	v_pk_fma_f32 v[122:123], v[116:117], v[234:235], v[218:219] op_sel_hi:[1,0,1]
	v_mul_f32_e32 v116, v119, v119
	v_mul_f32_e32 v117, v121, v121
	v_pk_fma_f32 v[114:115], v[114:115], v[234:235], v[232:233] op_sel_hi:[1,0,1]
	v_fmac_f32_e32 v116, v118, v118
	v_fmac_f32_e32 v117, v120, v120
	v_add_f32_e32 v116, v116, v117
	v_mul_f32_e32 v117, v115, v115
	v_mul_f32_e32 v125, v123, v123
	v_fmac_f32_e32 v117, v114, v114
	v_fmac_f32_e32 v125, v122, v122
	v_add_f32_e32 v117, v117, v125
	v_add_f32_e32 v116, v116, v117
	v_add_f32_e32 v124, v124, v116
	ds_bpermute_b32 v125, v204, v124
	v_cvt_pk_bf16_f32 v116, v118, v119
	v_cvt_pk_bf16_f32 v118, v114, v115
	v_cvt_pk_bf16_f32 v117, v120, v121
	v_lshl_add_u64 v[120:121], s[0:1], 0, v[224:225]
	s_waitcnt lgkmcnt(0)
	v_add_f32_e32 v114, v124, v125
	ds_bpermute_b32 v115, v205, v114
	v_lshl_add_u64 v[120:121], v[120:121], 0, v[220:221]
	v_cvt_pk_bf16_f32 v119, v122, v123
	v_lshl_add_u64 v[120:121], v[120:121], 0, v[174:175]
	global_store_dwordx4 v[120:121], v[116:119], off sc1
	s_and_saveexec_b64 s[42:43], s[4:5]
	s_cbranch_execz .Lwtp13_0
	v_lshlrev_b64 v[116:117], 8, v[178:179]
	v_lshl_add_u64 v[116:117], s[18:19], 0, v[116:117]
	v_lshl_add_u64 v[116:117], s[36:37], 2, v[116:117]
	s_lshl_b32 s14, s57, 2
	v_lshl_add_u64 v[116:117], v[116:117], 0, s[14:15]
	s_waitcnt lgkmcnt(0)
	v_add_f32_e32 v114, v114, v115
	global_store_dword v[116:117], v114, off sc1
.Lwtp13_0:
	s_or_b64 exec, exec, s[42:43]
	v_lshlrev_b32_e32 v116, 16, v151
	v_and_b32_e32 v117, 0xffff0000, v151
	v_lshlrev_b32_e32 v118, 16, v152
	v_and_b32_e32 v119, 0xffff0000, v152
	v_lshlrev_b32_e32 v122, 16, v146
	v_and_b32_e32 v123, 0xffff0000, v146
	v_mul_f32_e32 v146, v211, v211
	v_lshlrev_b32_e32 v114, 16, v150
	s_waitcnt lgkmcnt(0)
	v_and_b32_e32 v115, 0xffff0000, v150
	v_lshlrev_b32_e32 v120, 16, v153
	v_and_b32_e32 v121, 0xffff0000, v153
	v_pk_fma_f32 v[112:113], v[112:113], v[146:147], v[116:117] op_sel_hi:[1,0,1]
	v_pk_fma_f32 v[116:117], v[106:107], v[146:147], v[118:119] op_sel_hi:[1,0,1]
	v_lshl_add_u64 v[118:119], s[0:1], 0, v[200:201]
	v_pk_fma_f32 v[110:111], v[110:111], v[146:147], v[114:115] op_sel_hi:[1,0,1]
	v_pk_fma_f32 v[114:115], v[108:109], v[146:147], v[120:121] op_sel_hi:[1,0,1]
	v_lshl_add_u64 v[118:119], v[118:119], 0, v[162:163]
	v_cvt_pk_bf16_f32 v106, v110, v111
	v_cvt_pk_bf16_f32 v107, v112, v113
	v_cvt_pk_bf16_f32 v108, v116, v117
	v_cvt_pk_bf16_f32 v109, v114, v115
	v_lshl_add_u64 v[118:119], v[118:119], 0, v[174:175]
	global_store_dwordx4 v[118:119], v[106:109], off sc1
	v_lshlrev_b32_e32 v124, 16, v147
	v_and_b32_e32 v125, 0xffff0000, v147
	v_mul_f32_e32 v106, v111, v111
	v_mul_f32_e32 v107, v113, v113
	v_fmac_f32_e32 v106, v110, v110
	v_fmac_f32_e32 v107, v112, v112
	v_add_f32_e32 v106, v106, v107
	v_mul_f32_e32 v107, v117, v117
	v_mul_f32_e32 v108, v115, v115
	v_fmac_f32_e32 v107, v116, v116
	v_fmac_f32_e32 v108, v114, v114
	v_lshlrev_b32_e32 v128, 16, v149
	v_and_b32_e32 v129, 0xffff0000, v149
	v_add_f32_e32 v107, v107, v108
	v_pk_fma_f32 v[104:105], v[104:105], v[146:147], v[124:125] op_sel_hi:[1,0,1]
	v_pk_fma_f32 v[102:103], v[102:103], v[146:147], v[122:123] op_sel_hi:[1,0,1]
	v_lshlrev_b32_e32 v126, 16, v148
	v_and_b32_e32 v127, 0xffff0000, v148
	v_add_f32_e32 v108, v106, v107
	v_pk_fma_f32 v[106:107], v[100:101], v[146:147], v[128:129] op_sel_hi:[1,0,1]
	v_mul_f32_e32 v100, v103, v103
	v_mul_f32_e32 v101, v105, v105
	v_pk_fma_f32 v[98:99], v[98:99], v[146:147], v[126:127] op_sel_hi:[1,0,1]
	v_fmac_f32_e32 v100, v102, v102
	v_fmac_f32_e32 v101, v104, v104
	v_add_f32_e32 v100, v100, v101
	v_mul_f32_e32 v101, v99, v99
	v_mul_f32_e32 v109, v107, v107
	v_fmac_f32_e32 v101, v98, v98
	v_fmac_f32_e32 v109, v106, v106
	v_add_f32_e32 v101, v101, v109
	v_add_f32_e32 v100, v100, v101
	v_add_f32_e32 v108, v108, v100
	ds_bpermute_b32 v109, v204, v108
	v_cvt_pk_bf16_f32 v100, v102, v103
	v_cvt_pk_bf16_f32 v102, v98, v99
	v_cvt_pk_bf16_f32 v101, v104, v105
	v_lshl_add_u64 v[104:105], s[0:1], 0, v[198:199]
	s_waitcnt lgkmcnt(0)
	v_add_f32_e32 v98, v108, v109
	ds_bpermute_b32 v99, v205, v98
	v_lshl_add_u64 v[104:105], v[104:105], 0, v[162:163]
	v_cvt_pk_bf16_f32 v103, v106, v107
	v_lshl_add_u64 v[104:105], v[104:105], 0, v[174:175]
	global_store_dwordx4 v[104:105], v[100:103], off sc1
	s_and_saveexec_b64 s[42:43], s[4:5]
	s_cbranch_execz .Lwtp13_1
	v_lshlrev_b64 v[100:101], 8, v[196:197]
	v_lshl_add_u64 v[100:101], s[18:19], 0, v[100:101]
	v_lshl_add_u64 v[100:101], s[36:37], 2, v[100:101]
	s_lshl_b32 s14, s57, 2
	v_lshl_add_u64 v[100:101], v[100:101], 0, s[14:15]
	s_waitcnt lgkmcnt(0)
	v_add_f32_e32 v98, v98, v99
	global_store_dword v[100:101], v98, off sc1
.Lwtp13_1:
	s_or_b64 exec, exec, s[42:43]
	v_lshlrev_b32_e32 v100, 16, v143
	v_and_b32_e32 v101, 0xffff0000, v143
	v_lshlrev_b32_e32 v102, 16, v144
	v_and_b32_e32 v103, 0xffff0000, v144
	v_mul_f32_e32 v114, v210, v210
	v_lshlrev_b32_e32 v98, 16, v142
	s_waitcnt lgkmcnt(0)
	v_and_b32_e32 v99, 0xffff0000, v142
	v_lshlrev_b32_e32 v104, 16, v145
	v_and_b32_e32 v105, 0xffff0000, v145
	v_pk_fma_f32 v[96:97], v[96:97], v[114:115], v[100:101] op_sel_hi:[1,0,1]
	v_pk_fma_f32 v[100:101], v[90:91], v[114:115], v[102:103] op_sel_hi:[1,0,1]
	v_lshl_add_u64 v[102:103], s[0:1], 0, v[194:195]
	v_mov_b32_e32 v191, v163
	v_pk_fma_f32 v[94:95], v[94:95], v[114:115], v[98:99] op_sel_hi:[1,0,1]
	v_pk_fma_f32 v[98:99], v[92:93], v[114:115], v[104:105] op_sel_hi:[1,0,1]
	v_lshl_add_u64 v[102:103], v[102:103], 0, v[190:191]
	v_mov_b32_e32 v175, v163
	v_cvt_pk_bf16_f32 v90, v94, v95
	v_cvt_pk_bf16_f32 v91, v96, v97
	v_cvt_pk_bf16_f32 v92, v100, v101
	v_cvt_pk_bf16_f32 v93, v98, v99
	v_lshl_add_u64 v[102:103], v[102:103], 0, v[174:175]
	global_store_dwordx4 v[102:103], v[90:93], off sc1
	v_lshlrev_b32_e32 v106, 16, v138
	v_and_b32_e32 v107, 0xffff0000, v138
	v_mul_f32_e32 v90, v95, v95
	v_mul_f32_e32 v91, v97, v97
	v_fmac_f32_e32 v90, v94, v94
	v_fmac_f32_e32 v91, v96, v96
	v_add_f32_e32 v90, v90, v91
	v_mul_f32_e32 v91, v101, v101
	v_mul_f32_e32 v92, v99, v99
	v_lshlrev_b32_e32 v108, 16, v139
	v_and_b32_e32 v109, 0xffff0000, v139
	v_fmac_f32_e32 v91, v100, v100
	v_fmac_f32_e32 v92, v98, v98
	v_lshlrev_b32_e32 v112, 16, v141
	v_and_b32_e32 v113, 0xffff0000, v141
	v_add_f32_e32 v91, v91, v92
	v_pk_fma_f32 v[88:89], v[88:89], v[114:115], v[108:109] op_sel_hi:[1,0,1]
	v_pk_fma_f32 v[86:87], v[86:87], v[114:115], v[106:107] op_sel_hi:[1,0,1]
	v_lshlrev_b32_e32 v110, 16, v140
	v_and_b32_e32 v111, 0xffff0000, v140
	v_add_f32_e32 v92, v90, v91
	v_pk_fma_f32 v[90:91], v[84:85], v[114:115], v[112:113] op_sel_hi:[1,0,1]
	v_mul_f32_e32 v84, v87, v87
	v_mul_f32_e32 v85, v89, v89
	v_pk_fma_f32 v[82:83], v[82:83], v[114:115], v[110:111] op_sel_hi:[1,0,1]
	v_fmac_f32_e32 v84, v86, v86
	v_fmac_f32_e32 v85, v88, v88
	v_add_f32_e32 v84, v84, v85
	v_mul_f32_e32 v85, v83, v83
	v_mul_f32_e32 v93, v91, v91
	v_fmac_f32_e32 v85, v82, v82
	v_fmac_f32_e32 v93, v90, v90
	v_add_f32_e32 v85, v85, v93
	v_add_f32_e32 v84, v84, v85
	v_add_f32_e32 v92, v92, v84
	ds_bpermute_b32 v93, v204, v92
	v_cvt_pk_bf16_f32 v84, v86, v87
	v_cvt_pk_bf16_f32 v86, v82, v83
	v_cvt_pk_bf16_f32 v85, v88, v89
	v_lshl_add_u64 v[88:89], s[0:1], 0, v[192:193]
	s_waitcnt lgkmcnt(0)
	v_add_f32_e32 v82, v92, v93
	ds_bpermute_b32 v83, v205, v82
	v_lshl_add_u64 v[88:89], v[88:89], 0, v[190:191]
	v_cvt_pk_bf16_f32 v87, v90, v91
	v_lshl_add_u64 v[88:89], v[88:89], 0, v[174:175]
	global_store_dwordx4 v[88:89], v[84:87], off sc1
	s_and_saveexec_b64 s[42:43], s[4:5]
	s_cbranch_execz .Lwtp13_2
	v_lshlrev_b64 v[84:85], 8, v[186:187]
	v_lshl_add_u64 v[84:85], s[18:19], 0, v[84:85]
	v_lshl_add_u64 v[84:85], s[36:37], 2, v[84:85]
	s_lshl_b32 s14, s57, 2
	v_lshl_add_u64 v[84:85], v[84:85], 0, s[14:15]
	s_waitcnt lgkmcnt(0)
	v_add_f32_e32 v82, v82, v83
	global_store_dword v[84:85], v82, off sc1
.Lwtp13_2:
	s_or_b64 exec, exec, s[42:43]
	v_lshlrev_b32_e32 v84, 16, v135
	v_and_b32_e32 v85, 0xffff0000, v135
	v_lshlrev_b32_e32 v86, 16, v136
	v_and_b32_e32 v87, 0xffff0000, v136
	v_mul_f32_e32 v98, v209, v209
	v_lshlrev_b32_e32 v82, 16, v134
	s_waitcnt lgkmcnt(0)
	v_and_b32_e32 v83, 0xffff0000, v134
	v_lshlrev_b32_e32 v88, 16, v137
	v_and_b32_e32 v89, 0xffff0000, v137
	v_pk_fma_f32 v[80:81], v[80:81], v[98:99], v[84:85] op_sel_hi:[1,0,1]
	v_pk_fma_f32 v[84:85], v[74:75], v[98:99], v[86:87] op_sel_hi:[1,0,1]
	v_lshl_add_u64 v[86:87], s[0:1], 0, v[188:189]
	v_mov_b32_e32 v183, v163
	v_pk_fma_f32 v[78:79], v[78:79], v[98:99], v[82:83] op_sel_hi:[1,0,1]
	v_pk_fma_f32 v[82:83], v[76:77], v[98:99], v[88:89] op_sel_hi:[1,0,1]
	v_lshl_add_u64 v[86:87], v[86:87], 0, v[182:183]
	v_cvt_pk_bf16_f32 v74, v78, v79
	v_cvt_pk_bf16_f32 v75, v80, v81
	v_cvt_pk_bf16_f32 v76, v84, v85
	v_cvt_pk_bf16_f32 v77, v82, v83
	v_lshl_add_u64 v[86:87], v[86:87], 0, v[174:175]
	global_store_dwordx4 v[86:87], v[74:77], off sc1
	v_lshlrev_b32_e32 v90, 16, v130
	v_and_b32_e32 v91, 0xffff0000, v130
	v_mul_f32_e32 v74, v79, v79
	v_mul_f32_e32 v75, v81, v81
	v_fmac_f32_e32 v74, v78, v78
	v_fmac_f32_e32 v75, v80, v80
	v_add_f32_e32 v74, v74, v75
	v_mul_f32_e32 v75, v85, v85
	v_mul_f32_e32 v76, v83, v83
	v_lshlrev_b32_e32 v92, 16, v131
	v_and_b32_e32 v93, 0xffff0000, v131
	v_fmac_f32_e32 v75, v84, v84
	v_fmac_f32_e32 v76, v82, v82
	v_lshlrev_b32_e32 v96, 16, v133
	v_and_b32_e32 v97, 0xffff0000, v133
	v_add_f32_e32 v75, v75, v76
	v_pk_fma_f32 v[72:73], v[72:73], v[98:99], v[92:93] op_sel_hi:[1,0,1]
	v_pk_fma_f32 v[70:71], v[70:71], v[98:99], v[90:91] op_sel_hi:[1,0,1]
	v_lshlrev_b32_e32 v94, 16, v132
	v_and_b32_e32 v95, 0xffff0000, v132
	v_add_f32_e32 v76, v74, v75
	v_pk_fma_f32 v[74:75], v[68:69], v[98:99], v[96:97] op_sel_hi:[1,0,1]
	v_mul_f32_e32 v68, v71, v71
	v_mul_f32_e32 v69, v73, v73
	v_pk_fma_f32 v[66:67], v[66:67], v[98:99], v[94:95] op_sel_hi:[1,0,1]
	v_fmac_f32_e32 v68, v70, v70
	v_fmac_f32_e32 v69, v72, v72
	v_add_f32_e32 v68, v68, v69
	v_mul_f32_e32 v69, v67, v67
	v_mul_f32_e32 v77, v75, v75
	v_fmac_f32_e32 v69, v66, v66
	v_fmac_f32_e32 v77, v74, v74
	v_add_f32_e32 v69, v69, v77
	v_add_f32_e32 v68, v68, v69
	v_add_f32_e32 v76, v76, v68
	ds_bpermute_b32 v77, v204, v76
	v_cvt_pk_bf16_f32 v68, v70, v71
	v_cvt_pk_bf16_f32 v70, v66, v67
	v_cvt_pk_bf16_f32 v69, v72, v73
	v_lshl_add_u64 v[72:73], s[0:1], 0, v[184:185]
	s_waitcnt lgkmcnt(0)
	v_add_f32_e32 v66, v76, v77
	ds_bpermute_b32 v67, v205, v66
	v_lshl_add_u64 v[72:73], v[72:73], 0, v[182:183]
	v_cvt_pk_bf16_f32 v71, v74, v75
	v_lshl_add_u64 v[72:73], v[72:73], 0, v[174:175]
	global_store_dwordx4 v[72:73], v[68:71], off sc1
	s_and_saveexec_b64 s[42:43], s[4:5]
	s_cbranch_execz .Lwtp13_3
	v_lshlrev_b64 v[68:69], 8, v[180:181]
	v_lshl_add_u64 v[68:69], s[18:19], 0, v[68:69]
	v_lshl_add_u64 v[68:69], s[36:37], 2, v[68:69]
	s_lshl_b32 s14, s57, 2
	v_lshl_add_u64 v[68:69], v[68:69], 0, s[14:15]
	s_waitcnt lgkmcnt(0)
	v_add_f32_e32 v66, v66, v67
	global_store_dword v[68:69], v66, off sc1
.Lwtp13_3:
	s_or_b64 exec, exec, s[42:43]
	v_add_u32_e32 v108, 0x80, v178
	v_ashrrev_i32_e32 v109, 31, v108
	s_waitcnt lgkmcnt(0)
	v_lshrrev_b64 v[66:67], 1, v[108:109]
	v_and_b32_e32 v67, 0x7fffffff, v67
	v_and_b32_e32 v66, 0xffffffc0, v66
	v_lshlrev_b32_e32 v68, 7, v108
	v_and_b32_e32 v126, 0x3f80, v68
	v_mov_b32_e32 v127, v163
	v_lshl_add_u64 v[70:71], v[66:67], 0, s[38:39]
	v_lshl_add_u64 v[68:69], v[164:165], 0, v[126:127]
	v_lshlrev_b64 v[128:129], 14, v[70:71]
	v_lshl_add_u64 v[70:71], v[68:69], 0, v[128:129]
	global_load_dwordx4 v[118:121], v[70:71], off
	global_load_dword v117, v[176:177], off offset:512
	v_lshl_add_u64 v[66:67], v[66:67], 0, s[40:41]
	v_lshlrev_b64 v[130:131], 14, v[66:67]
	v_lshl_add_u64 v[66:67], v[68:69], 0, v[130:131]
	global_load_dwordx4 v[122:125], v[66:67], off
	v_add_u32_e32 v104, 0x90, v178
	v_add_u32_e32 v96, 0xa0, v178
	v_add_u32_e32 v90, 0xb0, v178
	v_ashrrev_i32_e32 v105, 31, v104
	v_ashrrev_i32_e32 v97, 31, v96
	v_lshlrev_b32_e32 v68, 6, v104
	v_ashrrev_i32_e32 v91, 31, v90
	v_lshlrev_b32_e32 v70, 6, v96
	v_lshrrev_b64 v[66:67], 1, v[104:105]
	v_and_b32_e32 v73, 0x1fc0, v68
	v_lshrrev_b64 v[68:69], 1, v[96:97]
	v_lshlrev_b32_e32 v72, 6, v90
	v_and_b32_e32 v74, 0x1fc0, v70
	v_lshrrev_b64 v[70:71], 1, v[90:91]
	v_and_b32_e32 v67, 0x7fffffff, v67
	v_and_b32_e32 v66, 0xffffffc0, v66
	v_and_b32_e32 v69, 0x7fffffff, v69
	v_and_b32_e32 v68, 0xffffffc0, v68
	v_mov_b32_e32 v101, v163
	v_and_b32_e32 v72, 0x1fc0, v72
	v_lshlrev_b32_e32 v162, 1, v73
	v_lshlrev_b32_e32 v100, 1, v74
	v_and_b32_e32 v71, 0x7fffffff, v71
	v_and_b32_e32 v70, 0xffffffc0, v70
	v_lshl_add_u64 v[74:75], v[66:67], 0, s[38:39]
	v_lshl_add_u64 v[66:67], v[66:67], 0, s[40:41]
	v_lshl_add_u64 v[78:79], v[68:69], 0, s[38:39]
	v_lshl_add_u64 v[68:69], v[68:69], 0, s[40:41]
	v_mov_b32_e32 v93, v163
	v_lshlrev_b32_e32 v92, 1, v72
	v_lshl_add_u64 v[72:73], v[164:165], 0, v[162:163]
	v_lshl_add_u64 v[76:77], v[164:165], 0, v[100:101]
	v_lshl_add_u64 v[82:83], v[70:71], 0, s[38:39]
	v_lshl_add_u64 v[70:71], v[70:71], 0, s[40:41]
	v_lshlrev_b64 v[112:113], 14, v[74:75]
	v_lshlrev_b64 v[110:111], 14, v[66:67]
	v_lshlrev_b64 v[106:107], 14, v[78:79]
	v_lshlrev_b64 v[102:103], 14, v[68:69]
	v_lshl_add_u64 v[80:81], v[164:165], 0, v[92:93]
	v_lshlrev_b64 v[98:99], 14, v[82:83]
	v_lshlrev_b64 v[94:95], 14, v[70:71]
	v_lshl_add_u64 v[66:67], v[72:73], 0, v[112:113]
	v_lshl_add_u64 v[68:69], v[72:73], 0, v[110:111]
	v_lshl_add_u64 v[70:71], v[76:77], 0, v[106:107]
	v_lshl_add_u64 v[72:73], v[76:77], 0, v[102:103]
	global_load_dword v116, v[176:177], off offset:576
	global_load_dword v115, v[176:177], off offset:640
	global_load_dword v114, v[176:177], off offset:704
	v_lshl_add_u64 v[132:133], v[80:81], 0, v[98:99]
	v_lshl_add_u64 v[134:135], v[80:81], 0, v[94:95]
	global_load_dwordx4 v[86:89], v[66:67], off
	global_load_dwordx4 v[82:85], v[68:69], off
	global_load_dwordx4 v[78:81], v[70:71], off
	global_load_dwordx4 v[74:77], v[72:73], off
	s_nop 0
	global_load_dwordx4 v[70:73], v[132:133], off
	global_load_dwordx4 v[66:69], v[134:135], off
	v_lshl_add_u64 v[128:129], s[0:1], 0, v[128:129]
	v_lshl_add_u64 v[128:129], v[128:129], 0, v[126:127]
	v_mov_b32_e32 v175, v163
	v_lshl_add_u64 v[128:129], v[128:129], 0, v[174:175]
	s_waitcnt vmcnt(11)
	v_lshlrev_b32_e32 v132, 16, v118
	v_and_b32_e32 v133, 0xffff0000, v118
	v_lshlrev_b32_e32 v118, 16, v119
	v_and_b32_e32 v119, 0xffff0000, v119
	v_lshlrev_b32_e32 v134, 16, v120
	v_and_b32_e32 v135, 0xffff0000, v120
	v_lshlrev_b32_e32 v120, 16, v121
	v_and_b32_e32 v121, 0xffff0000, v121
	s_waitcnt vmcnt(10)
	v_mul_f32_e32 v140, v117, v117
	v_pk_fma_f32 v[64:65], v[64:65], v[140:141], v[118:119] op_sel_hi:[1,0,1]
	v_pk_fma_f32 v[62:63], v[62:63], v[140:141], v[132:133] op_sel_hi:[1,0,1]
	v_pk_fma_f32 v[118:119], v[60:61], v[140:141], v[120:121] op_sel_hi:[1,0,1]
	v_pk_fma_f32 v[120:121], v[58:59], v[140:141], v[134:135] op_sel_hi:[1,0,1]
	v_cvt_pk_bf16_f32 v58, v62, v63
	v_cvt_pk_bf16_f32 v59, v64, v65
	v_cvt_pk_bf16_f32 v60, v120, v121
	v_cvt_pk_bf16_f32 v61, v118, v119
	global_store_dwordx4 v[128:129], v[58:61], off sc1
	s_waitcnt vmcnt(10)
	v_lshlrev_b32_e32 v136, 16, v122
	v_and_b32_e32 v137, 0xffff0000, v122
	v_mul_f32_e32 v58, v63, v63
	v_mul_f32_e32 v59, v65, v65
	v_fmac_f32_e32 v58, v62, v62
	v_fmac_f32_e32 v59, v64, v64
	v_add_f32_e32 v58, v58, v59
	v_mul_f32_e32 v59, v121, v121
	v_mul_f32_e32 v60, v119, v119
	v_lshlrev_b32_e32 v122, 16, v123
	v_and_b32_e32 v123, 0xffff0000, v123
	v_fmac_f32_e32 v59, v120, v120
	v_fmac_f32_e32 v60, v118, v118
	v_lshlrev_b32_e32 v138, 16, v124
	v_and_b32_e32 v139, 0xffff0000, v124
	v_lshlrev_b32_e32 v124, 16, v125
	v_and_b32_e32 v125, 0xffff0000, v125
	v_add_f32_e32 v59, v59, v60
	v_pk_fma_f32 v[56:57], v[56:57], v[140:141], v[122:123] op_sel_hi:[1,0,1]
	v_pk_fma_f32 v[54:55], v[54:55], v[140:141], v[136:137] op_sel_hi:[1,0,1]
	v_add_f32_e32 v60, v58, v59
	v_pk_fma_f32 v[58:59], v[52:53], v[140:141], v[124:125] op_sel_hi:[1,0,1]
	v_mul_f32_e32 v52, v55, v55
	v_mul_f32_e32 v53, v57, v57
	v_pk_fma_f32 v[50:51], v[50:51], v[140:141], v[138:139] op_sel_hi:[1,0,1]
	v_fmac_f32_e32 v52, v54, v54
	v_fmac_f32_e32 v53, v56, v56
	v_add_f32_e32 v52, v52, v53
	v_mul_f32_e32 v53, v51, v51
	v_mul_f32_e32 v61, v59, v59
	v_fmac_f32_e32 v53, v50, v50
	v_fmac_f32_e32 v61, v58, v58
	v_add_f32_e32 v53, v53, v61
	v_add_f32_e32 v52, v52, v53
	v_add_f32_e32 v60, v60, v52
	ds_bpermute_b32 v61, v204, v60
	v_cvt_pk_bf16_f32 v52, v54, v55
	v_cvt_pk_bf16_f32 v54, v50, v51
	v_cvt_pk_bf16_f32 v53, v56, v57
	v_lshl_add_u64 v[56:57], s[0:1], 0, v[130:131]
	s_waitcnt lgkmcnt(0)
	v_add_f32_e32 v50, v60, v61
	ds_bpermute_b32 v51, v205, v50
	v_lshl_add_u64 v[56:57], v[56:57], 0, v[126:127]
	v_cvt_pk_bf16_f32 v55, v58, v59
	v_lshl_add_u64 v[56:57], v[56:57], 0, v[174:175]
	global_store_dwordx4 v[56:57], v[52:55], off sc1
	s_and_saveexec_b64 s[38:39], s[4:5]
	s_cbranch_execz .Lwtp13_4
	v_lshlrev_b64 v[52:53], 8, v[108:109]
	v_lshl_add_u64 v[52:53], s[18:19], 0, v[52:53]
	v_lshl_add_u64 v[52:53], s[36:37], 2, v[52:53]
	s_lshl_b32 s14, s57, 2
	v_lshl_add_u64 v[52:53], v[52:53], 0, s[14:15]
	s_waitcnt lgkmcnt(0)
	v_add_f32_e32 v50, v50, v51
	global_store_dword v[52:53], v50, off sc1
.Lwtp13_4:
	s_or_b64 exec, exec, s[38:39]
	s_waitcnt vmcnt(7)
	v_lshlrev_b32_e32 v52, 16, v87
	v_and_b32_e32 v53, 0xffff0000, v87
	v_lshlrev_b32_e32 v54, 16, v88
	v_and_b32_e32 v55, 0xffff0000, v88
	s_waitcnt vmcnt(6)
	v_lshlrev_b32_e32 v58, 16, v82
	v_and_b32_e32 v59, 0xffff0000, v82
	v_mul_f32_e32 v82, v116, v116
	v_lshlrev_b32_e32 v50, 16, v86
	s_waitcnt lgkmcnt(0)
	v_and_b32_e32 v51, 0xffff0000, v86
	v_lshlrev_b32_e32 v56, 16, v89
	v_and_b32_e32 v57, 0xffff0000, v89
	v_pk_fma_f32 v[48:49], v[48:49], v[82:83], v[52:53] op_sel_hi:[1,0,1]
	v_pk_fma_f32 v[52:53], v[42:43], v[82:83], v[54:55] op_sel_hi:[1,0,1]
	v_lshl_add_u64 v[54:55], s[0:1], 0, v[112:113]
	v_pk_fma_f32 v[46:47], v[46:47], v[82:83], v[50:51] op_sel_hi:[1,0,1]
	v_pk_fma_f32 v[50:51], v[44:45], v[82:83], v[56:57] op_sel_hi:[1,0,1]
	v_lshl_add_u64 v[54:55], v[54:55], 0, v[162:163]
	v_cvt_pk_bf16_f32 v42, v46, v47
	v_cvt_pk_bf16_f32 v43, v48, v49
	v_cvt_pk_bf16_f32 v44, v52, v53
	v_cvt_pk_bf16_f32 v45, v50, v51
	v_lshl_add_u64 v[54:55], v[54:55], 0, v[174:175]
	global_store_dwordx4 v[54:55], v[42:45], off sc1
	v_lshlrev_b32_e32 v60, 16, v83
	v_and_b32_e32 v61, 0xffff0000, v83
	v_mul_f32_e32 v42, v47, v47
	v_mul_f32_e32 v43, v49, v49
	v_fmac_f32_e32 v42, v46, v46
	v_fmac_f32_e32 v43, v48, v48
	v_add_f32_e32 v42, v42, v43
	v_mul_f32_e32 v43, v53, v53
	v_mul_f32_e32 v44, v51, v51
	v_fmac_f32_e32 v43, v52, v52
	v_fmac_f32_e32 v44, v50, v50
	v_lshlrev_b32_e32 v64, 16, v85
	v_and_b32_e32 v65, 0xffff0000, v85
	v_add_f32_e32 v43, v43, v44
	v_pk_fma_f32 v[40:41], v[40:41], v[82:83], v[60:61] op_sel_hi:[1,0,1]
	v_pk_fma_f32 v[38:39], v[38:39], v[82:83], v[58:59] op_sel_hi:[1,0,1]
	v_lshlrev_b32_e32 v62, 16, v84
	v_and_b32_e32 v63, 0xffff0000, v84
	v_add_f32_e32 v44, v42, v43
	v_pk_fma_f32 v[42:43], v[36:37], v[82:83], v[64:65] op_sel_hi:[1,0,1]
	v_mul_f32_e32 v36, v39, v39
	v_mul_f32_e32 v37, v41, v41
	v_pk_fma_f32 v[34:35], v[34:35], v[82:83], v[62:63] op_sel_hi:[1,0,1]
	v_fmac_f32_e32 v36, v38, v38
	v_fmac_f32_e32 v37, v40, v40
	v_add_f32_e32 v36, v36, v37
	v_mul_f32_e32 v37, v35, v35
	v_mul_f32_e32 v45, v43, v43
	v_fmac_f32_e32 v37, v34, v34
	v_fmac_f32_e32 v45, v42, v42
	v_add_f32_e32 v37, v37, v45
	v_add_f32_e32 v36, v36, v37
	v_add_f32_e32 v44, v44, v36
	ds_bpermute_b32 v45, v204, v44
	v_cvt_pk_bf16_f32 v36, v38, v39
	v_cvt_pk_bf16_f32 v38, v34, v35
	v_cvt_pk_bf16_f32 v37, v40, v41
	v_lshl_add_u64 v[40:41], s[0:1], 0, v[110:111]
	s_waitcnt lgkmcnt(0)
	v_add_f32_e32 v34, v44, v45
	ds_bpermute_b32 v35, v205, v34
	v_lshl_add_u64 v[40:41], v[40:41], 0, v[162:163]
	v_cvt_pk_bf16_f32 v39, v42, v43
	v_lshl_add_u64 v[40:41], v[40:41], 0, v[174:175]
	global_store_dwordx4 v[40:41], v[36:39], off sc1
	s_and_saveexec_b64 s[38:39], s[4:5]
	s_cbranch_execz .Lwtp13_5
	v_lshlrev_b64 v[36:37], 8, v[104:105]
	v_lshl_add_u64 v[36:37], s[18:19], 0, v[36:37]
	v_lshl_add_u64 v[36:37], s[36:37], 2, v[36:37]
	s_lshl_b32 s14, s57, 2
	v_lshl_add_u64 v[36:37], v[36:37], 0, s[14:15]
	s_waitcnt lgkmcnt(0)
	v_add_f32_e32 v34, v34, v35
	global_store_dword v[36:37], v34, off sc1
.Lwtp13_5:
	s_or_b64 exec, exec, s[38:39]
	s_waitcnt vmcnt(7)
	v_lshlrev_b32_e32 v36, 16, v79
	v_and_b32_e32 v37, 0xffff0000, v79
	v_lshlrev_b32_e32 v38, 16, v80
	v_and_b32_e32 v39, 0xffff0000, v80
	v_mul_f32_e32 v50, v115, v115
	v_lshlrev_b32_e32 v34, 16, v78
	s_waitcnt lgkmcnt(0)
	v_and_b32_e32 v35, 0xffff0000, v78
	v_lshlrev_b32_e32 v40, 16, v81
	v_and_b32_e32 v41, 0xffff0000, v81
	v_pk_fma_f32 v[32:33], v[32:33], v[50:51], v[36:37] op_sel_hi:[1,0,1]
	v_pk_fma_f32 v[36:37], v[26:27], v[50:51], v[38:39] op_sel_hi:[1,0,1]
	v_lshl_add_u64 v[38:39], s[0:1], 0, v[106:107]
	v_mov_b32_e32 v101, v163
	v_pk_fma_f32 v[30:31], v[30:31], v[50:51], v[34:35] op_sel_hi:[1,0,1]
	v_pk_fma_f32 v[34:35], v[28:29], v[50:51], v[40:41] op_sel_hi:[1,0,1]
	v_lshl_add_u64 v[38:39], v[38:39], 0, v[100:101]
	v_mov_b32_e32 v175, v163
	v_cvt_pk_bf16_f32 v26, v30, v31
	v_cvt_pk_bf16_f32 v27, v32, v33
	v_cvt_pk_bf16_f32 v28, v36, v37
	v_cvt_pk_bf16_f32 v29, v34, v35
	v_lshl_add_u64 v[38:39], v[38:39], 0, v[174:175]
	global_store_dwordx4 v[38:39], v[26:29], off sc1
	s_waitcnt vmcnt(7)
	v_lshlrev_b32_e32 v42, 16, v74
	v_and_b32_e32 v43, 0xffff0000, v74
	v_mul_f32_e32 v26, v31, v31
	v_mul_f32_e32 v27, v33, v33
	v_fmac_f32_e32 v26, v30, v30
	v_fmac_f32_e32 v27, v32, v32
	v_add_f32_e32 v26, v26, v27
	v_mul_f32_e32 v27, v37, v37
	v_mul_f32_e32 v28, v35, v35
	v_lshlrev_b32_e32 v44, 16, v75
	v_and_b32_e32 v45, 0xffff0000, v75
	v_fmac_f32_e32 v27, v36, v36
	v_fmac_f32_e32 v28, v34, v34
	v_lshlrev_b32_e32 v48, 16, v77
	v_and_b32_e32 v49, 0xffff0000, v77
	v_add_f32_e32 v27, v27, v28
	v_pk_fma_f32 v[24:25], v[24:25], v[50:51], v[44:45] op_sel_hi:[1,0,1]
	v_pk_fma_f32 v[22:23], v[22:23], v[50:51], v[42:43] op_sel_hi:[1,0,1]
	v_lshlrev_b32_e32 v46, 16, v76
	v_and_b32_e32 v47, 0xffff0000, v76
	v_add_f32_e32 v28, v26, v27
	v_pk_fma_f32 v[26:27], v[20:21], v[50:51], v[48:49] op_sel_hi:[1,0,1]
	v_mul_f32_e32 v20, v23, v23
	v_mul_f32_e32 v21, v25, v25
	v_pk_fma_f32 v[18:19], v[18:19], v[50:51], v[46:47] op_sel_hi:[1,0,1]
	v_fmac_f32_e32 v20, v22, v22
	v_fmac_f32_e32 v21, v24, v24
	v_add_f32_e32 v20, v20, v21
	v_mul_f32_e32 v21, v19, v19
	v_mul_f32_e32 v29, v27, v27
	v_fmac_f32_e32 v21, v18, v18
	v_fmac_f32_e32 v29, v26, v26
	v_add_f32_e32 v21, v21, v29
	v_add_f32_e32 v20, v20, v21
	v_add_f32_e32 v28, v28, v20
	ds_bpermute_b32 v29, v204, v28
	v_cvt_pk_bf16_f32 v20, v22, v23
	v_cvt_pk_bf16_f32 v22, v18, v19
	v_cvt_pk_bf16_f32 v21, v24, v25
	v_lshl_add_u64 v[24:25], s[0:1], 0, v[102:103]
	s_waitcnt lgkmcnt(0)
	v_add_f32_e32 v18, v28, v29
	ds_bpermute_b32 v19, v205, v18
	v_lshl_add_u64 v[24:25], v[24:25], 0, v[100:101]
	v_cvt_pk_bf16_f32 v23, v26, v27
	v_lshl_add_u64 v[24:25], v[24:25], 0, v[174:175]
	global_store_dwordx4 v[24:25], v[20:23], off sc1
	s_and_saveexec_b64 s[38:39], s[4:5]
	s_cbranch_execz .Lwtp13_6
	v_lshlrev_b64 v[20:21], 8, v[96:97]
	v_lshl_add_u64 v[20:21], s[18:19], 0, v[20:21]
	v_lshl_add_u64 v[20:21], s[36:37], 2, v[20:21]
	s_lshl_b32 s14, s57, 2
	v_lshl_add_u64 v[20:21], v[20:21], 0, s[14:15]
	s_waitcnt lgkmcnt(0)
	v_add_f32_e32 v18, v18, v19
	global_store_dword v[20:21], v18, off sc1
.Lwtp13_6:
	s_or_b64 exec, exec, s[38:39]
	s_waitcnt vmcnt(7)
	v_lshlrev_b32_e32 v20, 16, v71
	v_and_b32_e32 v21, 0xffff0000, v71
	v_lshlrev_b32_e32 v22, 16, v72
	v_and_b32_e32 v23, 0xffff0000, v72
	v_mul_f32_e32 v34, v114, v114
	v_lshlrev_b32_e32 v18, 16, v70
	s_waitcnt lgkmcnt(0)
	v_and_b32_e32 v19, 0xffff0000, v70
	v_lshlrev_b32_e32 v24, 16, v73
	v_and_b32_e32 v25, 0xffff0000, v73
	v_pk_fma_f32 v[16:17], v[16:17], v[34:35], v[20:21] op_sel_hi:[1,0,1]
	v_pk_fma_f32 v[20:21], v[10:11], v[34:35], v[22:23] op_sel_hi:[1,0,1]
	v_lshl_add_u64 v[22:23], s[0:1], 0, v[98:99]
	v_mov_b32_e32 v93, v163
	v_pk_fma_f32 v[14:15], v[14:15], v[34:35], v[18:19] op_sel_hi:[1,0,1]
	v_pk_fma_f32 v[18:19], v[12:13], v[34:35], v[24:25] op_sel_hi:[1,0,1]
	v_lshl_add_u64 v[22:23], v[22:23], 0, v[92:93]
	v_cvt_pk_bf16_f32 v10, v14, v15
	v_cvt_pk_bf16_f32 v11, v16, v17
	v_cvt_pk_bf16_f32 v12, v20, v21
	v_cvt_pk_bf16_f32 v13, v18, v19
	v_lshl_add_u64 v[22:23], v[22:23], 0, v[174:175]
	global_store_dwordx4 v[22:23], v[10:13], off sc1
	s_waitcnt vmcnt(7)
	v_lshlrev_b32_e32 v26, 16, v66
	v_and_b32_e32 v27, 0xffff0000, v66
	v_mul_f32_e32 v10, v15, v15
	v_mul_f32_e32 v11, v17, v17
	v_fmac_f32_e32 v10, v14, v14
	v_fmac_f32_e32 v11, v16, v16
	v_add_f32_e32 v10, v10, v11
	v_mul_f32_e32 v11, v21, v21
	v_mul_f32_e32 v12, v19, v19
	v_lshlrev_b32_e32 v28, 16, v67
	v_and_b32_e32 v29, 0xffff0000, v67
	v_fmac_f32_e32 v11, v20, v20
	v_fmac_f32_e32 v12, v18, v18
	v_lshlrev_b32_e32 v32, 16, v69
	v_and_b32_e32 v33, 0xffff0000, v69
	v_add_f32_e32 v11, v11, v12
	v_pk_fma_f32 v[8:9], v[8:9], v[34:35], v[28:29] op_sel_hi:[1,0,1]
	v_pk_fma_f32 v[6:7], v[6:7], v[34:35], v[26:27] op_sel_hi:[1,0,1]
	v_lshlrev_b32_e32 v30, 16, v68
	v_and_b32_e32 v31, 0xffff0000, v68
	v_add_f32_e32 v12, v10, v11
	v_pk_fma_f32 v[10:11], v[4:5], v[34:35], v[32:33] op_sel_hi:[1,0,1]
	v_mul_f32_e32 v4, v7, v7
	v_mul_f32_e32 v5, v9, v9
	v_pk_fma_f32 v[2:3], v[2:3], v[34:35], v[30:31] op_sel_hi:[1,0,1]
	v_fmac_f32_e32 v4, v6, v6
	v_fmac_f32_e32 v5, v8, v8
	v_add_f32_e32 v4, v4, v5
	v_mul_f32_e32 v5, v3, v3
	v_mul_f32_e32 v13, v11, v11
	v_fmac_f32_e32 v5, v2, v2
	v_fmac_f32_e32 v13, v10, v10
	v_add_f32_e32 v5, v5, v13
	v_add_f32_e32 v4, v4, v5
	v_add_f32_e32 v12, v12, v4
	ds_bpermute_b32 v13, v204, v12
	v_cvt_pk_bf16_f32 v4, v6, v7
	v_cvt_pk_bf16_f32 v6, v2, v3
	v_cvt_pk_bf16_f32 v5, v8, v9
	v_lshl_add_u64 v[8:9], s[0:1], 0, v[94:95]
	s_waitcnt lgkmcnt(0)
	v_add_f32_e32 v2, v12, v13
	ds_bpermute_b32 v3, v205, v2
	v_lshl_add_u64 v[8:9], v[8:9], 0, v[92:93]
	v_cvt_pk_bf16_f32 v7, v10, v11
	v_lshl_add_u64 v[8:9], v[8:9], 0, v[174:175]
	global_store_dwordx4 v[8:9], v[4:7], off sc1
	s_and_saveexec_b64 s[38:39], s[4:5]
	s_cbranch_execz .Lwtp13_7
	v_lshlrev_b64 v[4:5], 8, v[90:91]
	v_lshl_add_u64 v[4:5], s[18:19], 0, v[4:5]
	v_lshl_add_u64 v[4:5], s[36:37], 2, v[4:5]
	s_lshl_b32 s14, s57, 2
	v_lshl_add_u64 v[4:5], v[4:5], 0, s[14:15]
	s_waitcnt lgkmcnt(0)
	v_add_f32_e32 v2, v2, v3
	global_store_dword v[4:5], v2, off sc1
.Lwtp13_7:
	s_or_b64 exec, exec, s[38:39]
	s_andn2_b64 vcc, exec, s[6:7]
	s_mov_b64 s[6:7], -1
	s_branch .Lwtp13_join

.LBB0_1390:
	s_and_b64 vcc, exec, s[2:3]
	s_cbranch_vccz .Lwtp15_entry
	v_lshl_add_u32 v190, s26, 8, v181
	v_ashrrev_i32_e32 v191, 31, v190
	v_lshlrev_b64 v[152:153], 2, v[190:191]
	v_lshl_add_u64 v[154:155], s[16:17], 0, v[152:153]
	global_load_dword v222, v[154:155], off
	s_lshl_b32 s19, s28, 8
	s_or_b32 s19, s19, s45
	v_or_b32_e32 v62, s19, v183
	v_ashrrev_i32_e32 v63, 31, v62
	v_bitop3_b32 v64, s19, 56, v183 bitop3:0xc8
	v_lshlrev_b64 v[240:241], 13, v[190:191]
	v_lshrrev_b64 v[66:67], 1, v[190:191]
	s_ashr_i32 s26, s19, 6
	v_lshlrev_b32_e32 v170, 1, v64
	v_lshl_add_u64 v[64:65], s[8:9], 0, v[240:241]
	v_and_b32_e32 v147, 0x7fffffff, v67
	v_and_b32_e32 v146, 0xffffffc0, v66
	v_lshlrev_b32_e32 v66, 7, v190
	v_lshlrev_b64 v[184:185], 1, v[62:63]
	s_ashr_i32 s27, s26, 31
	v_lshl_add_u64 v[192:193], s[0:1], 0, v[170:171]
	v_lshl_add_u64 v[148:149], v[64:65], 0, v[184:185]
	v_and_b32_e32 v170, 0x2780, v66
	v_lshl_add_u64 v[64:65], v[146:147], 0, s[26:27]
	v_readlane_b32 s52, v251, 0
	v_lshl_add_u64 v[150:151], v[192:193], 0, v[170:171]
	v_lshlrev_b64 v[64:65], 14, v[64:65]
	v_readlane_b32 s54, v251, 2
	v_readlane_b32 s55, v251, 3
	global_load_dwordx4 v[224:227], v[148:149], off
	v_lshl_add_u64 v[64:65], v[150:151], 0, v[64:65]
	v_lshl_add_u64 v[66:67], v[62:63], 2, s[54:55]
	v_lshl_add_u64 v[152:153], s[6:7], 0, v[152:153]
	global_load_dwordx4 v[228:231], v[64:65], off
	global_load_dwordx4 v[74:77], v[66:67], off offset:16
	global_load_dwordx4 v[78:81], v[66:67], off
	s_nop 0
	global_load_dwordx4 v[62:65], v[66:67], off offset:528
	s_nop 0
	global_load_dwordx4 v[66:69], v[66:67], off offset:512
	v_or_b32_e32 v212, 32, v190
	global_load_dword v220, v[152:153], off
	v_ashrrev_i32_e32 v213, 31, v212
	v_or_b32_e32 v210, 48, v190
	s_bitset1_b32 s19, 7
	v_or_b32_e32 v156, 16, v190
	v_lshlrev_b64 v[198:199], 2, v[212:213]
	v_ashrrev_i32_e32 v211, 31, v210
	s_ashr_i32 s28, s19, 6
	v_ashrrev_i32_e32 v157, 31, v156
	v_lshl_add_u64 v[202:203], s[16:17], 0, v[198:199]
	v_lshl_add_u64 v[204:205], s[6:7], 0, v[198:199]
	v_lshlrev_b64 v[198:199], 2, v[210:211]
	s_ashr_i32 s29, s28, 31
	v_lshlrev_b64 v[158:159], 2, v[156:157]
	v_lshl_add_u64 v[232:233], s[6:7], 0, v[198:199]
	v_lshl_add_u64 v[146:147], v[146:147], 0, s[28:29]
	v_lshl_add_u64 v[160:161], s[16:17], 0, v[158:159]
	v_lshl_add_u64 v[158:159], s[6:7], 0, v[158:159]
	v_lshl_add_u64 v[218:219], s[16:17], 0, v[198:199]
	global_load_dword v200, v[154:155], off offset:512
	global_load_dword v198, v[152:153], off offset:512
	global_load_dword v196, v[154:155], off offset:576
	global_load_dword v194, v[152:153], off offset:576
	global_load_dword v188, v[154:155], off offset:640
	global_load_dword v182, v[154:155], off offset:704
	global_load_dword v216, v[160:161], off
	global_load_dword v214, v[158:159], off
	global_load_dword v208, v[202:203], off
	global_load_dword v206, v[204:205], off
	s_nop 0
	global_load_dword v204, v[218:219], off
	global_load_dword v202, v[232:233], off
	global_load_dword v186, v[152:153], off offset:640
	global_load_dword v180, v[152:153], off offset:704
	v_lshlrev_b64 v[146:147], 14, v[146:147]
	global_load_dwordx4 v[232:235], v[148:149], off offset:256
	v_lshl_add_u64 v[146:147], v[150:151], 0, v[146:147]
	global_load_dwordx4 v[236:239], v[146:147], off
	v_lshrrev_b64 v[148:149], 1, v[156:157]
	v_lshlrev_b64 v[218:219], 13, v[156:157]
	v_and_b32_e32 v149, 0x7fffffff, v149
	v_and_b32_e32 v148, 0xffffffc0, v148
	v_lshlrev_b32_e32 v150, 7, v156
	v_lshl_add_u64 v[146:147], s[8:9], 0, v[218:219]
	v_and_b32_e32 v170, 0x3f80, v150
	v_lshl_add_u64 v[150:151], v[148:149], 0, s[26:27]
	v_lshl_add_u64 v[154:155], v[192:193], 0, v[170:171]
	v_lshl_add_u64 v[146:147], v[146:147], 0, v[184:185]
	v_lshlrev_b64 v[150:151], 14, v[150:151]
	v_lshl_add_u64 v[156:157], v[154:155], 0, v[150:151]
	global_load_dwordx4 v[158:161], v[146:147], off
	global_load_dwordx4 v[150:153], v[146:147], off offset:256
	v_lshl_add_u64 v[146:147], v[148:149], 0, s[28:29]
	v_lshlrev_b64 v[146:147], 14, v[146:147]
	v_lshl_add_u64 v[146:147], v[154:155], 0, v[146:147]
	global_load_dwordx4 v[154:157], v[156:157], off
	s_nop 0
	global_load_dwordx4 v[146:149], v[146:147], off
	s_andn2_b64 vcc, exec, s[2:3]
	s_mov_b64 s[2:3], -1
	v_readlane_b32 s53, v251, 1
	v_readlane_b32 s56, v251, 4
	v_readlane_b32 s57, v251, 5
	v_readlane_b32 s58, v251, 6
	v_readlane_b32 s59, v251, 7
	s_waitcnt vmcnt(0)
	v_pk_mul_f32 v[142:143], v[142:143], v[222:223] op_sel_hi:[1,0]
	v_pk_mul_f32 v[138:139], v[138:139], v[222:223] op_sel_hi:[1,0]
	v_mul_f32_e32 v142, 0xbfb8aa3b, v142
	v_exp_f32_e32 v170, v142
	v_mul_f32_e32 v142, 0xbfb8aa3b, v143
	v_exp_f32_e32 v191, v142
	v_pk_mul_f32 v[142:143], v[144:145], v[222:223] op_sel_hi:[1,0]
	v_mul_f32_e32 v138, 0xbfb8aa3b, v138
	v_add_f32_e32 v144, 1.0, v170
	v_mul_f32_e32 v142, 0xbfb8aa3b, v142
	v_mul_f32_e32 v143, 0xbfb8aa3b, v143
	v_exp_f32_e32 v170, v138
	v_mul_f32_e32 v138, 0xbfb8aa3b, v139
	v_add_f32_e32 v145, 1.0, v191
	v_exp_f32_e32 v142, v142
	v_exp_f32_e32 v143, v143
	v_exp_f32_e32 v191, v138
	v_pk_mul_f32 v[138:139], v[140:141], v[222:223] op_sel_hi:[1,0]
	v_add_f32_e32 v142, 1.0, v142
	v_mul_f32_e32 v138, 0xbfb8aa3b, v138
	v_mul_f32_e32 v139, 0xbfb8aa3b, v139
	v_exp_f32_e32 v138, v138
	v_exp_f32_e32 v139, v139
	v_add_f32_e32 v143, 1.0, v143
	v_pk_mul_f32 v[134:135], v[134:135], v[222:223] op_sel_hi:[1,0]
	v_rcp_f32_e32 v142, v142
	v_rcp_f32_e32 v143, v143
	v_mul_f32_e32 v134, 0xbfb8aa3b, v134
	v_lshlrev_b32_e32 v242, 16, v224
	v_and_b32_e32 v243, 0xffff0000, v224
	v_lshlrev_b32_e32 v224, 16, v225
	v_and_b32_e32 v225, 0xffff0000, v225
	v_add_f32_e32 v140, 1.0, v170
	v_add_f32_e32 v141, 1.0, v191
	v_add_f32_e32 v138, 1.0, v138
	v_add_f32_e32 v139, 1.0, v139
	v_exp_f32_e32 v170, v134
	v_mul_f32_e32 v134, 0xbfb8aa3b, v135
	v_rcp_f32_e32 v144, v144
	v_rcp_f32_e32 v145, v145
	v_pk_mul_f32 v[224:225], v[220:221], v[224:225] op_sel_hi:[0,1]
	v_rcp_f32_e32 v140, v140
	v_rcp_f32_e32 v141, v141
	v_rcp_f32_e32 v138, v138
	v_rcp_f32_e32 v139, v139
	v_exp_f32_e32 v191, v134
	v_lshlrev_b32_e32 v244, 16, v226
	v_and_b32_e32 v245, 0xffff0000, v226
	v_lshlrev_b32_e32 v226, 16, v227
	v_and_b32_e32 v227, 0xffff0000, v227
	v_lshlrev_b32_e32 v246, 16, v228
	v_and_b32_e32 v247, 0xffff0000, v228
	v_lshlrev_b32_e32 v228, 16, v229
	v_and_b32_e32 v229, 0xffff0000, v229
	v_pk_mul_f32 v[224:225], v[80:81], v[224:225]
	v_pk_mul_f32 v[242:243], v[220:221], v[242:243] op_sel_hi:[0,1]
	v_pk_fma_f32 v[142:143], v[142:143], v[224:225], v[228:229]
	v_pk_mul_f32 v[224:225], v[220:221], v[226:227] op_sel_hi:[0,1]
	v_pk_mul_f32 v[226:227], v[220:221], v[244:245] op_sel_hi:[0,1]
	v_lshlrev_b32_e32 v248, 16, v230
	v_and_b32_e32 v249, 0xffff0000, v230
	v_lshlrev_b32_e32 v230, 16, v231
	v_and_b32_e32 v231, 0xffff0000, v231
	v_pk_mul_f32 v[242:243], v[78:79], v[242:243]
	v_pk_mul_f32 v[226:227], v[74:75], v[226:227]
	v_pk_mul_f32 v[224:225], v[76:77], v[224:225]
	v_pk_fma_f32 v[144:145], v[144:145], v[242:243], v[246:247]
	v_pk_fma_f32 v[224:225], v[138:139], v[224:225], v[230:231]
	v_pk_fma_f32 v[140:141], v[140:141], v[226:227], v[248:249]
	v_cvt_pk_bf16_f32 v139, v142, v143
	v_lshl_add_u64 v[142:143], s[10:11], 0, v[240:241]
	v_pk_mul_f32 v[134:135], v[136:137], v[222:223] op_sel_hi:[1,0]
	v_add_f32_e32 v136, 1.0, v170
	v_add_f32_e32 v137, 1.0, v191
	v_cvt_pk_bf16_f32 v138, v144, v145
	v_cvt_pk_bf16_f32 v140, v140, v141
	v_cvt_pk_bf16_f32 v141, v224, v225
	v_lshl_add_u64 v[142:143], v[142:143], 0, v[184:185]
	v_rcp_f32_e32 v136, v136
	v_rcp_f32_e32 v137, v137
	global_store_dwordx4 v[142:143], v[138:141], off
	v_pk_mul_f32 v[130:131], v[130:131], v[222:223] op_sel_hi:[1,0]
	v_lshlrev_b32_e32 v226, 16, v236
	v_lshlrev_b32_e32 v138, 16, v232
	v_and_b32_e32 v139, 0xffff0000, v232
	v_pk_mul_f32 v[138:139], v[220:221], v[138:139] op_sel_hi:[0,1]
	v_and_b32_e32 v227, 0xffff0000, v236
	v_pk_mul_f32 v[138:139], v[66:67], v[138:139]
	v_mul_f32_e32 v130, 0xbfb8aa3b, v130
	v_mul_f32_e32 v134, 0xbfb8aa3b, v134
	v_mul_f32_e32 v135, 0xbfb8aa3b, v135
	v_pk_fma_f32 v[136:137], v[136:137], v[138:139], v[226:227]
	v_exp_f32_e32 v138, v130
	v_mul_f32_e32 v130, 0xbfb8aa3b, v131
	v_exp_f32_e32 v134, v134
	v_exp_f32_e32 v135, v135
	v_exp_f32_e32 v139, v130
	v_pk_mul_f32 v[130:131], v[132:133], v[222:223] op_sel_hi:[1,0]
	v_add_f32_e32 v134, 1.0, v134
	v_mul_f32_e32 v130, 0xbfb8aa3b, v130
	v_mul_f32_e32 v131, 0xbfb8aa3b, v131
	v_exp_f32_e32 v130, v130
	v_exp_f32_e32 v131, v131
	v_add_f32_e32 v135, 1.0, v135
	v_rcp_f32_e32 v134, v134
	v_rcp_f32_e32 v135, v135
	v_lshlrev_b32_e32 v140, 16, v233
	v_and_b32_e32 v141, 0xffff0000, v233
	v_add_f32_e32 v132, 1.0, v138
	v_add_f32_e32 v133, 1.0, v139
	v_add_f32_e32 v130, 1.0, v130
	v_add_f32_e32 v131, 1.0, v131
	v_pk_mul_f32 v[140:141], v[220:221], v[140:141] op_sel_hi:[0,1]
	v_rcp_f32_e32 v132, v132
	v_rcp_f32_e32 v133, v133
	v_rcp_f32_e32 v130, v130
	v_rcp_f32_e32 v131, v131
	v_lshlrev_b32_e32 v144, 16, v234
	v_and_b32_e32 v145, 0xffff0000, v234
	v_lshlrev_b32_e32 v224, 16, v235
	v_and_b32_e32 v225, 0xffff0000, v235
	v_lshlrev_b32_e32 v228, 16, v237
	v_and_b32_e32 v229, 0xffff0000, v237
	v_pk_mul_f32 v[140:141], v[68:69], v[140:141]
	v_pk_mul_f32 v[138:139], v[220:221], v[224:225] op_sel_hi:[0,1]
	v_pk_fma_f32 v[134:135], v[134:135], v[140:141], v[228:229]
	v_pk_mul_f32 v[140:141], v[220:221], v[144:145] op_sel_hi:[0,1]
	v_lshlrev_b32_e32 v230, 16, v238
	v_and_b32_e32 v231, 0xffff0000, v238
	v_lshlrev_b32_e32 v232, 16, v239
	v_and_b32_e32 v233, 0xffff0000, v239
	v_pk_mul_f32 v[140:141], v[62:63], v[140:141]
	v_pk_mul_f32 v[138:139], v[64:65], v[138:139]
	v_pk_mul_f32 v[126:127], v[126:127], v[216:217] op_sel_hi:[1,0]
	v_pk_fma_f32 v[138:139], v[130:131], v[138:139], v[232:233]
	v_pk_fma_f32 v[132:133], v[132:133], v[140:141], v[230:231]
	v_mul_f32_e32 v126, 0xbfb8aa3b, v126
	v_cvt_pk_bf16_f32 v132, v132, v133
	v_cvt_pk_bf16_f32 v133, v138, v139
	v_lshlrev_b32_e32 v138, 16, v154
	v_and_b32_e32 v139, 0xffff0000, v154
	v_exp_f32_e32 v154, v126
	v_mul_f32_e32 v126, 0xbfb8aa3b, v127
	v_lshlrev_b32_e32 v140, 16, v155
	v_and_b32_e32 v141, 0xffff0000, v155
	v_exp_f32_e32 v155, v126
	v_pk_mul_f32 v[126:127], v[128:129], v[216:217] op_sel_hi:[1,0]
	v_add_f32_e32 v128, 1.0, v154
	v_cvt_pk_bf16_f32 v130, v136, v137
	v_add_f32_e32 v129, 1.0, v155
	v_cvt_pk_bf16_f32 v131, v134, v135
	v_rcp_f32_e32 v128, v128
	v_rcp_f32_e32 v129, v129
	global_store_dwordx4 v[142:143], v[130:133], off offset:256
	v_mul_f32_e32 v126, 0xbfb8aa3b, v126
	v_mul_f32_e32 v127, 0xbfb8aa3b, v127
	v_lshlrev_b32_e32 v130, 16, v158
	v_and_b32_e32 v131, 0xffff0000, v158
	v_exp_f32_e32 v126, v126
	v_exp_f32_e32 v127, v127
	v_pk_mul_f32 v[130:131], v[214:215], v[130:131] op_sel_hi:[0,1]
	v_pk_mul_f32 v[122:123], v[122:123], v[216:217] op_sel_hi:[1,0]
	v_pk_mul_f32 v[130:131], v[78:79], v[130:131]
	v_mul_f32_e32 v122, 0xbfb8aa3b, v122
	v_pk_fma_f32 v[128:129], v[128:129], v[130:131], v[138:139]
	v_exp_f32_e32 v130, v122
	v_mul_f32_e32 v122, 0xbfb8aa3b, v123
	v_exp_f32_e32 v131, v122
	v_pk_mul_f32 v[122:123], v[124:125], v[216:217] op_sel_hi:[1,0]
	v_add_f32_e32 v126, 1.0, v126
	v_add_f32_e32 v127, 1.0, v127
	v_mul_f32_e32 v122, 0xbfb8aa3b, v122
	v_mul_f32_e32 v123, 0xbfb8aa3b, v123
	v_rcp_f32_e32 v126, v126
	v_rcp_f32_e32 v127, v127
	v_exp_f32_e32 v122, v122
	v_exp_f32_e32 v123, v123
	v_lshlrev_b32_e32 v132, 16, v159
	v_and_b32_e32 v133, 0xffff0000, v159
	v_pk_mul_f32 v[132:133], v[214:215], v[132:133] op_sel_hi:[0,1]
	v_pk_mul_f32 v[118:119], v[118:119], v[216:217] op_sel_hi:[1,0]
	v_pk_mul_f32 v[132:133], v[80:81], v[132:133]
	v_mul_f32_e32 v118, 0xbfb8aa3b, v118
	v_pk_fma_f32 v[126:127], v[126:127], v[132:133], v[140:141]
	v_add_f32_e32 v124, 1.0, v130
	v_add_f32_e32 v125, 1.0, v131
	v_add_f32_e32 v122, 1.0, v122
	v_add_f32_e32 v123, 1.0, v123
	v_exp_f32_e32 v140, v118
	v_mul_f32_e32 v118, 0xbfb8aa3b, v119
	v_rcp_f32_e32 v124, v124
	v_rcp_f32_e32 v125, v125
	v_rcp_f32_e32 v122, v122
	v_rcp_f32_e32 v123, v123
	v_exp_f32_e32 v141, v118
	v_lshlrev_b32_e32 v134, 16, v160
	v_and_b32_e32 v135, 0xffff0000, v160
	v_lshlrev_b32_e32 v136, 16, v161
	v_and_b32_e32 v137, 0xffff0000, v161
	v_pk_mul_f32 v[130:131], v[214:215], v[136:137] op_sel_hi:[0,1]
	v_pk_mul_f32 v[132:133], v[214:215], v[134:135] op_sel_hi:[0,1]
	v_lshlrev_b32_e32 v142, 16, v156
	v_and_b32_e32 v143, 0xffff0000, v156
	v_lshlrev_b32_e32 v144, 16, v157
	v_and_b32_e32 v145, 0xffff0000, v157
	v_pk_mul_f32 v[132:133], v[74:75], v[132:133]
	v_pk_mul_f32 v[130:131], v[76:77], v[130:131]
	v_pk_fma_f32 v[124:125], v[124:125], v[132:133], v[142:143]
	v_pk_fma_f32 v[130:131], v[122:123], v[130:131], v[144:145]
	v_cvt_pk_bf16_f32 v123, v126, v127
	v_lshl_add_u64 v[126:127], s[10:11], 0, v[218:219]
	v_pk_mul_f32 v[118:119], v[120:121], v[216:217] op_sel_hi:[1,0]
	v_add_f32_e32 v120, 1.0, v140
	v_add_f32_e32 v121, 1.0, v141
	v_cvt_pk_bf16_f32 v122, v128, v129
	v_cvt_pk_bf16_f32 v124, v124, v125
	v_cvt_pk_bf16_f32 v125, v130, v131
	v_lshl_add_u64 v[126:127], v[126:127], 0, v[184:185]
	v_rcp_f32_e32 v120, v120
	v_rcp_f32_e32 v121, v121
	global_store_dwordx4 v[126:127], v[122:125], off
	v_pk_mul_f32 v[114:115], v[114:115], v[216:217] op_sel_hi:[1,0]
	v_lshlrev_b32_e32 v132, 16, v146
	v_lshlrev_b32_e32 v122, 16, v150
	v_and_b32_e32 v123, 0xffff0000, v150
	v_pk_mul_f32 v[122:123], v[214:215], v[122:123] op_sel_hi:[0,1]
	v_and_b32_e32 v133, 0xffff0000, v146
	v_pk_mul_f32 v[122:123], v[66:67], v[122:123]
	v_mul_f32_e32 v114, 0xbfb8aa3b, v114
	v_mul_f32_e32 v118, 0xbfb8aa3b, v118
	v_mul_f32_e32 v119, 0xbfb8aa3b, v119
	v_pk_fma_f32 v[120:121], v[120:121], v[122:123], v[132:133]
	v_exp_f32_e32 v122, v114
	v_mul_f32_e32 v114, 0xbfb8aa3b, v115
	v_exp_f32_e32 v118, v118
	v_exp_f32_e32 v119, v119
	v_exp_f32_e32 v123, v114
	v_pk_mul_f32 v[114:115], v[116:117], v[216:217] op_sel_hi:[1,0]
	v_add_f32_e32 v118, 1.0, v118
	v_mul_f32_e32 v114, 0xbfb8aa3b, v114
	v_mul_f32_e32 v115, 0xbfb8aa3b, v115
	v_exp_f32_e32 v114, v114
	v_exp_f32_e32 v115, v115
	v_add_f32_e32 v119, 1.0, v119
	v_rcp_f32_e32 v118, v118
	v_rcp_f32_e32 v119, v119
	v_lshlrev_b32_e32 v124, 16, v151
	v_and_b32_e32 v125, 0xffff0000, v151
	v_add_f32_e32 v116, 1.0, v122
	v_add_f32_e32 v117, 1.0, v123
	v_add_f32_e32 v114, 1.0, v114
	v_add_f32_e32 v115, 1.0, v115
	v_pk_mul_f32 v[124:125], v[214:215], v[124:125] op_sel_hi:[0,1]
	v_rcp_f32_e32 v116, v116
	v_rcp_f32_e32 v117, v117
	v_rcp_f32_e32 v114, v114
	v_rcp_f32_e32 v115, v115
	v_lshlrev_b32_e32 v128, 16, v152
	v_and_b32_e32 v129, 0xffff0000, v152
	v_lshlrev_b32_e32 v130, 16, v153
	v_and_b32_e32 v131, 0xffff0000, v153
	v_lshlrev_b32_e32 v134, 16, v147
	v_and_b32_e32 v135, 0xffff0000, v147
	v_pk_mul_f32 v[124:125], v[68:69], v[124:125]
	v_pk_mul_f32 v[122:123], v[214:215], v[130:131] op_sel_hi:[0,1]
	v_pk_fma_f32 v[118:119], v[118:119], v[124:125], v[134:135]
	v_pk_mul_f32 v[124:125], v[214:215], v[128:129] op_sel_hi:[0,1]
	v_lshlrev_b32_e32 v136, 16, v148
	v_and_b32_e32 v137, 0xffff0000, v148
	v_lshlrev_b32_e32 v138, 16, v149
	v_and_b32_e32 v139, 0xffff0000, v149
	v_pk_mul_f32 v[124:125], v[62:63], v[124:125]
	v_pk_mul_f32 v[122:123], v[64:65], v[122:123]
	v_pk_fma_f32 v[116:117], v[116:117], v[124:125], v[136:137]
	v_pk_fma_f32 v[122:123], v[114:115], v[122:123], v[138:139]
	v_cvt_pk_bf16_f32 v114, v120, v121
	v_cvt_pk_bf16_f32 v115, v118, v119
	v_cvt_pk_bf16_f32 v116, v116, v117
	v_cvt_pk_bf16_f32 v117, v122, v123
	global_store_dwordx4 v[126:127], v[114:117], off offset:256
	v_lshlrev_b64 v[150:151], 13, v[212:213]
	v_lshlrev_b32_e32 v118, 7, v212
	v_lshrrev_b64 v[116:117], 1, v[212:213]
	v_lshl_add_u64 v[114:115], s[8:9], 0, v[150:151]
	v_and_b32_e32 v117, 0x7fffffff, v117
	v_and_b32_e32 v116, 0xffffffc0, v116
	v_lshl_add_u64 v[114:115], v[114:115], 0, v[184:185]
	v_and_b32_e32 v170, 0x3f80, v118
	v_lshl_add_u64 v[120:121], v[116:117], 0, s[26:27]
	global_load_dwordx4 v[126:129], v[114:115], off
	global_load_dwordx4 v[134:137], v[114:115], off offset:256
	v_lshl_add_u64 v[118:119], v[192:193], 0, v[170:171]
	v_lshlrev_b64 v[120:121], 14, v[120:121]
	v_lshl_add_u64 v[120:121], v[118:119], 0, v[120:121]
	global_load_dwordx4 v[130:133], v[120:121], off
	v_lshl_add_u64 v[114:115], v[116:117], 0, s[28:29]
	v_lshlrev_b64 v[114:115], 14, v[114:115]
	v_lshl_add_u64 v[114:115], v[118:119], 0, v[114:115]
	global_load_dwordx4 v[138:141], v[114:115], off
	v_lshrrev_b64 v[116:117], 1, v[210:211]
	v_lshlrev_b64 v[124:125], 13, v[210:211]
	v_and_b32_e32 v117, 0x7fffffff, v117
	v_and_b32_e32 v116, 0xffffffc0, v116
	v_lshlrev_b32_e32 v118, 7, v210
	v_lshl_add_u64 v[114:115], s[8:9], 0, v[124:125]
	v_and_b32_e32 v170, 0x3f80, v118
	v_lshl_add_u64 v[118:119], v[116:117], 0, s[26:27]
	v_lshl_add_u64 v[146:147], v[192:193], 0, v[170:171]
	v_lshl_add_u64 v[114:115], v[114:115], 0, v[184:185]
	v_lshlrev_b64 v[118:119], 14, v[118:119]
	v_lshl_add_u64 v[148:149], v[146:147], 0, v[118:119]
	global_load_dwordx4 v[142:145], v[114:115], off
	global_load_dwordx4 v[118:121], v[114:115], off offset:256
	v_lshl_add_u64 v[114:115], v[116:117], 0, s[28:29]
	v_lshlrev_b64 v[114:115], 14, v[114:115]
	v_lshl_add_u64 v[114:115], v[146:147], 0, v[114:115]
	global_load_dwordx4 v[146:149], v[148:149], off
	s_nop 0
	global_load_dwordx4 v[114:117], v[114:115], off
	v_pk_mul_f32 v[110:111], v[110:111], v[208:209] op_sel_hi:[1,0]
	v_pk_mul_f32 v[106:107], v[106:107], v[208:209] op_sel_hi:[1,0]
	v_mul_f32_e32 v110, 0xbfb8aa3b, v110
	v_exp_f32_e32 v160, v110
	v_mul_f32_e32 v110, 0xbfb8aa3b, v111
	v_exp_f32_e32 v161, v110
	v_pk_mul_f32 v[110:111], v[112:113], v[208:209] op_sel_hi:[1,0]
	v_mul_f32_e32 v106, 0xbfb8aa3b, v106
	v_mul_f32_e32 v110, 0xbfb8aa3b, v110
	v_mul_f32_e32 v111, 0xbfb8aa3b, v111
	v_exp_f32_e32 v110, v110
	v_exp_f32_e32 v111, v111
	v_add_f32_e32 v112, 1.0, v160
	v_add_f32_e32 v113, 1.0, v161
	v_add_f32_e32 v110, 1.0, v110
	v_add_f32_e32 v111, 1.0, v111
	v_rcp_f32_e32 v110, v110
	v_rcp_f32_e32 v111, v111
	v_rcp_f32_e32 v112, v112
	v_rcp_f32_e32 v113, v113
	v_pk_mul_f32 v[102:103], v[102:103], v[208:209] op_sel_hi:[1,0]
	v_pk_mul_f32 v[98:99], v[98:99], v[208:209] op_sel_hi:[1,0]
	v_mul_f32_e32 v102, 0xbfb8aa3b, v102
	v_mul_f32_e32 v98, 0xbfb8aa3b, v98
	v_pk_mul_f32 v[94:95], v[94:95], v[204:205] op_sel_hi:[1,0]
	v_pk_mul_f32 v[90:91], v[90:91], v[204:205] op_sel_hi:[1,0]
	v_mul_f32_e32 v94, 0xbfb8aa3b, v94
	v_mul_f32_e32 v90, 0xbfb8aa3b, v90
	v_pk_mul_f32 v[86:87], v[86:87], v[204:205] op_sel_hi:[1,0]
	v_pk_mul_f32 v[82:83], v[82:83], v[204:205] op_sel_hi:[1,0]
	v_mul_f32_e32 v86, 0xbfb8aa3b, v86
	v_mul_f32_e32 v82, 0xbfb8aa3b, v82
	v_add_u32_e32 v122, 0x80, v190
	v_ashrrev_i32_e32 v123, 31, v122
	v_pk_mul_f32 v[70:71], v[70:71], v[200:201] op_sel_hi:[1,0]
	v_pk_mul_f32 v[58:59], v[58:59], v[200:201] op_sel_hi:[1,0]
	v_mul_f32_e32 v70, 0xbfb8aa3b, v70
	v_mul_f32_e32 v58, 0xbfb8aa3b, v58
	v_pk_mul_f32 v[54:55], v[54:55], v[200:201] op_sel_hi:[1,0]
	v_pk_mul_f32 v[50:51], v[50:51], v[200:201] op_sel_hi:[1,0]
	v_mul_f32_e32 v54, 0xbfb8aa3b, v54
	v_mul_f32_e32 v50, 0xbfb8aa3b, v50
	v_pk_mul_f32 v[46:47], v[46:47], v[196:197] op_sel_hi:[1,0]
	v_pk_mul_f32 v[42:43], v[42:43], v[196:197] op_sel_hi:[1,0]
	v_mul_f32_e32 v46, 0xbfb8aa3b, v46
	v_mul_f32_e32 v42, 0xbfb8aa3b, v42
	v_pk_mul_f32 v[38:39], v[38:39], v[196:197] op_sel_hi:[1,0]
	v_pk_mul_f32 v[34:35], v[34:35], v[196:197] op_sel_hi:[1,0]
	v_mul_f32_e32 v38, 0xbfb8aa3b, v38
	v_mul_f32_e32 v34, 0xbfb8aa3b, v34
	v_pk_mul_f32 v[30:31], v[30:31], v[188:189] op_sel_hi:[1,0]
	v_pk_mul_f32 v[26:27], v[26:27], v[188:189] op_sel_hi:[1,0]
	v_mul_f32_e32 v30, 0xbfb8aa3b, v30
	s_waitcnt vmcnt(7)
	v_lshlrev_b32_e32 v152, 16, v126
	v_and_b32_e32 v153, 0xffff0000, v126
	v_lshlrev_b32_e32 v126, 16, v127
	v_and_b32_e32 v127, 0xffff0000, v127
	v_pk_mul_f32 v[126:127], v[206:207], v[126:127] op_sel_hi:[0,1]
	s_waitcnt vmcnt(5)
	v_lshlrev_b32_e32 v156, 16, v130
	v_and_b32_e32 v157, 0xffff0000, v130
	v_lshlrev_b32_e32 v130, 16, v131
	v_and_b32_e32 v131, 0xffff0000, v131
	v_pk_mul_f32 v[126:127], v[80:81], v[126:127]
	v_lshlrev_b32_e32 v154, 16, v128
	v_pk_fma_f32 v[110:111], v[110:111], v[126:127], v[130:131]
	v_exp_f32_e32 v126, v106
	v_mul_f32_e32 v106, 0xbfb8aa3b, v107
	v_exp_f32_e32 v127, v106
	v_pk_mul_f32 v[106:107], v[108:109], v[208:209] op_sel_hi:[1,0]
	v_add_f32_e32 v108, 1.0, v126
	v_mul_f32_e32 v106, 0xbfb8aa3b, v106
	v_mul_f32_e32 v107, 0xbfb8aa3b, v107
	v_exp_f32_e32 v106, v106
	v_exp_f32_e32 v107, v107
	v_add_f32_e32 v109, 1.0, v127
	v_rcp_f32_e32 v108, v108
	v_add_f32_e32 v106, 1.0, v106
	v_add_f32_e32 v107, 1.0, v107
	v_rcp_f32_e32 v109, v109
	v_rcp_f32_e32 v106, v106
	v_rcp_f32_e32 v107, v107
	v_and_b32_e32 v155, 0xffff0000, v128
	v_lshlrev_b32_e32 v128, 16, v129
	v_and_b32_e32 v129, 0xffff0000, v129
	v_pk_mul_f32 v[152:153], v[206:207], v[152:153] op_sel_hi:[0,1]
	v_pk_mul_f32 v[152:153], v[78:79], v[152:153]
	v_pk_mul_f32 v[126:127], v[206:207], v[128:129] op_sel_hi:[0,1]
	v_pk_mul_f32 v[128:129], v[206:207], v[154:155] op_sel_hi:[0,1]
	v_lshlrev_b32_e32 v158, 16, v132
	v_and_b32_e32 v159, 0xffff0000, v132
	v_lshlrev_b32_e32 v132, 16, v133
	v_and_b32_e32 v133, 0xffff0000, v133
	v_pk_fma_f32 v[112:113], v[112:113], v[152:153], v[156:157]
	v_pk_mul_f32 v[128:129], v[74:75], v[128:129]
	v_pk_mul_f32 v[126:127], v[76:77], v[126:127]
	v_pk_fma_f32 v[108:109], v[108:109], v[128:129], v[158:159]
	v_pk_fma_f32 v[126:127], v[106:107], v[126:127], v[132:133]
	v_cvt_pk_bf16_f32 v106, v112, v113
	v_lshlrev_b32_e32 v112, 16, v136
	v_and_b32_e32 v113, 0xffff0000, v136
	v_exp_f32_e32 v136, v102
	v_mul_f32_e32 v102, 0xbfb8aa3b, v103
	v_cvt_pk_bf16_f32 v108, v108, v109
	v_cvt_pk_bf16_f32 v109, v126, v127
	v_lshlrev_b32_e32 v126, 16, v137
	v_and_b32_e32 v127, 0xffff0000, v137
	v_exp_f32_e32 v137, v102
	v_cvt_pk_bf16_f32 v107, v110, v111
	v_lshl_add_u64 v[110:111], s[10:11], 0, v[150:151]
	v_pk_mul_f32 v[102:103], v[104:105], v[208:209] op_sel_hi:[1,0]
	v_add_f32_e32 v104, 1.0, v136
	v_add_f32_e32 v105, 1.0, v137
	v_lshl_add_u64 v[110:111], v[110:111], 0, v[184:185]
	v_rcp_f32_e32 v104, v104
	v_rcp_f32_e32 v105, v105
	global_store_dwordx4 v[110:111], v[106:109], off
	s_waitcnt vmcnt(5)
	v_lshlrev_b32_e32 v128, 16, v138
	v_and_b32_e32 v129, 0xffff0000, v138
	v_lshlrev_b32_e32 v106, 16, v134
	v_and_b32_e32 v107, 0xffff0000, v134
	v_pk_mul_f32 v[106:107], v[206:207], v[106:107] op_sel_hi:[0,1]
	v_pk_mul_f32 v[106:107], v[66:67], v[106:107]
	v_mul_f32_e32 v102, 0xbfb8aa3b, v102
	v_mul_f32_e32 v103, 0xbfb8aa3b, v103
	v_pk_fma_f32 v[104:105], v[104:105], v[106:107], v[128:129]
	v_exp_f32_e32 v106, v98
	v_mul_f32_e32 v98, 0xbfb8aa3b, v99
	v_exp_f32_e32 v102, v102
	v_exp_f32_e32 v103, v103
	v_exp_f32_e32 v107, v98
	v_pk_mul_f32 v[98:99], v[100:101], v[208:209] op_sel_hi:[1,0]
	v_add_f32_e32 v102, 1.0, v102
	v_mul_f32_e32 v98, 0xbfb8aa3b, v98
	v_mul_f32_e32 v99, 0xbfb8aa3b, v99
	v_exp_f32_e32 v98, v98
	v_exp_f32_e32 v99, v99
	v_add_f32_e32 v103, 1.0, v103
	v_rcp_f32_e32 v102, v102
	v_rcp_f32_e32 v103, v103
	v_lshlrev_b32_e32 v108, 16, v135
	v_and_b32_e32 v109, 0xffff0000, v135
	v_add_f32_e32 v100, 1.0, v106
	v_add_f32_e32 v101, 1.0, v107
	v_add_f32_e32 v98, 1.0, v98
	v_add_f32_e32 v99, 1.0, v99
	v_pk_mul_f32 v[106:107], v[206:207], v[126:127] op_sel_hi:[0,1]
	v_exp_f32_e32 v126, v94
	v_mul_f32_e32 v94, 0xbfb8aa3b, v95
	v_pk_mul_f32 v[108:109], v[206:207], v[108:109] op_sel_hi:[0,1]
	v_rcp_f32_e32 v100, v100
	v_rcp_f32_e32 v101, v101
	v_rcp_f32_e32 v98, v98
	v_rcp_f32_e32 v99, v99
	v_exp_f32_e32 v127, v94
	v_lshlrev_b32_e32 v130, 16, v139
	v_and_b32_e32 v131, 0xffff0000, v139
	v_pk_mul_f32 v[108:109], v[68:69], v[108:109]
	v_lshlrev_b32_e32 v132, 16, v140
	v_pk_fma_f32 v[102:103], v[102:103], v[108:109], v[130:131]
	v_pk_mul_f32 v[108:109], v[206:207], v[112:113] op_sel_hi:[0,1]
	v_and_b32_e32 v133, 0xffff0000, v140
	v_lshlrev_b32_e32 v134, 16, v141
	v_and_b32_e32 v135, 0xffff0000, v141
	v_pk_mul_f32 v[108:109], v[62:63], v[108:109]
	v_pk_mul_f32 v[106:107], v[64:65], v[106:107]
	v_pk_fma_f32 v[100:101], v[100:101], v[108:109], v[132:133]
	v_pk_fma_f32 v[106:107], v[98:99], v[106:107], v[134:135]
	v_pk_mul_f32 v[94:95], v[96:97], v[204:205] op_sel_hi:[1,0]
	v_add_f32_e32 v96, 1.0, v126
	v_add_f32_e32 v97, 1.0, v127
	v_cvt_pk_bf16_f32 v98, v104, v105
	v_cvt_pk_bf16_f32 v99, v102, v103
	v_cvt_pk_bf16_f32 v100, v100, v101
	v_cvt_pk_bf16_f32 v101, v106, v107
	v_rcp_f32_e32 v96, v96
	v_rcp_f32_e32 v97, v97
	global_store_dwordx4 v[110:111], v[98:101], off offset:256
	v_mul_f32_e32 v94, 0xbfb8aa3b, v94
	v_mul_f32_e32 v95, 0xbfb8aa3b, v95
	s_waitcnt vmcnt(5)
	v_lshlrev_b32_e32 v98, 16, v142
	v_and_b32_e32 v99, 0xffff0000, v142
	v_exp_f32_e32 v94, v94
	v_exp_f32_e32 v95, v95
	v_pk_mul_f32 v[98:99], v[202:203], v[98:99] op_sel_hi:[0,1]
	s_waitcnt vmcnt(3)
	v_lshlrev_b32_e32 v106, 16, v146
	v_and_b32_e32 v107, 0xffff0000, v146
	v_pk_mul_f32 v[98:99], v[78:79], v[98:99]
	v_add_f32_e32 v94, 1.0, v94
	v_pk_fma_f32 v[96:97], v[96:97], v[98:99], v[106:107]
	v_exp_f32_e32 v98, v90
	v_mul_f32_e32 v90, 0xbfb8aa3b, v91
	v_exp_f32_e32 v99, v90
	v_pk_mul_f32 v[90:91], v[92:93], v[204:205] op_sel_hi:[1,0]
	v_add_f32_e32 v95, 1.0, v95
	v_mul_f32_e32 v90, 0xbfb8aa3b, v90
	v_mul_f32_e32 v91, 0xbfb8aa3b, v91
	v_rcp_f32_e32 v94, v94
	v_rcp_f32_e32 v95, v95
	v_exp_f32_e32 v90, v90
	v_exp_f32_e32 v91, v91
	v_lshlrev_b32_e32 v100, 16, v143
	v_and_b32_e32 v101, 0xffff0000, v143
	v_pk_mul_f32 v[100:101], v[202:203], v[100:101] op_sel_hi:[0,1]
	v_lshlrev_b32_e32 v108, 16, v147
	v_and_b32_e32 v109, 0xffff0000, v147
	v_pk_mul_f32 v[100:101], v[80:81], v[100:101]
	v_add_f32_e32 v92, 1.0, v98
	v_pk_fma_f32 v[94:95], v[94:95], v[100:101], v[108:109]
	v_add_f32_e32 v93, 1.0, v99
	v_add_f32_e32 v90, 1.0, v90
	v_add_f32_e32 v91, 1.0, v91
	v_exp_f32_e32 v108, v86
	v_mul_f32_e32 v86, 0xbfb8aa3b, v87
	v_rcp_f32_e32 v92, v92
	v_rcp_f32_e32 v93, v93
	v_rcp_f32_e32 v90, v90
	v_rcp_f32_e32 v91, v91
	v_exp_f32_e32 v109, v86
	v_lshlrev_b32_e32 v102, 16, v144
	v_and_b32_e32 v103, 0xffff0000, v144
	v_lshlrev_b32_e32 v104, 16, v145
	v_and_b32_e32 v105, 0xffff0000, v145
	v_pk_mul_f32 v[98:99], v[202:203], v[104:105] op_sel_hi:[0,1]
	v_pk_mul_f32 v[100:101], v[202:203], v[102:103] op_sel_hi:[0,1]
	v_lshlrev_b32_e32 v110, 16, v148
	v_and_b32_e32 v111, 0xffff0000, v148
	v_lshlrev_b32_e32 v112, 16, v149
	v_and_b32_e32 v113, 0xffff0000, v149
	v_pk_mul_f32 v[100:101], v[74:75], v[100:101]
	v_pk_mul_f32 v[98:99], v[76:77], v[98:99]
	v_pk_fma_f32 v[92:93], v[92:93], v[100:101], v[110:111]
	v_pk_fma_f32 v[98:99], v[90:91], v[98:99], v[112:113]
	v_cvt_pk_bf16_f32 v91, v94, v95
	v_lshl_add_u64 v[94:95], s[10:11], 0, v[124:125]
	v_pk_mul_f32 v[86:87], v[88:89], v[204:205] op_sel_hi:[1,0]
	v_add_f32_e32 v88, 1.0, v108
	v_add_f32_e32 v89, 1.0, v109
	v_cvt_pk_bf16_f32 v90, v96, v97
	v_cvt_pk_bf16_f32 v92, v92, v93
	v_cvt_pk_bf16_f32 v93, v98, v99
	v_lshl_add_u64 v[94:95], v[94:95], 0, v[184:185]
	v_rcp_f32_e32 v88, v88
	v_rcp_f32_e32 v89, v89
	global_store_dwordx4 v[94:95], v[90:93], off
	s_waitcnt vmcnt(3)
	v_lshlrev_b32_e32 v100, 16, v114
	v_and_b32_e32 v101, 0xffff0000, v114
	v_lshlrev_b32_e32 v90, 16, v118
	v_and_b32_e32 v91, 0xffff0000, v118
	v_pk_mul_f32 v[90:91], v[202:203], v[90:91] op_sel_hi:[0,1]
	v_pk_mul_f32 v[90:91], v[66:67], v[90:91]
	v_mul_f32_e32 v86, 0xbfb8aa3b, v86
	v_mul_f32_e32 v87, 0xbfb8aa3b, v87
	v_pk_fma_f32 v[88:89], v[88:89], v[90:91], v[100:101]
	v_exp_f32_e32 v90, v82
	v_mul_f32_e32 v82, 0xbfb8aa3b, v83
	v_exp_f32_e32 v86, v86
	v_exp_f32_e32 v87, v87
	v_exp_f32_e32 v91, v82
	v_pk_mul_f32 v[82:83], v[84:85], v[204:205] op_sel_hi:[1,0]
	v_add_f32_e32 v86, 1.0, v86
	v_mul_f32_e32 v82, 0xbfb8aa3b, v82
	v_mul_f32_e32 v83, 0xbfb8aa3b, v83
	v_exp_f32_e32 v82, v82
	v_exp_f32_e32 v83, v83
	v_add_f32_e32 v87, 1.0, v87
	v_rcp_f32_e32 v86, v86
	v_rcp_f32_e32 v87, v87
	v_lshlrev_b32_e32 v92, 16, v119
	v_and_b32_e32 v93, 0xffff0000, v119
	v_add_f32_e32 v84, 1.0, v90
	v_add_f32_e32 v85, 1.0, v91
	v_add_f32_e32 v82, 1.0, v82
	v_add_f32_e32 v83, 1.0, v83
	v_pk_mul_f32 v[92:93], v[202:203], v[92:93] op_sel_hi:[0,1]
	v_rcp_f32_e32 v84, v84
	v_rcp_f32_e32 v85, v85
	v_rcp_f32_e32 v82, v82
	v_rcp_f32_e32 v83, v83
	v_lshlrev_b32_e32 v96, 16, v120
	v_and_b32_e32 v97, 0xffff0000, v120
	v_lshlrev_b32_e32 v98, 16, v121
	v_and_b32_e32 v99, 0xffff0000, v121
	v_lshlrev_b32_e32 v102, 16, v115
	v_and_b32_e32 v103, 0xffff0000, v115
	v_pk_mul_f32 v[92:93], v[68:69], v[92:93]
	v_pk_mul_f32 v[90:91], v[202:203], v[98:99] op_sel_hi:[0,1]
	v_pk_fma_f32 v[86:87], v[86:87], v[92:93], v[102:103]
	v_pk_mul_f32 v[92:93], v[202:203], v[96:97] op_sel_hi:[0,1]
	v_lshlrev_b32_e32 v104, 16, v116
	v_and_b32_e32 v105, 0xffff0000, v116
	v_lshlrev_b32_e32 v106, 16, v117
	v_and_b32_e32 v107, 0xffff0000, v117
	v_pk_mul_f32 v[92:93], v[62:63], v[92:93]
	v_pk_mul_f32 v[90:91], v[64:65], v[90:91]
	v_pk_fma_f32 v[84:85], v[84:85], v[92:93], v[104:105]
	v_pk_fma_f32 v[90:91], v[82:83], v[90:91], v[106:107]
	v_cvt_pk_bf16_f32 v82, v88, v89
	v_cvt_pk_bf16_f32 v83, v86, v87
	v_cvt_pk_bf16_f32 v84, v84, v85
	v_cvt_pk_bf16_f32 v85, v90, v91
	global_store_dwordx4 v[94:95], v[82:85], off offset:256
	v_lshlrev_b64 v[118:119], 13, v[122:123]
	v_lshlrev_b32_e32 v86, 7, v122
	v_lshrrev_b64 v[84:85], 1, v[122:123]
	v_lshl_add_u64 v[82:83], s[8:9], 0, v[118:119]
	v_and_b32_e32 v85, 0x7fffffff, v85
	v_and_b32_e32 v84, 0xffffffc0, v84
	v_lshl_add_u64 v[82:83], v[82:83], 0, v[184:185]
	v_and_b32_e32 v170, 0x3f80, v86
	v_lshl_add_u64 v[88:89], v[84:85], 0, s[26:27]
	global_load_dwordx4 v[94:97], v[82:83], off
	global_load_dwordx4 v[102:105], v[82:83], off offset:256
	v_lshl_add_u64 v[86:87], v[192:193], 0, v[170:171]
	v_lshlrev_b64 v[88:89], 14, v[88:89]
	v_lshl_add_u64 v[88:89], v[86:87], 0, v[88:89]
	global_load_dwordx4 v[98:101], v[88:89], off
	v_lshl_add_u64 v[82:83], v[84:85], 0, s[28:29]
	v_lshlrev_b64 v[82:83], 14, v[82:83]
	v_lshl_add_u64 v[82:83], v[86:87], 0, v[82:83]
	global_load_dwordx4 v[106:109], v[82:83], off
	v_add_u32_e32 v88, 0x90, v190
	v_ashrrev_i32_e32 v89, 31, v88
	v_lshrrev_b64 v[84:85], 1, v[88:89]
	v_lshlrev_b64 v[92:93], 13, v[88:89]
	v_and_b32_e32 v85, 0x7fffffff, v85
	v_and_b32_e32 v84, 0xffffffc0, v84
	v_lshlrev_b32_e32 v86, 7, v88
	v_lshl_add_u64 v[82:83], s[8:9], 0, v[92:93]
	v_and_b32_e32 v170, 0x3f80, v86
	v_lshl_add_u64 v[86:87], v[84:85], 0, s[26:27]
	v_lshl_add_u64 v[114:115], v[192:193], 0, v[170:171]
	v_lshl_add_u64 v[82:83], v[82:83], 0, v[184:185]
	v_lshlrev_b64 v[86:87], 14, v[86:87]
	v_lshl_add_u64 v[116:117], v[114:115], 0, v[86:87]
	global_load_dwordx4 v[110:113], v[82:83], off
	global_load_dwordx4 v[86:89], v[82:83], off offset:256
	v_lshl_add_u64 v[82:83], v[84:85], 0, s[28:29]
	v_lshlrev_b64 v[82:83], 14, v[82:83]
	v_lshl_add_u64 v[82:83], v[114:115], 0, v[82:83]
	global_load_dwordx4 v[114:117], v[116:117], off
	s_nop 0
	global_load_dwordx4 v[82:85], v[82:83], off
	v_exp_f32_e32 v128, v70
	v_mul_f32_e32 v70, 0xbfb8aa3b, v71
	v_exp_f32_e32 v129, v70
	v_pk_mul_f32 v[70:71], v[72:73], v[200:201] op_sel_hi:[1,0]
	v_add_f32_e32 v72, 1.0, v128
	v_mul_f32_e32 v70, 0xbfb8aa3b, v70
	v_mul_f32_e32 v71, 0xbfb8aa3b, v71
	v_exp_f32_e32 v70, v70
	v_exp_f32_e32 v71, v71
	v_add_f32_e32 v73, 1.0, v129
	v_rcp_f32_e32 v72, v72
	v_add_f32_e32 v70, 1.0, v70
	v_add_f32_e32 v71, 1.0, v71
	v_rcp_f32_e32 v70, v70
	v_rcp_f32_e32 v71, v71
	v_rcp_f32_e32 v73, v73
	v_add_u32_e32 v90, 0xa0, v190
	v_ashrrev_i32_e32 v91, 31, v90
	v_mul_f32_e32 v26, 0xbfb8aa3b, v26
	v_pk_mul_f32 v[22:23], v[22:23], v[188:189] op_sel_hi:[1,0]
	v_pk_mul_f32 v[18:19], v[18:19], v[188:189] op_sel_hi:[1,0]
	v_mul_f32_e32 v22, 0xbfb8aa3b, v22
	v_mul_f32_e32 v18, 0xbfb8aa3b, v18
	v_pk_mul_f32 v[14:15], v[14:15], v[182:183] op_sel_hi:[1,0]
	v_pk_mul_f32 v[10:11], v[10:11], v[182:183] op_sel_hi:[1,0]
	v_mul_f32_e32 v14, 0xbfb8aa3b, v14
	v_mul_f32_e32 v10, 0xbfb8aa3b, v10
	v_pk_mul_f32 v[6:7], v[6:7], v[182:183] op_sel_hi:[1,0]
	v_pk_mul_f32 v[2:3], v[2:3], v[182:183] op_sel_hi:[1,0]
	v_mul_f32_e32 v6, 0xbfb8aa3b, v6
	v_mul_f32_e32 v2, 0xbfb8aa3b, v2
	s_waitcnt vmcnt(7)
	v_lshlrev_b32_e32 v120, 16, v94
	v_and_b32_e32 v121, 0xffff0000, v94
	v_lshlrev_b32_e32 v94, 16, v95
	v_and_b32_e32 v95, 0xffff0000, v95
	v_pk_mul_f32 v[94:95], v[198:199], v[94:95] op_sel_hi:[0,1]
	s_waitcnt vmcnt(5)
	v_lshlrev_b32_e32 v124, 16, v98
	v_and_b32_e32 v125, 0xffff0000, v98
	v_lshlrev_b32_e32 v98, 16, v99
	v_and_b32_e32 v99, 0xffff0000, v99
	v_pk_mul_f32 v[94:95], v[80:81], v[94:95]
	v_lshlrev_b32_e32 v122, 16, v96
	v_pk_fma_f32 v[70:71], v[70:71], v[94:95], v[98:99]
	v_exp_f32_e32 v94, v58
	v_mul_f32_e32 v58, 0xbfb8aa3b, v59
	v_exp_f32_e32 v95, v58
	v_pk_mul_f32 v[58:59], v[60:61], v[200:201] op_sel_hi:[1,0]
	v_add_f32_e32 v60, 1.0, v94
	v_mul_f32_e32 v58, 0xbfb8aa3b, v58
	v_mul_f32_e32 v59, 0xbfb8aa3b, v59
	v_exp_f32_e32 v58, v58
	v_exp_f32_e32 v59, v59
	v_add_f32_e32 v61, 1.0, v95
	v_rcp_f32_e32 v60, v60
	v_add_f32_e32 v58, 1.0, v58
	v_add_f32_e32 v59, 1.0, v59
	v_rcp_f32_e32 v61, v61
	v_rcp_f32_e32 v58, v58
	v_rcp_f32_e32 v59, v59
	v_and_b32_e32 v123, 0xffff0000, v96
	v_lshlrev_b32_e32 v96, 16, v97
	v_and_b32_e32 v97, 0xffff0000, v97
	v_pk_mul_f32 v[120:121], v[198:199], v[120:121] op_sel_hi:[0,1]
	v_pk_mul_f32 v[120:121], v[78:79], v[120:121]
	v_pk_mul_f32 v[94:95], v[198:199], v[96:97] op_sel_hi:[0,1]
	v_pk_mul_f32 v[96:97], v[198:199], v[122:123] op_sel_hi:[0,1]
	v_lshlrev_b32_e32 v126, 16, v100
	v_and_b32_e32 v127, 0xffff0000, v100
	v_lshlrev_b32_e32 v100, 16, v101
	v_and_b32_e32 v101, 0xffff0000, v101
	v_pk_fma_f32 v[72:73], v[72:73], v[120:121], v[124:125]
	v_pk_mul_f32 v[96:97], v[74:75], v[96:97]
	v_pk_mul_f32 v[94:95], v[76:77], v[94:95]
	v_pk_fma_f32 v[60:61], v[60:61], v[96:97], v[126:127]
	v_pk_fma_f32 v[94:95], v[58:59], v[94:95], v[100:101]
	v_cvt_pk_bf16_f32 v58, v72, v73
	v_lshlrev_b32_e32 v72, 16, v104
	v_and_b32_e32 v73, 0xffff0000, v104
	v_exp_f32_e32 v104, v54
	v_mul_f32_e32 v54, 0xbfb8aa3b, v55
	v_cvt_pk_bf16_f32 v60, v60, v61
	v_cvt_pk_bf16_f32 v61, v94, v95
	v_lshlrev_b32_e32 v94, 16, v105
	v_and_b32_e32 v95, 0xffff0000, v105
	v_exp_f32_e32 v105, v54
	v_cvt_pk_bf16_f32 v59, v70, v71
	v_lshl_add_u64 v[70:71], s[10:11], 0, v[118:119]
	v_pk_mul_f32 v[54:55], v[56:57], v[200:201] op_sel_hi:[1,0]
	v_add_f32_e32 v56, 1.0, v104
	v_add_f32_e32 v57, 1.0, v105
	v_lshl_add_u64 v[70:71], v[70:71], 0, v[184:185]
	v_rcp_f32_e32 v56, v56
	v_rcp_f32_e32 v57, v57
	global_store_dwordx4 v[70:71], v[58:61], off
	s_waitcnt vmcnt(5)
	v_lshlrev_b32_e32 v96, 16, v106
	v_and_b32_e32 v97, 0xffff0000, v106
	v_lshlrev_b32_e32 v58, 16, v102
	v_and_b32_e32 v59, 0xffff0000, v102
	v_pk_mul_f32 v[58:59], v[198:199], v[58:59] op_sel_hi:[0,1]
	v_pk_mul_f32 v[58:59], v[66:67], v[58:59]
	v_mul_f32_e32 v54, 0xbfb8aa3b, v54
	v_mul_f32_e32 v55, 0xbfb8aa3b, v55
	v_pk_fma_f32 v[56:57], v[56:57], v[58:59], v[96:97]
	v_exp_f32_e32 v58, v50
	v_mul_f32_e32 v50, 0xbfb8aa3b, v51
	v_exp_f32_e32 v54, v54
	v_exp_f32_e32 v55, v55
	v_exp_f32_e32 v59, v50
	v_pk_mul_f32 v[50:51], v[52:53], v[200:201] op_sel_hi:[1,0]
	v_add_f32_e32 v54, 1.0, v54
	v_mul_f32_e32 v50, 0xbfb8aa3b, v50
	v_mul_f32_e32 v51, 0xbfb8aa3b, v51
	v_exp_f32_e32 v50, v50
	v_exp_f32_e32 v51, v51
	v_add_f32_e32 v55, 1.0, v55
	v_rcp_f32_e32 v54, v54
	v_rcp_f32_e32 v55, v55
	v_lshlrev_b32_e32 v60, 16, v103
	v_and_b32_e32 v61, 0xffff0000, v103
	v_add_f32_e32 v52, 1.0, v58
	v_add_f32_e32 v53, 1.0, v59
	v_add_f32_e32 v50, 1.0, v50
	v_add_f32_e32 v51, 1.0, v51
	v_pk_mul_f32 v[58:59], v[198:199], v[94:95] op_sel_hi:[0,1]
	v_exp_f32_e32 v94, v46
	v_mul_f32_e32 v46, 0xbfb8aa3b, v47
	v_pk_mul_f32 v[60:61], v[198:199], v[60:61] op_sel_hi:[0,1]
	v_rcp_f32_e32 v52, v52
	v_rcp_f32_e32 v53, v53
	v_rcp_f32_e32 v50, v50
	v_rcp_f32_e32 v51, v51
	v_exp_f32_e32 v95, v46
	v_lshlrev_b32_e32 v98, 16, v107
	v_and_b32_e32 v99, 0xffff0000, v107
	v_pk_mul_f32 v[60:61], v[68:69], v[60:61]
	v_lshlrev_b32_e32 v100, 16, v108
	v_pk_fma_f32 v[54:55], v[54:55], v[60:61], v[98:99]
	v_pk_mul_f32 v[60:61], v[198:199], v[72:73] op_sel_hi:[0,1]
	v_and_b32_e32 v101, 0xffff0000, v108
	v_lshlrev_b32_e32 v102, 16, v109
	v_and_b32_e32 v103, 0xffff0000, v109
	v_pk_mul_f32 v[60:61], v[62:63], v[60:61]
	v_pk_mul_f32 v[58:59], v[64:65], v[58:59]
	v_pk_fma_f32 v[52:53], v[52:53], v[60:61], v[100:101]
	v_pk_fma_f32 v[58:59], v[50:51], v[58:59], v[102:103]
	v_pk_mul_f32 v[46:47], v[48:49], v[196:197] op_sel_hi:[1,0]
	v_add_f32_e32 v48, 1.0, v94
	v_add_f32_e32 v49, 1.0, v95
	v_cvt_pk_bf16_f32 v50, v56, v57
	v_cvt_pk_bf16_f32 v51, v54, v55
	v_cvt_pk_bf16_f32 v52, v52, v53
	v_cvt_pk_bf16_f32 v53, v58, v59
	v_rcp_f32_e32 v48, v48
	v_rcp_f32_e32 v49, v49
	global_store_dwordx4 v[70:71], v[50:53], off offset:256
	v_mul_f32_e32 v46, 0xbfb8aa3b, v46
	v_mul_f32_e32 v47, 0xbfb8aa3b, v47
	s_waitcnt vmcnt(5)
	v_lshlrev_b32_e32 v50, 16, v110
	v_and_b32_e32 v51, 0xffff0000, v110
	v_exp_f32_e32 v46, v46
	v_exp_f32_e32 v47, v47
	v_pk_mul_f32 v[50:51], v[194:195], v[50:51] op_sel_hi:[0,1]
	s_waitcnt vmcnt(3)
	v_lshlrev_b32_e32 v58, 16, v114
	v_and_b32_e32 v59, 0xffff0000, v114
	v_pk_mul_f32 v[50:51], v[78:79], v[50:51]
	v_add_f32_e32 v46, 1.0, v46
	v_pk_fma_f32 v[48:49], v[48:49], v[50:51], v[58:59]
	v_exp_f32_e32 v50, v42
	v_mul_f32_e32 v42, 0xbfb8aa3b, v43
	v_exp_f32_e32 v51, v42
	v_pk_mul_f32 v[42:43], v[44:45], v[196:197] op_sel_hi:[1,0]
	v_add_f32_e32 v47, 1.0, v47
	v_mul_f32_e32 v42, 0xbfb8aa3b, v42
	v_mul_f32_e32 v43, 0xbfb8aa3b, v43
	v_rcp_f32_e32 v46, v46
	v_rcp_f32_e32 v47, v47
	v_exp_f32_e32 v42, v42
	v_exp_f32_e32 v43, v43
	v_lshlrev_b32_e32 v52, 16, v111
	v_and_b32_e32 v53, 0xffff0000, v111
	v_pk_mul_f32 v[52:53], v[194:195], v[52:53] op_sel_hi:[0,1]
	v_lshlrev_b32_e32 v60, 16, v115
	v_and_b32_e32 v61, 0xffff0000, v115
	v_pk_mul_f32 v[52:53], v[80:81], v[52:53]
	v_add_f32_e32 v44, 1.0, v50
	v_pk_fma_f32 v[46:47], v[46:47], v[52:53], v[60:61]
	v_add_f32_e32 v45, 1.0, v51
	v_add_f32_e32 v42, 1.0, v42
	v_add_f32_e32 v43, 1.0, v43
	v_exp_f32_e32 v60, v38
	v_mul_f32_e32 v38, 0xbfb8aa3b, v39
	v_rcp_f32_e32 v44, v44
	v_rcp_f32_e32 v45, v45
	v_rcp_f32_e32 v42, v42
	v_rcp_f32_e32 v43, v43
	v_exp_f32_e32 v61, v38
	v_lshlrev_b32_e32 v54, 16, v112
	v_and_b32_e32 v55, 0xffff0000, v112
	v_lshlrev_b32_e32 v56, 16, v113
	v_and_b32_e32 v57, 0xffff0000, v113
	v_pk_mul_f32 v[50:51], v[194:195], v[56:57] op_sel_hi:[0,1]
	v_pk_mul_f32 v[52:53], v[194:195], v[54:55] op_sel_hi:[0,1]
	v_lshlrev_b32_e32 v70, 16, v116
	v_and_b32_e32 v71, 0xffff0000, v116
	v_lshlrev_b32_e32 v72, 16, v117
	v_and_b32_e32 v73, 0xffff0000, v117
	v_pk_mul_f32 v[52:53], v[74:75], v[52:53]
	v_pk_mul_f32 v[50:51], v[76:77], v[50:51]
	v_pk_fma_f32 v[44:45], v[44:45], v[52:53], v[70:71]
	v_pk_fma_f32 v[50:51], v[42:43], v[50:51], v[72:73]
	v_cvt_pk_bf16_f32 v43, v46, v47
	v_lshl_add_u64 v[46:47], s[10:11], 0, v[92:93]
	v_pk_mul_f32 v[38:39], v[40:41], v[196:197] op_sel_hi:[1,0]
	v_add_f32_e32 v40, 1.0, v60
	v_add_f32_e32 v41, 1.0, v61
	v_cvt_pk_bf16_f32 v42, v48, v49
	v_cvt_pk_bf16_f32 v44, v44, v45
	v_cvt_pk_bf16_f32 v45, v50, v51
	v_lshl_add_u64 v[46:47], v[46:47], 0, v[184:185]
	v_rcp_f32_e32 v40, v40
	v_rcp_f32_e32 v41, v41
	global_store_dwordx4 v[46:47], v[42:45], off
	s_waitcnt vmcnt(3)
	v_lshlrev_b32_e32 v52, 16, v82
	v_and_b32_e32 v53, 0xffff0000, v82
	v_lshlrev_b32_e32 v42, 16, v86
	v_and_b32_e32 v43, 0xffff0000, v86
	v_pk_mul_f32 v[42:43], v[194:195], v[42:43] op_sel_hi:[0,1]
	v_pk_mul_f32 v[42:43], v[66:67], v[42:43]
	v_mul_f32_e32 v38, 0xbfb8aa3b, v38
	v_mul_f32_e32 v39, 0xbfb8aa3b, v39
	v_pk_fma_f32 v[40:41], v[40:41], v[42:43], v[52:53]
	v_exp_f32_e32 v42, v34
	v_mul_f32_e32 v34, 0xbfb8aa3b, v35
	v_exp_f32_e32 v38, v38
	v_exp_f32_e32 v39, v39
	v_exp_f32_e32 v43, v34
	v_pk_mul_f32 v[34:35], v[36:37], v[196:197] op_sel_hi:[1,0]
	v_add_f32_e32 v38, 1.0, v38
	v_mul_f32_e32 v34, 0xbfb8aa3b, v34
	v_mul_f32_e32 v35, 0xbfb8aa3b, v35
	v_exp_f32_e32 v34, v34
	v_exp_f32_e32 v35, v35
	v_add_f32_e32 v39, 1.0, v39
	v_rcp_f32_e32 v38, v38
	v_rcp_f32_e32 v39, v39
	v_lshlrev_b32_e32 v44, 16, v87
	v_and_b32_e32 v45, 0xffff0000, v87
	v_add_f32_e32 v36, 1.0, v42
	v_add_f32_e32 v37, 1.0, v43
	v_add_f32_e32 v34, 1.0, v34
	v_add_f32_e32 v35, 1.0, v35
	v_pk_mul_f32 v[44:45], v[194:195], v[44:45] op_sel_hi:[0,1]
	v_rcp_f32_e32 v36, v36
	v_rcp_f32_e32 v37, v37
	v_rcp_f32_e32 v34, v34
	v_rcp_f32_e32 v35, v35
	v_lshlrev_b32_e32 v48, 16, v88
	v_and_b32_e32 v49, 0xffff0000, v88
	v_lshlrev_b32_e32 v50, 16, v89
	v_and_b32_e32 v51, 0xffff0000, v89
	v_lshlrev_b32_e32 v54, 16, v83
	v_and_b32_e32 v55, 0xffff0000, v83
	v_pk_mul_f32 v[44:45], v[68:69], v[44:45]
	v_pk_mul_f32 v[42:43], v[194:195], v[50:51] op_sel_hi:[0,1]
	v_pk_fma_f32 v[38:39], v[38:39], v[44:45], v[54:55]
	v_pk_mul_f32 v[44:45], v[194:195], v[48:49] op_sel_hi:[0,1]
	v_lshlrev_b32_e32 v56, 16, v84
	v_and_b32_e32 v57, 0xffff0000, v84
	v_lshlrev_b32_e32 v58, 16, v85
	v_and_b32_e32 v59, 0xffff0000, v85
	v_pk_mul_f32 v[44:45], v[62:63], v[44:45]
	v_pk_mul_f32 v[42:43], v[64:65], v[42:43]
	v_pk_fma_f32 v[36:37], v[36:37], v[44:45], v[56:57]
	v_pk_fma_f32 v[42:43], v[34:35], v[42:43], v[58:59]
	v_cvt_pk_bf16_f32 v34, v40, v41
	v_cvt_pk_bf16_f32 v35, v38, v39
	v_cvt_pk_bf16_f32 v36, v36, v37
	v_cvt_pk_bf16_f32 v37, v42, v43
	global_store_dwordx4 v[46:47], v[34:37], off offset:256
	v_lshlrev_b64 v[60:61], 13, v[90:91]
	v_lshlrev_b32_e32 v38, 7, v90
	v_lshrrev_b64 v[36:37], 1, v[90:91]
	v_lshl_add_u64 v[34:35], s[8:9], 0, v[60:61]
	v_and_b32_e32 v37, 0x7fffffff, v37
	v_and_b32_e32 v36, 0xffffffc0, v36
	v_lshl_add_u64 v[34:35], v[34:35], 0, v[184:185]
	v_and_b32_e32 v170, 0x3f80, v38
	v_lshl_add_u64 v[40:41], v[36:37], 0, s[26:27]
	global_load_dwordx4 v[44:47], v[34:35], off
	global_load_dwordx4 v[52:55], v[34:35], off offset:256
	v_lshl_add_u64 v[38:39], v[192:193], 0, v[170:171]
	v_lshlrev_b64 v[40:41], 14, v[40:41]
	v_lshl_add_u64 v[40:41], v[38:39], 0, v[40:41]
	global_load_dwordx4 v[48:51], v[40:41], off
	v_lshl_add_u64 v[34:35], v[36:37], 0, s[28:29]
	v_lshlrev_b64 v[34:35], 14, v[34:35]
	v_lshl_add_u64 v[34:35], v[38:39], 0, v[34:35]
	global_load_dwordx4 v[56:59], v[34:35], off
	v_add_u32_e32 v40, 0xb0, v190
	v_ashrrev_i32_e32 v41, 31, v40
	v_lshrrev_b64 v[36:37], 1, v[40:41]
	v_lshlrev_b64 v[42:43], 13, v[40:41]
	v_and_b32_e32 v37, 0x7fffffff, v37
	v_and_b32_e32 v36, 0xffffffc0, v36
	v_lshlrev_b32_e32 v38, 7, v40
	v_lshl_add_u64 v[34:35], s[8:9], 0, v[42:43]
	v_and_b32_e32 v170, 0x3f80, v38
	v_lshl_add_u64 v[38:39], v[36:37], 0, s[26:27]
	v_lshl_add_u64 v[82:83], v[192:193], 0, v[170:171]
	v_lshl_add_u64 v[34:35], v[34:35], 0, v[184:185]
	v_lshlrev_b64 v[38:39], 14, v[38:39]
	v_lshl_add_u64 v[84:85], v[82:83], 0, v[38:39]
	global_load_dwordx4 v[70:73], v[34:35], off
	global_load_dwordx4 v[38:41], v[34:35], off offset:256
	v_lshl_add_u64 v[34:35], v[36:37], 0, s[28:29]
	v_lshlrev_b64 v[34:35], 14, v[34:35]
	v_lshl_add_u64 v[34:35], v[82:83], 0, v[34:35]
	global_load_dwordx4 v[82:85], v[84:85], off
	s_nop 0
	global_load_dwordx4 v[34:37], v[34:35], off
	v_exp_f32_e32 v94, v30
	v_mul_f32_e32 v30, 0xbfb8aa3b, v31
	v_exp_f32_e32 v95, v30
	v_pk_mul_f32 v[30:31], v[32:33], v[188:189] op_sel_hi:[1,0]
	v_add_f32_e32 v32, 1.0, v94
	v_mul_f32_e32 v30, 0xbfb8aa3b, v30
	v_mul_f32_e32 v31, 0xbfb8aa3b, v31
	v_exp_f32_e32 v30, v30
	v_exp_f32_e32 v31, v31
	v_add_f32_e32 v33, 1.0, v95
	v_rcp_f32_e32 v32, v32
	v_add_f32_e32 v30, 1.0, v30
	v_add_f32_e32 v31, 1.0, v31
	v_rcp_f32_e32 v30, v30
	v_rcp_f32_e32 v31, v31
	v_rcp_f32_e32 v33, v33
	s_waitcnt vmcnt(7)
	v_lshlrev_b32_e32 v86, 16, v44
	v_and_b32_e32 v87, 0xffff0000, v44
	v_lshlrev_b32_e32 v44, 16, v45
	v_and_b32_e32 v45, 0xffff0000, v45
	v_pk_mul_f32 v[44:45], v[186:187], v[44:45] op_sel_hi:[0,1]
	s_waitcnt vmcnt(5)
	v_lshlrev_b32_e32 v90, 16, v48
	v_and_b32_e32 v91, 0xffff0000, v48
	v_lshlrev_b32_e32 v48, 16, v49
	v_and_b32_e32 v49, 0xffff0000, v49
	v_pk_mul_f32 v[44:45], v[80:81], v[44:45]
	v_lshlrev_b32_e32 v88, 16, v46
	v_pk_fma_f32 v[30:31], v[30:31], v[44:45], v[48:49]
	v_exp_f32_e32 v44, v26
	v_mul_f32_e32 v26, 0xbfb8aa3b, v27
	v_exp_f32_e32 v45, v26
	v_pk_mul_f32 v[26:27], v[28:29], v[188:189] op_sel_hi:[1,0]
	v_add_f32_e32 v28, 1.0, v44
	v_mul_f32_e32 v26, 0xbfb8aa3b, v26
	v_mul_f32_e32 v27, 0xbfb8aa3b, v27
	v_exp_f32_e32 v26, v26
	v_exp_f32_e32 v27, v27
	v_add_f32_e32 v29, 1.0, v45
	v_rcp_f32_e32 v28, v28
	v_add_f32_e32 v26, 1.0, v26
	v_add_f32_e32 v27, 1.0, v27
	v_rcp_f32_e32 v29, v29
	v_rcp_f32_e32 v26, v26
	v_rcp_f32_e32 v27, v27
	v_and_b32_e32 v89, 0xffff0000, v46
	v_lshlrev_b32_e32 v46, 16, v47
	v_and_b32_e32 v47, 0xffff0000, v47
	v_pk_mul_f32 v[86:87], v[186:187], v[86:87] op_sel_hi:[0,1]
	v_pk_mul_f32 v[86:87], v[78:79], v[86:87]
	v_pk_mul_f32 v[44:45], v[186:187], v[46:47] op_sel_hi:[0,1]
	v_pk_mul_f32 v[46:47], v[186:187], v[88:89] op_sel_hi:[0,1]
	v_lshlrev_b32_e32 v92, 16, v50
	v_and_b32_e32 v93, 0xffff0000, v50
	v_lshlrev_b32_e32 v50, 16, v51
	v_and_b32_e32 v51, 0xffff0000, v51
	v_pk_fma_f32 v[32:33], v[32:33], v[86:87], v[90:91]
	v_pk_mul_f32 v[46:47], v[74:75], v[46:47]
	v_pk_mul_f32 v[44:45], v[76:77], v[44:45]
	v_pk_fma_f32 v[28:29], v[28:29], v[46:47], v[92:93]
	v_pk_fma_f32 v[44:45], v[26:27], v[44:45], v[50:51]
	v_cvt_pk_bf16_f32 v26, v32, v33
	v_lshlrev_b32_e32 v32, 16, v54
	v_and_b32_e32 v33, 0xffff0000, v54
	v_exp_f32_e32 v54, v22
	v_mul_f32_e32 v22, 0xbfb8aa3b, v23
	v_cvt_pk_bf16_f32 v28, v28, v29
	v_cvt_pk_bf16_f32 v29, v44, v45
	v_lshlrev_b32_e32 v44, 16, v55
	v_and_b32_e32 v45, 0xffff0000, v55
	v_exp_f32_e32 v55, v22
	v_cvt_pk_bf16_f32 v27, v30, v31
	v_lshl_add_u64 v[30:31], s[10:11], 0, v[60:61]
	v_pk_mul_f32 v[22:23], v[24:25], v[188:189] op_sel_hi:[1,0]
	v_add_f32_e32 v24, 1.0, v54
	v_add_f32_e32 v25, 1.0, v55
	v_lshl_add_u64 v[30:31], v[30:31], 0, v[184:185]
	v_rcp_f32_e32 v24, v24
	v_rcp_f32_e32 v25, v25
	global_store_dwordx4 v[30:31], v[26:29], off
	s_waitcnt vmcnt(5)
	v_lshlrev_b32_e32 v46, 16, v56
	v_and_b32_e32 v47, 0xffff0000, v56
	v_lshlrev_b32_e32 v26, 16, v52
	v_and_b32_e32 v27, 0xffff0000, v52
	v_pk_mul_f32 v[26:27], v[186:187], v[26:27] op_sel_hi:[0,1]
	v_pk_mul_f32 v[26:27], v[66:67], v[26:27]
	v_mul_f32_e32 v22, 0xbfb8aa3b, v22
	v_mul_f32_e32 v23, 0xbfb8aa3b, v23
	v_pk_fma_f32 v[24:25], v[24:25], v[26:27], v[46:47]
	v_exp_f32_e32 v26, v18
	v_mul_f32_e32 v18, 0xbfb8aa3b, v19
	v_exp_f32_e32 v22, v22
	v_exp_f32_e32 v23, v23
	v_exp_f32_e32 v27, v18
	v_pk_mul_f32 v[18:19], v[20:21], v[188:189] op_sel_hi:[1,0]
	v_add_f32_e32 v22, 1.0, v22
	v_mul_f32_e32 v18, 0xbfb8aa3b, v18
	v_mul_f32_e32 v19, 0xbfb8aa3b, v19
	v_exp_f32_e32 v18, v18
	v_exp_f32_e32 v19, v19
	v_add_f32_e32 v23, 1.0, v23
	v_rcp_f32_e32 v22, v22
	v_rcp_f32_e32 v23, v23
	v_lshlrev_b32_e32 v28, 16, v53
	v_and_b32_e32 v29, 0xffff0000, v53
	v_add_f32_e32 v20, 1.0, v26
	v_add_f32_e32 v21, 1.0, v27
	v_add_f32_e32 v18, 1.0, v18
	v_add_f32_e32 v19, 1.0, v19
	v_pk_mul_f32 v[26:27], v[186:187], v[44:45] op_sel_hi:[0,1]
	v_exp_f32_e32 v44, v14
	v_mul_f32_e32 v14, 0xbfb8aa3b, v15
	v_pk_mul_f32 v[28:29], v[186:187], v[28:29] op_sel_hi:[0,1]
	v_rcp_f32_e32 v20, v20
	v_rcp_f32_e32 v21, v21
	v_rcp_f32_e32 v18, v18
	v_rcp_f32_e32 v19, v19
	v_exp_f32_e32 v45, v14
	v_lshlrev_b32_e32 v48, 16, v57
	v_and_b32_e32 v49, 0xffff0000, v57
	v_pk_mul_f32 v[28:29], v[68:69], v[28:29]
	v_lshlrev_b32_e32 v50, 16, v58
	v_pk_fma_f32 v[22:23], v[22:23], v[28:29], v[48:49]
	v_pk_mul_f32 v[28:29], v[186:187], v[32:33] op_sel_hi:[0,1]
	v_and_b32_e32 v51, 0xffff0000, v58
	v_lshlrev_b32_e32 v52, 16, v59
	v_and_b32_e32 v53, 0xffff0000, v59
	v_pk_mul_f32 v[28:29], v[62:63], v[28:29]
	v_pk_mul_f32 v[26:27], v[64:65], v[26:27]
	v_pk_fma_f32 v[20:21], v[20:21], v[28:29], v[50:51]
	v_pk_fma_f32 v[26:27], v[18:19], v[26:27], v[52:53]
	v_pk_mul_f32 v[14:15], v[16:17], v[182:183] op_sel_hi:[1,0]
	v_add_f32_e32 v16, 1.0, v44
	v_add_f32_e32 v17, 1.0, v45
	v_cvt_pk_bf16_f32 v18, v24, v25
	v_cvt_pk_bf16_f32 v19, v22, v23
	v_cvt_pk_bf16_f32 v20, v20, v21
	v_cvt_pk_bf16_f32 v21, v26, v27
	v_rcp_f32_e32 v16, v16
	v_rcp_f32_e32 v17, v17
	global_store_dwordx4 v[30:31], v[18:21], off offset:256
	v_mul_f32_e32 v14, 0xbfb8aa3b, v14
	v_mul_f32_e32 v15, 0xbfb8aa3b, v15
	s_waitcnt vmcnt(5)
	v_lshlrev_b32_e32 v18, 16, v70
	v_and_b32_e32 v19, 0xffff0000, v70
	v_exp_f32_e32 v14, v14
	v_exp_f32_e32 v15, v15
	v_pk_mul_f32 v[18:19], v[180:181], v[18:19] op_sel_hi:[0,1]
	s_waitcnt vmcnt(3)
	v_lshlrev_b32_e32 v26, 16, v82
	v_and_b32_e32 v27, 0xffff0000, v82
	v_pk_mul_f32 v[18:19], v[78:79], v[18:19]
	v_add_f32_e32 v14, 1.0, v14
	v_pk_fma_f32 v[16:17], v[16:17], v[18:19], v[26:27]
	v_exp_f32_e32 v18, v10
	v_mul_f32_e32 v10, 0xbfb8aa3b, v11
	v_exp_f32_e32 v19, v10
	v_pk_mul_f32 v[10:11], v[12:13], v[182:183] op_sel_hi:[1,0]
	v_add_f32_e32 v15, 1.0, v15
	v_mul_f32_e32 v10, 0xbfb8aa3b, v10
	v_mul_f32_e32 v11, 0xbfb8aa3b, v11
	v_rcp_f32_e32 v14, v14
	v_rcp_f32_e32 v15, v15
	v_exp_f32_e32 v10, v10
	v_exp_f32_e32 v11, v11
	v_lshlrev_b32_e32 v20, 16, v71
	v_and_b32_e32 v21, 0xffff0000, v71
	v_pk_mul_f32 v[20:21], v[180:181], v[20:21] op_sel_hi:[0,1]
	v_lshlrev_b32_e32 v28, 16, v83
	v_and_b32_e32 v29, 0xffff0000, v83
	v_pk_mul_f32 v[20:21], v[80:81], v[20:21]
	v_add_f32_e32 v12, 1.0, v18
	v_pk_fma_f32 v[14:15], v[14:15], v[20:21], v[28:29]
	v_add_f32_e32 v13, 1.0, v19
	v_add_f32_e32 v10, 1.0, v10
	v_add_f32_e32 v11, 1.0, v11
	v_exp_f32_e32 v28, v6
	v_mul_f32_e32 v6, 0xbfb8aa3b, v7
	v_rcp_f32_e32 v12, v12
	v_rcp_f32_e32 v13, v13
	v_rcp_f32_e32 v10, v10
	v_rcp_f32_e32 v11, v11
	v_exp_f32_e32 v29, v6
	v_lshlrev_b32_e32 v22, 16, v72
	v_and_b32_e32 v23, 0xffff0000, v72
	v_lshlrev_b32_e32 v24, 16, v73
	v_and_b32_e32 v25, 0xffff0000, v73
	v_pk_mul_f32 v[18:19], v[180:181], v[24:25] op_sel_hi:[0,1]
	v_pk_mul_f32 v[20:21], v[180:181], v[22:23] op_sel_hi:[0,1]
	v_lshlrev_b32_e32 v30, 16, v84
	v_and_b32_e32 v31, 0xffff0000, v84
	v_lshlrev_b32_e32 v32, 16, v85
	v_and_b32_e32 v33, 0xffff0000, v85
	v_pk_mul_f32 v[20:21], v[74:75], v[20:21]
	v_pk_mul_f32 v[18:19], v[76:77], v[18:19]
	v_pk_fma_f32 v[12:13], v[12:13], v[20:21], v[30:31]
	v_pk_fma_f32 v[18:19], v[10:11], v[18:19], v[32:33]
	v_cvt_pk_bf16_f32 v11, v14, v15
	v_lshl_add_u64 v[14:15], s[10:11], 0, v[42:43]
	v_pk_mul_f32 v[6:7], v[8:9], v[182:183] op_sel_hi:[1,0]
	v_add_f32_e32 v8, 1.0, v28
	v_add_f32_e32 v9, 1.0, v29
	v_cvt_pk_bf16_f32 v10, v16, v17
	v_cvt_pk_bf16_f32 v12, v12, v13
	v_cvt_pk_bf16_f32 v13, v18, v19
	v_lshl_add_u64 v[14:15], v[14:15], 0, v[184:185]
	v_rcp_f32_e32 v8, v8
	v_rcp_f32_e32 v9, v9
	global_store_dwordx4 v[14:15], v[10:13], off
	s_waitcnt vmcnt(3)
	v_lshlrev_b32_e32 v20, 16, v34
	v_and_b32_e32 v21, 0xffff0000, v34
	v_lshlrev_b32_e32 v10, 16, v38
	v_and_b32_e32 v11, 0xffff0000, v38
	v_pk_mul_f32 v[10:11], v[180:181], v[10:11] op_sel_hi:[0,1]
	v_pk_mul_f32 v[10:11], v[66:67], v[10:11]
	v_mul_f32_e32 v6, 0xbfb8aa3b, v6
	v_mul_f32_e32 v7, 0xbfb8aa3b, v7
	v_pk_fma_f32 v[8:9], v[8:9], v[10:11], v[20:21]
	v_exp_f32_e32 v10, v2
	v_mul_f32_e32 v2, 0xbfb8aa3b, v3
	v_exp_f32_e32 v6, v6
	v_exp_f32_e32 v7, v7
	v_exp_f32_e32 v11, v2
	v_pk_mul_f32 v[2:3], v[4:5], v[182:183] op_sel_hi:[1,0]
	v_add_f32_e32 v6, 1.0, v6
	v_mul_f32_e32 v2, 0xbfb8aa3b, v2
	v_mul_f32_e32 v3, 0xbfb8aa3b, v3
	v_exp_f32_e32 v2, v2
	v_exp_f32_e32 v3, v3
	v_add_f32_e32 v7, 1.0, v7
	v_rcp_f32_e32 v6, v6
	v_rcp_f32_e32 v7, v7
	v_lshlrev_b32_e32 v12, 16, v39
	v_and_b32_e32 v13, 0xffff0000, v39
	v_add_f32_e32 v4, 1.0, v10
	v_add_f32_e32 v5, 1.0, v11
	v_add_f32_e32 v2, 1.0, v2
	v_add_f32_e32 v3, 1.0, v3
	v_pk_mul_f32 v[12:13], v[180:181], v[12:13] op_sel_hi:[0,1]
	v_rcp_f32_e32 v4, v4
	v_rcp_f32_e32 v5, v5
	v_rcp_f32_e32 v2, v2
	v_rcp_f32_e32 v3, v3
	v_lshlrev_b32_e32 v16, 16, v40
	v_and_b32_e32 v17, 0xffff0000, v40
	v_lshlrev_b32_e32 v18, 16, v41
	v_and_b32_e32 v19, 0xffff0000, v41
	v_lshlrev_b32_e32 v22, 16, v35
	v_and_b32_e32 v23, 0xffff0000, v35
	v_pk_mul_f32 v[12:13], v[68:69], v[12:13]
	v_pk_mul_f32 v[10:11], v[180:181], v[18:19] op_sel_hi:[0,1]
	v_pk_fma_f32 v[6:7], v[6:7], v[12:13], v[22:23]
	v_pk_mul_f32 v[12:13], v[180:181], v[16:17] op_sel_hi:[0,1]
	v_lshlrev_b32_e32 v24, 16, v36
	v_and_b32_e32 v25, 0xffff0000, v36
	v_lshlrev_b32_e32 v26, 16, v37
	v_and_b32_e32 v27, 0xffff0000, v37
	v_pk_mul_f32 v[12:13], v[62:63], v[12:13]
	v_pk_mul_f32 v[10:11], v[64:65], v[10:11]
	v_pk_fma_f32 v[4:5], v[4:5], v[12:13], v[24:25]
	v_pk_fma_f32 v[10:11], v[2:3], v[10:11], v[26:27]
	v_cvt_pk_bf16_f32 v2, v8, v9
	v_cvt_pk_bf16_f32 v3, v6, v7
	v_cvt_pk_bf16_f32 v4, v4, v5
	v_cvt_pk_bf16_f32 v5, v10, v11
	global_store_dwordx4 v[14:15], v[2:5], off offset:256
.Lwtp15_join:
	s_cbranch_vccnz .LBB0_1379
	s_andn2_b64 vcc, exec, s[4:5]
	s_cbranch_vccnz .LBB0_1378
	s_barrier
	s_branch .LBB0_1378
.Lwtp15_entry:
	v_lshl_add_u32 v190, s26, 8, v181
	v_ashrrev_i32_e32 v191, 31, v190
	v_lshlrev_b64 v[152:153], 2, v[190:191]
	v_lshl_add_u64 v[154:155], s[16:17], 0, v[152:153]
	global_load_dword v222, v[154:155], off
	s_lshl_b32 s19, s28, 8
	s_or_b32 s19, s19, s45
	v_or_b32_e32 v62, s19, v183
	v_ashrrev_i32_e32 v63, 31, v62
	v_bitop3_b32 v64, s19, 56, v183 bitop3:0xc8
	v_lshlrev_b64 v[240:241], 13, v[190:191]
	v_lshrrev_b64 v[66:67], 1, v[190:191]
	s_ashr_i32 s26, s19, 6
	v_lshlrev_b32_e32 v170, 1, v64
	v_lshl_add_u64 v[64:65], s[8:9], 0, v[240:241]
	v_and_b32_e32 v147, 0x7fffffff, v67
	v_and_b32_e32 v146, 0xffffffc0, v66
	v_lshlrev_b32_e32 v66, 7, v190
	v_lshlrev_b64 v[184:185], 1, v[62:63]
	s_ashr_i32 s27, s26, 31
	v_lshl_add_u64 v[192:193], s[0:1], 0, v[170:171]
	v_lshl_add_u64 v[148:149], v[64:65], 0, v[184:185]
	v_and_b32_e32 v170, 0x2780, v66
	v_lshl_add_u64 v[64:65], v[146:147], 0, s[26:27]
	v_readlane_b32 s52, v251, 0
	v_lshl_add_u64 v[150:151], v[192:193], 0, v[170:171]
	v_lshlrev_b64 v[64:65], 14, v[64:65]
	v_readlane_b32 s54, v251, 2
	v_readlane_b32 s55, v251, 3
	global_load_dwordx4 v[224:227], v[148:149], off
	v_lshl_add_u64 v[64:65], v[150:151], 0, v[64:65]
	v_lshl_add_u64 v[66:67], v[62:63], 2, s[54:55]
	v_lshl_add_u64 v[152:153], s[6:7], 0, v[152:153]
	global_load_dwordx4 v[228:231], v[64:65], off
	global_load_dwordx4 v[74:77], v[66:67], off offset:16
	global_load_dwordx4 v[78:81], v[66:67], off
	s_nop 0
	global_load_dwordx4 v[62:65], v[66:67], off offset:528
	s_nop 0
	global_load_dwordx4 v[66:69], v[66:67], off offset:512
	v_or_b32_e32 v212, 32, v190
	global_load_dword v220, v[152:153], off
	v_ashrrev_i32_e32 v213, 31, v212
	v_or_b32_e32 v210, 48, v190
	s_bitset1_b32 s19, 7
	v_or_b32_e32 v156, 16, v190
	v_lshlrev_b64 v[198:199], 2, v[212:213]
	v_ashrrev_i32_e32 v211, 31, v210
	s_ashr_i32 s28, s19, 6
	v_ashrrev_i32_e32 v157, 31, v156
	v_lshl_add_u64 v[202:203], s[16:17], 0, v[198:199]
	v_lshl_add_u64 v[204:205], s[6:7], 0, v[198:199]
	v_lshlrev_b64 v[198:199], 2, v[210:211]
	s_ashr_i32 s29, s28, 31
	v_lshlrev_b64 v[158:159], 2, v[156:157]
	v_lshl_add_u64 v[232:233], s[6:7], 0, v[198:199]
	v_lshl_add_u64 v[146:147], v[146:147], 0, s[28:29]
	v_lshl_add_u64 v[160:161], s[16:17], 0, v[158:159]
	v_lshl_add_u64 v[158:159], s[6:7], 0, v[158:159]
	v_lshl_add_u64 v[218:219], s[16:17], 0, v[198:199]
	global_load_dword v200, v[154:155], off offset:512
	global_load_dword v198, v[152:153], off offset:512
	global_load_dword v196, v[154:155], off offset:576
	global_load_dword v194, v[152:153], off offset:576
	global_load_dword v188, v[154:155], off offset:640
	global_load_dword v182, v[154:155], off offset:704
	global_load_dword v216, v[160:161], off
	global_load_dword v214, v[158:159], off
	global_load_dword v208, v[202:203], off
	global_load_dword v206, v[204:205], off
	s_nop 0
	global_load_dword v204, v[218:219], off
	global_load_dword v202, v[232:233], off
	global_load_dword v186, v[152:153], off offset:640
	global_load_dword v180, v[152:153], off offset:704
	v_lshlrev_b64 v[146:147], 14, v[146:147]
	global_load_dwordx4 v[232:235], v[148:149], off offset:256
	v_lshl_add_u64 v[146:147], v[150:151], 0, v[146:147]
	global_load_dwordx4 v[236:239], v[146:147], off
	v_lshrrev_b64 v[148:149], 1, v[156:157]
	v_lshlrev_b64 v[218:219], 13, v[156:157]
	v_and_b32_e32 v149, 0x7fffffff, v149
	v_and_b32_e32 v148, 0xffffffc0, v148
	v_lshlrev_b32_e32 v150, 7, v156
	v_lshl_add_u64 v[146:147], s[8:9], 0, v[218:219]
	v_and_b32_e32 v170, 0x3f80, v150
	v_lshl_add_u64 v[150:151], v[148:149], 0, s[26:27]
	v_lshl_add_u64 v[154:155], v[192:193], 0, v[170:171]
	v_lshl_add_u64 v[146:147], v[146:147], 0, v[184:185]
	v_lshlrev_b64 v[150:151], 14, v[150:151]
	v_lshl_add_u64 v[156:157], v[154:155], 0, v[150:151]
	global_load_dwordx4 v[158:161], v[146:147], off
	global_load_dwordx4 v[150:153], v[146:147], off offset:256
	v_lshl_add_u64 v[146:147], v[148:149], 0, s[28:29]
	v_lshlrev_b64 v[146:147], 14, v[146:147]
	v_lshl_add_u64 v[146:147], v[154:155], 0, v[146:147]
	global_load_dwordx4 v[154:157], v[156:157], off
	s_nop 0
	global_load_dwordx4 v[146:149], v[146:147], off
	s_andn2_b64 vcc, exec, s[2:3]
	s_mov_b64 s[2:3], -1
	v_readlane_b32 s53, v251, 1
	v_readlane_b32 s56, v251, 4
	v_readlane_b32 s57, v251, 5
	v_readlane_b32 s58, v251, 6
	v_readlane_b32 s59, v251, 7
	s_waitcnt vmcnt(0)
	v_pk_mul_f32 v[142:143], v[142:143], v[222:223] op_sel_hi:[1,0]
	v_pk_mul_f32 v[138:139], v[138:139], v[222:223] op_sel_hi:[1,0]
	v_mul_f32_e32 v142, 0xbfb8aa3b, v142
	v_exp_f32_e32 v170, v142
	v_mul_f32_e32 v142, 0xbfb8aa3b, v143
	v_exp_f32_e32 v191, v142
	v_pk_mul_f32 v[142:143], v[144:145], v[222:223] op_sel_hi:[1,0]
	v_mul_f32_e32 v138, 0xbfb8aa3b, v138
	v_add_f32_e32 v144, 1.0, v170
	v_mul_f32_e32 v142, 0xbfb8aa3b, v142
	v_mul_f32_e32 v143, 0xbfb8aa3b, v143
	v_exp_f32_e32 v170, v138
	v_mul_f32_e32 v138, 0xbfb8aa3b, v139
	v_add_f32_e32 v145, 1.0, v191
	v_exp_f32_e32 v142, v142
	v_exp_f32_e32 v143, v143
	v_exp_f32_e32 v191, v138
	v_pk_mul_f32 v[138:139], v[140:141], v[222:223] op_sel_hi:[1,0]
	v_add_f32_e32 v142, 1.0, v142
	v_mul_f32_e32 v138, 0xbfb8aa3b, v138
	v_mul_f32_e32 v139, 0xbfb8aa3b, v139
	v_exp_f32_e32 v138, v138
	v_exp_f32_e32 v139, v139
	v_add_f32_e32 v143, 1.0, v143
	v_pk_mul_f32 v[134:135], v[134:135], v[222:223] op_sel_hi:[1,0]
	v_rcp_f32_e32 v142, v142
	v_rcp_f32_e32 v143, v143
	v_mul_f32_e32 v134, 0xbfb8aa3b, v134
	v_lshlrev_b32_e32 v242, 16, v224
	v_and_b32_e32 v243, 0xffff0000, v224
	v_lshlrev_b32_e32 v224, 16, v225
	v_and_b32_e32 v225, 0xffff0000, v225
	v_add_f32_e32 v140, 1.0, v170
	v_add_f32_e32 v141, 1.0, v191
	v_add_f32_e32 v138, 1.0, v138
	v_add_f32_e32 v139, 1.0, v139
	v_exp_f32_e32 v170, v134
	v_mul_f32_e32 v134, 0xbfb8aa3b, v135
	v_rcp_f32_e32 v144, v144
	v_rcp_f32_e32 v145, v145
	v_pk_mul_f32 v[224:225], v[220:221], v[224:225] op_sel_hi:[0,1]
	v_rcp_f32_e32 v140, v140
	v_rcp_f32_e32 v141, v141
	v_rcp_f32_e32 v138, v138
	v_rcp_f32_e32 v139, v139
	v_exp_f32_e32 v191, v134
	v_lshlrev_b32_e32 v244, 16, v226
	v_and_b32_e32 v245, 0xffff0000, v226
	v_lshlrev_b32_e32 v226, 16, v227
	v_and_b32_e32 v227, 0xffff0000, v227
	v_lshlrev_b32_e32 v246, 16, v228
	v_and_b32_e32 v247, 0xffff0000, v228
	v_lshlrev_b32_e32 v228, 16, v229
	v_and_b32_e32 v229, 0xffff0000, v229
	v_pk_mul_f32 v[224:225], v[80:81], v[224:225]
	v_pk_mul_f32 v[242:243], v[220:221], v[242:243] op_sel_hi:[0,1]
	v_pk_fma_f32 v[142:143], v[142:143], v[224:225], v[228:229]
	v_pk_mul_f32 v[224:225], v[220:221], v[226:227] op_sel_hi:[0,1]
	v_pk_mul_f32 v[226:227], v[220:221], v[244:245] op_sel_hi:[0,1]
	v_lshlrev_b32_e32 v248, 16, v230
	v_and_b32_e32 v249, 0xffff0000, v230
	v_lshlrev_b32_e32 v230, 16, v231
	v_and_b32_e32 v231, 0xffff0000, v231
	v_pk_mul_f32 v[242:243], v[78:79], v[242:243]
	v_pk_mul_f32 v[226:227], v[74:75], v[226:227]
	v_pk_mul_f32 v[224:225], v[76:77], v[224:225]
	v_pk_fma_f32 v[144:145], v[144:145], v[242:243], v[246:247]
	v_pk_fma_f32 v[224:225], v[138:139], v[224:225], v[230:231]
	v_pk_fma_f32 v[140:141], v[140:141], v[226:227], v[248:249]
	v_cvt_pk_bf16_f32 v139, v142, v143
	v_lshl_add_u64 v[142:143], s[10:11], 0, v[240:241]
	v_pk_mul_f32 v[134:135], v[136:137], v[222:223] op_sel_hi:[1,0]
	v_add_f32_e32 v136, 1.0, v170
	v_add_f32_e32 v137, 1.0, v191
	v_cvt_pk_bf16_f32 v138, v144, v145
	v_cvt_pk_bf16_f32 v140, v140, v141
	v_cvt_pk_bf16_f32 v141, v224, v225
	v_lshl_add_u64 v[142:143], v[142:143], 0, v[184:185]
	v_rcp_f32_e32 v136, v136
	v_rcp_f32_e32 v137, v137
	global_store_dwordx4 v[142:143], v[138:141], off sc1
	v_pk_mul_f32 v[130:131], v[130:131], v[222:223] op_sel_hi:[1,0]
	v_lshlrev_b32_e32 v226, 16, v236
	v_lshlrev_b32_e32 v138, 16, v232
	v_and_b32_e32 v139, 0xffff0000, v232
	v_pk_mul_f32 v[138:139], v[220:221], v[138:139] op_sel_hi:[0,1]
	v_and_b32_e32 v227, 0xffff0000, v236
	v_pk_mul_f32 v[138:139], v[66:67], v[138:139]
	v_mul_f32_e32 v130, 0xbfb8aa3b, v130
	v_mul_f32_e32 v134, 0xbfb8aa3b, v134
	v_mul_f32_e32 v135, 0xbfb8aa3b, v135
	v_pk_fma_f32 v[136:137], v[136:137], v[138:139], v[226:227]
	v_exp_f32_e32 v138, v130
	v_mul_f32_e32 v130, 0xbfb8aa3b, v131
	v_exp_f32_e32 v134, v134
	v_exp_f32_e32 v135, v135
	v_exp_f32_e32 v139, v130
	v_pk_mul_f32 v[130:131], v[132:133], v[222:223] op_sel_hi:[1,0]
	v_add_f32_e32 v134, 1.0, v134
	v_mul_f32_e32 v130, 0xbfb8aa3b, v130
	v_mul_f32_e32 v131, 0xbfb8aa3b, v131
	v_exp_f32_e32 v130, v130
	v_exp_f32_e32 v131, v131
	v_add_f32_e32 v135, 1.0, v135
	v_rcp_f32_e32 v134, v134
	v_rcp_f32_e32 v135, v135
	v_lshlrev_b32_e32 v140, 16, v233
	v_and_b32_e32 v141, 0xffff0000, v233
	v_add_f32_e32 v132, 1.0, v138
	v_add_f32_e32 v133, 1.0, v139
	v_add_f32_e32 v130, 1.0, v130
	v_add_f32_e32 v131, 1.0, v131
	v_pk_mul_f32 v[140:141], v[220:221], v[140:141] op_sel_hi:[0,1]
	v_rcp_f32_e32 v132, v132
	v_rcp_f32_e32 v133, v133
	v_rcp_f32_e32 v130, v130
	v_rcp_f32_e32 v131, v131
	v_lshlrev_b32_e32 v144, 16, v234
	v_and_b32_e32 v145, 0xffff0000, v234
	v_lshlrev_b32_e32 v224, 16, v235
	v_and_b32_e32 v225, 0xffff0000, v235
	v_lshlrev_b32_e32 v228, 16, v237
	v_and_b32_e32 v229, 0xffff0000, v237
	v_pk_mul_f32 v[140:141], v[68:69], v[140:141]
	v_pk_mul_f32 v[138:139], v[220:221], v[224:225] op_sel_hi:[0,1]
	v_pk_fma_f32 v[134:135], v[134:135], v[140:141], v[228:229]
	v_pk_mul_f32 v[140:141], v[220:221], v[144:145] op_sel_hi:[0,1]
	v_lshlrev_b32_e32 v230, 16, v238
	v_and_b32_e32 v231, 0xffff0000, v238
	v_lshlrev_b32_e32 v232, 16, v239
	v_and_b32_e32 v233, 0xffff0000, v239
	v_pk_mul_f32 v[140:141], v[62:63], v[140:141]
	v_pk_mul_f32 v[138:139], v[64:65], v[138:139]
	v_pk_mul_f32 v[126:127], v[126:127], v[216:217] op_sel_hi:[1,0]
	v_pk_fma_f32 v[138:139], v[130:131], v[138:139], v[232:233]
	v_pk_fma_f32 v[132:133], v[132:133], v[140:141], v[230:231]
	v_mul_f32_e32 v126, 0xbfb8aa3b, v126
	v_cvt_pk_bf16_f32 v132, v132, v133
	v_cvt_pk_bf16_f32 v133, v138, v139
	v_lshlrev_b32_e32 v138, 16, v154
	v_and_b32_e32 v139, 0xffff0000, v154
	v_exp_f32_e32 v154, v126
	v_mul_f32_e32 v126, 0xbfb8aa3b, v127
	v_lshlrev_b32_e32 v140, 16, v155
	v_and_b32_e32 v141, 0xffff0000, v155
	v_exp_f32_e32 v155, v126
	v_pk_mul_f32 v[126:127], v[128:129], v[216:217] op_sel_hi:[1,0]
	v_add_f32_e32 v128, 1.0, v154
	v_cvt_pk_bf16_f32 v130, v136, v137
	v_add_f32_e32 v129, 1.0, v155
	v_cvt_pk_bf16_f32 v131, v134, v135
	v_rcp_f32_e32 v128, v128
	v_rcp_f32_e32 v129, v129
	global_store_dwordx4 v[142:143], v[130:133], off offset:256 sc1
	v_mul_f32_e32 v126, 0xbfb8aa3b, v126
	v_mul_f32_e32 v127, 0xbfb8aa3b, v127
	v_lshlrev_b32_e32 v130, 16, v158
	v_and_b32_e32 v131, 0xffff0000, v158
	v_exp_f32_e32 v126, v126
	v_exp_f32_e32 v127, v127
	v_pk_mul_f32 v[130:131], v[214:215], v[130:131] op_sel_hi:[0,1]
	v_pk_mul_f32 v[122:123], v[122:123], v[216:217] op_sel_hi:[1,0]
	v_pk_mul_f32 v[130:131], v[78:79], v[130:131]
	v_mul_f32_e32 v122, 0xbfb8aa3b, v122
	v_pk_fma_f32 v[128:129], v[128:129], v[130:131], v[138:139]
	v_exp_f32_e32 v130, v122
	v_mul_f32_e32 v122, 0xbfb8aa3b, v123
	v_exp_f32_e32 v131, v122
	v_pk_mul_f32 v[122:123], v[124:125], v[216:217] op_sel_hi:[1,0]
	v_add_f32_e32 v126, 1.0, v126
	v_add_f32_e32 v127, 1.0, v127
	v_mul_f32_e32 v122, 0xbfb8aa3b, v122
	v_mul_f32_e32 v123, 0xbfb8aa3b, v123
	v_rcp_f32_e32 v126, v126
	v_rcp_f32_e32 v127, v127
	v_exp_f32_e32 v122, v122
	v_exp_f32_e32 v123, v123
	v_lshlrev_b32_e32 v132, 16, v159
	v_and_b32_e32 v133, 0xffff0000, v159
	v_pk_mul_f32 v[132:133], v[214:215], v[132:133] op_sel_hi:[0,1]
	v_pk_mul_f32 v[118:119], v[118:119], v[216:217] op_sel_hi:[1,0]
	v_pk_mul_f32 v[132:133], v[80:81], v[132:133]
	v_mul_f32_e32 v118, 0xbfb8aa3b, v118
	v_pk_fma_f32 v[126:127], v[126:127], v[132:133], v[140:141]
	v_add_f32_e32 v124, 1.0, v130
	v_add_f32_e32 v125, 1.0, v131
	v_add_f32_e32 v122, 1.0, v122
	v_add_f32_e32 v123, 1.0, v123
	v_exp_f32_e32 v140, v118
	v_mul_f32_e32 v118, 0xbfb8aa3b, v119
	v_rcp_f32_e32 v124, v124
	v_rcp_f32_e32 v125, v125
	v_rcp_f32_e32 v122, v122
	v_rcp_f32_e32 v123, v123
	v_exp_f32_e32 v141, v118
	v_lshlrev_b32_e32 v134, 16, v160
	v_and_b32_e32 v135, 0xffff0000, v160
	v_lshlrev_b32_e32 v136, 16, v161
	v_and_b32_e32 v137, 0xffff0000, v161
	v_pk_mul_f32 v[130:131], v[214:215], v[136:137] op_sel_hi:[0,1]
	v_pk_mul_f32 v[132:133], v[214:215], v[134:135] op_sel_hi:[0,1]
	v_lshlrev_b32_e32 v142, 16, v156
	v_and_b32_e32 v143, 0xffff0000, v156
	v_lshlrev_b32_e32 v144, 16, v157
	v_and_b32_e32 v145, 0xffff0000, v157
	v_pk_mul_f32 v[132:133], v[74:75], v[132:133]
	v_pk_mul_f32 v[130:131], v[76:77], v[130:131]
	v_pk_fma_f32 v[124:125], v[124:125], v[132:133], v[142:143]
	v_pk_fma_f32 v[130:131], v[122:123], v[130:131], v[144:145]
	v_cvt_pk_bf16_f32 v123, v126, v127
	v_lshl_add_u64 v[126:127], s[10:11], 0, v[218:219]
	v_pk_mul_f32 v[118:119], v[120:121], v[216:217] op_sel_hi:[1,0]
	v_add_f32_e32 v120, 1.0, v140
	v_add_f32_e32 v121, 1.0, v141
	v_cvt_pk_bf16_f32 v122, v128, v129
	v_cvt_pk_bf16_f32 v124, v124, v125
	v_cvt_pk_bf16_f32 v125, v130, v131
	v_lshl_add_u64 v[126:127], v[126:127], 0, v[184:185]
	v_rcp_f32_e32 v120, v120
	v_rcp_f32_e32 v121, v121
	global_store_dwordx4 v[126:127], v[122:125], off sc1
	v_pk_mul_f32 v[114:115], v[114:115], v[216:217] op_sel_hi:[1,0]
	v_lshlrev_b32_e32 v132, 16, v146
	v_lshlrev_b32_e32 v122, 16, v150
	v_and_b32_e32 v123, 0xffff0000, v150
	v_pk_mul_f32 v[122:123], v[214:215], v[122:123] op_sel_hi:[0,1]
	v_and_b32_e32 v133, 0xffff0000, v146
	v_pk_mul_f32 v[122:123], v[66:67], v[122:123]
	v_mul_f32_e32 v114, 0xbfb8aa3b, v114
	v_mul_f32_e32 v118, 0xbfb8aa3b, v118
	v_mul_f32_e32 v119, 0xbfb8aa3b, v119
	v_pk_fma_f32 v[120:121], v[120:121], v[122:123], v[132:133]
	v_exp_f32_e32 v122, v114
	v_mul_f32_e32 v114, 0xbfb8aa3b, v115
	v_exp_f32_e32 v118, v118
	v_exp_f32_e32 v119, v119
	v_exp_f32_e32 v123, v114
	v_pk_mul_f32 v[114:115], v[116:117], v[216:217] op_sel_hi:[1,0]
	v_add_f32_e32 v118, 1.0, v118
	v_mul_f32_e32 v114, 0xbfb8aa3b, v114
	v_mul_f32_e32 v115, 0xbfb8aa3b, v115
	v_exp_f32_e32 v114, v114
	v_exp_f32_e32 v115, v115
	v_add_f32_e32 v119, 1.0, v119
	v_rcp_f32_e32 v118, v118
	v_rcp_f32_e32 v119, v119
	v_lshlrev_b32_e32 v124, 16, v151
	v_and_b32_e32 v125, 0xffff0000, v151
	v_add_f32_e32 v116, 1.0, v122
	v_add_f32_e32 v117, 1.0, v123
	v_add_f32_e32 v114, 1.0, v114
	v_add_f32_e32 v115, 1.0, v115
	v_pk_mul_f32 v[124:125], v[214:215], v[124:125] op_sel_hi:[0,1]
	v_rcp_f32_e32 v116, v116
	v_rcp_f32_e32 v117, v117
	v_rcp_f32_e32 v114, v114
	v_rcp_f32_e32 v115, v115
	v_lshlrev_b32_e32 v128, 16, v152
	v_and_b32_e32 v129, 0xffff0000, v152
	v_lshlrev_b32_e32 v130, 16, v153
	v_and_b32_e32 v131, 0xffff0000, v153
	v_lshlrev_b32_e32 v134, 16, v147
	v_and_b32_e32 v135, 0xffff0000, v147
	v_pk_mul_f32 v[124:125], v[68:69], v[124:125]
	v_pk_mul_f32 v[122:123], v[214:215], v[130:131] op_sel_hi:[0,1]
	v_pk_fma_f32 v[118:119], v[118:119], v[124:125], v[134:135]
	v_pk_mul_f32 v[124:125], v[214:215], v[128:129] op_sel_hi:[0,1]
	v_lshlrev_b32_e32 v136, 16, v148
	v_and_b32_e32 v137, 0xffff0000, v148
	v_lshlrev_b32_e32 v138, 16, v149
	v_and_b32_e32 v139, 0xffff0000, v149
	v_pk_mul_f32 v[124:125], v[62:63], v[124:125]
	v_pk_mul_f32 v[122:123], v[64:65], v[122:123]
	v_pk_fma_f32 v[116:117], v[116:117], v[124:125], v[136:137]
	v_pk_fma_f32 v[122:123], v[114:115], v[122:123], v[138:139]
	v_cvt_pk_bf16_f32 v114, v120, v121
	v_cvt_pk_bf16_f32 v115, v118, v119
	v_cvt_pk_bf16_f32 v116, v116, v117
	v_cvt_pk_bf16_f32 v117, v122, v123
	global_store_dwordx4 v[126:127], v[114:117], off offset:256 sc1
	v_lshlrev_b64 v[150:151], 13, v[212:213]
	v_lshlrev_b32_e32 v118, 7, v212
	v_lshrrev_b64 v[116:117], 1, v[212:213]
	v_lshl_add_u64 v[114:115], s[8:9], 0, v[150:151]
	v_and_b32_e32 v117, 0x7fffffff, v117
	v_and_b32_e32 v116, 0xffffffc0, v116
	v_lshl_add_u64 v[114:115], v[114:115], 0, v[184:185]
	v_and_b32_e32 v170, 0x3f80, v118
	v_lshl_add_u64 v[120:121], v[116:117], 0, s[26:27]
	global_load_dwordx4 v[126:129], v[114:115], off
	global_load_dwordx4 v[134:137], v[114:115], off offset:256
	v_lshl_add_u64 v[118:119], v[192:193], 0, v[170:171]
	v_lshlrev_b64 v[120:121], 14, v[120:121]
	v_lshl_add_u64 v[120:121], v[118:119], 0, v[120:121]
	global_load_dwordx4 v[130:133], v[120:121], off
	v_lshl_add_u64 v[114:115], v[116:117], 0, s[28:29]
	v_lshlrev_b64 v[114:115], 14, v[114:115]
	v_lshl_add_u64 v[114:115], v[118:119], 0, v[114:115]
	global_load_dwordx4 v[138:141], v[114:115], off
	v_lshrrev_b64 v[116:117], 1, v[210:211]
	v_lshlrev_b64 v[124:125], 13, v[210:211]
	v_and_b32_e32 v117, 0x7fffffff, v117
	v_and_b32_e32 v116, 0xffffffc0, v116
	v_lshlrev_b32_e32 v118, 7, v210
	v_lshl_add_u64 v[114:115], s[8:9], 0, v[124:125]
	v_and_b32_e32 v170, 0x3f80, v118
	v_lshl_add_u64 v[118:119], v[116:117], 0, s[26:27]
	v_lshl_add_u64 v[146:147], v[192:193], 0, v[170:171]
	v_lshl_add_u64 v[114:115], v[114:115], 0, v[184:185]
	v_lshlrev_b64 v[118:119], 14, v[118:119]
	v_lshl_add_u64 v[148:149], v[146:147], 0, v[118:119]
	global_load_dwordx4 v[142:145], v[114:115], off
	global_load_dwordx4 v[118:121], v[114:115], off offset:256
	v_lshl_add_u64 v[114:115], v[116:117], 0, s[28:29]
	v_lshlrev_b64 v[114:115], 14, v[114:115]
	v_lshl_add_u64 v[114:115], v[146:147], 0, v[114:115]
	global_load_dwordx4 v[146:149], v[148:149], off
	s_nop 0
	global_load_dwordx4 v[114:117], v[114:115], off
	v_pk_mul_f32 v[110:111], v[110:111], v[208:209] op_sel_hi:[1,0]
	v_pk_mul_f32 v[106:107], v[106:107], v[208:209] op_sel_hi:[1,0]
	v_mul_f32_e32 v110, 0xbfb8aa3b, v110
	v_exp_f32_e32 v160, v110
	v_mul_f32_e32 v110, 0xbfb8aa3b, v111
	v_exp_f32_e32 v161, v110
	v_pk_mul_f32 v[110:111], v[112:113], v[208:209] op_sel_hi:[1,0]
	v_mul_f32_e32 v106, 0xbfb8aa3b, v106
	v_mul_f32_e32 v110, 0xbfb8aa3b, v110
	v_mul_f32_e32 v111, 0xbfb8aa3b, v111
	v_exp_f32_e32 v110, v110
	v_exp_f32_e32 v111, v111
	v_add_f32_e32 v112, 1.0, v160
	v_add_f32_e32 v113, 1.0, v161
	v_add_f32_e32 v110, 1.0, v110
	v_add_f32_e32 v111, 1.0, v111
	v_rcp_f32_e32 v110, v110
	v_rcp_f32_e32 v111, v111
	v_rcp_f32_e32 v112, v112
	v_rcp_f32_e32 v113, v113
	v_pk_mul_f32 v[102:103], v[102:103], v[208:209] op_sel_hi:[1,0]
	v_pk_mul_f32 v[98:99], v[98:99], v[208:209] op_sel_hi:[1,0]
	v_mul_f32_e32 v102, 0xbfb8aa3b, v102
	v_mul_f32_e32 v98, 0xbfb8aa3b, v98
	v_pk_mul_f32 v[94:95], v[94:95], v[204:205] op_sel_hi:[1,0]
	v_pk_mul_f32 v[90:91], v[90:91], v[204:205] op_sel_hi:[1,0]
	v_mul_f32_e32 v94, 0xbfb8aa3b, v94
	v_mul_f32_e32 v90, 0xbfb8aa3b, v90
	v_pk_mul_f32 v[86:87], v[86:87], v[204:205] op_sel_hi:[1,0]
	v_pk_mul_f32 v[82:83], v[82:83], v[204:205] op_sel_hi:[1,0]
	v_mul_f32_e32 v86, 0xbfb8aa3b, v86
	v_mul_f32_e32 v82, 0xbfb8aa3b, v82
	v_add_u32_e32 v122, 0x80, v190
	v_ashrrev_i32_e32 v123, 31, v122
	v_pk_mul_f32 v[70:71], v[70:71], v[200:201] op_sel_hi:[1,0]
	v_pk_mul_f32 v[58:59], v[58:59], v[200:201] op_sel_hi:[1,0]
	v_mul_f32_e32 v70, 0xbfb8aa3b, v70
	v_mul_f32_e32 v58, 0xbfb8aa3b, v58
	v_pk_mul_f32 v[54:55], v[54:55], v[200:201] op_sel_hi:[1,0]
	v_pk_mul_f32 v[50:51], v[50:51], v[200:201] op_sel_hi:[1,0]
	v_mul_f32_e32 v54, 0xbfb8aa3b, v54
	v_mul_f32_e32 v50, 0xbfb8aa3b, v50
	v_pk_mul_f32 v[46:47], v[46:47], v[196:197] op_sel_hi:[1,0]
	v_pk_mul_f32 v[42:43], v[42:43], v[196:197] op_sel_hi:[1,0]
	v_mul_f32_e32 v46, 0xbfb8aa3b, v46
	v_mul_f32_e32 v42, 0xbfb8aa3b, v42
	v_pk_mul_f32 v[38:39], v[38:39], v[196:197] op_sel_hi:[1,0]
	v_pk_mul_f32 v[34:35], v[34:35], v[196:197] op_sel_hi:[1,0]
	v_mul_f32_e32 v38, 0xbfb8aa3b, v38
	v_mul_f32_e32 v34, 0xbfb8aa3b, v34
	v_pk_mul_f32 v[30:31], v[30:31], v[188:189] op_sel_hi:[1,0]
	v_pk_mul_f32 v[26:27], v[26:27], v[188:189] op_sel_hi:[1,0]
	v_mul_f32_e32 v30, 0xbfb8aa3b, v30
	s_waitcnt vmcnt(7)
	v_lshlrev_b32_e32 v152, 16, v126
	v_and_b32_e32 v153, 0xffff0000, v126
	v_lshlrev_b32_e32 v126, 16, v127
	v_and_b32_e32 v127, 0xffff0000, v127
	v_pk_mul_f32 v[126:127], v[206:207], v[126:127] op_sel_hi:[0,1]
	s_waitcnt vmcnt(5)
	v_lshlrev_b32_e32 v156, 16, v130
	v_and_b32_e32 v157, 0xffff0000, v130
	v_lshlrev_b32_e32 v130, 16, v131
	v_and_b32_e32 v131, 0xffff0000, v131
	v_pk_mul_f32 v[126:127], v[80:81], v[126:127]
	v_lshlrev_b32_e32 v154, 16, v128
	v_pk_fma_f32 v[110:111], v[110:111], v[126:127], v[130:131]
	v_exp_f32_e32 v126, v106
	v_mul_f32_e32 v106, 0xbfb8aa3b, v107
	v_exp_f32_e32 v127, v106
	v_pk_mul_f32 v[106:107], v[108:109], v[208:209] op_sel_hi:[1,0]
	v_add_f32_e32 v108, 1.0, v126
	v_mul_f32_e32 v106, 0xbfb8aa3b, v106
	v_mul_f32_e32 v107, 0xbfb8aa3b, v107
	v_exp_f32_e32 v106, v106
	v_exp_f32_e32 v107, v107
	v_add_f32_e32 v109, 1.0, v127
	v_rcp_f32_e32 v108, v108
	v_add_f32_e32 v106, 1.0, v106
	v_add_f32_e32 v107, 1.0, v107
	v_rcp_f32_e32 v109, v109
	v_rcp_f32_e32 v106, v106
	v_rcp_f32_e32 v107, v107
	v_and_b32_e32 v155, 0xffff0000, v128
	v_lshlrev_b32_e32 v128, 16, v129
	v_and_b32_e32 v129, 0xffff0000, v129
	v_pk_mul_f32 v[152:153], v[206:207], v[152:153] op_sel_hi:[0,1]
	v_pk_mul_f32 v[152:153], v[78:79], v[152:153]
	v_pk_mul_f32 v[126:127], v[206:207], v[128:129] op_sel_hi:[0,1]
	v_pk_mul_f32 v[128:129], v[206:207], v[154:155] op_sel_hi:[0,1]
	v_lshlrev_b32_e32 v158, 16, v132
	v_and_b32_e32 v159, 0xffff0000, v132
	v_lshlrev_b32_e32 v132, 16, v133
	v_and_b32_e32 v133, 0xffff0000, v133
	v_pk_fma_f32 v[112:113], v[112:113], v[152:153], v[156:157]
	v_pk_mul_f32 v[128:129], v[74:75], v[128:129]
	v_pk_mul_f32 v[126:127], v[76:77], v[126:127]
	v_pk_fma_f32 v[108:109], v[108:109], v[128:129], v[158:159]
	v_pk_fma_f32 v[126:127], v[106:107], v[126:127], v[132:133]
	v_cvt_pk_bf16_f32 v106, v112, v113
	v_lshlrev_b32_e32 v112, 16, v136
	v_and_b32_e32 v113, 0xffff0000, v136
	v_exp_f32_e32 v136, v102
	v_mul_f32_e32 v102, 0xbfb8aa3b, v103
	v_cvt_pk_bf16_f32 v108, v108, v109
	v_cvt_pk_bf16_f32 v109, v126, v127
	v_lshlrev_b32_e32 v126, 16, v137
	v_and_b32_e32 v127, 0xffff0000, v137
	v_exp_f32_e32 v137, v102
	v_cvt_pk_bf16_f32 v107, v110, v111
	v_lshl_add_u64 v[110:111], s[10:11], 0, v[150:151]
	v_pk_mul_f32 v[102:103], v[104:105], v[208:209] op_sel_hi:[1,0]
	v_add_f32_e32 v104, 1.0, v136
	v_add_f32_e32 v105, 1.0, v137
	v_lshl_add_u64 v[110:111], v[110:111], 0, v[184:185]
	v_rcp_f32_e32 v104, v104
	v_rcp_f32_e32 v105, v105
	global_store_dwordx4 v[110:111], v[106:109], off sc1
	s_waitcnt vmcnt(5)
	v_lshlrev_b32_e32 v128, 16, v138
	v_and_b32_e32 v129, 0xffff0000, v138
	v_lshlrev_b32_e32 v106, 16, v134
	v_and_b32_e32 v107, 0xffff0000, v134
	v_pk_mul_f32 v[106:107], v[206:207], v[106:107] op_sel_hi:[0,1]
	v_pk_mul_f32 v[106:107], v[66:67], v[106:107]
	v_mul_f32_e32 v102, 0xbfb8aa3b, v102
	v_mul_f32_e32 v103, 0xbfb8aa3b, v103
	v_pk_fma_f32 v[104:105], v[104:105], v[106:107], v[128:129]
	v_exp_f32_e32 v106, v98
	v_mul_f32_e32 v98, 0xbfb8aa3b, v99
	v_exp_f32_e32 v102, v102
	v_exp_f32_e32 v103, v103
	v_exp_f32_e32 v107, v98
	v_pk_mul_f32 v[98:99], v[100:101], v[208:209] op_sel_hi:[1,0]
	v_add_f32_e32 v102, 1.0, v102
	v_mul_f32_e32 v98, 0xbfb8aa3b, v98
	v_mul_f32_e32 v99, 0xbfb8aa3b, v99
	v_exp_f32_e32 v98, v98
	v_exp_f32_e32 v99, v99
	v_add_f32_e32 v103, 1.0, v103
	v_rcp_f32_e32 v102, v102
	v_rcp_f32_e32 v103, v103
	v_lshlrev_b32_e32 v108, 16, v135
	v_and_b32_e32 v109, 0xffff0000, v135
	v_add_f32_e32 v100, 1.0, v106
	v_add_f32_e32 v101, 1.0, v107
	v_add_f32_e32 v98, 1.0, v98
	v_add_f32_e32 v99, 1.0, v99
	v_pk_mul_f32 v[106:107], v[206:207], v[126:127] op_sel_hi:[0,1]
	v_exp_f32_e32 v126, v94
	v_mul_f32_e32 v94, 0xbfb8aa3b, v95
	v_pk_mul_f32 v[108:109], v[206:207], v[108:109] op_sel_hi:[0,1]
	v_rcp_f32_e32 v100, v100
	v_rcp_f32_e32 v101, v101
	v_rcp_f32_e32 v98, v98
	v_rcp_f32_e32 v99, v99
	v_exp_f32_e32 v127, v94
	v_lshlrev_b32_e32 v130, 16, v139
	v_and_b32_e32 v131, 0xffff0000, v139
	v_pk_mul_f32 v[108:109], v[68:69], v[108:109]
	v_lshlrev_b32_e32 v132, 16, v140
	v_pk_fma_f32 v[102:103], v[102:103], v[108:109], v[130:131]
	v_pk_mul_f32 v[108:109], v[206:207], v[112:113] op_sel_hi:[0,1]
	v_and_b32_e32 v133, 0xffff0000, v140
	v_lshlrev_b32_e32 v134, 16, v141
	v_and_b32_e32 v135, 0xffff0000, v141
	v_pk_mul_f32 v[108:109], v[62:63], v[108:109]
	v_pk_mul_f32 v[106:107], v[64:65], v[106:107]
	v_pk_fma_f32 v[100:101], v[100:101], v[108:109], v[132:133]
	v_pk_fma_f32 v[106:107], v[98:99], v[106:107], v[134:135]
	v_pk_mul_f32 v[94:95], v[96:97], v[204:205] op_sel_hi:[1,0]
	v_add_f32_e32 v96, 1.0, v126
	v_add_f32_e32 v97, 1.0, v127
	v_cvt_pk_bf16_f32 v98, v104, v105
	v_cvt_pk_bf16_f32 v99, v102, v103
	v_cvt_pk_bf16_f32 v100, v100, v101
	v_cvt_pk_bf16_f32 v101, v106, v107
	v_rcp_f32_e32 v96, v96
	v_rcp_f32_e32 v97, v97
	global_store_dwordx4 v[110:111], v[98:101], off offset:256 sc1
	v_mul_f32_e32 v94, 0xbfb8aa3b, v94
	v_mul_f32_e32 v95, 0xbfb8aa3b, v95
	s_waitcnt vmcnt(5)
	v_lshlrev_b32_e32 v98, 16, v142
	v_and_b32_e32 v99, 0xffff0000, v142
	v_exp_f32_e32 v94, v94
	v_exp_f32_e32 v95, v95
	v_pk_mul_f32 v[98:99], v[202:203], v[98:99] op_sel_hi:[0,1]
	s_waitcnt vmcnt(3)
	v_lshlrev_b32_e32 v106, 16, v146
	v_and_b32_e32 v107, 0xffff0000, v146
	v_pk_mul_f32 v[98:99], v[78:79], v[98:99]
	v_add_f32_e32 v94, 1.0, v94
	v_pk_fma_f32 v[96:97], v[96:97], v[98:99], v[106:107]
	v_exp_f32_e32 v98, v90
	v_mul_f32_e32 v90, 0xbfb8aa3b, v91
	v_exp_f32_e32 v99, v90
	v_pk_mul_f32 v[90:91], v[92:93], v[204:205] op_sel_hi:[1,0]
	v_add_f32_e32 v95, 1.0, v95
	v_mul_f32_e32 v90, 0xbfb8aa3b, v90
	v_mul_f32_e32 v91, 0xbfb8aa3b, v91
	v_rcp_f32_e32 v94, v94
	v_rcp_f32_e32 v95, v95
	v_exp_f32_e32 v90, v90
	v_exp_f32_e32 v91, v91
	v_lshlrev_b32_e32 v100, 16, v143
	v_and_b32_e32 v101, 0xffff0000, v143
	v_pk_mul_f32 v[100:101], v[202:203], v[100:101] op_sel_hi:[0,1]
	v_lshlrev_b32_e32 v108, 16, v147
	v_and_b32_e32 v109, 0xffff0000, v147
	v_pk_mul_f32 v[100:101], v[80:81], v[100:101]
	v_add_f32_e32 v92, 1.0, v98
	v_pk_fma_f32 v[94:95], v[94:95], v[100:101], v[108:109]
	v_add_f32_e32 v93, 1.0, v99
	v_add_f32_e32 v90, 1.0, v90
	v_add_f32_e32 v91, 1.0, v91
	v_exp_f32_e32 v108, v86
	v_mul_f32_e32 v86, 0xbfb8aa3b, v87
	v_rcp_f32_e32 v92, v92
	v_rcp_f32_e32 v93, v93
	v_rcp_f32_e32 v90, v90
	v_rcp_f32_e32 v91, v91
	v_exp_f32_e32 v109, v86
	v_lshlrev_b32_e32 v102, 16, v144
	v_and_b32_e32 v103, 0xffff0000, v144
	v_lshlrev_b32_e32 v104, 16, v145
	v_and_b32_e32 v105, 0xffff0000, v145
	v_pk_mul_f32 v[98:99], v[202:203], v[104:105] op_sel_hi:[0,1]
	v_pk_mul_f32 v[100:101], v[202:203], v[102:103] op_sel_hi:[0,1]
	v_lshlrev_b32_e32 v110, 16, v148
	v_and_b32_e32 v111, 0xffff0000, v148
	v_lshlrev_b32_e32 v112, 16, v149
	v_and_b32_e32 v113, 0xffff0000, v149
	v_pk_mul_f32 v[100:101], v[74:75], v[100:101]
	v_pk_mul_f32 v[98:99], v[76:77], v[98:99]
	v_pk_fma_f32 v[92:93], v[92:93], v[100:101], v[110:111]
	v_pk_fma_f32 v[98:99], v[90:91], v[98:99], v[112:113]
	v_cvt_pk_bf16_f32 v91, v94, v95
	v_lshl_add_u64 v[94:95], s[10:11], 0, v[124:125]
	v_pk_mul_f32 v[86:87], v[88:89], v[204:205] op_sel_hi:[1,0]
	v_add_f32_e32 v88, 1.0, v108
	v_add_f32_e32 v89, 1.0, v109
	v_cvt_pk_bf16_f32 v90, v96, v97
	v_cvt_pk_bf16_f32 v92, v92, v93
	v_cvt_pk_bf16_f32 v93, v98, v99
	v_lshl_add_u64 v[94:95], v[94:95], 0, v[184:185]
	v_rcp_f32_e32 v88, v88
	v_rcp_f32_e32 v89, v89
	global_store_dwordx4 v[94:95], v[90:93], off sc1
	s_waitcnt vmcnt(3)
	v_lshlrev_b32_e32 v100, 16, v114
	v_and_b32_e32 v101, 0xffff0000, v114
	v_lshlrev_b32_e32 v90, 16, v118
	v_and_b32_e32 v91, 0xffff0000, v118
	v_pk_mul_f32 v[90:91], v[202:203], v[90:91] op_sel_hi:[0,1]
	v_pk_mul_f32 v[90:91], v[66:67], v[90:91]
	v_mul_f32_e32 v86, 0xbfb8aa3b, v86
	v_mul_f32_e32 v87, 0xbfb8aa3b, v87
	v_pk_fma_f32 v[88:89], v[88:89], v[90:91], v[100:101]
	v_exp_f32_e32 v90, v82
	v_mul_f32_e32 v82, 0xbfb8aa3b, v83
	v_exp_f32_e32 v86, v86
	v_exp_f32_e32 v87, v87
	v_exp_f32_e32 v91, v82
	v_pk_mul_f32 v[82:83], v[84:85], v[204:205] op_sel_hi:[1,0]
	v_add_f32_e32 v86, 1.0, v86
	v_mul_f32_e32 v82, 0xbfb8aa3b, v82
	v_mul_f32_e32 v83, 0xbfb8aa3b, v83
	v_exp_f32_e32 v82, v82
	v_exp_f32_e32 v83, v83
	v_add_f32_e32 v87, 1.0, v87
	v_rcp_f32_e32 v86, v86
	v_rcp_f32_e32 v87, v87
	v_lshlrev_b32_e32 v92, 16, v119
	v_and_b32_e32 v93, 0xffff0000, v119
	v_add_f32_e32 v84, 1.0, v90
	v_add_f32_e32 v85, 1.0, v91
	v_add_f32_e32 v82, 1.0, v82
	v_add_f32_e32 v83, 1.0, v83
	v_pk_mul_f32 v[92:93], v[202:203], v[92:93] op_sel_hi:[0,1]
	v_rcp_f32_e32 v84, v84
	v_rcp_f32_e32 v85, v85
	v_rcp_f32_e32 v82, v82
	v_rcp_f32_e32 v83, v83
	v_lshlrev_b32_e32 v96, 16, v120
	v_and_b32_e32 v97, 0xffff0000, v120
	v_lshlrev_b32_e32 v98, 16, v121
	v_and_b32_e32 v99, 0xffff0000, v121
	v_lshlrev_b32_e32 v102, 16, v115
	v_and_b32_e32 v103, 0xffff0000, v115
	v_pk_mul_f32 v[92:93], v[68:69], v[92:93]
	v_pk_mul_f32 v[90:91], v[202:203], v[98:99] op_sel_hi:[0,1]
	v_pk_fma_f32 v[86:87], v[86:87], v[92:93], v[102:103]
	v_pk_mul_f32 v[92:93], v[202:203], v[96:97] op_sel_hi:[0,1]
	v_lshlrev_b32_e32 v104, 16, v116
	v_and_b32_e32 v105, 0xffff0000, v116
	v_lshlrev_b32_e32 v106, 16, v117
	v_and_b32_e32 v107, 0xffff0000, v117
	v_pk_mul_f32 v[92:93], v[62:63], v[92:93]
	v_pk_mul_f32 v[90:91], v[64:65], v[90:91]
	v_pk_fma_f32 v[84:85], v[84:85], v[92:93], v[104:105]
	v_pk_fma_f32 v[90:91], v[82:83], v[90:91], v[106:107]
	v_cvt_pk_bf16_f32 v82, v88, v89
	v_cvt_pk_bf16_f32 v83, v86, v87
	v_cvt_pk_bf16_f32 v84, v84, v85
	v_cvt_pk_bf16_f32 v85, v90, v91
	global_store_dwordx4 v[94:95], v[82:85], off offset:256 sc1
	v_lshlrev_b64 v[118:119], 13, v[122:123]
	v_lshlrev_b32_e32 v86, 7, v122
	v_lshrrev_b64 v[84:85], 1, v[122:123]
	v_lshl_add_u64 v[82:83], s[8:9], 0, v[118:119]
	v_and_b32_e32 v85, 0x7fffffff, v85
	v_and_b32_e32 v84, 0xffffffc0, v84
	v_lshl_add_u64 v[82:83], v[82:83], 0, v[184:185]
	v_and_b32_e32 v170, 0x3f80, v86
	v_lshl_add_u64 v[88:89], v[84:85], 0, s[26:27]
	global_load_dwordx4 v[94:97], v[82:83], off
	global_load_dwordx4 v[102:105], v[82:83], off offset:256
	v_lshl_add_u64 v[86:87], v[192:193], 0, v[170:171]
	v_lshlrev_b64 v[88:89], 14, v[88:89]
	v_lshl_add_u64 v[88:89], v[86:87], 0, v[88:89]
	global_load_dwordx4 v[98:101], v[88:89], off
	v_lshl_add_u64 v[82:83], v[84:85], 0, s[28:29]
	v_lshlrev_b64 v[82:83], 14, v[82:83]
	v_lshl_add_u64 v[82:83], v[86:87], 0, v[82:83]
	global_load_dwordx4 v[106:109], v[82:83], off
	v_add_u32_e32 v88, 0x90, v190
	v_ashrrev_i32_e32 v89, 31, v88
	v_lshrrev_b64 v[84:85], 1, v[88:89]
	v_lshlrev_b64 v[92:93], 13, v[88:89]
	v_and_b32_e32 v85, 0x7fffffff, v85
	v_and_b32_e32 v84, 0xffffffc0, v84
	v_lshlrev_b32_e32 v86, 7, v88
	v_lshl_add_u64 v[82:83], s[8:9], 0, v[92:93]
	v_and_b32_e32 v170, 0x3f80, v86
	v_lshl_add_u64 v[86:87], v[84:85], 0, s[26:27]
	v_lshl_add_u64 v[114:115], v[192:193], 0, v[170:171]
	v_lshl_add_u64 v[82:83], v[82:83], 0, v[184:185]
	v_lshlrev_b64 v[86:87], 14, v[86:87]
	v_lshl_add_u64 v[116:117], v[114:115], 0, v[86:87]
	global_load_dwordx4 v[110:113], v[82:83], off
	global_load_dwordx4 v[86:89], v[82:83], off offset:256
	v_lshl_add_u64 v[82:83], v[84:85], 0, s[28:29]
	v_lshlrev_b64 v[82:83], 14, v[82:83]
	v_lshl_add_u64 v[82:83], v[114:115], 0, v[82:83]
	global_load_dwordx4 v[114:117], v[116:117], off
	s_nop 0
	global_load_dwordx4 v[82:85], v[82:83], off
	v_exp_f32_e32 v128, v70
	v_mul_f32_e32 v70, 0xbfb8aa3b, v71
	v_exp_f32_e32 v129, v70
	v_pk_mul_f32 v[70:71], v[72:73], v[200:201] op_sel_hi:[1,0]
	v_add_f32_e32 v72, 1.0, v128
	v_mul_f32_e32 v70, 0xbfb8aa3b, v70
	v_mul_f32_e32 v71, 0xbfb8aa3b, v71
	v_exp_f32_e32 v70, v70
	v_exp_f32_e32 v71, v71
	v_add_f32_e32 v73, 1.0, v129
	v_rcp_f32_e32 v72, v72
	v_add_f32_e32 v70, 1.0, v70
	v_add_f32_e32 v71, 1.0, v71
	v_rcp_f32_e32 v70, v70
	v_rcp_f32_e32 v71, v71
	v_rcp_f32_e32 v73, v73
	v_add_u32_e32 v90, 0xa0, v190
	v_ashrrev_i32_e32 v91, 31, v90
	v_mul_f32_e32 v26, 0xbfb8aa3b, v26
	v_pk_mul_f32 v[22:23], v[22:23], v[188:189] op_sel_hi:[1,0]
	v_pk_mul_f32 v[18:19], v[18:19], v[188:189] op_sel_hi:[1,0]
	v_mul_f32_e32 v22, 0xbfb8aa3b, v22
	v_mul_f32_e32 v18, 0xbfb8aa3b, v18
	v_pk_mul_f32 v[14:15], v[14:15], v[182:183] op_sel_hi:[1,0]
	v_pk_mul_f32 v[10:11], v[10:11], v[182:183] op_sel_hi:[1,0]
	v_mul_f32_e32 v14, 0xbfb8aa3b, v14
	v_mul_f32_e32 v10, 0xbfb8aa3b, v10
	v_pk_mul_f32 v[6:7], v[6:7], v[182:183] op_sel_hi:[1,0]
	v_pk_mul_f32 v[2:3], v[2:3], v[182:183] op_sel_hi:[1,0]
	v_mul_f32_e32 v6, 0xbfb8aa3b, v6
	v_mul_f32_e32 v2, 0xbfb8aa3b, v2
	s_waitcnt vmcnt(7)
	v_lshlrev_b32_e32 v120, 16, v94
	v_and_b32_e32 v121, 0xffff0000, v94
	v_lshlrev_b32_e32 v94, 16, v95
	v_and_b32_e32 v95, 0xffff0000, v95
	v_pk_mul_f32 v[94:95], v[198:199], v[94:95] op_sel_hi:[0,1]
	s_waitcnt vmcnt(5)
	v_lshlrev_b32_e32 v124, 16, v98
	v_and_b32_e32 v125, 0xffff0000, v98
	v_lshlrev_b32_e32 v98, 16, v99
	v_and_b32_e32 v99, 0xffff0000, v99
	v_pk_mul_f32 v[94:95], v[80:81], v[94:95]
	v_lshlrev_b32_e32 v122, 16, v96
	v_pk_fma_f32 v[70:71], v[70:71], v[94:95], v[98:99]
	v_exp_f32_e32 v94, v58
	v_mul_f32_e32 v58, 0xbfb8aa3b, v59
	v_exp_f32_e32 v95, v58
	v_pk_mul_f32 v[58:59], v[60:61], v[200:201] op_sel_hi:[1,0]
	v_add_f32_e32 v60, 1.0, v94
	v_mul_f32_e32 v58, 0xbfb8aa3b, v58
	v_mul_f32_e32 v59, 0xbfb8aa3b, v59
	v_exp_f32_e32 v58, v58
	v_exp_f32_e32 v59, v59
	v_add_f32_e32 v61, 1.0, v95
	v_rcp_f32_e32 v60, v60
	v_add_f32_e32 v58, 1.0, v58
	v_add_f32_e32 v59, 1.0, v59
	v_rcp_f32_e32 v61, v61
	v_rcp_f32_e32 v58, v58
	v_rcp_f32_e32 v59, v59
	v_and_b32_e32 v123, 0xffff0000, v96
	v_lshlrev_b32_e32 v96, 16, v97
	v_and_b32_e32 v97, 0xffff0000, v97
	v_pk_mul_f32 v[120:121], v[198:199], v[120:121] op_sel_hi:[0,1]
	v_pk_mul_f32 v[120:121], v[78:79], v[120:121]
	v_pk_mul_f32 v[94:95], v[198:199], v[96:97] op_sel_hi:[0,1]
	v_pk_mul_f32 v[96:97], v[198:199], v[122:123] op_sel_hi:[0,1]
	v_lshlrev_b32_e32 v126, 16, v100
	v_and_b32_e32 v127, 0xffff0000, v100
	v_lshlrev_b32_e32 v100, 16, v101
	v_and_b32_e32 v101, 0xffff0000, v101
	v_pk_fma_f32 v[72:73], v[72:73], v[120:121], v[124:125]
	v_pk_mul_f32 v[96:97], v[74:75], v[96:97]
	v_pk_mul_f32 v[94:95], v[76:77], v[94:95]
	v_pk_fma_f32 v[60:61], v[60:61], v[96:97], v[126:127]
	v_pk_fma_f32 v[94:95], v[58:59], v[94:95], v[100:101]
	v_cvt_pk_bf16_f32 v58, v72, v73
	v_lshlrev_b32_e32 v72, 16, v104
	v_and_b32_e32 v73, 0xffff0000, v104
	v_exp_f32_e32 v104, v54
	v_mul_f32_e32 v54, 0xbfb8aa3b, v55
	v_cvt_pk_bf16_f32 v60, v60, v61
	v_cvt_pk_bf16_f32 v61, v94, v95
	v_lshlrev_b32_e32 v94, 16, v105
	v_and_b32_e32 v95, 0xffff0000, v105
	v_exp_f32_e32 v105, v54
	v_cvt_pk_bf16_f32 v59, v70, v71
	v_lshl_add_u64 v[70:71], s[10:11], 0, v[118:119]
	v_pk_mul_f32 v[54:55], v[56:57], v[200:201] op_sel_hi:[1,0]
	v_add_f32_e32 v56, 1.0, v104
	v_add_f32_e32 v57, 1.0, v105
	v_lshl_add_u64 v[70:71], v[70:71], 0, v[184:185]
	v_rcp_f32_e32 v56, v56
	v_rcp_f32_e32 v57, v57
	global_store_dwordx4 v[70:71], v[58:61], off sc1
	s_waitcnt vmcnt(5)
	v_lshlrev_b32_e32 v96, 16, v106
	v_and_b32_e32 v97, 0xffff0000, v106
	v_lshlrev_b32_e32 v58, 16, v102
	v_and_b32_e32 v59, 0xffff0000, v102
	v_pk_mul_f32 v[58:59], v[198:199], v[58:59] op_sel_hi:[0,1]
	v_pk_mul_f32 v[58:59], v[66:67], v[58:59]
	v_mul_f32_e32 v54, 0xbfb8aa3b, v54
	v_mul_f32_e32 v55, 0xbfb8aa3b, v55
	v_pk_fma_f32 v[56:57], v[56:57], v[58:59], v[96:97]
	v_exp_f32_e32 v58, v50
	v_mul_f32_e32 v50, 0xbfb8aa3b, v51
	v_exp_f32_e32 v54, v54
	v_exp_f32_e32 v55, v55
	v_exp_f32_e32 v59, v50
	v_pk_mul_f32 v[50:51], v[52:53], v[200:201] op_sel_hi:[1,0]
	v_add_f32_e32 v54, 1.0, v54
	v_mul_f32_e32 v50, 0xbfb8aa3b, v50
	v_mul_f32_e32 v51, 0xbfb8aa3b, v51
	v_exp_f32_e32 v50, v50
	v_exp_f32_e32 v51, v51
	v_add_f32_e32 v55, 1.0, v55
	v_rcp_f32_e32 v54, v54
	v_rcp_f32_e32 v55, v55
	v_lshlrev_b32_e32 v60, 16, v103
	v_and_b32_e32 v61, 0xffff0000, v103
	v_add_f32_e32 v52, 1.0, v58
	v_add_f32_e32 v53, 1.0, v59
	v_add_f32_e32 v50, 1.0, v50
	v_add_f32_e32 v51, 1.0, v51
	v_pk_mul_f32 v[58:59], v[198:199], v[94:95] op_sel_hi:[0,1]
	v_exp_f32_e32 v94, v46
	v_mul_f32_e32 v46, 0xbfb8aa3b, v47
	v_pk_mul_f32 v[60:61], v[198:199], v[60:61] op_sel_hi:[0,1]
	v_rcp_f32_e32 v52, v52
	v_rcp_f32_e32 v53, v53
	v_rcp_f32_e32 v50, v50
	v_rcp_f32_e32 v51, v51
	v_exp_f32_e32 v95, v46
	v_lshlrev_b32_e32 v98, 16, v107
	v_and_b32_e32 v99, 0xffff0000, v107
	v_pk_mul_f32 v[60:61], v[68:69], v[60:61]
	v_lshlrev_b32_e32 v100, 16, v108
	v_pk_fma_f32 v[54:55], v[54:55], v[60:61], v[98:99]
	v_pk_mul_f32 v[60:61], v[198:199], v[72:73] op_sel_hi:[0,1]
	v_and_b32_e32 v101, 0xffff0000, v108
	v_lshlrev_b32_e32 v102, 16, v109
	v_and_b32_e32 v103, 0xffff0000, v109
	v_pk_mul_f32 v[60:61], v[62:63], v[60:61]
	v_pk_mul_f32 v[58:59], v[64:65], v[58:59]
	v_pk_fma_f32 v[52:53], v[52:53], v[60:61], v[100:101]
	v_pk_fma_f32 v[58:59], v[50:51], v[58:59], v[102:103]
	v_pk_mul_f32 v[46:47], v[48:49], v[196:197] op_sel_hi:[1,0]
	v_add_f32_e32 v48, 1.0, v94
	v_add_f32_e32 v49, 1.0, v95
	v_cvt_pk_bf16_f32 v50, v56, v57
	v_cvt_pk_bf16_f32 v51, v54, v55
	v_cvt_pk_bf16_f32 v52, v52, v53
	v_cvt_pk_bf16_f32 v53, v58, v59
	v_rcp_f32_e32 v48, v48
	v_rcp_f32_e32 v49, v49
	global_store_dwordx4 v[70:71], v[50:53], off offset:256 sc1
	v_mul_f32_e32 v46, 0xbfb8aa3b, v46
	v_mul_f32_e32 v47, 0xbfb8aa3b, v47
	s_waitcnt vmcnt(5)
	v_lshlrev_b32_e32 v50, 16, v110
	v_and_b32_e32 v51, 0xffff0000, v110
	v_exp_f32_e32 v46, v46
	v_exp_f32_e32 v47, v47
	v_pk_mul_f32 v[50:51], v[194:195], v[50:51] op_sel_hi:[0,1]
	s_waitcnt vmcnt(3)
	v_lshlrev_b32_e32 v58, 16, v114
	v_and_b32_e32 v59, 0xffff0000, v114
	v_pk_mul_f32 v[50:51], v[78:79], v[50:51]
	v_add_f32_e32 v46, 1.0, v46
	v_pk_fma_f32 v[48:49], v[48:49], v[50:51], v[58:59]
	v_exp_f32_e32 v50, v42
	v_mul_f32_e32 v42, 0xbfb8aa3b, v43
	v_exp_f32_e32 v51, v42
	v_pk_mul_f32 v[42:43], v[44:45], v[196:197] op_sel_hi:[1,0]
	v_add_f32_e32 v47, 1.0, v47
	v_mul_f32_e32 v42, 0xbfb8aa3b, v42
	v_mul_f32_e32 v43, 0xbfb8aa3b, v43
	v_rcp_f32_e32 v46, v46
	v_rcp_f32_e32 v47, v47
	v_exp_f32_e32 v42, v42
	v_exp_f32_e32 v43, v43
	v_lshlrev_b32_e32 v52, 16, v111
	v_and_b32_e32 v53, 0xffff0000, v111
	v_pk_mul_f32 v[52:53], v[194:195], v[52:53] op_sel_hi:[0,1]
	v_lshlrev_b32_e32 v60, 16, v115
	v_and_b32_e32 v61, 0xffff0000, v115
	v_pk_mul_f32 v[52:53], v[80:81], v[52:53]
	v_add_f32_e32 v44, 1.0, v50
	v_pk_fma_f32 v[46:47], v[46:47], v[52:53], v[60:61]
	v_add_f32_e32 v45, 1.0, v51
	v_add_f32_e32 v42, 1.0, v42
	v_add_f32_e32 v43, 1.0, v43
	v_exp_f32_e32 v60, v38
	v_mul_f32_e32 v38, 0xbfb8aa3b, v39
	v_rcp_f32_e32 v44, v44
	v_rcp_f32_e32 v45, v45
	v_rcp_f32_e32 v42, v42
	v_rcp_f32_e32 v43, v43
	v_exp_f32_e32 v61, v38
	v_lshlrev_b32_e32 v54, 16, v112
	v_and_b32_e32 v55, 0xffff0000, v112
	v_lshlrev_b32_e32 v56, 16, v113
	v_and_b32_e32 v57, 0xffff0000, v113
	v_pk_mul_f32 v[50:51], v[194:195], v[56:57] op_sel_hi:[0,1]
	v_pk_mul_f32 v[52:53], v[194:195], v[54:55] op_sel_hi:[0,1]
	v_lshlrev_b32_e32 v70, 16, v116
	v_and_b32_e32 v71, 0xffff0000, v116
	v_lshlrev_b32_e32 v72, 16, v117
	v_and_b32_e32 v73, 0xffff0000, v117
	v_pk_mul_f32 v[52:53], v[74:75], v[52:53]
	v_pk_mul_f32 v[50:51], v[76:77], v[50:51]
	v_pk_fma_f32 v[44:45], v[44:45], v[52:53], v[70:71]
	v_pk_fma_f32 v[50:51], v[42:43], v[50:51], v[72:73]
	v_cvt_pk_bf16_f32 v43, v46, v47
	v_lshl_add_u64 v[46:47], s[10:11], 0, v[92:93]
	v_pk_mul_f32 v[38:39], v[40:41], v[196:197] op_sel_hi:[1,0]
	v_add_f32_e32 v40, 1.0, v60
	v_add_f32_e32 v41, 1.0, v61
	v_cvt_pk_bf16_f32 v42, v48, v49
	v_cvt_pk_bf16_f32 v44, v44, v45
	v_cvt_pk_bf16_f32 v45, v50, v51
	v_lshl_add_u64 v[46:47], v[46:47], 0, v[184:185]
	v_rcp_f32_e32 v40, v40
	v_rcp_f32_e32 v41, v41
	global_store_dwordx4 v[46:47], v[42:45], off sc1
	s_waitcnt vmcnt(3)
	v_lshlrev_b32_e32 v52, 16, v82
	v_and_b32_e32 v53, 0xffff0000, v82
	v_lshlrev_b32_e32 v42, 16, v86
	v_and_b32_e32 v43, 0xffff0000, v86
	v_pk_mul_f32 v[42:43], v[194:195], v[42:43] op_sel_hi:[0,1]
	v_pk_mul_f32 v[42:43], v[66:67], v[42:43]
	v_mul_f32_e32 v38, 0xbfb8aa3b, v38
	v_mul_f32_e32 v39, 0xbfb8aa3b, v39
	v_pk_fma_f32 v[40:41], v[40:41], v[42:43], v[52:53]
	v_exp_f32_e32 v42, v34
	v_mul_f32_e32 v34, 0xbfb8aa3b, v35
	v_exp_f32_e32 v38, v38
	v_exp_f32_e32 v39, v39
	v_exp_f32_e32 v43, v34
	v_pk_mul_f32 v[34:35], v[36:37], v[196:197] op_sel_hi:[1,0]
	v_add_f32_e32 v38, 1.0, v38
	v_mul_f32_e32 v34, 0xbfb8aa3b, v34
	v_mul_f32_e32 v35, 0xbfb8aa3b, v35
	v_exp_f32_e32 v34, v34
	v_exp_f32_e32 v35, v35
	v_add_f32_e32 v39, 1.0, v39
	v_rcp_f32_e32 v38, v38
	v_rcp_f32_e32 v39, v39
	v_lshlrev_b32_e32 v44, 16, v87
	v_and_b32_e32 v45, 0xffff0000, v87
	v_add_f32_e32 v36, 1.0, v42
	v_add_f32_e32 v37, 1.0, v43
	v_add_f32_e32 v34, 1.0, v34
	v_add_f32_e32 v35, 1.0, v35
	v_pk_mul_f32 v[44:45], v[194:195], v[44:45] op_sel_hi:[0,1]
	v_rcp_f32_e32 v36, v36
	v_rcp_f32_e32 v37, v37
	v_rcp_f32_e32 v34, v34
	v_rcp_f32_e32 v35, v35
	v_lshlrev_b32_e32 v48, 16, v88
	v_and_b32_e32 v49, 0xffff0000, v88
	v_lshlrev_b32_e32 v50, 16, v89
	v_and_b32_e32 v51, 0xffff0000, v89
	v_lshlrev_b32_e32 v54, 16, v83
	v_and_b32_e32 v55, 0xffff0000, v83
	v_pk_mul_f32 v[44:45], v[68:69], v[44:45]
	v_pk_mul_f32 v[42:43], v[194:195], v[50:51] op_sel_hi:[0,1]
	v_pk_fma_f32 v[38:39], v[38:39], v[44:45], v[54:55]
	v_pk_mul_f32 v[44:45], v[194:195], v[48:49] op_sel_hi:[0,1]
	v_lshlrev_b32_e32 v56, 16, v84
	v_and_b32_e32 v57, 0xffff0000, v84
	v_lshlrev_b32_e32 v58, 16, v85
	v_and_b32_e32 v59, 0xffff0000, v85
	v_pk_mul_f32 v[44:45], v[62:63], v[44:45]
	v_pk_mul_f32 v[42:43], v[64:65], v[42:43]
	v_pk_fma_f32 v[36:37], v[36:37], v[44:45], v[56:57]
	v_pk_fma_f32 v[42:43], v[34:35], v[42:43], v[58:59]
	v_cvt_pk_bf16_f32 v34, v40, v41
	v_cvt_pk_bf16_f32 v35, v38, v39
	v_cvt_pk_bf16_f32 v36, v36, v37
	v_cvt_pk_bf16_f32 v37, v42, v43
	global_store_dwordx4 v[46:47], v[34:37], off offset:256 sc1
	v_lshlrev_b64 v[60:61], 13, v[90:91]
	v_lshlrev_b32_e32 v38, 7, v90
	v_lshrrev_b64 v[36:37], 1, v[90:91]
	v_lshl_add_u64 v[34:35], s[8:9], 0, v[60:61]
	v_and_b32_e32 v37, 0x7fffffff, v37
	v_and_b32_e32 v36, 0xffffffc0, v36
	v_lshl_add_u64 v[34:35], v[34:35], 0, v[184:185]
	v_and_b32_e32 v170, 0x3f80, v38
	v_lshl_add_u64 v[40:41], v[36:37], 0, s[26:27]
	global_load_dwordx4 v[44:47], v[34:35], off
	global_load_dwordx4 v[52:55], v[34:35], off offset:256
	v_lshl_add_u64 v[38:39], v[192:193], 0, v[170:171]
	v_lshlrev_b64 v[40:41], 14, v[40:41]
	v_lshl_add_u64 v[40:41], v[38:39], 0, v[40:41]
	global_load_dwordx4 v[48:51], v[40:41], off
	v_lshl_add_u64 v[34:35], v[36:37], 0, s[28:29]
	v_lshlrev_b64 v[34:35], 14, v[34:35]
	v_lshl_add_u64 v[34:35], v[38:39], 0, v[34:35]
	global_load_dwordx4 v[56:59], v[34:35], off
	v_add_u32_e32 v40, 0xb0, v190
	v_ashrrev_i32_e32 v41, 31, v40
	v_lshrrev_b64 v[36:37], 1, v[40:41]
	v_lshlrev_b64 v[42:43], 13, v[40:41]
	v_and_b32_e32 v37, 0x7fffffff, v37
	v_and_b32_e32 v36, 0xffffffc0, v36
	v_lshlrev_b32_e32 v38, 7, v40
	v_lshl_add_u64 v[34:35], s[8:9], 0, v[42:43]
	v_and_b32_e32 v170, 0x3f80, v38
	v_lshl_add_u64 v[38:39], v[36:37], 0, s[26:27]
	v_lshl_add_u64 v[82:83], v[192:193], 0, v[170:171]
	v_lshl_add_u64 v[34:35], v[34:35], 0, v[184:185]
	v_lshlrev_b64 v[38:39], 14, v[38:39]
	v_lshl_add_u64 v[84:85], v[82:83], 0, v[38:39]
	global_load_dwordx4 v[70:73], v[34:35], off
	global_load_dwordx4 v[38:41], v[34:35], off offset:256
	v_lshl_add_u64 v[34:35], v[36:37], 0, s[28:29]
	v_lshlrev_b64 v[34:35], 14, v[34:35]
	v_lshl_add_u64 v[34:35], v[82:83], 0, v[34:35]
	global_load_dwordx4 v[82:85], v[84:85], off
	s_nop 0
	global_load_dwordx4 v[34:37], v[34:35], off
	v_exp_f32_e32 v94, v30
	v_mul_f32_e32 v30, 0xbfb8aa3b, v31
	v_exp_f32_e32 v95, v30
	v_pk_mul_f32 v[30:31], v[32:33], v[188:189] op_sel_hi:[1,0]
	v_add_f32_e32 v32, 1.0, v94
	v_mul_f32_e32 v30, 0xbfb8aa3b, v30
	v_mul_f32_e32 v31, 0xbfb8aa3b, v31
	v_exp_f32_e32 v30, v30
	v_exp_f32_e32 v31, v31
	v_add_f32_e32 v33, 1.0, v95
	v_rcp_f32_e32 v32, v32
	v_add_f32_e32 v30, 1.0, v30
	v_add_f32_e32 v31, 1.0, v31
	v_rcp_f32_e32 v30, v30
	v_rcp_f32_e32 v31, v31
	v_rcp_f32_e32 v33, v33
	s_waitcnt vmcnt(7)
	v_lshlrev_b32_e32 v86, 16, v44
	v_and_b32_e32 v87, 0xffff0000, v44
	v_lshlrev_b32_e32 v44, 16, v45
	v_and_b32_e32 v45, 0xffff0000, v45
	v_pk_mul_f32 v[44:45], v[186:187], v[44:45] op_sel_hi:[0,1]
	s_waitcnt vmcnt(5)
	v_lshlrev_b32_e32 v90, 16, v48
	v_and_b32_e32 v91, 0xffff0000, v48
	v_lshlrev_b32_e32 v48, 16, v49
	v_and_b32_e32 v49, 0xffff0000, v49
	v_pk_mul_f32 v[44:45], v[80:81], v[44:45]
	v_lshlrev_b32_e32 v88, 16, v46
	v_pk_fma_f32 v[30:31], v[30:31], v[44:45], v[48:49]
	v_exp_f32_e32 v44, v26
	v_mul_f32_e32 v26, 0xbfb8aa3b, v27
	v_exp_f32_e32 v45, v26
	v_pk_mul_f32 v[26:27], v[28:29], v[188:189] op_sel_hi:[1,0]
	v_add_f32_e32 v28, 1.0, v44
	v_mul_f32_e32 v26, 0xbfb8aa3b, v26
	v_mul_f32_e32 v27, 0xbfb8aa3b, v27
	v_exp_f32_e32 v26, v26
	v_exp_f32_e32 v27, v27
	v_add_f32_e32 v29, 1.0, v45
	v_rcp_f32_e32 v28, v28
	v_add_f32_e32 v26, 1.0, v26
	v_add_f32_e32 v27, 1.0, v27
	v_rcp_f32_e32 v29, v29
	v_rcp_f32_e32 v26, v26
	v_rcp_f32_e32 v27, v27
	v_and_b32_e32 v89, 0xffff0000, v46
	v_lshlrev_b32_e32 v46, 16, v47
	v_and_b32_e32 v47, 0xffff0000, v47
	v_pk_mul_f32 v[86:87], v[186:187], v[86:87] op_sel_hi:[0,1]
	v_pk_mul_f32 v[86:87], v[78:79], v[86:87]
	v_pk_mul_f32 v[44:45], v[186:187], v[46:47] op_sel_hi:[0,1]
	v_pk_mul_f32 v[46:47], v[186:187], v[88:89] op_sel_hi:[0,1]
	v_lshlrev_b32_e32 v92, 16, v50
	v_and_b32_e32 v93, 0xffff0000, v50
	v_lshlrev_b32_e32 v50, 16, v51
	v_and_b32_e32 v51, 0xffff0000, v51
	v_pk_fma_f32 v[32:33], v[32:33], v[86:87], v[90:91]
	v_pk_mul_f32 v[46:47], v[74:75], v[46:47]
	v_pk_mul_f32 v[44:45], v[76:77], v[44:45]
	v_pk_fma_f32 v[28:29], v[28:29], v[46:47], v[92:93]
	v_pk_fma_f32 v[44:45], v[26:27], v[44:45], v[50:51]
	v_cvt_pk_bf16_f32 v26, v32, v33
	v_lshlrev_b32_e32 v32, 16, v54
	v_and_b32_e32 v33, 0xffff0000, v54
	v_exp_f32_e32 v54, v22
	v_mul_f32_e32 v22, 0xbfb8aa3b, v23
	v_cvt_pk_bf16_f32 v28, v28, v29
	v_cvt_pk_bf16_f32 v29, v44, v45
	v_lshlrev_b32_e32 v44, 16, v55
	v_and_b32_e32 v45, 0xffff0000, v55
	v_exp_f32_e32 v55, v22
	v_cvt_pk_bf16_f32 v27, v30, v31
	v_lshl_add_u64 v[30:31], s[10:11], 0, v[60:61]
	v_pk_mul_f32 v[22:23], v[24:25], v[188:189] op_sel_hi:[1,0]
	v_add_f32_e32 v24, 1.0, v54
	v_add_f32_e32 v25, 1.0, v55
	v_lshl_add_u64 v[30:31], v[30:31], 0, v[184:185]
	v_rcp_f32_e32 v24, v24
	v_rcp_f32_e32 v25, v25
	global_store_dwordx4 v[30:31], v[26:29], off sc1
	s_waitcnt vmcnt(5)
	v_lshlrev_b32_e32 v46, 16, v56
	v_and_b32_e32 v47, 0xffff0000, v56
	v_lshlrev_b32_e32 v26, 16, v52
	v_and_b32_e32 v27, 0xffff0000, v52
	v_pk_mul_f32 v[26:27], v[186:187], v[26:27] op_sel_hi:[0,1]
	v_pk_mul_f32 v[26:27], v[66:67], v[26:27]
	v_mul_f32_e32 v22, 0xbfb8aa3b, v22
	v_mul_f32_e32 v23, 0xbfb8aa3b, v23
	v_pk_fma_f32 v[24:25], v[24:25], v[26:27], v[46:47]
	v_exp_f32_e32 v26, v18
	v_mul_f32_e32 v18, 0xbfb8aa3b, v19
	v_exp_f32_e32 v22, v22
	v_exp_f32_e32 v23, v23
	v_exp_f32_e32 v27, v18
	v_pk_mul_f32 v[18:19], v[20:21], v[188:189] op_sel_hi:[1,0]
	v_add_f32_e32 v22, 1.0, v22
	v_mul_f32_e32 v18, 0xbfb8aa3b, v18
	v_mul_f32_e32 v19, 0xbfb8aa3b, v19
	v_exp_f32_e32 v18, v18
	v_exp_f32_e32 v19, v19
	v_add_f32_e32 v23, 1.0, v23
	v_rcp_f32_e32 v22, v22
	v_rcp_f32_e32 v23, v23
	v_lshlrev_b32_e32 v28, 16, v53
	v_and_b32_e32 v29, 0xffff0000, v53
	v_add_f32_e32 v20, 1.0, v26
	v_add_f32_e32 v21, 1.0, v27
	v_add_f32_e32 v18, 1.0, v18
	v_add_f32_e32 v19, 1.0, v19
	v_pk_mul_f32 v[26:27], v[186:187], v[44:45] op_sel_hi:[0,1]
	v_exp_f32_e32 v44, v14
	v_mul_f32_e32 v14, 0xbfb8aa3b, v15
	v_pk_mul_f32 v[28:29], v[186:187], v[28:29] op_sel_hi:[0,1]
	v_rcp_f32_e32 v20, v20
	v_rcp_f32_e32 v21, v21
	v_rcp_f32_e32 v18, v18
	v_rcp_f32_e32 v19, v19
	v_exp_f32_e32 v45, v14
	v_lshlrev_b32_e32 v48, 16, v57
	v_and_b32_e32 v49, 0xffff0000, v57
	v_pk_mul_f32 v[28:29], v[68:69], v[28:29]
	v_lshlrev_b32_e32 v50, 16, v58
	v_pk_fma_f32 v[22:23], v[22:23], v[28:29], v[48:49]
	v_pk_mul_f32 v[28:29], v[186:187], v[32:33] op_sel_hi:[0,1]
	v_and_b32_e32 v51, 0xffff0000, v58
	v_lshlrev_b32_e32 v52, 16, v59
	v_and_b32_e32 v53, 0xffff0000, v59
	v_pk_mul_f32 v[28:29], v[62:63], v[28:29]
	v_pk_mul_f32 v[26:27], v[64:65], v[26:27]
	v_pk_fma_f32 v[20:21], v[20:21], v[28:29], v[50:51]
	v_pk_fma_f32 v[26:27], v[18:19], v[26:27], v[52:53]
	v_pk_mul_f32 v[14:15], v[16:17], v[182:183] op_sel_hi:[1,0]
	v_add_f32_e32 v16, 1.0, v44
	v_add_f32_e32 v17, 1.0, v45
	v_cvt_pk_bf16_f32 v18, v24, v25
	v_cvt_pk_bf16_f32 v19, v22, v23
	v_cvt_pk_bf16_f32 v20, v20, v21
	v_cvt_pk_bf16_f32 v21, v26, v27
	v_rcp_f32_e32 v16, v16
	v_rcp_f32_e32 v17, v17
	global_store_dwordx4 v[30:31], v[18:21], off offset:256 sc1
	v_mul_f32_e32 v14, 0xbfb8aa3b, v14
	v_mul_f32_e32 v15, 0xbfb8aa3b, v15
	s_waitcnt vmcnt(5)
	v_lshlrev_b32_e32 v18, 16, v70
	v_and_b32_e32 v19, 0xffff0000, v70
	v_exp_f32_e32 v14, v14
	v_exp_f32_e32 v15, v15
	v_pk_mul_f32 v[18:19], v[180:181], v[18:19] op_sel_hi:[0,1]
	s_waitcnt vmcnt(3)
	v_lshlrev_b32_e32 v26, 16, v82
	v_and_b32_e32 v27, 0xffff0000, v82
	v_pk_mul_f32 v[18:19], v[78:79], v[18:19]
	v_add_f32_e32 v14, 1.0, v14
	v_pk_fma_f32 v[16:17], v[16:17], v[18:19], v[26:27]
	v_exp_f32_e32 v18, v10
	v_mul_f32_e32 v10, 0xbfb8aa3b, v11
	v_exp_f32_e32 v19, v10
	v_pk_mul_f32 v[10:11], v[12:13], v[182:183] op_sel_hi:[1,0]
	v_add_f32_e32 v15, 1.0, v15
	v_mul_f32_e32 v10, 0xbfb8aa3b, v10
	v_mul_f32_e32 v11, 0xbfb8aa3b, v11
	v_rcp_f32_e32 v14, v14
	v_rcp_f32_e32 v15, v15
	v_exp_f32_e32 v10, v10
	v_exp_f32_e32 v11, v11
	v_lshlrev_b32_e32 v20, 16, v71
	v_and_b32_e32 v21, 0xffff0000, v71
	v_pk_mul_f32 v[20:21], v[180:181], v[20:21] op_sel_hi:[0,1]
	v_lshlrev_b32_e32 v28, 16, v83
	v_and_b32_e32 v29, 0xffff0000, v83
	v_pk_mul_f32 v[20:21], v[80:81], v[20:21]
	v_add_f32_e32 v12, 1.0, v18
	v_pk_fma_f32 v[14:15], v[14:15], v[20:21], v[28:29]
	v_add_f32_e32 v13, 1.0, v19
	v_add_f32_e32 v10, 1.0, v10
	v_add_f32_e32 v11, 1.0, v11
	v_exp_f32_e32 v28, v6
	v_mul_f32_e32 v6, 0xbfb8aa3b, v7
	v_rcp_f32_e32 v12, v12
	v_rcp_f32_e32 v13, v13
	v_rcp_f32_e32 v10, v10
	v_rcp_f32_e32 v11, v11
	v_exp_f32_e32 v29, v6
	v_lshlrev_b32_e32 v22, 16, v72
	v_and_b32_e32 v23, 0xffff0000, v72
	v_lshlrev_b32_e32 v24, 16, v73
	v_and_b32_e32 v25, 0xffff0000, v73
	v_pk_mul_f32 v[18:19], v[180:181], v[24:25] op_sel_hi:[0,1]
	v_pk_mul_f32 v[20:21], v[180:181], v[22:23] op_sel_hi:[0,1]
	v_lshlrev_b32_e32 v30, 16, v84
	v_and_b32_e32 v31, 0xffff0000, v84
	v_lshlrev_b32_e32 v32, 16, v85
	v_and_b32_e32 v33, 0xffff0000, v85
	v_pk_mul_f32 v[20:21], v[74:75], v[20:21]
	v_pk_mul_f32 v[18:19], v[76:77], v[18:19]
	v_pk_fma_f32 v[12:13], v[12:13], v[20:21], v[30:31]
	v_pk_fma_f32 v[18:19], v[10:11], v[18:19], v[32:33]
	v_cvt_pk_bf16_f32 v11, v14, v15
	v_lshl_add_u64 v[14:15], s[10:11], 0, v[42:43]
	v_pk_mul_f32 v[6:7], v[8:9], v[182:183] op_sel_hi:[1,0]
	v_add_f32_e32 v8, 1.0, v28
	v_add_f32_e32 v9, 1.0, v29
	v_cvt_pk_bf16_f32 v10, v16, v17
	v_cvt_pk_bf16_f32 v12, v12, v13
	v_cvt_pk_bf16_f32 v13, v18, v19
	v_lshl_add_u64 v[14:15], v[14:15], 0, v[184:185]
	v_rcp_f32_e32 v8, v8
	v_rcp_f32_e32 v9, v9
	global_store_dwordx4 v[14:15], v[10:13], off sc1
	s_waitcnt vmcnt(3)
	v_lshlrev_b32_e32 v20, 16, v34
	v_and_b32_e32 v21, 0xffff0000, v34
	v_lshlrev_b32_e32 v10, 16, v38
	v_and_b32_e32 v11, 0xffff0000, v38
	v_pk_mul_f32 v[10:11], v[180:181], v[10:11] op_sel_hi:[0,1]
	v_pk_mul_f32 v[10:11], v[66:67], v[10:11]
	v_mul_f32_e32 v6, 0xbfb8aa3b, v6
	v_mul_f32_e32 v7, 0xbfb8aa3b, v7
	v_pk_fma_f32 v[8:9], v[8:9], v[10:11], v[20:21]
	v_exp_f32_e32 v10, v2
	v_mul_f32_e32 v2, 0xbfb8aa3b, v3
	v_exp_f32_e32 v6, v6
	v_exp_f32_e32 v7, v7
	v_exp_f32_e32 v11, v2
	v_pk_mul_f32 v[2:3], v[4:5], v[182:183] op_sel_hi:[1,0]
	v_add_f32_e32 v6, 1.0, v6
	v_mul_f32_e32 v2, 0xbfb8aa3b, v2
	v_mul_f32_e32 v3, 0xbfb8aa3b, v3
	v_exp_f32_e32 v2, v2
	v_exp_f32_e32 v3, v3
	v_add_f32_e32 v7, 1.0, v7
	v_rcp_f32_e32 v6, v6
	v_rcp_f32_e32 v7, v7
	v_lshlrev_b32_e32 v12, 16, v39
	v_and_b32_e32 v13, 0xffff0000, v39
	v_add_f32_e32 v4, 1.0, v10
	v_add_f32_e32 v5, 1.0, v11
	v_add_f32_e32 v2, 1.0, v2
	v_add_f32_e32 v3, 1.0, v3
	v_pk_mul_f32 v[12:13], v[180:181], v[12:13] op_sel_hi:[0,1]
	v_rcp_f32_e32 v4, v4
	v_rcp_f32_e32 v5, v5
	v_rcp_f32_e32 v2, v2
	v_rcp_f32_e32 v3, v3
	v_lshlrev_b32_e32 v16, 16, v40
	v_and_b32_e32 v17, 0xffff0000, v40
	v_lshlrev_b32_e32 v18, 16, v41
	v_and_b32_e32 v19, 0xffff0000, v41
	v_lshlrev_b32_e32 v22, 16, v35
	v_and_b32_e32 v23, 0xffff0000, v35
	v_pk_mul_f32 v[12:13], v[68:69], v[12:13]
	v_pk_mul_f32 v[10:11], v[180:181], v[18:19] op_sel_hi:[0,1]
	v_pk_fma_f32 v[6:7], v[6:7], v[12:13], v[22:23]
	v_pk_mul_f32 v[12:13], v[180:181], v[16:17] op_sel_hi:[0,1]
	v_lshlrev_b32_e32 v24, 16, v36
	v_and_b32_e32 v25, 0xffff0000, v36
	v_lshlrev_b32_e32 v26, 16, v37
	v_and_b32_e32 v27, 0xffff0000, v37
	v_pk_mul_f32 v[12:13], v[62:63], v[12:13]
	v_pk_mul_f32 v[10:11], v[64:65], v[10:11]
	v_pk_fma_f32 v[4:5], v[4:5], v[12:13], v[24:25]
	v_pk_fma_f32 v[10:11], v[2:3], v[10:11], v[26:27]
	v_cvt_pk_bf16_f32 v2, v8, v9
	v_cvt_pk_bf16_f32 v3, v6, v7
	v_cvt_pk_bf16_f32 v4, v4, v5
	v_cvt_pk_bf16_f32 v5, v10, v11
	global_store_dwordx4 v[14:15], v[2:5], off offset:256 sc1
	s_branch .Lwtp15_join
